# speedup vs baseline: 1.0208x; 1.0142x over previous
.LBB0_109:
	s_lshl_b32 s62, s86, 3
	v_cvt_f32_u32_e32 v2, s62
	s_sub_i32 s65, 0, s62
	s_abs_i32 s63, s85
	s_ashr_i32 s64, s85, 31
	v_rcp_iflag_f32_e32 v2, v2
	v_bfe_i32 v5, v171, 27, 1
	v_lshlrev_b32_e32 v169, 4, v171
	v_lshrrev_b32_e32 v5, 22, v5
	v_mul_f32_e32 v2, 0x4f7ffffe, v2
	v_cvt_u32_f32_e32 v2, v2
	v_add_u32_e32 v5, v169, v5
	v_and_b32_e32 v5, 0xfffffc00, v5
	v_sub_u32_e32 v5, v169, v5
	v_readfirstlane_b32 s68, v2
	s_mul_i32 s65, s65, s68
	s_mul_hi_u32 s65, s68, s65
	s_add_i32 s68, s68, s65
	s_mul_hi_u32 s65, s63, s68
	s_mul_i32 s68, s65, s62
	s_sub_i32 s63, s63, s68
	s_add_i32 s69, s65, 1
	s_sub_i32 s68, s63, s62
	s_cmp_ge_u32 s63, s62
	s_cselect_b32 s65, s69, s65
	s_cselect_b32 s63, s68, s63
	s_add_i32 s68, s65, 1
	s_cmp_ge_u32 s63, s62
	s_cselect_b32 s63, s68, s65
	s_xor_b32 s65, s63, s64
	s_sub_i32 s70, s65, s64
	v_lshrrev_b32_e32 v6, 4, v5
	s_mul_i32 s62, s70, s62
	v_bitop3_b32 v5, v6, v5, 32 bitop3:0x6c
	s_sub_i32 s62, s85, s62
	v_ashrrev_i32_e32 v6, 31, v5
	s_ashr_i32 s89, s62, 3
	s_lshl_b32 s62, s62, 8
	v_lshrrev_b32_e32 v6, 26, v6
	s_and_b32 s71, s62, 0x700
	s_lshl_b32 s62, s89, 8
	v_ashrrev_i32_e32 v2, 31, v171
	v_add_u32_e32 v6, v5, v6
	v_lshrrev_b32_e32 v2, 26, v2
	v_ashrrev_i32_e32 v133, 6, v6
	v_and_b32_e32 v6, 0xc0, v6
	s_ashr_i32 s63, s62, 31
	v_and_b32_e32 v3, 15, v0
	v_and_b32_e32 v4, 48, v0
	v_add_u32_e32 v2, v171, v2
	v_sub_u32_e32 v5, v5, v6
	v_and_b32_e32 v6, 32, v0
	v_lshlrev_b32_e32 v10, 2, v0
	s_lshl_b64 s[72:73], s[62:63], 6
	v_lshlrev_b32_e32 v0, 6, v0
	s_lshl_b32 s63, s65, 11
	v_ashrrev_i32_e32 v131, 6, v2
	v_lshlrev_b32_e32 v3, 6, v3
	v_and_b32_e32 v10, 32, v10
	v_and_b32_e32 v0, 0x3c0, v0
	s_or_b32 s63, s63, s71
	s_lshl_b32 s64, s64, 11
	v_or_b32_e32 v9, v3, v4
	v_bitop3_b32 v3, v3, v10, v4 bitop3:0x36
	v_bitop3_b32 v4, v0, v10, v4 bitop3:0x36
	s_sub_i32 s64, s63, s64
	v_lshlrev_b32_e32 v0, 15, v131
	s_ashr_i32 s65, s64, 31
	v_and_b32_e32 v0, 0xffff0000, v0
	v_ashrrev_i16_sdwa v5, v167, sext(v5) dst_sel:DWORD dst_unused:UNUSED_PAD src0_sel:DWORD src1_sel:BYTE_0
	s_lshl_b64 s[64:65], s[64:65], 12
	v_lshl_add_u32 v0, v133, 12, v0
	v_bfe_i32 v134, v5, 0, 16
	v_and_or_b32 v0, v2, 64, v0
	s_add_u32 s64, s54, s64
	s_waitcnt vmcnt(0)
	v_lshl_add_u32 v164, v134, 1, v0
	s_addc_u32 s65, s55, s65
	v_lshlrev_b32_e32 v14, 13, v1
	v_lshl_add_u64 v[0:1], s[64:65], 0, v[164:165]
	s_mul_i32 s64, s4, 0x1800
	s_mul_hi_u32 s63, s4, 0x1800
	s_add_u32 s64, s64, s72
	s_addc_u32 s63, s63, s73
	s_add_u32 s64, s66, s64
	v_bfe_i32 v7, v171, 6, 1
	s_addc_u32 s65, s67, s63
	s_lshl_b64 s[68:69], s[4:5], 12
	v_and_b32_e32 v7, s4, v7
	v_lshrrev_b32_e32 v8, 7, v171
	s_add_u32 s4, s68, s72
	v_add_lshl_u32 v7, v7, v8, 10
	v_lshlrev_b32_e32 v8, 6, v171
	s_addc_u32 s63, s69, s73
	v_and_b32_e32 v5, 0x3f0, v169
	v_and_b32_e32 v8, 0x3000, v8
	v_bitop3_b32 v11, v9, s77, v10 bitop3:0xde
	v_bitop3_b32 v12, v9, s78, v10 bitop3:0xde
	v_bitop3_b32 v13, v9, s79, v10 bitop3:0xde
	v_bitop3_b32 v9, v9, s80, v10 bitop3:0xde
	v_or_b32_e32 v10, 0x800, v14
	v_or_b32_e32 v15, 0x1000, v14
	s_waitcnt vmcnt(0)
	v_or_b32_e32 v16, 0x1800, v14
	v_lshl_add_u64 v[128:129], v[0:1], 0, s[20:21]
	s_add_u32 s66, s66, s4
	v_mov_b32_e32 v0, 0
	v_bitop3_b32 v164, v5, v7, v6 bitop3:0xde
	s_addc_u32 s67, s67, s63
	s_mov_b32 s4, -2
	v_add_u32_e32 v138, v11, v8
	v_add_u32_e32 v192, v3, v14
	v_add_u32_e32 v191, v4, v10
	v_add_u32_e32 v190, v4, v15
	v_add_u32_e32 v189, v4, v16
	v_add_u32_e32 v137, 0xc000, v169
	v_add_u32_e32 v136, 0xe000, v169
	v_add_u32_e32 v135, v12, v8
	v_add_u32_e32 v188, 0x10000, v169
	v_add_u32_e32 v187, 0x12000, v169
	v_add_u32_e32 v186, 0x2000, v169
	v_add_u32_e32 v185, 0x14000, v169
	v_add_u32_e32 v184, 0x16000, v169
	v_add_u32_e32 v130, v13, v8
	v_add_u32_e32 v183, 0x4000, v169
	v_add_u32_e32 v182, 0x6000, v169
	v_add_u32_e32 v132, v9, v8
	v_add_u32_e32 v181, 0x18000, v169
	v_add_u32_e32 v180, 0x1a000, v169
	v_add_u32_e32 v179, 0x8000, v169
	v_add_u32_e32 v177, 0xa000, v169
	v_add_u32_e32 v175, 0x1c000, v169
	v_add_u32_e32 v173, 0x1e000, v169
	v_mov_b32_e32 v1, v0
	v_mov_b32_e32 v2, v0
	v_mov_b32_e32 v3, v0
	v_mov_b32_e32 v4, v0
	v_mov_b32_e32 v5, v0
	v_mov_b32_e32 v6, v0
	v_mov_b32_e32 v7, v0
	v_mov_b32_e32 v8, v0
	v_mov_b32_e32 v9, v0
	v_mov_b32_e32 v10, v0
	v_mov_b32_e32 v11, v0
	v_mov_b32_e32 v12, v0
	v_mov_b32_e32 v13, v0
	v_mov_b32_e32 v14, v0
	v_mov_b32_e32 v15, v0
	v_mov_b32_e32 v16, v0
	v_mov_b32_e32 v17, v0
	v_mov_b32_e32 v18, v0
	v_mov_b32_e32 v19, v0
	v_mov_b32_e32 v20, v0
	v_mov_b32_e32 v21, v0
	v_mov_b32_e32 v22, v0
	v_mov_b32_e32 v23, v0
	v_mov_b32_e32 v24, v0
	v_mov_b32_e32 v25, v0
	v_mov_b32_e32 v26, v0
	v_mov_b32_e32 v27, v0
	v_mov_b32_e32 v28, v0
	v_mov_b32_e32 v29, v0
	v_mov_b32_e32 v30, v0
	v_mov_b32_e32 v31, v0
	v_mov_b32_e32 v32, v0
	v_mov_b32_e32 v33, v0
	v_mov_b32_e32 v34, v0
	v_mov_b32_e32 v35, v0
	v_mov_b32_e32 v36, v0
	v_mov_b32_e32 v37, v0
	v_mov_b32_e32 v38, v0
	v_mov_b32_e32 v39, v0
	v_mov_b32_e32 v40, v0
	v_mov_b32_e32 v41, v0
	v_mov_b32_e32 v42, v0
	v_mov_b32_e32 v43, v0
	v_mov_b32_e32 v44, v0
	v_mov_b32_e32 v45, v0
	v_mov_b32_e32 v46, v0
	v_mov_b32_e32 v47, v0
	v_mov_b32_e32 v48, v0
	v_mov_b32_e32 v49, v0
	v_mov_b32_e32 v50, v0
	v_mov_b32_e32 v51, v0
	v_mov_b32_e32 v52, v0
	v_mov_b32_e32 v53, v0
	v_mov_b32_e32 v54, v0
	v_mov_b32_e32 v55, v0
	v_mov_b32_e32 v56, v0
	v_mov_b32_e32 v57, v0
	v_mov_b32_e32 v58, v0
	v_mov_b32_e32 v59, v0
	v_mov_b32_e32 v60, v0
	v_mov_b32_e32 v61, v0
	v_mov_b32_e32 v62, v0
	v_mov_b32_e32 v63, v0
	v_mov_b32_e32 v64, v0
	v_mov_b32_e32 v65, v0
	v_mov_b32_e32 v66, v0
	v_mov_b32_e32 v67, v0
	v_mov_b32_e32 v68, v0
	v_mov_b32_e32 v69, v0
	v_mov_b32_e32 v70, v0
	v_mov_b32_e32 v71, v0
	v_mov_b32_e32 v72, v0
	v_mov_b32_e32 v73, v0
	v_mov_b32_e32 v74, v0
	v_mov_b32_e32 v75, v0
	v_mov_b32_e32 v76, v0
	v_mov_b32_e32 v77, v0
	v_mov_b32_e32 v78, v0
	v_mov_b32_e32 v79, v0
	v_mov_b32_e32 v80, v0
	v_mov_b32_e32 v81, v0
	v_mov_b32_e32 v82, v0
	v_mov_b32_e32 v83, v0
	v_mov_b32_e32 v84, v0
	v_mov_b32_e32 v85, v0
	v_mov_b32_e32 v86, v0
	v_mov_b32_e32 v87, v0
	v_mov_b32_e32 v88, v0
	v_mov_b32_e32 v89, v0
	v_mov_b32_e32 v90, v0
	v_mov_b32_e32 v91, v0
	v_mov_b32_e32 v92, v0
	v_mov_b32_e32 v93, v0
	v_mov_b32_e32 v94, v0
	v_mov_b32_e32 v95, v0
	v_mov_b32_e32 v96, v0
	v_mov_b32_e32 v97, v0
	v_mov_b32_e32 v98, v0
	v_mov_b32_e32 v99, v0
	v_mov_b32_e32 v100, v0
	v_mov_b32_e32 v101, v0
	v_mov_b32_e32 v102, v0
	v_mov_b32_e32 v103, v0
	v_mov_b32_e32 v104, v0
	v_mov_b32_e32 v105, v0
	v_mov_b32_e32 v106, v0
	v_mov_b32_e32 v107, v0
	v_mov_b32_e32 v108, v0
	v_mov_b32_e32 v109, v0
	v_mov_b32_e32 v110, v0
	v_mov_b32_e32 v111, v0
	v_mov_b32_e32 v112, v0
	v_mov_b32_e32 v113, v0
	v_mov_b32_e32 v114, v0
	v_mov_b32_e32 v115, v0
	v_mov_b32_e32 v116, v0
	v_mov_b32_e32 v117, v0
	v_mov_b32_e32 v118, v0
	v_mov_b32_e32 v119, v0
	v_mov_b32_e32 v120, v0
	v_mov_b32_e32 v121, v0
	v_mov_b32_e32 v122, v0
	v_mov_b32_e32 v123, v0
	v_mov_b32_e32 v124, v0
	v_mov_b32_e32 v125, v0
	v_mov_b32_e32 v126, v0
	v_mov_b32_e32 v127, v0
	s_barrier
	v_readfirstlane_b32 s63, v137
	v_lshl_add_u64 v[142:143], v[128:129], 0, s[22:23]
	s_mov_b32 m0, s63
	v_readfirstlane_b32 s63, v136
	global_load_lds_dwordx4 v[142:143], off
	v_lshl_add_u64 v[142:143], v[128:129], 0, s[24:25]
	s_mov_b32 m0, s63
	s_nop 0
	global_load_lds_dwordx4 v[142:143], off
.LBB0_110:
	ds_read_b128 v[140:143], v138
	ds_read_b128 v[144:147], v138 offset:1024
	ds_read_b128 v[148:151], v138 offset:2048
	ds_read_b128 v[152:155], v138 offset:3072
	ds_read_b128 v[156:159], v192
	ds_read_b128 v[160:163], v192 offset:1024
	ds_read_b128 v[194:197], v191
	ds_read_b128 v[198:201], v191 offset:1024
	ds_read_b128 v[202:205], v190
	ds_read_b128 v[206:209], v190 offset:1024
	ds_read_b128 v[210:213], v189
	ds_read_b128 v[214:217], v189 offset:1024
	s_waitcnt lgkmcnt(8)
	s_barrier
	s_waitcnt lgkmcnt(0)
	s_setprio 1
	s_waitcnt lgkmcnt(0)
	v_mfma_f32_16x16x32_bf16 v[124:127], v[140:143], v[156:159], v[124:127]
	v_mfma_f32_16x16x32_bf16 v[120:123], v[148:151], v[156:159], v[120:123]
	v_mfma_f32_16x16x32_bf16 v[116:119], v[140:143], v[194:197], v[116:119]
	v_mfma_f32_16x16x32_bf16 v[112:115], v[148:151], v[194:197], v[112:115]
	v_mfma_f32_16x16x32_bf16 v[108:111], v[140:143], v[202:205], v[108:111]
	v_mfma_f32_16x16x32_bf16 v[104:107], v[148:151], v[202:205], v[104:107]
	v_mfma_f32_16x16x32_bf16 v[100:103], v[140:143], v[210:213], v[100:103]
	v_mfma_f32_16x16x32_bf16 v[96:99], v[148:151], v[210:213], v[96:99]
	v_mfma_f32_16x16x32_bf16 v[124:127], v[144:147], v[160:163], v[124:127]
	v_mfma_f32_16x16x32_bf16 v[120:123], v[152:155], v[160:163], v[120:123]
	v_mfma_f32_16x16x32_bf16 v[116:119], v[144:147], v[198:201], v[116:119]
	v_mfma_f32_16x16x32_bf16 v[112:115], v[152:155], v[198:201], v[112:115]
	v_mfma_f32_16x16x32_bf16 v[108:111], v[144:147], v[206:209], v[108:111]
	v_mfma_f32_16x16x32_bf16 v[104:107], v[152:155], v[206:209], v[104:107]
	v_mfma_f32_16x16x32_bf16 v[100:103], v[144:147], v[214:217], v[100:103]
	v_mfma_f32_16x16x32_bf16 v[96:99], v[152:155], v[214:217], v[96:99]
	s_setprio 0
	s_barrier
	v_readfirstlane_b32 s63, v188
	v_lshl_add_u64 v[234:235], s[66:67], 0, v[164:165]
	s_mov_b32 m0, s63
	v_readfirstlane_b32 s63, v187
	ds_read_b128 v[218:221], v135
	ds_read_b128 v[222:225], v135 offset:1024
	ds_read_b128 v[226:229], v135 offset:2048
	ds_read_b128 v[230:233], v135 offset:3072
	global_load_lds_dwordx4 v[234:235], off
	v_lshl_add_u64 v[236:237], v[234:235], 0, s[10:11]
	s_mov_b32 m0, s63
	s_nop 0
	global_load_lds_dwordx4 v[236:237], off
	s_barrier
	s_waitcnt lgkmcnt(0)
	s_setprio 1
	s_waitcnt lgkmcnt(0)
	v_mfma_f32_16x16x32_bf16 v[92:95], v[218:221], v[156:159], v[92:95]
	v_mfma_f32_16x16x32_bf16 v[88:91], v[226:229], v[156:159], v[88:91]
	v_mfma_f32_16x16x32_bf16 v[84:87], v[218:221], v[194:197], v[84:87]
	v_mfma_f32_16x16x32_bf16 v[80:83], v[226:229], v[194:197], v[80:83]
	v_mfma_f32_16x16x32_bf16 v[76:79], v[218:221], v[202:205], v[76:79]
	v_mfma_f32_16x16x32_bf16 v[72:75], v[226:229], v[202:205], v[72:75]
	v_mfma_f32_16x16x32_bf16 v[68:71], v[218:221], v[210:213], v[68:71]
	v_mfma_f32_16x16x32_bf16 v[64:67], v[226:229], v[210:213], v[64:67]
	v_mfma_f32_16x16x32_bf16 v[92:95], v[222:225], v[160:163], v[92:95]
	v_mfma_f32_16x16x32_bf16 v[88:91], v[230:233], v[160:163], v[88:91]
	v_mfma_f32_16x16x32_bf16 v[84:87], v[222:225], v[198:201], v[84:87]
	v_mfma_f32_16x16x32_bf16 v[80:83], v[230:233], v[198:201], v[80:83]
	v_mfma_f32_16x16x32_bf16 v[76:79], v[222:225], v[206:209], v[76:79]
	v_mfma_f32_16x16x32_bf16 v[72:75], v[230:233], v[206:209], v[72:75]
	v_mfma_f32_16x16x32_bf16 v[68:71], v[222:225], v[214:217], v[68:71]
	v_mfma_f32_16x16x32_bf16 v[64:67], v[230:233], v[214:217], v[64:67]
	s_setprio 0
	v_readfirstlane_b32 s63, v169
	v_lshl_add_u64 v[236:237], v[128:129], 0, s[26:27]
	s_mov_b32 m0, s63
	v_readfirstlane_b32 s63, v186
	s_barrier
	ds_read_b128 v[156:159], v192 offset:16384
	ds_read_b128 v[160:163], v192 offset:17408
	ds_read_b128 v[194:197], v191 offset:16384
	ds_read_b128 v[198:201], v191 offset:17408
	ds_read_b128 v[202:205], v190 offset:16384
	ds_read_b128 v[206:209], v190 offset:17408
	ds_read_b128 v[210:213], v189 offset:16384
	ds_read_b128 v[214:217], v189 offset:17408
	global_load_lds_dwordx4 v[236:237], off
	v_lshl_add_u64 v[236:237], v[128:129], 0, s[28:29]
	s_mov_b32 m0, s63
	s_nop 0
	global_load_lds_dwordx4 v[236:237], off
	s_barrier
	s_waitcnt lgkmcnt(0)
	s_setprio 1
	s_waitcnt lgkmcnt(0)
	v_mfma_f32_16x16x32_bf16 v[60:63], v[140:143], v[156:159], v[60:63]
	v_mfma_f32_16x16x32_bf16 v[56:59], v[148:151], v[156:159], v[56:59]
	v_mfma_f32_16x16x32_bf16 v[52:55], v[140:143], v[194:197], v[52:55]
	v_mfma_f32_16x16x32_bf16 v[48:51], v[148:151], v[194:197], v[48:51]
	v_mfma_f32_16x16x32_bf16 v[44:47], v[140:143], v[202:205], v[44:47]
	v_mfma_f32_16x16x32_bf16 v[40:43], v[148:151], v[202:205], v[40:43]
	v_mfma_f32_16x16x32_bf16 v[36:39], v[140:143], v[210:213], v[36:39]
	v_mfma_f32_16x16x32_bf16 v[32:35], v[148:151], v[210:213], v[32:35]
	v_mfma_f32_16x16x32_bf16 v[60:63], v[144:147], v[160:163], v[60:63]
	v_mfma_f32_16x16x32_bf16 v[56:59], v[152:155], v[160:163], v[56:59]
	v_mfma_f32_16x16x32_bf16 v[52:55], v[144:147], v[198:201], v[52:55]
	v_mfma_f32_16x16x32_bf16 v[48:51], v[152:155], v[198:201], v[48:51]
	v_mfma_f32_16x16x32_bf16 v[44:47], v[144:147], v[206:209], v[44:47]
	v_mfma_f32_16x16x32_bf16 v[40:43], v[152:155], v[206:209], v[40:43]
	v_mfma_f32_16x16x32_bf16 v[36:39], v[144:147], v[214:217], v[36:39]
	v_mfma_f32_16x16x32_bf16 v[32:35], v[152:155], v[214:217], v[32:35]
	s_setprio 0
	s_barrier
	v_readfirstlane_b32 s63, v185
	v_lshl_add_u64 v[140:141], v[234:235], 0, s[30:31]
	s_mov_b32 m0, s63
	v_readfirstlane_b32 s63, v184
	global_load_lds_dwordx4 v[140:141], off
	v_lshl_add_u64 v[140:141], v[234:235], 0, s[34:35]
	s_mov_b32 m0, s63
	s_nop 0
	global_load_lds_dwordx4 v[140:141], off
	v_readfirstlane_b32 s63, v183
	v_lshl_add_u64 v[142:143], v[128:129], 0, s[40:41]
	s_mov_b32 m0, s63
	v_readfirstlane_b32 s63, v182
	global_load_lds_dwordx4 v[142:143], off
	s_mov_b32 m0, s63
	s_nop 0
	global_load_lds_dwordx4 v[128:129], off
	s_waitcnt vmcnt(8)
	s_barrier
	s_setprio 1
	v_mfma_f32_16x16x32_bf16 v[28:31], v[218:221], v[156:159], v[28:31]
	v_mfma_f32_16x16x32_bf16 v[24:27], v[226:229], v[156:159], v[24:27]
	v_mfma_f32_16x16x32_bf16 v[20:23], v[218:221], v[194:197], v[20:23]
	v_mfma_f32_16x16x32_bf16 v[16:19], v[226:229], v[194:197], v[16:19]
	v_mfma_f32_16x16x32_bf16 v[12:15], v[218:221], v[202:205], v[12:15]
	v_mfma_f32_16x16x32_bf16 v[8:11], v[226:229], v[202:205], v[8:11]
	v_mfma_f32_16x16x32_bf16 v[4:7], v[218:221], v[210:213], v[4:7]
	v_mfma_f32_16x16x32_bf16 v[0:3], v[226:229], v[210:213], v[0:3]
	v_mfma_f32_16x16x32_bf16 v[28:31], v[222:225], v[160:163], v[28:31]
	v_mfma_f32_16x16x32_bf16 v[24:27], v[230:233], v[160:163], v[24:27]
	v_mfma_f32_16x16x32_bf16 v[20:23], v[222:225], v[198:201], v[20:23]
	v_mfma_f32_16x16x32_bf16 v[16:19], v[230:233], v[198:201], v[16:19]
	v_mfma_f32_16x16x32_bf16 v[12:15], v[222:225], v[206:209], v[12:15]
	v_mfma_f32_16x16x32_bf16 v[8:11], v[230:233], v[206:209], v[8:11]
	v_mfma_f32_16x16x32_bf16 v[4:7], v[222:225], v[214:217], v[4:7]
	v_mfma_f32_16x16x32_bf16 v[0:3], v[230:233], v[214:217], v[0:3]
	s_setprio 0
	s_barrier
	ds_read_b128 v[140:143], v130
	ds_read_b128 v[144:147], v130 offset:1024
	ds_read_b128 v[148:151], v130 offset:2048
	ds_read_b128 v[152:155], v130 offset:3072
	ds_read_b128 v[156:159], v192 offset:32768
	ds_read_b128 v[160:163], v192 offset:33792
	ds_read_b128 v[194:197], v191 offset:32768
	ds_read_b128 v[198:201], v191 offset:33792
	ds_read_b128 v[202:205], v190 offset:32768
	ds_read_b128 v[206:209], v190 offset:33792
	ds_read_b128 v[210:213], v189 offset:32768
	ds_read_b128 v[214:217], v189 offset:33792
	s_waitcnt lgkmcnt(8)
	s_barrier
	s_waitcnt lgkmcnt(0)
	s_setprio 1
	s_waitcnt lgkmcnt(0)
	v_mfma_f32_16x16x32_bf16 v[124:127], v[140:143], v[156:159], v[124:127]
	v_mfma_f32_16x16x32_bf16 v[120:123], v[148:151], v[156:159], v[120:123]
	v_mfma_f32_16x16x32_bf16 v[116:119], v[140:143], v[194:197], v[116:119]
	v_mfma_f32_16x16x32_bf16 v[112:115], v[148:151], v[194:197], v[112:115]
	v_mfma_f32_16x16x32_bf16 v[108:111], v[140:143], v[202:205], v[108:111]
	v_mfma_f32_16x16x32_bf16 v[104:107], v[148:151], v[202:205], v[104:107]
	v_mfma_f32_16x16x32_bf16 v[100:103], v[140:143], v[210:213], v[100:103]
	v_mfma_f32_16x16x32_bf16 v[96:99], v[148:151], v[210:213], v[96:99]
	v_mfma_f32_16x16x32_bf16 v[124:127], v[144:147], v[160:163], v[124:127]
	v_mfma_f32_16x16x32_bf16 v[120:123], v[152:155], v[160:163], v[120:123]
	v_mfma_f32_16x16x32_bf16 v[116:119], v[144:147], v[198:201], v[116:119]
	v_mfma_f32_16x16x32_bf16 v[112:115], v[152:155], v[198:201], v[112:115]
	v_mfma_f32_16x16x32_bf16 v[108:111], v[144:147], v[206:209], v[108:111]
	v_mfma_f32_16x16x32_bf16 v[104:107], v[152:155], v[206:209], v[104:107]
	v_mfma_f32_16x16x32_bf16 v[100:103], v[144:147], v[214:217], v[100:103]
	v_mfma_f32_16x16x32_bf16 v[96:99], v[152:155], v[214:217], v[96:99]
	s_setprio 0
	s_barrier
	v_readfirstlane_b32 s63, v181
	v_lshl_add_u64 v[234:235], s[64:65], 0, v[164:165]
	s_mov_b32 m0, s63
	v_readfirstlane_b32 s63, v180
	ds_read_b128 v[218:221], v132
	ds_read_b128 v[222:225], v132 offset:1024
	ds_read_b128 v[226:229], v132 offset:2048
	ds_read_b128 v[230:233], v132 offset:3072
	global_load_lds_dwordx4 v[234:235], off
	v_lshl_add_u64 v[236:237], v[234:235], 0, s[10:11]
	s_mov_b32 m0, s63
	s_nop 0
	global_load_lds_dwordx4 v[236:237], off
	s_barrier
	s_waitcnt lgkmcnt(0)
	s_setprio 1
	s_waitcnt lgkmcnt(0)
	v_mfma_f32_16x16x32_bf16 v[92:95], v[218:221], v[156:159], v[92:95]
	v_mfma_f32_16x16x32_bf16 v[88:91], v[226:229], v[156:159], v[88:91]
	v_mfma_f32_16x16x32_bf16 v[84:87], v[218:221], v[194:197], v[84:87]
	v_mfma_f32_16x16x32_bf16 v[80:83], v[226:229], v[194:197], v[80:83]
	v_mfma_f32_16x16x32_bf16 v[76:79], v[218:221], v[202:205], v[76:79]
	v_mfma_f32_16x16x32_bf16 v[72:75], v[226:229], v[202:205], v[72:75]
	v_mfma_f32_16x16x32_bf16 v[68:71], v[218:221], v[210:213], v[68:71]
	v_mfma_f32_16x16x32_bf16 v[64:67], v[226:229], v[210:213], v[64:67]
	v_mfma_f32_16x16x32_bf16 v[92:95], v[222:225], v[160:163], v[92:95]
	v_mfma_f32_16x16x32_bf16 v[88:91], v[230:233], v[160:163], v[88:91]
	v_mfma_f32_16x16x32_bf16 v[84:87], v[222:225], v[198:201], v[84:87]
	v_mfma_f32_16x16x32_bf16 v[80:83], v[230:233], v[198:201], v[80:83]
	v_mfma_f32_16x16x32_bf16 v[76:79], v[222:225], v[206:209], v[76:79]
	v_mfma_f32_16x16x32_bf16 v[72:75], v[230:233], v[206:209], v[72:75]
	v_mfma_f32_16x16x32_bf16 v[68:71], v[222:225], v[214:217], v[68:71]
	v_mfma_f32_16x16x32_bf16 v[64:67], v[230:233], v[214:217], v[64:67]
	s_setprio 0
	v_readfirstlane_b32 s63, v179
	v_lshl_add_u64 v[236:237], v[128:129], 0, s[44:45]
	s_mov_b32 m0, s63
	v_readfirstlane_b32 s63, v177
	s_barrier
	ds_read_b128 v[156:159], v192 offset:49152
	ds_read_b128 v[160:163], v192 offset:50176
	ds_read_b128 v[194:197], v191 offset:49152
	ds_read_b128 v[198:201], v191 offset:50176
	ds_read_b128 v[202:205], v190 offset:49152
	ds_read_b128 v[206:209], v190 offset:50176
	ds_read_b128 v[210:213], v189 offset:49152
	ds_read_b128 v[214:217], v189 offset:50176
	global_load_lds_dwordx4 v[236:237], off
	v_lshl_add_u64 v[236:237], v[128:129], 0, s[46:47]
	s_mov_b32 m0, s63
	s_nop 0
	global_load_lds_dwordx4 v[236:237], off
	s_barrier
	s_waitcnt lgkmcnt(0)
	s_setprio 1
	s_waitcnt lgkmcnt(0)
	v_mfma_f32_16x16x32_bf16 v[60:63], v[140:143], v[156:159], v[60:63]
	v_mfma_f32_16x16x32_bf16 v[56:59], v[148:151], v[156:159], v[56:59]
	v_mfma_f32_16x16x32_bf16 v[52:55], v[140:143], v[194:197], v[52:55]
	v_mfma_f32_16x16x32_bf16 v[48:51], v[148:151], v[194:197], v[48:51]
	v_mfma_f32_16x16x32_bf16 v[44:47], v[140:143], v[202:205], v[44:47]
	v_mfma_f32_16x16x32_bf16 v[40:43], v[148:151], v[202:205], v[40:43]
	v_mfma_f32_16x16x32_bf16 v[36:39], v[140:143], v[210:213], v[36:39]
	v_mfma_f32_16x16x32_bf16 v[32:35], v[148:151], v[210:213], v[32:35]
	v_mfma_f32_16x16x32_bf16 v[60:63], v[144:147], v[160:163], v[60:63]
	v_mfma_f32_16x16x32_bf16 v[56:59], v[152:155], v[160:163], v[56:59]
	v_mfma_f32_16x16x32_bf16 v[52:55], v[144:147], v[198:201], v[52:55]
	v_mfma_f32_16x16x32_bf16 v[48:51], v[152:155], v[198:201], v[48:51]
	v_mfma_f32_16x16x32_bf16 v[44:47], v[144:147], v[206:209], v[44:47]
	v_mfma_f32_16x16x32_bf16 v[40:43], v[152:155], v[206:209], v[40:43]
	v_mfma_f32_16x16x32_bf16 v[36:39], v[144:147], v[214:217], v[36:39]
	v_mfma_f32_16x16x32_bf16 v[32:35], v[152:155], v[214:217], v[32:35]
	s_setprio 0
	s_barrier
	v_readfirstlane_b32 s63, v175
	v_lshl_add_u64 v[140:141], v[234:235], 0, s[30:31]
	s_mov_b32 m0, s63
	v_readfirstlane_b32 s63, v173
	global_load_lds_dwordx4 v[140:141], off
	v_lshl_add_u64 v[140:141], v[234:235], 0, s[34:35]
	s_mov_b32 m0, s63
	s_nop 0
	global_load_lds_dwordx4 v[140:141], off
	v_lshl_add_u64 v[128:129], v[128:129], 0, s[56:57]
	v_readfirstlane_b32 s63, v137
	v_lshl_add_u64 v[142:143], v[128:129], 0, s[22:23]
	s_mov_b32 m0, s63
	v_readfirstlane_b32 s63, v136
	global_load_lds_dwordx4 v[142:143], off
	v_lshl_add_u64 v[142:143], v[128:129], 0, s[24:25]
	s_mov_b32 m0, s63
	s_nop 0
	global_load_lds_dwordx4 v[142:143], off
	s_waitcnt vmcnt(8)
	s_barrier
	s_setprio 1
	v_mfma_f32_16x16x32_bf16 v[28:31], v[218:221], v[156:159], v[28:31]
	v_mfma_f32_16x16x32_bf16 v[24:27], v[226:229], v[156:159], v[24:27]
	v_mfma_f32_16x16x32_bf16 v[20:23], v[218:221], v[194:197], v[20:23]
	v_mfma_f32_16x16x32_bf16 v[16:19], v[226:229], v[194:197], v[16:19]
	v_mfma_f32_16x16x32_bf16 v[12:15], v[218:221], v[202:205], v[12:15]
	v_mfma_f32_16x16x32_bf16 v[8:11], v[226:229], v[202:205], v[8:11]
	v_mfma_f32_16x16x32_bf16 v[4:7], v[218:221], v[210:213], v[4:7]
	v_mfma_f32_16x16x32_bf16 v[0:3], v[226:229], v[210:213], v[0:3]
	v_mfma_f32_16x16x32_bf16 v[28:31], v[222:225], v[160:163], v[28:31]
	v_mfma_f32_16x16x32_bf16 v[24:27], v[230:233], v[160:163], v[24:27]
	v_mfma_f32_16x16x32_bf16 v[20:23], v[222:225], v[198:201], v[20:23]
	v_mfma_f32_16x16x32_bf16 v[16:19], v[230:233], v[198:201], v[16:19]
	v_mfma_f32_16x16x32_bf16 v[12:15], v[222:225], v[206:209], v[12:15]
	v_mfma_f32_16x16x32_bf16 v[8:11], v[230:233], v[206:209], v[8:11]
	v_mfma_f32_16x16x32_bf16 v[4:7], v[222:225], v[214:217], v[4:7]
	v_mfma_f32_16x16x32_bf16 v[0:3], v[230:233], v[214:217], v[0:3]
	s_setprio 0
	s_add_i32 s4, s4, 2
	s_add_u32 s64, s64, s68
	s_addc_u32 s65, s65, s69
	s_add_u32 s66, s66, s68
	s_addc_u32 s67, s67, s69
	s_cmp_lt_u32 s4, 28
	s_barrier
	s_cbranch_scc1 .LBB0_110
	s_lshl_b32 s4, s70, 11
	s_or_b32 s64, s71, s4
	s_or_b32 s66, s64, 0x80
	v_lshlrev_b32_e32 v128, 3, v131
	v_lshlrev_b32_e32 v129, 5, v131
	s_ashr_i32 s67, s66, 31
	v_and_b32_e32 v128, 0xffff0, v128
	v_and_b32_e32 v129, 32, v129
	s_lshl_b64 s[66:67], s[66:67], 12
	v_add_u32_e32 v129, v129, v134
	v_add_lshl_u32 v128, v133, v128, 12
	s_add_u32 s66, s54, s66
	v_lshl_add_u32 v164, v129, 1, v128
	s_addc_u32 s67, s55, s67
	v_lshl_add_u64 v[128:129], s[66:67], 0, v[164:165]
	v_readfirstlane_b32 s4, v137
	ds_read_b128 v[140:143], v138
	ds_read_b128 v[144:147], v138 offset:1024
	ds_read_b128 v[148:151], v138 offset:2048
	ds_read_b128 v[152:155], v138 offset:3072
	ds_read_b128 v[156:159], v192
	ds_read_b128 v[160:163], v192 offset:1024
	ds_read_b128 v[194:197], v191
	ds_read_b128 v[198:201], v191 offset:1024
	ds_read_b128 v[202:205], v190
	ds_read_b128 v[206:209], v190 offset:1024
	ds_read_b128 v[210:213], v189
	ds_read_b128 v[214:217], v189 offset:1024
	v_lshl_add_u64 v[138:139], v[128:129], 0, s[58:59]
	s_mov_b32 m0, s4
	v_readfirstlane_b32 s4, v136
	global_load_lds_dwordx4 v[138:139], off
	v_lshl_add_u64 v[128:129], v[128:129], 0, s[60:61]
	s_mov_b32 m0, s4
	s_ashr_i32 s65, s64, 31
	global_load_lds_dwordx4 v[128:129], off
	s_barrier
	s_waitcnt lgkmcnt(0)
	s_setprio 1
	s_waitcnt lgkmcnt(0)
	v_mfma_f32_16x16x32_bf16 v[124:127], v[140:143], v[156:159], v[124:127]
	v_mfma_f32_16x16x32_bf16 v[120:123], v[148:151], v[156:159], v[120:123]
	v_mfma_f32_16x16x32_bf16 v[116:119], v[140:143], v[194:197], v[116:119]
	v_mfma_f32_16x16x32_bf16 v[112:115], v[148:151], v[194:197], v[112:115]
	v_mfma_f32_16x16x32_bf16 v[108:111], v[140:143], v[202:205], v[108:111]
	v_mfma_f32_16x16x32_bf16 v[104:107], v[148:151], v[202:205], v[104:107]
	v_mfma_f32_16x16x32_bf16 v[100:103], v[140:143], v[210:213], v[100:103]
	v_mfma_f32_16x16x32_bf16 v[96:99], v[148:151], v[210:213], v[96:99]
	v_mfma_f32_16x16x32_bf16 v[124:127], v[144:147], v[160:163], v[124:127]
	v_mfma_f32_16x16x32_bf16 v[120:123], v[152:155], v[160:163], v[120:123]
	v_mfma_f32_16x16x32_bf16 v[116:119], v[144:147], v[198:201], v[116:119]
	v_mfma_f32_16x16x32_bf16 v[112:115], v[152:155], v[198:201], v[112:115]
	v_mfma_f32_16x16x32_bf16 v[108:111], v[144:147], v[206:209], v[108:111]
	v_mfma_f32_16x16x32_bf16 v[104:107], v[152:155], v[206:209], v[104:107]
	v_mfma_f32_16x16x32_bf16 v[100:103], v[144:147], v[214:217], v[100:103]
	v_mfma_f32_16x16x32_bf16 v[96:99], v[152:155], v[214:217], v[96:99]
	s_setprio 0
	s_barrier
	ds_read_b128 v[136:139], v135
	ds_read_b128 v[218:221], v135 offset:1024
	ds_read_b128 v[222:225], v135 offset:2048
	ds_read_b128 v[226:229], v135 offset:3072
	s_barrier
	s_waitcnt lgkmcnt(0)
	s_setprio 1
	s_waitcnt lgkmcnt(0)
	v_mfma_f32_16x16x32_bf16 v[92:95], v[136:139], v[156:159], v[92:95]
	v_mfma_f32_16x16x32_bf16 v[88:91], v[222:225], v[156:159], v[88:91]
	v_mfma_f32_16x16x32_bf16 v[84:87], v[136:139], v[194:197], v[84:87]
	v_mfma_f32_16x16x32_bf16 v[80:83], v[222:225], v[194:197], v[80:83]
	v_mfma_f32_16x16x32_bf16 v[76:79], v[136:139], v[202:205], v[76:79]
	v_mfma_f32_16x16x32_bf16 v[72:75], v[222:225], v[202:205], v[72:75]
	v_mfma_f32_16x16x32_bf16 v[68:71], v[136:139], v[210:213], v[68:71]
	v_mfma_f32_16x16x32_bf16 v[64:67], v[222:225], v[210:213], v[64:67]
	v_mfma_f32_16x16x32_bf16 v[156:159], v[218:221], v[160:163], v[92:95]
	v_mfma_f32_16x16x32_bf16 v[160:163], v[226:229], v[160:163], v[88:91]
	v_mfma_f32_16x16x32_bf16 v[194:197], v[218:221], v[198:201], v[84:87]
	v_mfma_f32_16x16x32_bf16 v[198:201], v[226:229], v[198:201], v[80:83]
	v_mfma_f32_16x16x32_bf16 v[202:205], v[218:221], v[206:209], v[76:79]
	v_mfma_f32_16x16x32_bf16 v[206:209], v[226:229], v[206:209], v[72:75]
	v_mfma_f32_16x16x32_bf16 v[210:213], v[218:221], v[214:217], v[68:71]
	v_mfma_f32_16x16x32_bf16 v[214:217], v[226:229], v[214:217], v[64:67]
	s_setprio 0
	s_barrier
	s_nop 0
	ds_read_b128 v[64:67], v192 offset:16384
	ds_read_b128 v[68:71], v192 offset:17408
	ds_read_b128 v[72:75], v191 offset:16384
	ds_read_b128 v[76:79], v191 offset:17408
	ds_read_b128 v[80:83], v190 offset:16384
	ds_read_b128 v[84:87], v190 offset:17408
	ds_read_b128 v[88:91], v189 offset:16384
	ds_read_b128 v[92:95], v189 offset:17408
	s_waitcnt vmcnt(4)
	s_barrier
	s_waitcnt lgkmcnt(0)
	s_setprio 1
	s_waitcnt lgkmcnt(0)
	v_mfma_f32_16x16x32_bf16 v[60:63], v[140:143], v[64:67], v[60:63]
	v_mfma_f32_16x16x32_bf16 v[56:59], v[148:151], v[64:67], v[56:59]
	v_mfma_f32_16x16x32_bf16 v[52:55], v[140:143], v[72:75], v[52:55]
	v_mfma_f32_16x16x32_bf16 v[48:51], v[148:151], v[72:75], v[48:51]
	v_mfma_f32_16x16x32_bf16 v[230:233], v[140:143], v[80:83], v[44:47]
	v_mfma_f32_16x16x32_bf16 v[234:237], v[148:151], v[80:83], v[40:43]
	v_mfma_f32_16x16x32_bf16 v[140:143], v[140:143], v[88:91], v[36:39]
	v_mfma_f32_16x16x32_bf16 v[148:151], v[148:151], v[88:91], v[32:35]
	v_mfma_f32_16x16x32_bf16 v[32:35], v[144:147], v[68:71], v[60:63]
	v_mfma_f32_16x16x32_bf16 v[36:39], v[152:155], v[68:71], v[56:59]
	v_mfma_f32_16x16x32_bf16 v[40:43], v[144:147], v[76:79], v[52:55]
	v_mfma_f32_16x16x32_bf16 v[44:47], v[152:155], v[76:79], v[48:51]
	v_mfma_f32_16x16x32_bf16 v[48:51], v[144:147], v[84:87], v[230:233]
	v_mfma_f32_16x16x32_bf16 v[52:55], v[152:155], v[84:87], v[234:237]
	v_mfma_f32_16x16x32_bf16 v[56:59], v[144:147], v[92:95], v[140:143]
	v_mfma_f32_16x16x32_bf16 v[60:63], v[152:155], v[92:95], v[148:151]
	s_setprio 0
	s_setprio 1
	v_mfma_f32_16x16x32_bf16 v[28:31], v[136:139], v[64:67], v[28:31]
	v_mfma_f32_16x16x32_bf16 v[24:27], v[222:225], v[64:67], v[24:27]
	v_mfma_f32_16x16x32_bf16 v[20:23], v[136:139], v[72:75], v[20:23]
	v_mfma_f32_16x16x32_bf16 v[64:67], v[222:225], v[72:75], v[16:19]
	v_mfma_f32_16x16x32_bf16 v[12:15], v[136:139], v[80:83], v[12:15]
	v_mfma_f32_16x16x32_bf16 v[8:11], v[222:225], v[80:83], v[8:11]
	v_mfma_f32_16x16x32_bf16 v[72:75], v[136:139], v[88:91], v[4:7]
	v_mfma_f32_16x16x32_bf16 v[80:83], v[222:225], v[88:91], v[0:3]
	v_mfma_f32_16x16x32_bf16 v[0:3], v[218:221], v[68:71], v[28:31]
	v_mfma_f32_16x16x32_bf16 v[4:7], v[226:229], v[68:71], v[24:27]
	v_mfma_f32_16x16x32_bf16 v[16:19], v[218:221], v[76:79], v[20:23]
	v_mfma_f32_16x16x32_bf16 v[20:23], v[226:229], v[76:79], v[64:67]
	v_mfma_f32_16x16x32_bf16 v[64:67], v[218:221], v[84:87], v[12:15]
	v_mfma_f32_16x16x32_bf16 v[68:71], v[226:229], v[84:87], v[8:11]
	v_mfma_f32_16x16x32_bf16 v[72:75], v[218:221], v[92:95], v[72:75]
	v_mfma_f32_16x16x32_bf16 v[76:79], v[226:229], v[92:95], v[80:83]
	s_setprio 0
	s_barrier
	ds_read_b128 v[12:15], v130
	ds_read_b128 v[8:11], v130 offset:1024
	ds_read_b128 v[24:27], v130 offset:2048
	ds_read_b128 v[80:83], v130 offset:3072
	ds_read_b128 v[140:143], v192 offset:32768
	ds_read_b128 v[148:151], v192 offset:33792
	ds_read_b128 v[218:221], v191 offset:32768
	ds_read_b128 v[222:225], v191 offset:33792
	ds_read_b128 v[226:229], v190 offset:32768
	ds_read_b128 v[230:233], v190 offset:33792
	ds_read_b128 v[234:237], v189 offset:32768
	ds_read_b128 v[238:241], v189 offset:33792
	s_waitcnt vmcnt(2)
	s_barrier
	s_waitcnt lgkmcnt(0)
	s_setprio 1
	s_waitcnt lgkmcnt(0)
	v_mfma_f32_16x16x32_bf16 v[28:31], v[12:15], v[140:143], v[124:127]
	v_mfma_f32_16x16x32_bf16 v[84:87], v[24:27], v[140:143], v[120:123]
	v_mfma_f32_16x16x32_bf16 v[88:91], v[12:15], v[218:221], v[116:119]
	v_mfma_f32_16x16x32_bf16 v[92:95], v[24:27], v[218:221], v[112:115]
	v_mfma_f32_16x16x32_bf16 v[108:111], v[12:15], v[226:229], v[108:111]
	v_mfma_f32_16x16x32_bf16 v[104:107], v[24:27], v[226:229], v[104:107]
	v_mfma_f32_16x16x32_bf16 v[100:103], v[12:15], v[234:237], v[100:103]
	v_mfma_f32_16x16x32_bf16 v[96:99], v[24:27], v[234:237], v[96:99]
	v_mfma_f32_16x16x32_bf16 v[152:155], v[8:11], v[148:151], v[28:31]
	v_mfma_f32_16x16x32_bf16 v[144:147], v[80:83], v[148:151], v[84:87]
	v_mfma_f32_16x16x32_bf16 v[136:139], v[8:11], v[222:225], v[88:91]
	v_mfma_f32_16x16x32_bf16 v[128:131], v[80:83], v[222:225], v[92:95]
	v_mfma_f32_16x16x32_bf16 v[120:123], v[8:11], v[230:233], v[108:111]
	v_mfma_f32_16x16x32_bf16 v[112:115], v[80:83], v[230:233], v[104:107]
	v_mfma_f32_16x16x32_bf16 v[104:107], v[8:11], v[238:241], v[100:103]
	v_mfma_f32_16x16x32_bf16 v[28:31], v[80:83], v[238:241], v[96:99]
	s_setprio 0
	s_barrier
	ds_read_b128 v[92:95], v132
	ds_read_b128 v[84:87], v132 offset:1024
	ds_read_b128 v[96:99], v132 offset:2048
	ds_read_b128 v[88:91], v132 offset:3072
	s_waitcnt vmcnt(0)
	s_barrier
	s_waitcnt lgkmcnt(0)
	s_setprio 1
	s_waitcnt lgkmcnt(0)
	v_mfma_f32_16x16x32_bf16 v[100:103], v[92:95], v[140:143], v[156:159]
	v_mfma_f32_16x16x32_bf16 v[108:111], v[96:99], v[140:143], v[160:163]
	v_mfma_f32_16x16x32_bf16 v[116:119], v[92:95], v[218:221], v[194:197]
	v_mfma_f32_16x16x32_bf16 v[124:127], v[96:99], v[218:221], v[198:201]
	v_mfma_f32_16x16x32_bf16 v[160:163], v[92:95], v[226:229], v[202:205]
	v_mfma_f32_16x16x32_bf16 v[194:197], v[96:99], v[226:229], v[206:209]
	v_mfma_f32_16x16x32_bf16 v[198:201], v[92:95], v[234:237], v[210:213]
	v_mfma_f32_16x16x32_bf16 v[202:205], v[96:99], v[234:237], v[214:217]
	v_mfma_f32_16x16x32_bf16 v[156:159], v[84:87], v[148:151], v[100:103]
	v_mfma_f32_16x16x32_bf16 v[148:151], v[88:91], v[148:151], v[108:111]
	v_mfma_f32_16x16x32_bf16 v[140:143], v[84:87], v[222:225], v[116:119]
	v_mfma_f32_16x16x32_bf16 v[132:135], v[88:91], v[222:225], v[124:127]
	v_mfma_f32_16x16x32_bf16 v[124:127], v[84:87], v[230:233], v[160:163]
	v_mfma_f32_16x16x32_bf16 v[116:119], v[88:91], v[230:233], v[194:197]
	v_mfma_f32_16x16x32_bf16 v[108:111], v[84:87], v[238:241], v[198:201]
	v_mfma_f32_16x16x32_bf16 v[100:103], v[88:91], v[238:241], v[202:205]
	s_setprio 0
	s_lshl_b64 s[66:67], s[64:65], 2
	s_barrier
	v_mbcnt_lo_u32_b32 v162, -1, 0
	v_mbcnt_hi_u32_b32 v162, -1, v162
	s_add_u32 s66, s87, s66
	v_add_u32_e32 v160, s76, v162
	s_addc_u32 s67, s88, s67
	v_and_b32_e32 v164, 0x100, v160
	v_and_b32_e32 v162, 15, v162
	v_lshl_add_u64 v[160:161], s[66:67], 0, v[164:165]
	v_lshlrev_b32_e32 v164, 2, v162
	v_lshl_add_u64 v[160:161], v[160:161], 0, v[164:165]
	global_load_dword v178, v[160:161], off
	global_load_dword v176, v[160:161], off offset:64
	global_load_dword v174, v[160:161], off offset:128
	global_load_dword v164, v[160:161], off offset:192
	global_load_dword v172, v[160:161], off offset:512
	global_load_dword v170, v[160:161], off offset:576
	global_load_dword v168, v[160:161], off offset:640
	global_load_dword v166, v[160:161], off offset:704
	v_mbcnt_lo_u32_b32 v194, -1, 0
	v_mbcnt_hi_u32_b32 v194, -1, v194
	s_mov_b64 s[66:67], -1
	v_add_u32_e32 v160, s76, v194
	v_bfe_u32 v161, v160, 8, 1
	v_ashrrev_i32_e32 v196, 6, v160
	v_bfe_u32 v160, v194, 4, 2
	v_and_b32_e32 v198, 3, v196
	v_and_b32_e32 v195, 15, v194
	s_cmp_gt_i32 s74, 1
	v_lshlrev_b32_e32 v193, 6, v161
	v_lshlrev_b32_e32 v197, 4, v160
	s_cbranch_scc0 .LBB0_113
	v_lshlrev_b32_e32 v161, 6, v198
	v_or3_b32 v160, v193, v195, s64
	v_or3_b32 v161, v161, v197, s62
	v_lshl_add_u32 v199, v160, 12, v161
	s_waitcnt vmcnt(0)
	v_mul_f32_e32 v160, v178, v178
	v_pk_mul_f32 v[200:201], v[152:153], v[160:161] op_sel_hi:[1,0]
	v_pk_mul_f32 v[162:163], v[154:155], v[160:161] op_sel_hi:[1,0]
	v_pk_mul_f32 v[202:203], v[158:159], v[160:161] op_sel_hi:[1,0]
	v_pk_mul_f32 v[204:205], v[156:157], v[160:161] op_sel_hi:[1,0]
	v_mul_f32_e32 v160, v144, v200
	v_mul_f32_e32 v161, v145, v201
	v_cvt_pk_bf16_f32 v160, v160, v161
	v_mul_f32_e32 v161, v146, v162
	v_mul_f32_e32 v162, v147, v163
	v_cvt_pk_bf16_f32 v161, v161, v162
	v_mul_f32_e32 v162, v148, v204
	v_mul_f32_e32 v163, v149, v205
	v_cvt_pk_bf16_f32 v162, v162, v163
	v_mul_f32_e32 v163, v150, v202
	v_mul_f32_e32 v200, v151, v203
	v_cvt_pk_bf16_f32 v163, v163, v200
	global_store_dwordx4 v199, v[160:163], s[6:7]
	v_add_u32_e32 v206, 0x10000, v199
	s_mov_b64 s[66:67], 0
	v_mul_f32_e32 v160, v176, v176
	v_pk_mul_f32 v[200:201], v[136:137], v[160:161] op_sel_hi:[1,0]
	v_pk_mul_f32 v[162:163], v[138:139], v[160:161] op_sel_hi:[1,0]
	v_pk_mul_f32 v[202:203], v[142:143], v[160:161] op_sel_hi:[1,0]
	v_pk_mul_f32 v[204:205], v[140:141], v[160:161] op_sel_hi:[1,0]
	v_mul_f32_e32 v160, v128, v200
	v_mul_f32_e32 v161, v129, v201
	v_cvt_pk_bf16_f32 v160, v160, v161
	v_mul_f32_e32 v161, v130, v162
	v_mul_f32_e32 v162, v131, v163
	v_cvt_pk_bf16_f32 v161, v161, v162
	v_mul_f32_e32 v162, v132, v204
	v_mul_f32_e32 v163, v133, v205
	v_cvt_pk_bf16_f32 v162, v162, v163
	v_mul_f32_e32 v163, v134, v202
	v_mul_f32_e32 v200, v135, v203
	v_cvt_pk_bf16_f32 v163, v163, v200
	global_store_dwordx4 v206, v[160:163], s[6:7]
	v_add_u32_e32 v206, 0x20000, v199
	v_add_u32_e32 v199, 0x30000, v199
	v_mul_f32_e32 v160, v174, v174
	v_pk_mul_f32 v[200:201], v[120:121], v[160:161] op_sel_hi:[1,0]
	v_pk_mul_f32 v[162:163], v[122:123], v[160:161] op_sel_hi:[1,0]
	v_pk_mul_f32 v[202:203], v[126:127], v[160:161] op_sel_hi:[1,0]
	v_pk_mul_f32 v[204:205], v[124:125], v[160:161] op_sel_hi:[1,0]
	v_mul_f32_e32 v160, v112, v200
	v_mul_f32_e32 v161, v113, v201
	v_cvt_pk_bf16_f32 v160, v160, v161
	v_mul_f32_e32 v161, v114, v162
	v_mul_f32_e32 v162, v115, v163
	v_cvt_pk_bf16_f32 v161, v161, v162
	v_mul_f32_e32 v162, v116, v204
	v_mul_f32_e32 v163, v117, v205
	v_cvt_pk_bf16_f32 v162, v162, v163
	v_mul_f32_e32 v163, v118, v202
	v_mul_f32_e32 v200, v119, v203
	v_cvt_pk_bf16_f32 v163, v163, v200
	global_store_dwordx4 v206, v[160:163], s[6:7]
	s_nop 1
	v_mul_f32_e32 v160, v164, v164
	v_pk_mul_f32 v[200:201], v[104:105], v[160:161] op_sel_hi:[1,0]
	v_pk_mul_f32 v[162:163], v[106:107], v[160:161] op_sel_hi:[1,0]
	v_pk_mul_f32 v[202:203], v[110:111], v[160:161] op_sel_hi:[1,0]
	v_pk_mul_f32 v[204:205], v[108:109], v[160:161] op_sel_hi:[1,0]
	v_mul_f32_e32 v160, v28, v200
	v_mul_f32_e32 v161, v29, v201
	v_cvt_pk_bf16_f32 v160, v160, v161
	v_mul_f32_e32 v161, v30, v162
	v_mul_f32_e32 v162, v31, v163
	v_cvt_pk_bf16_f32 v161, v161, v162
	v_mul_f32_e32 v162, v100, v204
	v_mul_f32_e32 v163, v101, v205
	v_cvt_pk_bf16_f32 v162, v162, v163
	v_mul_f32_e32 v163, v102, v202
	v_mul_f32_e32 v200, v103, v203
	v_cvt_pk_bf16_f32 v163, v163, v200

.LBB0_177:
	v_bfe_i32 v5, v136, 27, 1
	v_lshlrev_b32_e32 v135, 4, v136
	v_lshrrev_b32_e32 v5, 22, v5
	v_add_u32_e32 v5, v135, v5
	v_and_b32_e32 v5, 0xfffffc00, v5
	v_sub_u32_e32 v5, v135, v5
	v_lshrrev_b32_e32 v6, 4, v5
	v_bitop3_b32 v5, v6, v5, 32 bitop3:0x6c
	v_ashrrev_i32_e32 v6, 31, v5
	v_lshrrev_b32_e32 v6, 26, v6
	v_add_u32_e32 v6, v5, v6
	v_ashrrev_i32_e32 v157, 6, v6
	v_and_b32_e32 v6, 0xc0, v6
	v_sub_u32_e32 v5, v5, v6
	v_ashrrev_i16_sdwa v5, v134, sext(v5) dst_sel:DWORD dst_unused:UNUSED_PAD src0_sel:DWORD src1_sel:BYTE_0
	v_and_b32_e32 v2, 15, v0
	v_and_b32_e32 v3, 48, v0
	v_bfe_i32 v158, v5, 0, 16
	v_and_b32_e32 v5, 32, v0
	v_lshlrev_b32_e32 v8, 2, v0
	v_lshlrev_b32_e32 v0, 6, v0
	s_movk_i32 s65, 0x3f0
	v_lshlrev_b32_e32 v2, 6, v2
	v_and_b32_e32 v8, 32, v8
	v_and_b32_e32 v0, 0x3c0, v0
	v_ashrrev_i32_e32 v4, 31, v136
	v_bitop3_b32 v5, v135, v5, s65 bitop3:0x6c
	v_or_b32_e32 v7, v2, v3
	v_bitop3_b32 v2, v2, v8, v3 bitop3:0x36
	v_bitop3_b32 v3, v0, v8, v3 bitop3:0x36
	v_lshlrev_b32_e32 v0, 11, v136
	v_lshrrev_b32_e32 v4, 26, v4
	v_and_or_b32 v0, v0, s76, v5
	v_lshlrev_b32_e32 v5, 3, v136
	s_bfe_u32 s64, s85, 0x30003
	v_add_u32_e32 v4, v136, v4
	s_mov_b32 s65, 0x14000
	v_and_b32_e32 v5, 0xfffffc00, v5
	s_lshl_b32 s24, s64, 14
	v_ashrrev_i32_e32 v156, 6, v4
	v_bitop3_b32 v10, v7, s65, v8 bitop3:0xde
	s_mov_b32 s65, 0x1c000
	v_add_u32_e32 v128, v0, v5
	v_bitop3_b32 v9, v7, s74, v8 bitop3:0xde
	v_bitop3_b32 v11, v7, s75, v8 bitop3:0xde
	v_bitop3_b32 v7, v7, s65, v8 bitop3:0xde
	v_lshl_add_u64 v[130:131], s[24:25], 0, v[128:129]
	v_lshlrev_b32_e32 v0, 15, v156
	s_lshl_b32 s24, s85, 17
	s_and_b32 s65, s85, 7
	v_and_b32_e32 v0, 0xffff0000, v0
	s_and_b32 s24, s24, 0x1800000
	s_lshl_b32 s65, s65, 20
	v_lshl_add_u32 v0, v157, 12, v0
	s_or_b32 s24, s24, s65
	v_lshlrev_b32_e32 v6, 6, v136
	v_lshlrev_b32_e32 v1, 13, v1
	v_and_or_b32 v0, v4, 64, v0
	s_add_u32 s66, s24, s90
	v_and_b32_e32 v6, 0x3000, v6
	v_or_b32_e32 v8, 0x800, v1
	v_or_b32_e32 v12, 0x1000, v1
	v_or_b32_e32 v13, 0x1800, v1
	v_lshl_add_u32 v128, v158, 1, v0
	s_addc_u32 s67, 0, 0
	v_mov_b32_e32 v0, 0
	v_lshl_add_u64 v[132:133], s[66:67], 0, v[128:129]
	s_mov_b32 s24, -2
	v_add_u32_e32 v162, v9, v6
	v_add_u32_e32 v153, v2, v1
	v_add_u32_e32 v152, v3, v8
	v_add_u32_e32 v151, v3, v12
	v_add_u32_e32 v150, v3, v13
	v_add_u32_e32 v161, 0xc000, v135
	v_add_u32_e32 v160, 0xe000, v135
	v_add_u32_e32 v159, v10, v6
	v_add_u32_e32 v149, 0x10000, v135
	v_add_u32_e32 v148, 0x12000, v135
	v_add_u32_e32 v147, 0x2000, v135
	v_add_u32_e32 v146, 0x14000, v135
	v_add_u32_e32 v145, 0x16000, v135
	v_add_u32_e32 v155, v11, v6
	v_add_u32_e32 v144, 0x4000, v135
	v_add_u32_e32 v143, 0x6000, v135
	v_add_u32_e32 v154, v7, v6
	v_add_u32_e32 v142, 0x18000, v135
	v_add_u32_e32 v141, 0x1a000, v135
	v_add_u32_e32 v140, 0x8000, v135
	v_add_u32_e32 v139, 0xa000, v135
	v_add_u32_e32 v138, 0x1c000, v135
	v_add_u32_e32 v137, 0x1e000, v135
	v_mov_b32_e32 v1, v0
	v_mov_b32_e32 v2, v0
	v_mov_b32_e32 v3, v0
	v_mov_b32_e32 v4, v0
	v_mov_b32_e32 v5, v0
	v_mov_b32_e32 v6, v0
	v_mov_b32_e32 v7, v0
	v_mov_b32_e32 v8, v0
	v_mov_b32_e32 v9, v0
	v_mov_b32_e32 v10, v0
	v_mov_b32_e32 v11, v0
	v_mov_b32_e32 v12, v0
	v_mov_b32_e32 v13, v0
	v_mov_b32_e32 v14, v0
	v_mov_b32_e32 v15, v0
	v_mov_b32_e32 v16, v0
	v_mov_b32_e32 v17, v0
	v_mov_b32_e32 v18, v0
	v_mov_b32_e32 v19, v0
	v_mov_b32_e32 v20, v0
	v_mov_b32_e32 v21, v0
	v_mov_b32_e32 v22, v0
	v_mov_b32_e32 v23, v0
	v_mov_b32_e32 v24, v0
	v_mov_b32_e32 v25, v0
	v_mov_b32_e32 v26, v0
	v_mov_b32_e32 v27, v0
	v_mov_b32_e32 v28, v0
	v_mov_b32_e32 v29, v0
	v_mov_b32_e32 v30, v0
	v_mov_b32_e32 v31, v0
	v_mov_b32_e32 v32, v0
	v_mov_b32_e32 v33, v0
	v_mov_b32_e32 v34, v0
	v_mov_b32_e32 v35, v0
	v_mov_b32_e32 v36, v0
	v_mov_b32_e32 v37, v0
	v_mov_b32_e32 v38, v0
	v_mov_b32_e32 v39, v0
	v_mov_b32_e32 v40, v0
	v_mov_b32_e32 v41, v0
	v_mov_b32_e32 v42, v0
	v_mov_b32_e32 v43, v0
	v_mov_b32_e32 v44, v0
	v_mov_b32_e32 v45, v0
	v_mov_b32_e32 v46, v0
	v_mov_b32_e32 v47, v0
	v_mov_b32_e32 v48, v0
	v_mov_b32_e32 v49, v0
	v_mov_b32_e32 v50, v0
	v_mov_b32_e32 v51, v0
	v_mov_b32_e32 v52, v0
	v_mov_b32_e32 v53, v0
	v_mov_b32_e32 v54, v0
	v_mov_b32_e32 v55, v0
	v_mov_b32_e32 v56, v0
	v_mov_b32_e32 v57, v0
	v_mov_b32_e32 v58, v0
	v_mov_b32_e32 v59, v0
	v_mov_b32_e32 v60, v0
	v_mov_b32_e32 v61, v0
	v_mov_b32_e32 v62, v0
	v_mov_b32_e32 v63, v0
	v_mov_b32_e32 v64, v0
	v_mov_b32_e32 v65, v0
	v_mov_b32_e32 v66, v0
	v_mov_b32_e32 v67, v0
	v_mov_b32_e32 v68, v0
	v_mov_b32_e32 v69, v0
	v_mov_b32_e32 v70, v0
	v_mov_b32_e32 v71, v0
	v_mov_b32_e32 v72, v0
	v_mov_b32_e32 v73, v0
	v_mov_b32_e32 v74, v0
	v_mov_b32_e32 v75, v0
	v_mov_b32_e32 v76, v0
	v_mov_b32_e32 v77, v0
	v_mov_b32_e32 v78, v0
	v_mov_b32_e32 v79, v0
	v_mov_b32_e32 v80, v0
	v_mov_b32_e32 v81, v0
	v_mov_b32_e32 v82, v0
	v_mov_b32_e32 v83, v0
	v_mov_b32_e32 v84, v0
	v_mov_b32_e32 v85, v0
	v_mov_b32_e32 v86, v0
	v_mov_b32_e32 v87, v0
	v_mov_b32_e32 v88, v0
	v_mov_b32_e32 v89, v0
	v_mov_b32_e32 v90, v0
	v_mov_b32_e32 v91, v0
	v_mov_b32_e32 v92, v0
	v_mov_b32_e32 v93, v0
	v_mov_b32_e32 v94, v0
	v_mov_b32_e32 v95, v0
	v_mov_b32_e32 v96, v0
	v_mov_b32_e32 v97, v0
	v_mov_b32_e32 v98, v0
	v_mov_b32_e32 v99, v0
	v_mov_b32_e32 v100, v0
	v_mov_b32_e32 v101, v0
	v_mov_b32_e32 v102, v0
	v_mov_b32_e32 v103, v0
	v_mov_b32_e32 v104, v0
	v_mov_b32_e32 v105, v0
	v_mov_b32_e32 v106, v0
	v_mov_b32_e32 v107, v0
	v_mov_b32_e32 v108, v0
	v_mov_b32_e32 v109, v0
	v_mov_b32_e32 v110, v0
	v_mov_b32_e32 v111, v0
	v_mov_b32_e32 v112, v0
	v_mov_b32_e32 v113, v0
	v_mov_b32_e32 v114, v0
	v_mov_b32_e32 v115, v0
	v_mov_b32_e32 v116, v0
	v_mov_b32_e32 v117, v0
	v_mov_b32_e32 v118, v0
	v_mov_b32_e32 v119, v0
	v_mov_b32_e32 v120, v0
	v_mov_b32_e32 v121, v0
	v_mov_b32_e32 v122, v0
	v_mov_b32_e32 v123, v0
	v_mov_b32_e32 v124, v0
	v_mov_b32_e32 v125, v0
	v_mov_b32_e32 v126, v0
	v_mov_b32_e32 v127, v0
	s_barrier
	v_lshl_add_u64 v[228:229], s[50:51], 0, v[132:133]
	s_mov_b64 s[66:67], 0xe080080
	v_readfirstlane_b32 s65, v161
	v_lshl_add_u64 v[166:167], v[228:229], 0, s[66:67]
	s_mov_b32 m0, s65
	s_mov_b64 s[66:67], 0xe0c0080
	v_readfirstlane_b32 s65, v160
	global_load_lds_dwordx4 v[166:167], off
	v_lshl_add_u64 v[166:167], v[228:229], 0, s[66:67]
	s_mov_b32 m0, s65
	s_nop 0
	global_load_lds_dwordx4 v[166:167], off
.LBB0_178:
	ds_read_b128 v[164:167], v162
	ds_read_b128 v[168:171], v162 offset:1024
	ds_read_b128 v[172:175], v162 offset:2048
	ds_read_b128 v[176:179], v162 offset:3072
	ds_read_b128 v[180:183], v153
	ds_read_b128 v[184:187], v153 offset:1024
	ds_read_b128 v[188:191], v152
	ds_read_b128 v[192:195], v152 offset:1024
	ds_read_b128 v[196:199], v151
	ds_read_b128 v[200:203], v151 offset:1024
	ds_read_b128 v[204:207], v150
	ds_read_b128 v[208:211], v150 offset:1024
	s_waitcnt lgkmcnt(8)
	s_barrier
	s_waitcnt lgkmcnt(0)
	s_setprio 1
	s_waitcnt lgkmcnt(0)
	v_mfma_f32_16x16x32_bf16 v[124:127], v[164:167], v[180:183], v[124:127]
	v_mfma_f32_16x16x32_bf16 v[120:123], v[172:175], v[180:183], v[120:123]
	v_mfma_f32_16x16x32_bf16 v[116:119], v[164:167], v[188:191], v[116:119]
	v_mfma_f32_16x16x32_bf16 v[112:115], v[172:175], v[188:191], v[112:115]
	v_mfma_f32_16x16x32_bf16 v[108:111], v[164:167], v[196:199], v[108:111]
	v_mfma_f32_16x16x32_bf16 v[104:107], v[172:175], v[196:199], v[104:107]
	v_mfma_f32_16x16x32_bf16 v[100:103], v[164:167], v[204:207], v[100:103]
	v_mfma_f32_16x16x32_bf16 v[96:99], v[172:175], v[204:207], v[96:99]
	v_mfma_f32_16x16x32_bf16 v[124:127], v[168:171], v[184:187], v[124:127]
	v_mfma_f32_16x16x32_bf16 v[120:123], v[176:179], v[184:187], v[120:123]
	v_mfma_f32_16x16x32_bf16 v[116:119], v[168:171], v[192:195], v[116:119]
	v_mfma_f32_16x16x32_bf16 v[112:115], v[176:179], v[192:195], v[112:115]
	v_mfma_f32_16x16x32_bf16 v[108:111], v[168:171], v[200:203], v[108:111]
	v_mfma_f32_16x16x32_bf16 v[104:107], v[176:179], v[200:203], v[104:107]
	v_mfma_f32_16x16x32_bf16 v[100:103], v[168:171], v[208:211], v[100:103]
	v_mfma_f32_16x16x32_bf16 v[96:99], v[176:179], v[208:211], v[96:99]
	s_setprio 0
	s_barrier
	v_lshl_add_u64 v[230:231], s[50:51], 0, v[130:131]
	s_mov_b64 s[66:67], 0x1880000
	v_readfirstlane_b32 s65, v149
	v_lshl_add_u64 v[232:233], v[230:231], 0, s[66:67]
	s_mov_b32 m0, s65
	s_mov_b64 s[66:67], 0x1881000
	v_readfirstlane_b32 s65, v148
	ds_read_b128 v[212:215], v159
	ds_read_b128 v[216:219], v159 offset:1024
	ds_read_b128 v[220:223], v159 offset:2048
	ds_read_b128 v[224:227], v159 offset:3072
	global_load_lds_dwordx4 v[232:233], off
	v_lshl_add_u64 v[232:233], v[230:231], 0, s[66:67]
	s_mov_b32 m0, s65
	s_nop 0
	global_load_lds_dwordx4 v[232:233], off
	s_barrier
	s_waitcnt lgkmcnt(0)
	s_setprio 1
	s_waitcnt lgkmcnt(0)
	v_mfma_f32_16x16x32_bf16 v[92:95], v[212:215], v[180:183], v[92:95]
	v_mfma_f32_16x16x32_bf16 v[88:91], v[220:223], v[180:183], v[88:91]
	v_mfma_f32_16x16x32_bf16 v[84:87], v[212:215], v[188:191], v[84:87]
	v_mfma_f32_16x16x32_bf16 v[80:83], v[220:223], v[188:191], v[80:83]
	v_mfma_f32_16x16x32_bf16 v[76:79], v[212:215], v[196:199], v[76:79]
	v_mfma_f32_16x16x32_bf16 v[72:75], v[220:223], v[196:199], v[72:75]
	v_mfma_f32_16x16x32_bf16 v[68:71], v[212:215], v[204:207], v[68:71]
	v_mfma_f32_16x16x32_bf16 v[64:67], v[220:223], v[204:207], v[64:67]
	v_mfma_f32_16x16x32_bf16 v[92:95], v[216:219], v[184:187], v[92:95]
	v_mfma_f32_16x16x32_bf16 v[88:91], v[224:227], v[184:187], v[88:91]
	v_mfma_f32_16x16x32_bf16 v[84:87], v[216:219], v[192:195], v[84:87]
	v_mfma_f32_16x16x32_bf16 v[80:83], v[224:227], v[192:195], v[80:83]
	v_mfma_f32_16x16x32_bf16 v[76:79], v[216:219], v[200:203], v[76:79]
	v_mfma_f32_16x16x32_bf16 v[72:75], v[224:227], v[200:203], v[72:75]
	v_mfma_f32_16x16x32_bf16 v[68:71], v[216:219], v[208:211], v[68:71]
	v_mfma_f32_16x16x32_bf16 v[64:67], v[224:227], v[208:211], v[64:67]
	s_setprio 0
	s_mov_b64 s[66:67], 0xe000100
	v_readfirstlane_b32 s65, v135
	v_lshl_add_u64 v[232:233], v[228:229], 0, s[66:67]
	s_mov_b32 m0, s65
	s_mov_b64 s[66:67], 0xe040100
	v_readfirstlane_b32 s65, v147
	s_barrier
	ds_read_b128 v[180:183], v153 offset:16384
	ds_read_b128 v[184:187], v153 offset:17408
	ds_read_b128 v[188:191], v152 offset:16384
	ds_read_b128 v[192:195], v152 offset:17408
	ds_read_b128 v[196:199], v151 offset:16384
	ds_read_b128 v[200:203], v151 offset:17408
	ds_read_b128 v[204:207], v150 offset:16384
	ds_read_b128 v[208:211], v150 offset:17408
	global_load_lds_dwordx4 v[232:233], off
	v_lshl_add_u64 v[232:233], v[228:229], 0, s[66:67]
	s_mov_b32 m0, s65
	s_nop 0
	global_load_lds_dwordx4 v[232:233], off
	s_barrier
	s_waitcnt lgkmcnt(0)
	s_setprio 1
	s_waitcnt lgkmcnt(0)
	v_mfma_f32_16x16x32_bf16 v[60:63], v[164:167], v[180:183], v[60:63]
	v_mfma_f32_16x16x32_bf16 v[56:59], v[172:175], v[180:183], v[56:59]
	v_mfma_f32_16x16x32_bf16 v[52:55], v[164:167], v[188:191], v[52:55]
	v_mfma_f32_16x16x32_bf16 v[48:51], v[172:175], v[188:191], v[48:51]
	v_mfma_f32_16x16x32_bf16 v[44:47], v[164:167], v[196:199], v[44:47]
	v_mfma_f32_16x16x32_bf16 v[40:43], v[172:175], v[196:199], v[40:43]
	v_mfma_f32_16x16x32_bf16 v[36:39], v[164:167], v[204:207], v[36:39]
	v_mfma_f32_16x16x32_bf16 v[32:35], v[172:175], v[204:207], v[32:35]
	v_mfma_f32_16x16x32_bf16 v[60:63], v[168:171], v[184:187], v[60:63]
	v_mfma_f32_16x16x32_bf16 v[56:59], v[176:179], v[184:187], v[56:59]
	v_mfma_f32_16x16x32_bf16 v[52:55], v[168:171], v[192:195], v[52:55]
	v_mfma_f32_16x16x32_bf16 v[48:51], v[176:179], v[192:195], v[48:51]
	v_mfma_f32_16x16x32_bf16 v[44:47], v[168:171], v[200:203], v[44:47]
	v_mfma_f32_16x16x32_bf16 v[40:43], v[176:179], v[200:203], v[40:43]
	v_mfma_f32_16x16x32_bf16 v[36:39], v[168:171], v[208:211], v[36:39]
	v_mfma_f32_16x16x32_bf16 v[32:35], v[176:179], v[208:211], v[32:35]
	s_setprio 0
	s_barrier
	s_mov_b64 s[66:67], 0x1882000
	v_readfirstlane_b32 s65, v146
	v_lshl_add_u64 v[164:165], v[230:231], 0, s[66:67]
	s_mov_b32 m0, s65
	s_mov_b64 s[66:67], 0x1883000
	v_readfirstlane_b32 s65, v145
	global_load_lds_dwordx4 v[164:165], off
	v_lshl_add_u64 v[164:165], v[230:231], 0, s[66:67]
	s_mov_b32 m0, s65
	s_nop 0
	global_load_lds_dwordx4 v[164:165], off
	v_readfirstlane_b32 s65, v144
	v_lshl_add_u64 v[166:167], v[228:229], 0, s[26:27]
	s_mov_b32 m0, s65
	v_readfirstlane_b32 s65, v143
	global_load_lds_dwordx4 v[166:167], off
	v_lshl_add_u64 v[166:167], v[228:229], 0, s[28:29]
	s_mov_b32 m0, s65
	s_nop 0
	global_load_lds_dwordx4 v[166:167], off
	s_waitcnt vmcnt(8)
	s_barrier
	s_setprio 1
	v_mfma_f32_16x16x32_bf16 v[28:31], v[212:215], v[180:183], v[28:31]
	v_mfma_f32_16x16x32_bf16 v[24:27], v[220:223], v[180:183], v[24:27]
	v_mfma_f32_16x16x32_bf16 v[20:23], v[212:215], v[188:191], v[20:23]
	v_mfma_f32_16x16x32_bf16 v[16:19], v[220:223], v[188:191], v[16:19]
	v_mfma_f32_16x16x32_bf16 v[12:15], v[212:215], v[196:199], v[12:15]
	v_mfma_f32_16x16x32_bf16 v[8:11], v[220:223], v[196:199], v[8:11]
	v_mfma_f32_16x16x32_bf16 v[4:7], v[212:215], v[204:207], v[4:7]
	v_mfma_f32_16x16x32_bf16 v[0:3], v[220:223], v[204:207], v[0:3]
	v_mfma_f32_16x16x32_bf16 v[28:31], v[216:219], v[184:187], v[28:31]
	v_mfma_f32_16x16x32_bf16 v[24:27], v[224:227], v[184:187], v[24:27]
	v_mfma_f32_16x16x32_bf16 v[20:23], v[216:219], v[192:195], v[20:23]
	v_mfma_f32_16x16x32_bf16 v[16:19], v[224:227], v[192:195], v[16:19]
	v_mfma_f32_16x16x32_bf16 v[12:15], v[216:219], v[200:203], v[12:15]
	v_mfma_f32_16x16x32_bf16 v[8:11], v[224:227], v[200:203], v[8:11]
	v_mfma_f32_16x16x32_bf16 v[4:7], v[216:219], v[208:211], v[4:7]
	v_mfma_f32_16x16x32_bf16 v[0:3], v[224:227], v[208:211], v[0:3]
	s_setprio 0
	s_barrier
	ds_read_b128 v[164:167], v155
	ds_read_b128 v[168:171], v155 offset:1024
	ds_read_b128 v[172:175], v155 offset:2048
	ds_read_b128 v[176:179], v155 offset:3072
	ds_read_b128 v[180:183], v153 offset:32768
	ds_read_b128 v[184:187], v153 offset:33792
	ds_read_b128 v[188:191], v152 offset:32768
	ds_read_b128 v[192:195], v152 offset:33792
	ds_read_b128 v[196:199], v151 offset:32768
	ds_read_b128 v[200:203], v151 offset:33792
	ds_read_b128 v[204:207], v150 offset:32768
	ds_read_b128 v[208:211], v150 offset:33792
	s_waitcnt lgkmcnt(8)
	s_barrier
	s_waitcnt lgkmcnt(0)
	s_setprio 1
	s_waitcnt lgkmcnt(0)
	v_mfma_f32_16x16x32_bf16 v[124:127], v[164:167], v[180:183], v[124:127]
	v_mfma_f32_16x16x32_bf16 v[120:123], v[172:175], v[180:183], v[120:123]
	v_mfma_f32_16x16x32_bf16 v[116:119], v[164:167], v[188:191], v[116:119]
	v_mfma_f32_16x16x32_bf16 v[112:115], v[172:175], v[188:191], v[112:115]
	v_mfma_f32_16x16x32_bf16 v[108:111], v[164:167], v[196:199], v[108:111]
	v_mfma_f32_16x16x32_bf16 v[104:107], v[172:175], v[196:199], v[104:107]
	v_mfma_f32_16x16x32_bf16 v[100:103], v[164:167], v[204:207], v[100:103]
	v_mfma_f32_16x16x32_bf16 v[96:99], v[172:175], v[204:207], v[96:99]
	v_mfma_f32_16x16x32_bf16 v[124:127], v[168:171], v[184:187], v[124:127]
	v_mfma_f32_16x16x32_bf16 v[120:123], v[176:179], v[184:187], v[120:123]
	v_mfma_f32_16x16x32_bf16 v[116:119], v[168:171], v[192:195], v[116:119]
	v_mfma_f32_16x16x32_bf16 v[112:115], v[176:179], v[192:195], v[112:115]
	v_mfma_f32_16x16x32_bf16 v[108:111], v[168:171], v[200:203], v[108:111]
	v_mfma_f32_16x16x32_bf16 v[104:107], v[176:179], v[200:203], v[104:107]
	v_mfma_f32_16x16x32_bf16 v[100:103], v[168:171], v[208:211], v[100:103]
	v_mfma_f32_16x16x32_bf16 v[96:99], v[176:179], v[208:211], v[96:99]
	s_setprio 0
	s_barrier
	v_readfirstlane_b32 s65, v142
	v_lshl_add_u64 v[232:233], v[230:231], 0, s[30:31]
	s_mov_b32 m0, s65
	v_readfirstlane_b32 s65, v141
	ds_read_b128 v[212:215], v154
	ds_read_b128 v[216:219], v154 offset:1024
	ds_read_b128 v[220:223], v154 offset:2048
	ds_read_b128 v[224:227], v154 offset:3072
	global_load_lds_dwordx4 v[232:233], off
	v_lshl_add_u64 v[232:233], v[230:231], 0, s[34:35]
	s_mov_b32 m0, s65
	s_nop 0
	global_load_lds_dwordx4 v[232:233], off
	s_barrier
	s_waitcnt lgkmcnt(0)
	s_setprio 1
	s_waitcnt lgkmcnt(0)
	v_mfma_f32_16x16x32_bf16 v[92:95], v[212:215], v[180:183], v[92:95]
	v_mfma_f32_16x16x32_bf16 v[88:91], v[220:223], v[180:183], v[88:91]
	v_mfma_f32_16x16x32_bf16 v[84:87], v[212:215], v[188:191], v[84:87]
	v_mfma_f32_16x16x32_bf16 v[80:83], v[220:223], v[188:191], v[80:83]
	v_mfma_f32_16x16x32_bf16 v[76:79], v[212:215], v[196:199], v[76:79]
	v_mfma_f32_16x16x32_bf16 v[72:75], v[220:223], v[196:199], v[72:75]
	v_mfma_f32_16x16x32_bf16 v[68:71], v[212:215], v[204:207], v[68:71]
	v_mfma_f32_16x16x32_bf16 v[64:67], v[220:223], v[204:207], v[64:67]
	v_mfma_f32_16x16x32_bf16 v[92:95], v[216:219], v[184:187], v[92:95]
	v_mfma_f32_16x16x32_bf16 v[88:91], v[224:227], v[184:187], v[88:91]
	v_mfma_f32_16x16x32_bf16 v[84:87], v[216:219], v[192:195], v[84:87]
	v_mfma_f32_16x16x32_bf16 v[80:83], v[224:227], v[192:195], v[80:83]
	v_mfma_f32_16x16x32_bf16 v[76:79], v[216:219], v[200:203], v[76:79]
	v_mfma_f32_16x16x32_bf16 v[72:75], v[224:227], v[200:203], v[72:75]
	v_mfma_f32_16x16x32_bf16 v[68:71], v[216:219], v[208:211], v[68:71]
	v_mfma_f32_16x16x32_bf16 v[64:67], v[224:227], v[208:211], v[64:67]
	s_setprio 0
	v_readfirstlane_b32 s65, v140
	v_lshl_add_u64 v[232:233], v[228:229], 0, s[40:41]
	s_mov_b32 m0, s65
	v_readfirstlane_b32 s65, v139
	s_barrier
	ds_read_b128 v[180:183], v153 offset:49152
	ds_read_b128 v[184:187], v153 offset:50176
	ds_read_b128 v[188:191], v152 offset:49152
	ds_read_b128 v[192:195], v152 offset:50176
	ds_read_b128 v[196:199], v151 offset:49152
	ds_read_b128 v[200:203], v151 offset:50176
	ds_read_b128 v[204:207], v150 offset:49152
	ds_read_b128 v[208:211], v150 offset:50176
	global_load_lds_dwordx4 v[232:233], off
	v_lshl_add_u64 v[228:229], v[228:229], 0, s[44:45]
	s_mov_b32 m0, s65
	s_nop 0
	global_load_lds_dwordx4 v[228:229], off
	s_barrier
	s_waitcnt lgkmcnt(0)
	s_setprio 1
	s_waitcnt lgkmcnt(0)
	v_mfma_f32_16x16x32_bf16 v[60:63], v[164:167], v[180:183], v[60:63]
	v_mfma_f32_16x16x32_bf16 v[56:59], v[172:175], v[180:183], v[56:59]
	v_mfma_f32_16x16x32_bf16 v[52:55], v[164:167], v[188:191], v[52:55]
	v_mfma_f32_16x16x32_bf16 v[48:51], v[172:175], v[188:191], v[48:51]
	v_mfma_f32_16x16x32_bf16 v[44:47], v[164:167], v[196:199], v[44:47]
	v_mfma_f32_16x16x32_bf16 v[40:43], v[172:175], v[196:199], v[40:43]
	v_mfma_f32_16x16x32_bf16 v[36:39], v[164:167], v[204:207], v[36:39]
	v_mfma_f32_16x16x32_bf16 v[32:35], v[172:175], v[204:207], v[32:35]
	v_mfma_f32_16x16x32_bf16 v[60:63], v[168:171], v[184:187], v[60:63]
	v_mfma_f32_16x16x32_bf16 v[56:59], v[176:179], v[184:187], v[56:59]
	v_mfma_f32_16x16x32_bf16 v[52:55], v[168:171], v[192:195], v[52:55]
	v_mfma_f32_16x16x32_bf16 v[48:51], v[176:179], v[192:195], v[48:51]
	v_mfma_f32_16x16x32_bf16 v[44:47], v[168:171], v[200:203], v[44:47]
	v_mfma_f32_16x16x32_bf16 v[40:43], v[176:179], v[200:203], v[40:43]
	v_mfma_f32_16x16x32_bf16 v[36:39], v[168:171], v[208:211], v[36:39]
	v_mfma_f32_16x16x32_bf16 v[32:35], v[176:179], v[208:211], v[32:35]
	s_setprio 0
	s_barrier
	v_readfirstlane_b32 s65, v138
	v_lshl_add_u64 v[164:165], v[230:231], 0, s[46:47]
	s_mov_b32 m0, s65
	v_readfirstlane_b32 s65, v137
	global_load_lds_dwordx4 v[164:165], off
	v_lshl_add_u64 v[164:165], v[230:231], 0, s[56:57]
	s_mov_b32 m0, s65
	s_nop 0
	global_load_lds_dwordx4 v[164:165], off
	v_lshl_add_u64 v[132:133], v[132:133], 0, s[58:59]
	v_lshl_add_u64 v[228:229], s[50:51], 0, v[132:133]
	s_mov_b64 s[66:67], 0xe080080
	v_readfirstlane_b32 s65, v161
	v_lshl_add_u64 v[166:167], v[228:229], 0, s[66:67]
	s_mov_b32 m0, s65
	s_mov_b64 s[66:67], 0xe0c0080
	v_readfirstlane_b32 s65, v160
	global_load_lds_dwordx4 v[166:167], off
	v_lshl_add_u64 v[166:167], v[228:229], 0, s[66:67]
	s_mov_b32 m0, s65
	s_nop 0
	global_load_lds_dwordx4 v[166:167], off
	s_waitcnt vmcnt(8)
	s_barrier
	s_setprio 1
	v_mfma_f32_16x16x32_bf16 v[28:31], v[212:215], v[180:183], v[28:31]
	v_mfma_f32_16x16x32_bf16 v[24:27], v[220:223], v[180:183], v[24:27]
	v_mfma_f32_16x16x32_bf16 v[20:23], v[212:215], v[188:191], v[20:23]
	v_mfma_f32_16x16x32_bf16 v[16:19], v[220:223], v[188:191], v[16:19]
	v_mfma_f32_16x16x32_bf16 v[12:15], v[212:215], v[196:199], v[12:15]
	v_mfma_f32_16x16x32_bf16 v[8:11], v[220:223], v[196:199], v[8:11]
	v_mfma_f32_16x16x32_bf16 v[4:7], v[212:215], v[204:207], v[4:7]
	v_mfma_f32_16x16x32_bf16 v[0:3], v[220:223], v[204:207], v[0:3]
	v_mfma_f32_16x16x32_bf16 v[28:31], v[216:219], v[184:187], v[28:31]
	v_mfma_f32_16x16x32_bf16 v[24:27], v[224:227], v[184:187], v[24:27]
	v_mfma_f32_16x16x32_bf16 v[20:23], v[216:219], v[192:195], v[20:23]
	v_mfma_f32_16x16x32_bf16 v[16:19], v[224:227], v[192:195], v[16:19]
	v_mfma_f32_16x16x32_bf16 v[12:15], v[216:219], v[200:203], v[12:15]
	v_mfma_f32_16x16x32_bf16 v[8:11], v[224:227], v[200:203], v[8:11]
	v_mfma_f32_16x16x32_bf16 v[4:7], v[216:219], v[208:211], v[4:7]
	v_mfma_f32_16x16x32_bf16 v[0:3], v[224:227], v[208:211], v[0:3]
	s_setprio 0
	s_add_i32 s24, s24, 2
	v_lshl_add_u64 v[130:131], v[130:131], 0, s[10:11]
	s_cmp_lt_u32 s24, 28
	s_barrier
	s_cbranch_scc1 .LBB0_178
	s_lshl_b32 s24, s85, 5
	s_lshl_b32 s65, s85, 8
	s_and_b32 s24, s24, 0x1800
	s_and_b32 s65, s65, 0x700
	s_or_b32 s24, s65, s24
	v_lshlrev_b32_e32 v128, 3, v156
	v_lshlrev_b32_e32 v130, 5, v156
	v_and_b32_e32 v128, 0xffff0, v128
	v_and_b32_e32 v130, 32, v130
	s_lshl_b32 s65, s24, 12
	v_add_u32_e32 v130, v130, v158
	v_add_lshl_u32 v128, v157, v128, 12
	s_add_u32 s66, s68, s65
	v_lshl_add_u32 v128, v130, 1, v128
	s_addc_u32 s67, s69, 0
	v_lshl_add_u64 v[156:157], s[66:67], 0, v[128:129]
	v_readfirstlane_b32 s65, v161
	ds_read_b128 v[130:133], v162
	ds_read_b128 v[164:167], v162 offset:1024
	ds_read_b128 v[168:171], v162 offset:2048
	ds_read_b128 v[172:175], v162 offset:3072
	ds_read_b128 v[176:179], v153
	ds_read_b128 v[180:183], v153 offset:1024
	ds_read_b128 v[184:187], v152
	ds_read_b128 v[188:191], v152 offset:1024
	ds_read_b128 v[192:195], v151
	ds_read_b128 v[196:199], v151 offset:1024
	ds_read_b128 v[200:203], v150
	ds_read_b128 v[204:207], v150 offset:1024
	v_lshl_add_u64 v[162:163], v[156:157], 0, s[60:61]
	s_mov_b32 m0, s65
	v_readfirstlane_b32 s65, v160
	global_load_lds_dwordx4 v[162:163], off
	v_lshl_add_u64 v[156:157], v[156:157], 0, s[62:63]
	s_mov_b32 m0, s65
	s_nop 0
	global_load_lds_dwordx4 v[156:157], off
	s_barrier
	s_waitcnt lgkmcnt(0)
	s_setprio 1
	s_waitcnt lgkmcnt(0)
	v_mfma_f32_16x16x32_bf16 v[124:127], v[130:133], v[176:179], v[124:127]
	v_mfma_f32_16x16x32_bf16 v[120:123], v[168:171], v[176:179], v[120:123]
	v_mfma_f32_16x16x32_bf16 v[116:119], v[130:133], v[184:187], v[116:119]
	v_mfma_f32_16x16x32_bf16 v[112:115], v[168:171], v[184:187], v[112:115]
	v_mfma_f32_16x16x32_bf16 v[108:111], v[130:133], v[192:195], v[108:111]
	v_mfma_f32_16x16x32_bf16 v[104:107], v[168:171], v[192:195], v[104:107]
	v_mfma_f32_16x16x32_bf16 v[100:103], v[130:133], v[200:203], v[100:103]
	v_mfma_f32_16x16x32_bf16 v[96:99], v[168:171], v[200:203], v[96:99]
	v_mfma_f32_16x16x32_bf16 v[124:127], v[164:167], v[180:183], v[124:127]
	v_mfma_f32_16x16x32_bf16 v[120:123], v[172:175], v[180:183], v[120:123]
	v_mfma_f32_16x16x32_bf16 v[116:119], v[164:167], v[188:191], v[116:119]
	v_mfma_f32_16x16x32_bf16 v[112:115], v[172:175], v[188:191], v[112:115]
	v_mfma_f32_16x16x32_bf16 v[108:111], v[164:167], v[196:199], v[108:111]
	v_mfma_f32_16x16x32_bf16 v[104:107], v[172:175], v[196:199], v[104:107]
	v_mfma_f32_16x16x32_bf16 v[100:103], v[164:167], v[204:207], v[100:103]
	v_mfma_f32_16x16x32_bf16 v[96:99], v[172:175], v[204:207], v[96:99]
	s_setprio 0
	s_barrier
	ds_read_b128 v[160:163], v159
	ds_read_b128 v[208:211], v159 offset:1024
	ds_read_b128 v[212:215], v159 offset:2048
	ds_read_b128 v[156:159], v159 offset:3072
	s_barrier
	s_waitcnt lgkmcnt(0)
	s_setprio 1
	s_waitcnt lgkmcnt(0)
	v_mfma_f32_16x16x32_bf16 v[92:95], v[160:163], v[176:179], v[92:95]
	v_mfma_f32_16x16x32_bf16 v[88:91], v[212:215], v[176:179], v[88:91]
	v_mfma_f32_16x16x32_bf16 v[84:87], v[160:163], v[184:187], v[84:87]
	v_mfma_f32_16x16x32_bf16 v[80:83], v[212:215], v[184:187], v[80:83]
	v_mfma_f32_16x16x32_bf16 v[76:79], v[160:163], v[192:195], v[76:79]
	v_mfma_f32_16x16x32_bf16 v[72:75], v[212:215], v[192:195], v[72:75]
	v_mfma_f32_16x16x32_bf16 v[68:71], v[160:163], v[200:203], v[68:71]
	v_mfma_f32_16x16x32_bf16 v[64:67], v[212:215], v[200:203], v[64:67]
	v_mfma_f32_16x16x32_bf16 v[176:179], v[208:211], v[180:183], v[92:95]
	v_mfma_f32_16x16x32_bf16 v[180:183], v[156:159], v[180:183], v[88:91]
	v_mfma_f32_16x16x32_bf16 v[184:187], v[208:211], v[188:191], v[84:87]
	v_mfma_f32_16x16x32_bf16 v[188:191], v[156:159], v[188:191], v[80:83]
	v_mfma_f32_16x16x32_bf16 v[192:195], v[208:211], v[196:199], v[76:79]
	v_mfma_f32_16x16x32_bf16 v[196:199], v[156:159], v[196:199], v[72:75]
	v_mfma_f32_16x16x32_bf16 v[200:203], v[208:211], v[204:207], v[68:71]
	v_mfma_f32_16x16x32_bf16 v[204:207], v[156:159], v[204:207], v[64:67]
	s_setprio 0
	s_barrier
	s_nop 0
	ds_read_b128 v[64:67], v153 offset:16384
	ds_read_b128 v[68:71], v153 offset:17408
	ds_read_b128 v[72:75], v152 offset:16384
	ds_read_b128 v[76:79], v152 offset:17408
	ds_read_b128 v[80:83], v151 offset:16384
	ds_read_b128 v[84:87], v151 offset:17408
	ds_read_b128 v[88:91], v150 offset:16384
	ds_read_b128 v[92:95], v150 offset:17408
	s_waitcnt vmcnt(4)
	s_barrier
	s_waitcnt lgkmcnt(0)
	s_setprio 1
	s_waitcnt lgkmcnt(0)
	v_mfma_f32_16x16x32_bf16 v[60:63], v[130:133], v[64:67], v[60:63]
	v_mfma_f32_16x16x32_bf16 v[56:59], v[168:171], v[64:67], v[56:59]
	v_mfma_f32_16x16x32_bf16 v[52:55], v[130:133], v[72:75], v[52:55]
	v_mfma_f32_16x16x32_bf16 v[48:51], v[168:171], v[72:75], v[48:51]
	v_mfma_f32_16x16x32_bf16 v[216:219], v[130:133], v[80:83], v[44:47]
	v_mfma_f32_16x16x32_bf16 v[220:223], v[168:171], v[80:83], v[40:43]
	v_mfma_f32_16x16x32_bf16 v[130:133], v[130:133], v[88:91], v[36:39]
	v_mfma_f32_16x16x32_bf16 v[168:171], v[168:171], v[88:91], v[32:35]
	v_mfma_f32_16x16x32_bf16 v[32:35], v[164:167], v[68:71], v[60:63]
	v_mfma_f32_16x16x32_bf16 v[36:39], v[172:175], v[68:71], v[56:59]
	v_mfma_f32_16x16x32_bf16 v[40:43], v[164:167], v[76:79], v[52:55]
	v_mfma_f32_16x16x32_bf16 v[44:47], v[172:175], v[76:79], v[48:51]
	v_mfma_f32_16x16x32_bf16 v[48:51], v[164:167], v[84:87], v[216:219]
	v_mfma_f32_16x16x32_bf16 v[52:55], v[172:175], v[84:87], v[220:223]
	v_mfma_f32_16x16x32_bf16 v[56:59], v[164:167], v[92:95], v[130:133]
	v_mfma_f32_16x16x32_bf16 v[60:63], v[172:175], v[92:95], v[168:171]
	s_setprio 0
	s_setprio 1
	v_mfma_f32_16x16x32_bf16 v[28:31], v[160:163], v[64:67], v[28:31]
	v_mfma_f32_16x16x32_bf16 v[24:27], v[212:215], v[64:67], v[24:27]
	v_mfma_f32_16x16x32_bf16 v[20:23], v[160:163], v[72:75], v[20:23]
	v_mfma_f32_16x16x32_bf16 v[64:67], v[212:215], v[72:75], v[16:19]
	v_mfma_f32_16x16x32_bf16 v[72:75], v[160:163], v[80:83], v[12:15]
	v_mfma_f32_16x16x32_bf16 v[8:11], v[212:215], v[80:83], v[8:11]
	v_mfma_f32_16x16x32_bf16 v[80:83], v[160:163], v[88:91], v[4:7]
	v_mfma_f32_16x16x32_bf16 v[0:3], v[212:215], v[88:91], v[0:3]
	v_mfma_f32_16x16x32_bf16 v[4:7], v[208:211], v[68:71], v[28:31]
	v_mfma_f32_16x16x32_bf16 v[12:15], v[156:159], v[68:71], v[24:27]
	v_mfma_f32_16x16x32_bf16 v[16:19], v[208:211], v[76:79], v[20:23]
	v_mfma_f32_16x16x32_bf16 v[20:23], v[156:159], v[76:79], v[64:67]
	v_mfma_f32_16x16x32_bf16 v[24:27], v[208:211], v[84:87], v[72:75]
	v_mfma_f32_16x16x32_bf16 v[28:31], v[156:159], v[84:87], v[8:11]
	v_mfma_f32_16x16x32_bf16 v[64:67], v[208:211], v[92:95], v[80:83]
	v_mfma_f32_16x16x32_bf16 v[68:71], v[156:159], v[92:95], v[0:3]
	s_setprio 0
	s_barrier
	ds_read_b128 v[8:11], v155
	ds_read_b128 v[0:3], v155 offset:1024
	ds_read_b128 v[76:79], v155 offset:2048
	ds_read_b128 v[72:75], v155 offset:3072
	ds_read_b128 v[130:133], v153 offset:32768
	ds_read_b128 v[156:159], v153 offset:33792
	ds_read_b128 v[160:163], v152 offset:32768
	ds_read_b128 v[164:167], v152 offset:33792
	ds_read_b128 v[168:171], v151 offset:32768
	ds_read_b128 v[172:175], v151 offset:33792
	ds_read_b128 v[208:211], v150 offset:32768
	ds_read_b128 v[212:215], v150 offset:33792
	s_waitcnt vmcnt(2)
	s_barrier
	s_waitcnt lgkmcnt(0)
	s_setprio 1
	s_waitcnt lgkmcnt(0)
	v_mfma_f32_16x16x32_bf16 v[80:83], v[8:11], v[130:133], v[124:127]
	v_mfma_f32_16x16x32_bf16 v[84:87], v[76:79], v[130:133], v[120:123]
	v_mfma_f32_16x16x32_bf16 v[88:91], v[8:11], v[160:163], v[116:119]
	v_mfma_f32_16x16x32_bf16 v[92:95], v[76:79], v[160:163], v[112:115]
	v_mfma_f32_16x16x32_bf16 v[108:111], v[8:11], v[168:171], v[108:111]
	v_mfma_f32_16x16x32_bf16 v[104:107], v[76:79], v[168:171], v[104:107]
	v_mfma_f32_16x16x32_bf16 v[100:103], v[8:11], v[208:211], v[100:103]
	v_mfma_f32_16x16x32_bf16 v[96:99], v[76:79], v[208:211], v[96:99]
	v_mfma_f32_16x16x32_bf16 v[112:115], v[0:3], v[156:159], v[80:83]
	v_mfma_f32_16x16x32_bf16 v[116:119], v[72:75], v[156:159], v[84:87]
	v_mfma_f32_16x16x32_bf16 v[120:123], v[0:3], v[164:167], v[88:91]
	v_mfma_f32_16x16x32_bf16 v[124:127], v[72:75], v[164:167], v[92:95]
	v_mfma_f32_16x16x32_bf16 v[108:111], v[0:3], v[172:175], v[108:111]
	v_mfma_f32_16x16x32_bf16 v[104:107], v[72:75], v[172:175], v[104:107]
	v_mfma_f32_16x16x32_bf16 v[100:103], v[0:3], v[212:215], v[100:103]
	v_mfma_f32_16x16x32_bf16 v[96:99], v[72:75], v[212:215], v[96:99]
	s_setprio 0
	s_barrier
	ds_read_b128 v[88:91], v154
	ds_read_b128 v[80:83], v154 offset:1024
	ds_read_b128 v[92:95], v154 offset:2048
	ds_read_b128 v[84:87], v154 offset:3072
	s_waitcnt vmcnt(0)
	s_barrier
	s_waitcnt lgkmcnt(0)
	s_setprio 1
	s_waitcnt lgkmcnt(0)
	v_mfma_f32_16x16x32_bf16 v[176:179], v[88:91], v[130:133], v[176:179]
	v_mfma_f32_16x16x32_bf16 v[130:133], v[92:95], v[130:133], v[180:183]
	v_mfma_f32_16x16x32_bf16 v[180:183], v[88:91], v[160:163], v[184:187]
	v_mfma_f32_16x16x32_bf16 v[160:163], v[92:95], v[160:163], v[188:191]
	v_mfma_f32_16x16x32_bf16 v[184:187], v[88:91], v[168:171], v[192:195]
	v_mfma_f32_16x16x32_bf16 v[168:171], v[92:95], v[168:171], v[196:199]
	v_mfma_f32_16x16x32_bf16 v[188:191], v[88:91], v[208:211], v[200:203]
	v_mfma_f32_16x16x32_bf16 v[192:195], v[92:95], v[208:211], v[204:207]
	v_mfma_f32_16x16x32_bf16 v[176:179], v[80:83], v[156:159], v[176:179]
	v_mfma_f32_16x16x32_bf16 v[130:133], v[84:87], v[156:159], v[130:133]
	v_mfma_f32_16x16x32_bf16 v[154:157], v[80:83], v[164:167], v[180:183]
	v_mfma_f32_16x16x32_bf16 v[158:161], v[84:87], v[164:167], v[160:163]
	v_mfma_f32_16x16x32_bf16 v[162:165], v[80:83], v[172:175], v[184:187]
	v_mfma_f32_16x16x32_bf16 v[166:169], v[84:87], v[172:175], v[168:171]
	v_mfma_f32_16x16x32_bf16 v[170:173], v[80:83], v[212:215], v[188:191]
	v_mfma_f32_16x16x32_bf16 v[180:183], v[84:87], v[212:215], v[192:195]
	s_setprio 0
	s_barrier
	v_mbcnt_lo_u32_b32 v128, -1, 0
	v_mbcnt_hi_u32_b32 v128, -1, v128
	v_cvt_pk_bf16_f32 v112, v112, v113
	v_cvt_pk_bf16_f32 v113, v114, v115
	v_cvt_pk_bf16_f32 v114, v116, v117
	v_cvt_pk_bf16_f32 v115, v118, v119
	s_lshl_b32 s66, s64, 9
	v_add_u32_e32 v174, s72, v128
	v_ashrrev_i32_e32 v175, 6, v174
	v_and_b32_e32 v184, 15, v128
	v_and_b32_e32 v185, 48, v128
	v_mul_lo_u32 v186, v175, s77
	v_bfe_u32 v187, v128, 3, 3
	v_lshlrev_b32_e32 v128, 4, v128
	v_add_u32_e32 v186, 0x20000, v186
	v_lshrrev_b32_e32 v174, 2, v174
	v_and_b32_e32 v128, 0x70, v128
	v_mul_u32_u24_e32 v184, 0x90, v184
	v_and_b32_e32 v174, 64, v174
	v_add3_u32 v184, v186, v184, v185
	v_or_b32_e32 v185, v186, v128
	v_or3_b32 v174, s24, v174, v187
	v_mad_u32_u24 v185, v187, s78, v185
	ds_write_b128 v184, v[112:115]
	v_cvt_pk_bf16_f32 v112, v176, v177
	v_cvt_pk_bf16_f32 v113, v178, v179
	v_cvt_pk_bf16_f32 v114, v130, v131
	v_cvt_pk_bf16_f32 v115, v132, v133
	ds_write_b128 v184, v[112:115] offset:64
	v_lshlrev_b32_e32 v175, 7, v175
	ds_read_b128 v[112:115], v185
	v_lshlrev_b32_e32 v116, 12, v174
	v_and_or_b32 v116, v175, s79, v116
	v_or3_b32 v128, v116, s66, v128
	ds_read_b128 v[116:119], v185 offset:1152
	v_lshl_add_u64 v[130:131], s[0:1], 0, v[128:129]
	s_mov_b32 s64, 0x8000
	s_waitcnt lgkmcnt(0)
	global_store_dwordx4 v128, v[112:115], s[0:1]
	v_cvt_pk_bf16_f32 v108, v108, v109
	v_cvt_pk_bf16_f32 v109, v110, v111
	v_cvt_pk_bf16_f32 v110, v104, v105
	v_cvt_pk_bf16_f32 v111, v106, v107
	v_cvt_pk_bf16_f32 v104, v162, v163
	s_nop 1
	v_add_co_u32_e32 v112, vcc, s64, v130
	v_cvt_pk_bf16_f32 v114, v124, v125
	v_cvt_pk_bf16_f32 v115, v126, v127
	v_cvt_pk_bf16_f32 v105, v164, v165
	v_cvt_pk_bf16_f32 v106, v166, v167
	s_nop 1
	v_addc_co_u32_e32 v113, vcc, 0, v131, vcc
	global_store_dwordx4 v[112:113], v[116:119], off
	v_cvt_pk_bf16_f32 v112, v120, v121
	v_cvt_pk_bf16_f32 v113, v122, v123
	ds_write_b128 v184, v[112:115]
	v_cvt_pk_bf16_f32 v112, v154, v155
	v_cvt_pk_bf16_f32 v113, v156, v157
	v_cvt_pk_bf16_f32 v114, v158, v159
	v_cvt_pk_bf16_f32 v115, v160, v161
	ds_write_b128 v184, v[112:115] offset:64
	ds_read_b128 v[112:115], v185
	ds_read_b128 v[116:119], v185 offset:1152
	v_add_co_u32_e32 v120, vcc, s74, v130
	ds_write_b128 v184, v[108:111]
	v_cvt_pk_bf16_f32 v107, v168, v169
	ds_write_b128 v184, v[104:107] offset:64
	v_addc_co_u32_e32 v121, vcc, 0, v131, vcc
	ds_read_b128 v[104:107], v185
	ds_read_b128 v[108:111], v185 offset:1152
	s_waitcnt lgkmcnt(0)
	global_store_dwordx4 v[120:121], v[112:115], off
	v_cvt_pk_bf16_f32 v100, v100, v101
	v_cvt_pk_bf16_f32 v101, v102, v103
	v_cvt_pk_bf16_f32 v102, v96, v97
	v_cvt_pk_bf16_f32 v103, v98, v99
	ds_write_b128 v184, v[100:103]
	s_nop 0
	v_add_co_u32_e32 v112, vcc, s75, v130
	v_cvt_pk_bf16_f32 v96, v170, v171
	v_cvt_pk_bf16_f32 v97, v172, v173
	v_cvt_pk_bf16_f32 v98, v180, v181
	v_cvt_pk_bf16_f32 v99, v182, v183
	s_nop 1
	v_addc_co_u32_e32 v113, vcc, 0, v131, vcc
	global_store_dwordx4 v[112:113], v[116:119], off
	v_add_co_u32_e32 v112, vcc, s76, v130
	ds_write_b128 v184, v[96:99] offset:64
	s_nop 0
	v_addc_co_u32_e32 v113, vcc, 0, v131, vcc
	ds_read_b128 v[96:99], v185
	ds_read_b128 v[100:103], v185 offset:1152
	global_store_dwordx4 v[112:113], v[104:107], off
	s_nop 1
	v_add_co_u32_e32 v104, vcc, s80, v130
	s_nop 1
	v_addc_co_u32_e32 v105, vcc, 0, v131, vcc
	global_store_dwordx4 v[104:105], v[108:111], off
	v_add_co_u32_e32 v104, vcc, s81, v130
	s_nop 1
	v_addc_co_u32_e32 v105, vcc, 0, v131, vcc
	s_waitcnt lgkmcnt(0)
	global_store_dwordx4 v[104:105], v[96:99], off
	s_nop 1
	v_add_co_u32_e32 v96, vcc, s82, v130
	s_nop 1
	v_addc_co_u32_e32 v97, vcc, 0, v131, vcc
	global_store_dwordx4 v[96:97], v[100:103], off
	ds_read_b128 v[96:99], v153 offset:49152
	ds_read_b128 v[100:103], v153 offset:50176
	ds_read_b128 v[104:107], v152 offset:49152
	ds_read_b128 v[108:111], v152 offset:50176
	ds_read_b128 v[112:115], v151 offset:49152
	ds_read_b128 v[116:119], v151 offset:50176
	ds_read_b128 v[120:123], v150 offset:49152
	ds_read_b128 v[124:127], v150 offset:50176
	s_barrier
	s_waitcnt lgkmcnt(0)
	s_setprio 1
	s_waitcnt lgkmcnt(0)
	v_mfma_f32_16x16x32_bf16 v[32:35], v[8:11], v[96:99], v[32:35]
	v_mfma_f32_16x16x32_bf16 v[36:39], v[76:79], v[96:99], v[36:39]
	v_mfma_f32_16x16x32_bf16 v[40:43], v[8:11], v[104:107], v[40:43]
	v_mfma_f32_16x16x32_bf16 v[130:133], v[76:79], v[104:107], v[44:47]
	v_mfma_f32_16x16x32_bf16 v[150:153], v[8:11], v[112:115], v[48:51]
	v_mfma_f32_16x16x32_bf16 v[52:55], v[76:79], v[112:115], v[52:55]
	v_mfma_f32_16x16x32_bf16 v[8:11], v[8:11], v[120:123], v[56:59]
	v_mfma_f32_16x16x32_bf16 v[60:63], v[76:79], v[120:123], v[60:63]
	v_mfma_f32_16x16x32_bf16 v[56:59], v[0:3], v[100:103], v[32:35]
	v_mfma_f32_16x16x32_bf16 v[48:51], v[72:75], v[100:103], v[36:39]
	v_mfma_f32_16x16x32_bf16 v[44:47], v[0:3], v[108:111], v[40:43]
	v_mfma_f32_16x16x32_bf16 v[40:43], v[72:75], v[108:111], v[130:133]
	v_mfma_f32_16x16x32_bf16 v[36:39], v[0:3], v[116:119], v[150:153]
	v_mfma_f32_16x16x32_bf16 v[32:35], v[72:75], v[116:119], v[52:55]
	v_mfma_f32_16x16x32_bf16 v[8:11], v[0:3], v[124:127], v[8:11]
	v_mfma_f32_16x16x32_bf16 v[0:3], v[72:75], v[124:127], v[60:63]
	s_setprio 0
	s_setprio 1
	v_mfma_f32_16x16x32_bf16 v[4:7], v[88:91], v[96:99], v[4:7]
	v_mfma_f32_16x16x32_bf16 v[12:15], v[92:95], v[96:99], v[12:15]
	v_mfma_f32_16x16x32_bf16 v[16:19], v[88:91], v[104:107], v[16:19]
	v_mfma_f32_16x16x32_bf16 v[20:23], v[92:95], v[104:107], v[20:23]
	v_mfma_f32_16x16x32_bf16 v[72:75], v[88:91], v[112:115], v[24:27]
	v_mfma_f32_16x16x32_bf16 v[76:79], v[92:95], v[112:115], v[28:31]
	v_mfma_f32_16x16x32_bf16 v[64:67], v[88:91], v[120:123], v[64:67]
	v_mfma_f32_16x16x32_bf16 v[68:71], v[92:95], v[120:123], v[68:71]
	v_mfma_f32_16x16x32_bf16 v[60:63], v[80:83], v[100:103], v[4:7]
	v_mfma_f32_16x16x32_bf16 v[52:55], v[84:87], v[100:103], v[12:15]
	v_mfma_f32_16x16x32_bf16 v[28:31], v[80:83], v[108:111], v[16:19]
	v_mfma_f32_16x16x32_bf16 v[24:27], v[84:87], v[108:111], v[20:23]
	v_mfma_f32_16x16x32_bf16 v[20:23], v[80:83], v[116:119], v[72:75]
	v_mfma_f32_16x16x32_bf16 v[16:19], v[84:87], v[116:119], v[76:79]
	v_mfma_f32_16x16x32_bf16 v[12:15], v[80:83], v[124:127], v[64:67]
	v_mfma_f32_16x16x32_bf16 v[4:7], v[84:87], v[124:127], v[68:71]
	s_setprio 0
	v_cmp_gt_u32_e32 vcc, s83, v136
	s_barrier
	s_and_saveexec_b64 s[64:65], vcc
	s_cbranch_execz .LBB0_181
	s_barrier

.LBB0_233:
	v_bfe_i32 v5, v179, 27, 1
	v_lshlrev_b32_e32 v169, 4, v179
	v_lshrrev_b32_e32 v5, 22, v5
	v_add_u32_e32 v5, v169, v5
	v_and_b32_e32 v5, 0xfffffc00, v5
	v_sub_u32_e32 v5, v169, v5
	v_lshrrev_b32_e32 v6, 4, v5
	v_bitop3_b32 v5, v6, v5, 32 bitop3:0x6c
	v_ashrrev_i32_e32 v6, 31, v5
	v_lshrrev_b32_e32 v6, 26, v6
	v_ashrrev_i32_e32 v4, 31, v179
	v_add_u32_e32 v6, v5, v6
	s_lshl_b32 s56, s83, 3
	v_lshrrev_b32_e32 v4, 26, v4
	v_ashrrev_i32_e32 v133, 6, v6
	v_and_b32_e32 v6, 0xc0, v6
	s_ff1_i32_b32 s57, s56
	s_add_i32 s56, s56, -1
	v_and_b32_e32 v2, 15, v0
	v_and_b32_e32 v3, 48, v0
	v_add_u32_e32 v4, v179, v4
	v_sub_u32_e32 v5, v5, v6
	v_and_b32_e32 v6, 32, v0
	v_lshlrev_b32_e32 v10, 2, v0
	v_lshlrev_b32_e32 v0, 6, v0
	s_lshr_b32 s62, s85, s57
	s_and_b32 s56, s85, s56
	s_and_b32 s63, s85, 7
	v_ashrrev_i32_e32 v131, 6, v4
	v_lshlrev_b32_e32 v2, 6, v2
	v_and_b32_e32 v10, 32, v10
	v_and_b32_e32 v0, 0x3c0, v0
	s_lshr_b32 s80, s56, 3
	v_or_b32_e32 v9, v2, v3
	v_bitop3_b32 v2, v2, v10, v3 bitop3:0x36
	v_bitop3_b32 v3, v0, v10, v3 bitop3:0x36
	s_lshl_b32 s56, s62, 11
	s_lshl_b32 s57, s63, 8
	v_lshlrev_b32_e32 v0, 16, v131
	s_or_b32 s56, s56, s57
	s_mov_b32 s57, s15
	v_and_b32_e32 v0, 0xfffe0000, v0
	s_lshl_b32 s60, s80, 14
	v_ashrrev_i16_sdwa v5, v167, sext(v5) dst_sel:DWORD dst_unused:UNUSED_PAD src0_sel:DWORD src1_sel:BYTE_0
	s_lshl_b64 s[56:57], s[56:57], 13
	v_lshl_add_u32 v0, v133, 13, v0
	v_bfe_i32 v134, v5, 0, 16
	v_and_or_b32 v0, v4, 64, v0
	s_add_u32 s56, s40, s56
	v_lshl_add_u32 v164, v134, 1, v0
	s_addc_u32 s57, s41, s57
	v_lshlrev_b32_e32 v14, 13, v1
	v_lshl_add_u64 v[0:1], s[56:57], 0, v[164:165]
	s_mul_i32 s57, s14, 0x1800
	s_mul_hi_u32 s56, s14, 0x1800
	s_add_u32 s57, s57, s60
	s_addc_u32 s58, s56, 0
	s_add_u32 s56, s65, s57
	v_bfe_i32 v7, v179, 6, 1
	s_addc_u32 s57, s66, s58
	s_lshl_b64 s[58:59], s[14:15], 12
	v_and_b32_e32 v7, s14, v7
	v_lshrrev_b32_e32 v8, 7, v179
	s_add_u32 s14, s58, s60
	v_add_lshl_u32 v7, v7, v8, 10
	v_lshlrev_b32_e32 v8, 6, v179
	s_addc_u32 s61, s59, 0
	v_and_b32_e32 v5, 0x3f0, v169
	v_and_b32_e32 v8, 0x3000, v8
	v_bitop3_b32 v11, v9, s67, v10 bitop3:0xde
	v_bitop3_b32 v12, v9, s69, v10 bitop3:0xde
	v_bitop3_b32 v13, v9, s70, v10 bitop3:0xde
	v_bitop3_b32 v9, v9, s71, v10 bitop3:0xde
	v_or_b32_e32 v10, 0x800, v14
	v_or_b32_e32 v15, 0x1000, v14
	v_or_b32_e32 v16, 0x1800, v14
	v_lshl_add_u64 v[128:129], v[0:1], 0, s[16:17]
	s_add_u32 s60, s65, s14
	v_mov_b32_e32 v0, 0
	v_bitop3_b32 v164, v5, v7, v6 bitop3:0xde
	s_addc_u32 s61, s66, s61
	s_mov_b32 s14, -2
	v_add_u32_e32 v138, v11, v8
	v_add_u32_e32 v193, v2, v14
	v_add_u32_e32 v192, v3, v10
	v_add_u32_e32 v191, v3, v15
	v_add_u32_e32 v190, v3, v16
	v_add_u32_e32 v137, 0xc000, v169
	v_add_u32_e32 v136, 0xe000, v169
	v_add_u32_e32 v135, v12, v8
	v_add_u32_e32 v189, 0x10000, v169
	v_add_u32_e32 v188, 0x12000, v169
	v_add_u32_e32 v187, 0x2000, v169
	v_add_u32_e32 v186, 0x14000, v169
	v_add_u32_e32 v185, 0x16000, v169
	v_add_u32_e32 v130, v13, v8
	v_add_u32_e32 v184, 0x4000, v169
	v_add_u32_e32 v183, 0x6000, v169
	v_add_u32_e32 v132, v9, v8
	v_add_u32_e32 v182, 0x18000, v169
	v_add_u32_e32 v181, 0x1a000, v169
	v_add_u32_e32 v177, 0x8000, v169
	v_add_u32_e32 v175, 0xa000, v169
	v_add_u32_e32 v173, 0x1c000, v169
	v_add_u32_e32 v171, 0x1e000, v169
	v_mov_b32_e32 v1, v0
	v_mov_b32_e32 v2, v0
	v_mov_b32_e32 v3, v0
	v_mov_b32_e32 v4, v0
	v_mov_b32_e32 v5, v0
	v_mov_b32_e32 v6, v0
	v_mov_b32_e32 v7, v0
	v_mov_b32_e32 v8, v0
	v_mov_b32_e32 v9, v0
	v_mov_b32_e32 v10, v0
	v_mov_b32_e32 v11, v0
	v_mov_b32_e32 v12, v0
	v_mov_b32_e32 v13, v0
	v_mov_b32_e32 v14, v0
	v_mov_b32_e32 v15, v0
	v_mov_b32_e32 v16, v0
	v_mov_b32_e32 v17, v0
	v_mov_b32_e32 v18, v0
	v_mov_b32_e32 v19, v0
	v_mov_b32_e32 v20, v0
	v_mov_b32_e32 v21, v0
	v_mov_b32_e32 v22, v0
	v_mov_b32_e32 v23, v0
	v_mov_b32_e32 v24, v0
	v_mov_b32_e32 v25, v0
	v_mov_b32_e32 v26, v0
	v_mov_b32_e32 v27, v0
	v_mov_b32_e32 v28, v0
	v_mov_b32_e32 v29, v0
	v_mov_b32_e32 v30, v0
	v_mov_b32_e32 v31, v0
	v_mov_b32_e32 v32, v0
	v_mov_b32_e32 v33, v0
	v_mov_b32_e32 v34, v0
	v_mov_b32_e32 v35, v0
	v_mov_b32_e32 v36, v0
	v_mov_b32_e32 v37, v0
	v_mov_b32_e32 v38, v0
	v_mov_b32_e32 v39, v0
	v_mov_b32_e32 v40, v0
	v_mov_b32_e32 v41, v0
	v_mov_b32_e32 v42, v0
	v_mov_b32_e32 v43, v0
	v_mov_b32_e32 v44, v0
	v_mov_b32_e32 v45, v0
	v_mov_b32_e32 v46, v0
	v_mov_b32_e32 v47, v0
	v_mov_b32_e32 v48, v0
	v_mov_b32_e32 v49, v0
	v_mov_b32_e32 v50, v0
	v_mov_b32_e32 v51, v0
	v_mov_b32_e32 v52, v0
	v_mov_b32_e32 v53, v0
	v_mov_b32_e32 v54, v0
	v_mov_b32_e32 v55, v0
	v_mov_b32_e32 v56, v0
	v_mov_b32_e32 v57, v0
	v_mov_b32_e32 v58, v0
	v_mov_b32_e32 v59, v0
	v_mov_b32_e32 v60, v0
	v_mov_b32_e32 v61, v0
	v_mov_b32_e32 v62, v0
	v_mov_b32_e32 v63, v0
	v_mov_b32_e32 v64, v0
	v_mov_b32_e32 v65, v0
	v_mov_b32_e32 v66, v0
	v_mov_b32_e32 v67, v0
	v_mov_b32_e32 v68, v0
	v_mov_b32_e32 v69, v0
	v_mov_b32_e32 v70, v0
	v_mov_b32_e32 v71, v0
	v_mov_b32_e32 v72, v0
	v_mov_b32_e32 v73, v0
	v_mov_b32_e32 v74, v0
	v_mov_b32_e32 v75, v0
	v_mov_b32_e32 v76, v0
	v_mov_b32_e32 v77, v0
	v_mov_b32_e32 v78, v0
	v_mov_b32_e32 v79, v0
	v_mov_b32_e32 v80, v0
	v_mov_b32_e32 v81, v0
	v_mov_b32_e32 v82, v0
	v_mov_b32_e32 v83, v0
	v_mov_b32_e32 v84, v0
	v_mov_b32_e32 v85, v0
	v_mov_b32_e32 v86, v0
	v_mov_b32_e32 v87, v0
	v_mov_b32_e32 v88, v0
	v_mov_b32_e32 v89, v0
	v_mov_b32_e32 v90, v0
	v_mov_b32_e32 v91, v0
	v_mov_b32_e32 v92, v0
	v_mov_b32_e32 v93, v0
	v_mov_b32_e32 v94, v0
	v_mov_b32_e32 v95, v0
	v_mov_b32_e32 v96, v0
	v_mov_b32_e32 v97, v0
	v_mov_b32_e32 v98, v0
	v_mov_b32_e32 v99, v0
	v_mov_b32_e32 v100, v0
	v_mov_b32_e32 v101, v0
	v_mov_b32_e32 v102, v0
	v_mov_b32_e32 v103, v0
	v_mov_b32_e32 v104, v0
	v_mov_b32_e32 v105, v0
	v_mov_b32_e32 v106, v0
	v_mov_b32_e32 v107, v0
	v_mov_b32_e32 v108, v0
	v_mov_b32_e32 v109, v0
	v_mov_b32_e32 v110, v0
	v_mov_b32_e32 v111, v0
	v_mov_b32_e32 v112, v0
	v_mov_b32_e32 v113, v0
	v_mov_b32_e32 v114, v0
	v_mov_b32_e32 v115, v0
	v_mov_b32_e32 v116, v0
	v_mov_b32_e32 v117, v0
	v_mov_b32_e32 v118, v0
	v_mov_b32_e32 v119, v0
	v_mov_b32_e32 v120, v0
	v_mov_b32_e32 v121, v0
	v_mov_b32_e32 v122, v0
	v_mov_b32_e32 v123, v0
	v_mov_b32_e32 v124, v0
	v_mov_b32_e32 v125, v0
	v_mov_b32_e32 v126, v0
	v_mov_b32_e32 v127, v0
	s_barrier
	v_readfirstlane_b32 s82, v137
	v_lshl_add_u64 v[142:143], v[128:129], 0, s[18:19]
	s_mov_b32 m0, s82
	v_readfirstlane_b32 s82, v136
	global_load_lds_dwordx4 v[142:143], off
	v_lshl_add_u64 v[142:143], v[128:129], 0, s[20:21]
	s_mov_b32 m0, s82
	s_nop 0
	global_load_lds_dwordx4 v[142:143], off
.LBB0_234:
	ds_read_b128 v[140:143], v138
	ds_read_b128 v[144:147], v138 offset:1024
	ds_read_b128 v[148:151], v138 offset:2048
	ds_read_b128 v[152:155], v138 offset:3072
	ds_read_b128 v[156:159], v193
	ds_read_b128 v[160:163], v193 offset:1024
	ds_read_b128 v[194:197], v192
	ds_read_b128 v[198:201], v192 offset:1024
	ds_read_b128 v[202:205], v191
	ds_read_b128 v[206:209], v191 offset:1024
	ds_read_b128 v[210:213], v190
	ds_read_b128 v[214:217], v190 offset:1024
	s_waitcnt lgkmcnt(8)
	s_barrier
	s_waitcnt lgkmcnt(0)
	s_setprio 1
	s_waitcnt lgkmcnt(0)
	v_mfma_f32_16x16x32_bf16 v[124:127], v[140:143], v[156:159], v[124:127]
	v_mfma_f32_16x16x32_bf16 v[120:123], v[148:151], v[156:159], v[120:123]
	v_mfma_f32_16x16x32_bf16 v[116:119], v[140:143], v[194:197], v[116:119]
	v_mfma_f32_16x16x32_bf16 v[112:115], v[148:151], v[194:197], v[112:115]
	v_mfma_f32_16x16x32_bf16 v[108:111], v[140:143], v[202:205], v[108:111]
	v_mfma_f32_16x16x32_bf16 v[104:107], v[148:151], v[202:205], v[104:107]
	v_mfma_f32_16x16x32_bf16 v[100:103], v[140:143], v[210:213], v[100:103]
	v_mfma_f32_16x16x32_bf16 v[96:99], v[148:151], v[210:213], v[96:99]
	v_mfma_f32_16x16x32_bf16 v[124:127], v[144:147], v[160:163], v[124:127]
	v_mfma_f32_16x16x32_bf16 v[120:123], v[152:155], v[160:163], v[120:123]
	v_mfma_f32_16x16x32_bf16 v[116:119], v[144:147], v[198:201], v[116:119]
	v_mfma_f32_16x16x32_bf16 v[112:115], v[152:155], v[198:201], v[112:115]
	v_mfma_f32_16x16x32_bf16 v[108:111], v[144:147], v[206:209], v[108:111]
	v_mfma_f32_16x16x32_bf16 v[104:107], v[152:155], v[206:209], v[104:107]
	v_mfma_f32_16x16x32_bf16 v[100:103], v[144:147], v[214:217], v[100:103]
	v_mfma_f32_16x16x32_bf16 v[96:99], v[152:155], v[214:217], v[96:99]
	s_setprio 0
	s_barrier
	v_readfirstlane_b32 s82, v189
	v_lshl_add_u64 v[234:235], s[60:61], 0, v[164:165]
	s_mov_b32 m0, s82
	v_readfirstlane_b32 s82, v188
	ds_read_b128 v[218:221], v135
	ds_read_b128 v[222:225], v135 offset:1024
	ds_read_b128 v[226:229], v135 offset:2048
	ds_read_b128 v[230:233], v135 offset:3072
	global_load_lds_dwordx4 v[234:235], off
	v_lshl_add_u64 v[236:237], v[234:235], 0, s[2:3]
	s_mov_b32 m0, s82
	s_nop 0
	global_load_lds_dwordx4 v[236:237], off
	s_barrier
	s_waitcnt lgkmcnt(0)
	s_setprio 1
	s_waitcnt lgkmcnt(0)
	v_mfma_f32_16x16x32_bf16 v[92:95], v[218:221], v[156:159], v[92:95]
	v_mfma_f32_16x16x32_bf16 v[88:91], v[226:229], v[156:159], v[88:91]
	v_mfma_f32_16x16x32_bf16 v[84:87], v[218:221], v[194:197], v[84:87]
	v_mfma_f32_16x16x32_bf16 v[80:83], v[226:229], v[194:197], v[80:83]
	v_mfma_f32_16x16x32_bf16 v[76:79], v[218:221], v[202:205], v[76:79]
	v_mfma_f32_16x16x32_bf16 v[72:75], v[226:229], v[202:205], v[72:75]
	v_mfma_f32_16x16x32_bf16 v[68:71], v[218:221], v[210:213], v[68:71]
	v_mfma_f32_16x16x32_bf16 v[64:67], v[226:229], v[210:213], v[64:67]
	v_mfma_f32_16x16x32_bf16 v[92:95], v[222:225], v[160:163], v[92:95]
	v_mfma_f32_16x16x32_bf16 v[88:91], v[230:233], v[160:163], v[88:91]
	v_mfma_f32_16x16x32_bf16 v[84:87], v[222:225], v[198:201], v[84:87]
	v_mfma_f32_16x16x32_bf16 v[80:83], v[230:233], v[198:201], v[80:83]
	v_mfma_f32_16x16x32_bf16 v[76:79], v[222:225], v[206:209], v[76:79]
	v_mfma_f32_16x16x32_bf16 v[72:75], v[230:233], v[206:209], v[72:75]
	v_mfma_f32_16x16x32_bf16 v[68:71], v[222:225], v[214:217], v[68:71]
	v_mfma_f32_16x16x32_bf16 v[64:67], v[230:233], v[214:217], v[64:67]
	s_setprio 0
	v_readfirstlane_b32 s82, v169
	v_lshl_add_u64 v[236:237], v[128:129], 0, s[22:23]
	s_mov_b32 m0, s82
	v_readfirstlane_b32 s82, v187
	s_barrier
	ds_read_b128 v[156:159], v193 offset:16384
	ds_read_b128 v[160:163], v193 offset:17408
	ds_read_b128 v[194:197], v192 offset:16384
	ds_read_b128 v[198:201], v192 offset:17408
	ds_read_b128 v[202:205], v191 offset:16384
	ds_read_b128 v[206:209], v191 offset:17408
	ds_read_b128 v[210:213], v190 offset:16384
	ds_read_b128 v[214:217], v190 offset:17408
	global_load_lds_dwordx4 v[236:237], off
	v_lshl_add_u64 v[236:237], v[128:129], 0, s[24:25]
	s_mov_b32 m0, s82
	s_nop 0
	global_load_lds_dwordx4 v[236:237], off
	s_barrier
	s_waitcnt lgkmcnt(0)
	s_setprio 1
	s_waitcnt lgkmcnt(0)
	v_mfma_f32_16x16x32_bf16 v[60:63], v[140:143], v[156:159], v[60:63]
	v_mfma_f32_16x16x32_bf16 v[56:59], v[148:151], v[156:159], v[56:59]
	v_mfma_f32_16x16x32_bf16 v[52:55], v[140:143], v[194:197], v[52:55]
	v_mfma_f32_16x16x32_bf16 v[48:51], v[148:151], v[194:197], v[48:51]
	v_mfma_f32_16x16x32_bf16 v[44:47], v[140:143], v[202:205], v[44:47]
	v_mfma_f32_16x16x32_bf16 v[40:43], v[148:151], v[202:205], v[40:43]
	v_mfma_f32_16x16x32_bf16 v[36:39], v[140:143], v[210:213], v[36:39]
	v_mfma_f32_16x16x32_bf16 v[32:35], v[148:151], v[210:213], v[32:35]
	v_mfma_f32_16x16x32_bf16 v[60:63], v[144:147], v[160:163], v[60:63]
	v_mfma_f32_16x16x32_bf16 v[56:59], v[152:155], v[160:163], v[56:59]
	v_mfma_f32_16x16x32_bf16 v[52:55], v[144:147], v[198:201], v[52:55]
	v_mfma_f32_16x16x32_bf16 v[48:51], v[152:155], v[198:201], v[48:51]
	v_mfma_f32_16x16x32_bf16 v[44:47], v[144:147], v[206:209], v[44:47]
	v_mfma_f32_16x16x32_bf16 v[40:43], v[152:155], v[206:209], v[40:43]
	v_mfma_f32_16x16x32_bf16 v[36:39], v[144:147], v[214:217], v[36:39]
	v_mfma_f32_16x16x32_bf16 v[32:35], v[152:155], v[214:217], v[32:35]
	s_setprio 0
	s_barrier
	v_readfirstlane_b32 s82, v186
	v_lshl_add_u64 v[140:141], v[234:235], 0, s[6:7]
	s_mov_b32 m0, s82
	v_readfirstlane_b32 s82, v185
	global_load_lds_dwordx4 v[140:141], off
	v_lshl_add_u64 v[140:141], v[234:235], 0, s[8:9]
	s_mov_b32 m0, s82
	s_nop 0
	global_load_lds_dwordx4 v[140:141], off
	v_readfirstlane_b32 s82, v184
	v_lshl_add_u64 v[142:143], v[128:129], 0, s[26:27]
	s_mov_b32 m0, s82
	v_readfirstlane_b32 s82, v183
	global_load_lds_dwordx4 v[142:143], off
	s_mov_b32 m0, s82
	s_nop 0
	global_load_lds_dwordx4 v[128:129], off
	s_waitcnt vmcnt(8)
	s_barrier
	s_setprio 1
	v_mfma_f32_16x16x32_bf16 v[28:31], v[218:221], v[156:159], v[28:31]
	v_mfma_f32_16x16x32_bf16 v[24:27], v[226:229], v[156:159], v[24:27]
	v_mfma_f32_16x16x32_bf16 v[20:23], v[218:221], v[194:197], v[20:23]
	v_mfma_f32_16x16x32_bf16 v[16:19], v[226:229], v[194:197], v[16:19]
	v_mfma_f32_16x16x32_bf16 v[12:15], v[218:221], v[202:205], v[12:15]
	v_mfma_f32_16x16x32_bf16 v[8:11], v[226:229], v[202:205], v[8:11]
	v_mfma_f32_16x16x32_bf16 v[4:7], v[218:221], v[210:213], v[4:7]
	v_mfma_f32_16x16x32_bf16 v[0:3], v[226:229], v[210:213], v[0:3]
	v_mfma_f32_16x16x32_bf16 v[28:31], v[222:225], v[160:163], v[28:31]
	v_mfma_f32_16x16x32_bf16 v[24:27], v[230:233], v[160:163], v[24:27]
	v_mfma_f32_16x16x32_bf16 v[20:23], v[222:225], v[198:201], v[20:23]
	v_mfma_f32_16x16x32_bf16 v[16:19], v[230:233], v[198:201], v[16:19]
	v_mfma_f32_16x16x32_bf16 v[12:15], v[222:225], v[206:209], v[12:15]
	v_mfma_f32_16x16x32_bf16 v[8:11], v[230:233], v[206:209], v[8:11]
	v_mfma_f32_16x16x32_bf16 v[4:7], v[222:225], v[214:217], v[4:7]
	v_mfma_f32_16x16x32_bf16 v[0:3], v[230:233], v[214:217], v[0:3]
	s_setprio 0
	s_barrier
	ds_read_b128 v[140:143], v130
	ds_read_b128 v[144:147], v130 offset:1024
	ds_read_b128 v[148:151], v130 offset:2048
	ds_read_b128 v[152:155], v130 offset:3072
	ds_read_b128 v[156:159], v193 offset:32768
	ds_read_b128 v[160:163], v193 offset:33792
	ds_read_b128 v[194:197], v192 offset:32768
	ds_read_b128 v[198:201], v192 offset:33792
	ds_read_b128 v[202:205], v191 offset:32768
	ds_read_b128 v[206:209], v191 offset:33792
	ds_read_b128 v[210:213], v190 offset:32768
	ds_read_b128 v[214:217], v190 offset:33792
	s_waitcnt lgkmcnt(8)
	s_barrier
	s_waitcnt lgkmcnt(0)
	s_setprio 1
	s_waitcnt lgkmcnt(0)
	v_mfma_f32_16x16x32_bf16 v[124:127], v[140:143], v[156:159], v[124:127]
	v_mfma_f32_16x16x32_bf16 v[120:123], v[148:151], v[156:159], v[120:123]
	v_mfma_f32_16x16x32_bf16 v[116:119], v[140:143], v[194:197], v[116:119]
	v_mfma_f32_16x16x32_bf16 v[112:115], v[148:151], v[194:197], v[112:115]
	v_mfma_f32_16x16x32_bf16 v[108:111], v[140:143], v[202:205], v[108:111]
	v_mfma_f32_16x16x32_bf16 v[104:107], v[148:151], v[202:205], v[104:107]
	v_mfma_f32_16x16x32_bf16 v[100:103], v[140:143], v[210:213], v[100:103]
	v_mfma_f32_16x16x32_bf16 v[96:99], v[148:151], v[210:213], v[96:99]
	v_mfma_f32_16x16x32_bf16 v[124:127], v[144:147], v[160:163], v[124:127]
	v_mfma_f32_16x16x32_bf16 v[120:123], v[152:155], v[160:163], v[120:123]
	v_mfma_f32_16x16x32_bf16 v[116:119], v[144:147], v[198:201], v[116:119]
	v_mfma_f32_16x16x32_bf16 v[112:115], v[152:155], v[198:201], v[112:115]
	v_mfma_f32_16x16x32_bf16 v[108:111], v[144:147], v[206:209], v[108:111]
	v_mfma_f32_16x16x32_bf16 v[104:107], v[152:155], v[206:209], v[104:107]
	v_mfma_f32_16x16x32_bf16 v[100:103], v[144:147], v[214:217], v[100:103]
	v_mfma_f32_16x16x32_bf16 v[96:99], v[152:155], v[214:217], v[96:99]
	s_setprio 0
	s_barrier
	v_readfirstlane_b32 s82, v182
	v_lshl_add_u64 v[234:235], s[56:57], 0, v[164:165]
	s_mov_b32 m0, s82
	v_readfirstlane_b32 s82, v181
	ds_read_b128 v[218:221], v132
	ds_read_b128 v[222:225], v132 offset:1024
	ds_read_b128 v[226:229], v132 offset:2048
	ds_read_b128 v[230:233], v132 offset:3072
	global_load_lds_dwordx4 v[234:235], off
	v_lshl_add_u64 v[236:237], v[234:235], 0, s[2:3]
	s_mov_b32 m0, s82
	s_nop 0
	global_load_lds_dwordx4 v[236:237], off
	s_barrier
	s_waitcnt lgkmcnt(0)
	s_setprio 1
	s_waitcnt lgkmcnt(0)
	v_mfma_f32_16x16x32_bf16 v[92:95], v[218:221], v[156:159], v[92:95]
	v_mfma_f32_16x16x32_bf16 v[88:91], v[226:229], v[156:159], v[88:91]
	v_mfma_f32_16x16x32_bf16 v[84:87], v[218:221], v[194:197], v[84:87]
	v_mfma_f32_16x16x32_bf16 v[80:83], v[226:229], v[194:197], v[80:83]
	v_mfma_f32_16x16x32_bf16 v[76:79], v[218:221], v[202:205], v[76:79]
	v_mfma_f32_16x16x32_bf16 v[72:75], v[226:229], v[202:205], v[72:75]
	v_mfma_f32_16x16x32_bf16 v[68:71], v[218:221], v[210:213], v[68:71]
	v_mfma_f32_16x16x32_bf16 v[64:67], v[226:229], v[210:213], v[64:67]
	v_mfma_f32_16x16x32_bf16 v[92:95], v[222:225], v[160:163], v[92:95]
	v_mfma_f32_16x16x32_bf16 v[88:91], v[230:233], v[160:163], v[88:91]
	v_mfma_f32_16x16x32_bf16 v[84:87], v[222:225], v[198:201], v[84:87]
	v_mfma_f32_16x16x32_bf16 v[80:83], v[230:233], v[198:201], v[80:83]
	v_mfma_f32_16x16x32_bf16 v[76:79], v[222:225], v[206:209], v[76:79]
	v_mfma_f32_16x16x32_bf16 v[72:75], v[230:233], v[206:209], v[72:75]
	v_mfma_f32_16x16x32_bf16 v[68:71], v[222:225], v[214:217], v[68:71]
	v_mfma_f32_16x16x32_bf16 v[64:67], v[230:233], v[214:217], v[64:67]
	s_setprio 0
	v_readfirstlane_b32 s82, v177
	v_lshl_add_u64 v[236:237], v[128:129], 0, s[28:29]
	s_mov_b32 m0, s82
	v_readfirstlane_b32 s82, v175
	s_barrier
	ds_read_b128 v[156:159], v193 offset:49152
	ds_read_b128 v[160:163], v193 offset:50176
	ds_read_b128 v[194:197], v192 offset:49152
	ds_read_b128 v[198:201], v192 offset:50176
	ds_read_b128 v[202:205], v191 offset:49152
	ds_read_b128 v[206:209], v191 offset:50176
	ds_read_b128 v[210:213], v190 offset:49152
	ds_read_b128 v[214:217], v190 offset:50176
	global_load_lds_dwordx4 v[236:237], off
	v_lshl_add_u64 v[236:237], v[128:129], 0, s[30:31]
	s_mov_b32 m0, s82
	s_nop 0
	global_load_lds_dwordx4 v[236:237], off
	s_barrier
	s_waitcnt lgkmcnt(0)
	s_setprio 1
	s_waitcnt lgkmcnt(0)
	v_mfma_f32_16x16x32_bf16 v[60:63], v[140:143], v[156:159], v[60:63]
	v_mfma_f32_16x16x32_bf16 v[56:59], v[148:151], v[156:159], v[56:59]
	v_mfma_f32_16x16x32_bf16 v[52:55], v[140:143], v[194:197], v[52:55]
	v_mfma_f32_16x16x32_bf16 v[48:51], v[148:151], v[194:197], v[48:51]
	v_mfma_f32_16x16x32_bf16 v[44:47], v[140:143], v[202:205], v[44:47]
	v_mfma_f32_16x16x32_bf16 v[40:43], v[148:151], v[202:205], v[40:43]
	v_mfma_f32_16x16x32_bf16 v[36:39], v[140:143], v[210:213], v[36:39]
	v_mfma_f32_16x16x32_bf16 v[32:35], v[148:151], v[210:213], v[32:35]
	v_mfma_f32_16x16x32_bf16 v[60:63], v[144:147], v[160:163], v[60:63]
	v_mfma_f32_16x16x32_bf16 v[56:59], v[152:155], v[160:163], v[56:59]
	v_mfma_f32_16x16x32_bf16 v[52:55], v[144:147], v[198:201], v[52:55]
	v_mfma_f32_16x16x32_bf16 v[48:51], v[152:155], v[198:201], v[48:51]
	v_mfma_f32_16x16x32_bf16 v[44:47], v[144:147], v[206:209], v[44:47]
	v_mfma_f32_16x16x32_bf16 v[40:43], v[152:155], v[206:209], v[40:43]
	v_mfma_f32_16x16x32_bf16 v[36:39], v[144:147], v[214:217], v[36:39]
	v_mfma_f32_16x16x32_bf16 v[32:35], v[152:155], v[214:217], v[32:35]
	s_setprio 0
	s_barrier
	v_readfirstlane_b32 s82, v173
	v_lshl_add_u64 v[140:141], v[234:235], 0, s[6:7]
	s_mov_b32 m0, s82
	v_readfirstlane_b32 s82, v171
	global_load_lds_dwordx4 v[140:141], off
	v_lshl_add_u64 v[140:141], v[234:235], 0, s[8:9]
	s_mov_b32 m0, s82
	s_nop 0
	global_load_lds_dwordx4 v[140:141], off
	v_lshl_add_u64 v[128:129], v[128:129], 0, s[34:35]
	v_readfirstlane_b32 s82, v137
	v_lshl_add_u64 v[142:143], v[128:129], 0, s[18:19]
	s_mov_b32 m0, s82
	v_readfirstlane_b32 s82, v136
	global_load_lds_dwordx4 v[142:143], off
	v_lshl_add_u64 v[142:143], v[128:129], 0, s[20:21]
	s_mov_b32 m0, s82
	s_nop 0
	global_load_lds_dwordx4 v[142:143], off
	s_waitcnt vmcnt(8)
	s_barrier
	s_setprio 1
	v_mfma_f32_16x16x32_bf16 v[28:31], v[218:221], v[156:159], v[28:31]
	v_mfma_f32_16x16x32_bf16 v[24:27], v[226:229], v[156:159], v[24:27]
	v_mfma_f32_16x16x32_bf16 v[20:23], v[218:221], v[194:197], v[20:23]
	v_mfma_f32_16x16x32_bf16 v[16:19], v[226:229], v[194:197], v[16:19]
	v_mfma_f32_16x16x32_bf16 v[12:15], v[218:221], v[202:205], v[12:15]
	v_mfma_f32_16x16x32_bf16 v[8:11], v[226:229], v[202:205], v[8:11]
	v_mfma_f32_16x16x32_bf16 v[4:7], v[218:221], v[210:213], v[4:7]
	v_mfma_f32_16x16x32_bf16 v[0:3], v[226:229], v[210:213], v[0:3]
	v_mfma_f32_16x16x32_bf16 v[28:31], v[222:225], v[160:163], v[28:31]
	v_mfma_f32_16x16x32_bf16 v[24:27], v[230:233], v[160:163], v[24:27]
	v_mfma_f32_16x16x32_bf16 v[20:23], v[222:225], v[198:201], v[20:23]
	v_mfma_f32_16x16x32_bf16 v[16:19], v[230:233], v[198:201], v[16:19]
	v_mfma_f32_16x16x32_bf16 v[12:15], v[222:225], v[206:209], v[12:15]
	v_mfma_f32_16x16x32_bf16 v[8:11], v[230:233], v[206:209], v[8:11]
	v_mfma_f32_16x16x32_bf16 v[4:7], v[222:225], v[214:217], v[4:7]
	v_mfma_f32_16x16x32_bf16 v[0:3], v[230:233], v[214:217], v[0:3]
	s_setprio 0
	s_add_i32 s14, s14, 2
	s_add_u32 s56, s56, s58
	s_addc_u32 s57, s57, s59
	s_add_u32 s60, s60, s58
	s_addc_u32 s61, s61, s59
	s_cmp_lt_u32 s14, 28
	s_barrier
	s_cbranch_scc1 .LBB0_234
	s_lshl_b32 s14, s62, 3
	s_or_b32 s82, s63, s14
	s_lshl_b32 s56, s82, 8
	v_lshlrev_b32_e32 v128, 3, v131
	v_lshlrev_b32_e32 v129, 5, v131
	s_or_b32 s14, s56, 0x80
	v_and_b32_e32 v128, 0x7fff0, v128
	v_and_b32_e32 v129, 32, v129
	s_lshl_b64 s[58:59], s[14:15], 13
	v_add_u32_e32 v129, v129, v134
	v_add_lshl_u32 v128, v133, v128, 13
	s_add_u32 s58, s40, s58
	v_lshl_add_u32 v164, v129, 1, v128
	s_addc_u32 s59, s41, s59
	v_lshl_add_u64 v[128:129], s[58:59], 0, v[164:165]
	v_readfirstlane_b32 s14, v137
	ds_read_b128 v[140:143], v138
	ds_read_b128 v[144:147], v138 offset:1024
	ds_read_b128 v[148:151], v138 offset:2048
	ds_read_b128 v[152:155], v138 offset:3072
	ds_read_b128 v[156:159], v193
	ds_read_b128 v[160:163], v193 offset:1024
	ds_read_b128 v[194:197], v192
	ds_read_b128 v[198:201], v192 offset:1024
	ds_read_b128 v[202:205], v191
	ds_read_b128 v[206:209], v191 offset:1024
	ds_read_b128 v[210:213], v190
	ds_read_b128 v[214:217], v190 offset:1024
	v_lshl_add_u64 v[138:139], v[128:129], 0, s[44:45]
	s_mov_b32 m0, s14
	v_readfirstlane_b32 s14, v136
	global_load_lds_dwordx4 v[138:139], off
	v_lshl_add_u64 v[128:129], v[128:129], 0, s[46:47]
	s_mov_b32 m0, s14
	s_mov_b32 s57, s15
	global_load_lds_dwordx4 v[128:129], off
	s_barrier
	s_waitcnt lgkmcnt(0)
	s_setprio 1
	s_waitcnt lgkmcnt(0)
	v_mfma_f32_16x16x32_bf16 v[124:127], v[140:143], v[156:159], v[124:127]
	v_mfma_f32_16x16x32_bf16 v[120:123], v[148:151], v[156:159], v[120:123]
	v_mfma_f32_16x16x32_bf16 v[116:119], v[140:143], v[194:197], v[116:119]
	v_mfma_f32_16x16x32_bf16 v[112:115], v[148:151], v[194:197], v[112:115]
	v_mfma_f32_16x16x32_bf16 v[108:111], v[140:143], v[202:205], v[108:111]
	v_mfma_f32_16x16x32_bf16 v[104:107], v[148:151], v[202:205], v[104:107]
	v_mfma_f32_16x16x32_bf16 v[100:103], v[140:143], v[210:213], v[100:103]
	v_mfma_f32_16x16x32_bf16 v[96:99], v[148:151], v[210:213], v[96:99]
	v_mfma_f32_16x16x32_bf16 v[124:127], v[144:147], v[160:163], v[124:127]
	v_mfma_f32_16x16x32_bf16 v[120:123], v[152:155], v[160:163], v[120:123]
	v_mfma_f32_16x16x32_bf16 v[116:119], v[144:147], v[198:201], v[116:119]
	v_mfma_f32_16x16x32_bf16 v[112:115], v[152:155], v[198:201], v[112:115]
	v_mfma_f32_16x16x32_bf16 v[108:111], v[144:147], v[206:209], v[108:111]
	v_mfma_f32_16x16x32_bf16 v[104:107], v[152:155], v[206:209], v[104:107]
	v_mfma_f32_16x16x32_bf16 v[100:103], v[144:147], v[214:217], v[100:103]
	v_mfma_f32_16x16x32_bf16 v[96:99], v[152:155], v[214:217], v[96:99]
	s_setprio 0
	s_barrier
	ds_read_b128 v[136:139], v135
	ds_read_b128 v[218:221], v135 offset:1024
	ds_read_b128 v[222:225], v135 offset:2048
	ds_read_b128 v[226:229], v135 offset:3072
	s_barrier
	s_waitcnt lgkmcnt(0)
	s_setprio 1
	s_waitcnt lgkmcnt(0)
	v_mfma_f32_16x16x32_bf16 v[92:95], v[136:139], v[156:159], v[92:95]
	v_mfma_f32_16x16x32_bf16 v[84:87], v[136:139], v[194:197], v[84:87]
	v_mfma_f32_16x16x32_bf16 v[80:83], v[222:225], v[194:197], v[80:83]
	v_mfma_f32_16x16x32_bf16 v[88:91], v[222:225], v[156:159], v[88:91]
	v_mfma_f32_16x16x32_bf16 v[76:79], v[136:139], v[202:205], v[76:79]
	v_mfma_f32_16x16x32_bf16 v[72:75], v[222:225], v[202:205], v[72:75]
	v_mfma_f32_16x16x32_bf16 v[68:71], v[136:139], v[210:213], v[68:71]
	v_mfma_f32_16x16x32_bf16 v[64:67], v[222:225], v[210:213], v[64:67]
	v_mfma_f32_16x16x32_bf16 v[156:159], v[218:221], v[160:163], v[92:95]
	v_mfma_f32_16x16x32_bf16 v[194:197], v[218:221], v[198:201], v[84:87]
	v_mfma_f32_16x16x32_bf16 v[198:201], v[226:229], v[198:201], v[80:83]
	v_mfma_f32_16x16x32_bf16 v[160:163], v[226:229], v[160:163], v[88:91]
	v_mfma_f32_16x16x32_bf16 v[202:205], v[218:221], v[206:209], v[76:79]
	v_mfma_f32_16x16x32_bf16 v[206:209], v[226:229], v[206:209], v[72:75]
	v_mfma_f32_16x16x32_bf16 v[210:213], v[218:221], v[214:217], v[68:71]
	v_mfma_f32_16x16x32_bf16 v[214:217], v[226:229], v[214:217], v[64:67]
	s_setprio 0
	s_barrier
	s_nop 0
	ds_read_b128 v[64:67], v193 offset:16384
	ds_read_b128 v[68:71], v193 offset:17408
	ds_read_b128 v[72:75], v192 offset:16384
	ds_read_b128 v[76:79], v192 offset:17408
	ds_read_b128 v[80:83], v191 offset:16384
	ds_read_b128 v[84:87], v191 offset:17408
	ds_read_b128 v[88:91], v190 offset:16384
	ds_read_b128 v[92:95], v190 offset:17408
	s_waitcnt vmcnt(4)
	s_barrier
	s_waitcnt lgkmcnt(0)
	s_setprio 1
	s_waitcnt lgkmcnt(0)
	v_mfma_f32_16x16x32_bf16 v[60:63], v[140:143], v[64:67], v[60:63]
	v_mfma_f32_16x16x32_bf16 v[56:59], v[148:151], v[64:67], v[56:59]
	v_mfma_f32_16x16x32_bf16 v[52:55], v[140:143], v[72:75], v[52:55]
	v_mfma_f32_16x16x32_bf16 v[48:51], v[148:151], v[72:75], v[48:51]
	v_mfma_f32_16x16x32_bf16 v[230:233], v[140:143], v[80:83], v[44:47]
	v_mfma_f32_16x16x32_bf16 v[234:237], v[148:151], v[80:83], v[40:43]
	v_mfma_f32_16x16x32_bf16 v[140:143], v[140:143], v[88:91], v[36:39]
	v_mfma_f32_16x16x32_bf16 v[148:151], v[148:151], v[88:91], v[32:35]
	v_mfma_f32_16x16x32_bf16 v[32:35], v[144:147], v[68:71], v[60:63]
	v_mfma_f32_16x16x32_bf16 v[36:39], v[152:155], v[68:71], v[56:59]
	v_mfma_f32_16x16x32_bf16 v[40:43], v[144:147], v[76:79], v[52:55]
	v_mfma_f32_16x16x32_bf16 v[44:47], v[152:155], v[76:79], v[48:51]
	v_mfma_f32_16x16x32_bf16 v[48:51], v[144:147], v[84:87], v[230:233]
	v_mfma_f32_16x16x32_bf16 v[52:55], v[152:155], v[84:87], v[234:237]
	v_mfma_f32_16x16x32_bf16 v[56:59], v[144:147], v[92:95], v[140:143]
	v_mfma_f32_16x16x32_bf16 v[60:63], v[152:155], v[92:95], v[148:151]
	s_setprio 0
	s_setprio 1
	v_mfma_f32_16x16x32_bf16 v[28:31], v[136:139], v[64:67], v[28:31]
	v_mfma_f32_16x16x32_bf16 v[24:27], v[222:225], v[64:67], v[24:27]
	v_mfma_f32_16x16x32_bf16 v[20:23], v[136:139], v[72:75], v[20:23]
	v_mfma_f32_16x16x32_bf16 v[64:67], v[222:225], v[72:75], v[16:19]
	v_mfma_f32_16x16x32_bf16 v[12:15], v[136:139], v[80:83], v[12:15]
	v_mfma_f32_16x16x32_bf16 v[8:11], v[222:225], v[80:83], v[8:11]
	v_mfma_f32_16x16x32_bf16 v[72:75], v[136:139], v[88:91], v[4:7]
	v_mfma_f32_16x16x32_bf16 v[80:83], v[222:225], v[88:91], v[0:3]
	v_mfma_f32_16x16x32_bf16 v[0:3], v[218:221], v[68:71], v[28:31]
	v_mfma_f32_16x16x32_bf16 v[4:7], v[226:229], v[68:71], v[24:27]
	v_mfma_f32_16x16x32_bf16 v[16:19], v[218:221], v[76:79], v[20:23]
	v_mfma_f32_16x16x32_bf16 v[20:23], v[226:229], v[76:79], v[64:67]
	v_mfma_f32_16x16x32_bf16 v[24:27], v[218:221], v[84:87], v[12:15]
	v_mfma_f32_16x16x32_bf16 v[28:31], v[226:229], v[84:87], v[8:11]
	v_mfma_f32_16x16x32_bf16 v[64:67], v[218:221], v[92:95], v[72:75]
	v_mfma_f32_16x16x32_bf16 v[68:71], v[226:229], v[92:95], v[80:83]
	s_setprio 0
	s_barrier
	ds_read_b128 v[12:15], v130
	ds_read_b128 v[8:11], v130 offset:1024
	ds_read_b128 v[76:79], v130 offset:2048
	ds_read_b128 v[72:75], v130 offset:3072
	ds_read_b128 v[140:143], v193 offset:32768
	ds_read_b128 v[148:151], v193 offset:33792
	ds_read_b128 v[218:221], v192 offset:32768
	ds_read_b128 v[222:225], v192 offset:33792
	ds_read_b128 v[226:229], v191 offset:32768
	ds_read_b128 v[230:233], v191 offset:33792
	ds_read_b128 v[234:237], v190 offset:32768
	ds_read_b128 v[238:241], v190 offset:33792
	s_waitcnt vmcnt(2)
	s_barrier
	s_waitcnt lgkmcnt(0)
	s_setprio 1
	s_waitcnt lgkmcnt(0)
	v_mfma_f32_16x16x32_bf16 v[80:83], v[12:15], v[140:143], v[124:127]
	v_mfma_f32_16x16x32_bf16 v[84:87], v[76:79], v[140:143], v[120:123]
	v_mfma_f32_16x16x32_bf16 v[88:91], v[12:15], v[218:221], v[116:119]
	v_mfma_f32_16x16x32_bf16 v[92:95], v[76:79], v[218:221], v[112:115]
	v_mfma_f32_16x16x32_bf16 v[108:111], v[12:15], v[226:229], v[108:111]
	v_mfma_f32_16x16x32_bf16 v[104:107], v[76:79], v[226:229], v[104:107]
	v_mfma_f32_16x16x32_bf16 v[100:103], v[12:15], v[234:237], v[100:103]
	v_mfma_f32_16x16x32_bf16 v[96:99], v[76:79], v[234:237], v[96:99]
	v_mfma_f32_16x16x32_bf16 v[152:155], v[8:11], v[148:151], v[80:83]
	v_mfma_f32_16x16x32_bf16 v[144:147], v[72:75], v[148:151], v[84:87]
	v_mfma_f32_16x16x32_bf16 v[136:139], v[8:11], v[222:225], v[88:91]
	v_mfma_f32_16x16x32_bf16 v[128:131], v[72:75], v[222:225], v[92:95]
	v_mfma_f32_16x16x32_bf16 v[120:123], v[8:11], v[230:233], v[108:111]
	v_mfma_f32_16x16x32_bf16 v[112:115], v[72:75], v[230:233], v[104:107]
	v_mfma_f32_16x16x32_bf16 v[104:107], v[8:11], v[238:241], v[100:103]
	v_mfma_f32_16x16x32_bf16 v[96:99], v[72:75], v[238:241], v[96:99]
	s_setprio 0
	s_barrier
	ds_read_b128 v[88:91], v132
	ds_read_b128 v[80:83], v132 offset:1024
	ds_read_b128 v[92:95], v132 offset:2048
	ds_read_b128 v[84:87], v132 offset:3072
	s_waitcnt vmcnt(0)
	s_barrier
	s_waitcnt lgkmcnt(0)
	s_setprio 1
	s_waitcnt lgkmcnt(0)
	v_mfma_f32_16x16x32_bf16 v[100:103], v[88:91], v[140:143], v[156:159]
	v_mfma_f32_16x16x32_bf16 v[108:111], v[92:95], v[140:143], v[160:163]
	v_mfma_f32_16x16x32_bf16 v[116:119], v[88:91], v[218:221], v[194:197]
	v_mfma_f32_16x16x32_bf16 v[124:127], v[92:95], v[218:221], v[198:201]
	v_mfma_f32_16x16x32_bf16 v[160:163], v[88:91], v[226:229], v[202:205]
	v_mfma_f32_16x16x32_bf16 v[194:197], v[92:95], v[226:229], v[206:209]
	v_mfma_f32_16x16x32_bf16 v[198:201], v[88:91], v[234:237], v[210:213]
	v_mfma_f32_16x16x32_bf16 v[202:205], v[92:95], v[234:237], v[214:217]
	v_mfma_f32_16x16x32_bf16 v[156:159], v[80:83], v[148:151], v[100:103]
	v_mfma_f32_16x16x32_bf16 v[148:151], v[84:87], v[148:151], v[108:111]
	v_mfma_f32_16x16x32_bf16 v[140:143], v[80:83], v[222:225], v[116:119]
	v_mfma_f32_16x16x32_bf16 v[132:135], v[84:87], v[222:225], v[124:127]
	v_mfma_f32_16x16x32_bf16 v[124:127], v[80:83], v[230:233], v[160:163]
	v_mfma_f32_16x16x32_bf16 v[116:119], v[84:87], v[230:233], v[194:197]
	v_mfma_f32_16x16x32_bf16 v[108:111], v[80:83], v[238:241], v[198:201]
	v_mfma_f32_16x16x32_bf16 v[100:103], v[84:87], v[238:241], v[202:205]
	s_setprio 0
	s_lshl_b64 s[58:59], s[56:57], 2
	s_barrier
	v_mbcnt_lo_u32_b32 v162, -1, 0
	v_mbcnt_hi_u32_b32 v162, -1, v162
	s_add_u32 s58, s87, s58
	v_add_u32_e32 v160, s64, v162
	s_addc_u32 s59, s88, s59
	v_and_b32_e32 v164, 0x100, v160
	v_and_b32_e32 v162, 15, v162
	v_lshl_add_u64 v[160:161], s[58:59], 0, v[164:165]
	v_lshlrev_b32_e32 v164, 2, v162
	v_lshl_add_u64 v[160:161], v[160:161], 0, v[164:165]
	global_load_dword v180, v[160:161], off
	global_load_dword v178, v[160:161], off offset:64
	global_load_dword v176, v[160:161], off offset:128
	global_load_dword v174, v[160:161], off offset:192
	global_load_dword v172, v[160:161], off offset:512
	global_load_dword v170, v[160:161], off offset:576
	global_load_dword v168, v[160:161], off offset:640
	global_load_dword v166, v[160:161], off offset:704
	v_mbcnt_lo_u32_b32 v194, -1, 0
	v_mbcnt_hi_u32_b32 v194, -1, v194
	s_cmp_lg_u32 s81, 0
	v_add_u32_e32 v160, s64, v194
	v_bfe_u32 v196, v160, 8, 1
	v_ashrrev_i32_e32 v199, 6, v160
	v_bfe_u32 v160, v194, 4, 2
	s_cselect_b64 s[58:59], -1, 0
	v_and_b32_e32 v197, 3, v199
	v_and_b32_e32 v195, 15, v194
	s_and_b64 vcc, exec, s[58:59]
	v_lshlrev_b32_e32 v198, 4, v160
	s_cbranch_vccz .LBB0_246
	s_lshl_b32 s14, s80, 22
	s_lshl_b32 s57, s82, 14
	s_add_i32 s57, s57, s14
	v_lshlrev_b32_e32 v160, 6, v195
	v_or3_b32 v160, s57, v160, v198
	v_lshl_add_u32 v160, v197, 20, v160
	v_lshl_or_b32 v164, v196, 12, v160
	s_waitcnt vmcnt(0)
	v_pk_mul_f32 v[160:161], v[154:155], v[180:181] op_sel_hi:[1,0]
	v_pk_mul_f32 v[200:201], v[146:147], v[180:181] op_sel_hi:[1,0]
	v_max_f32_e32 v160, 0, v160
	v_mul_f32_e32 v204, v160, v160
	v_max_f32_e32 v160, 0, v200
	v_pk_mul_f32 v[162:163], v[152:153], v[180:181] op_sel_hi:[1,0]
	v_mul_f32_e32 v200, v160, v160
	v_max_f32_e32 v160, 0, v161
	v_pk_mul_f32 v[202:203], v[144:145], v[180:181] op_sel_hi:[1,0]
	v_max_f32_e32 v162, 0, v162
	v_max_f32_e32 v163, 0, v163
	v_mul_f32_e32 v161, v160, v160
	v_max_f32_e32 v160, 0, v201
	v_mul_f32_e32 v162, v162, v162
	v_max_f32_e32 v202, 0, v202
	v_mul_f32_e32 v163, v163, v163
	v_max_f32_e32 v203, 0, v203
	v_mul_f32_e32 v201, v160, v160
	v_cvt_pk_bf16_f32 v160, v162, v163
	v_cvt_pk_bf16_f32 v161, v204, v161
	v_mul_f32_e32 v202, v202, v202
	v_mul_f32_e32 v203, v203, v203
	v_cvt_pk_bf16_f32 v162, v202, v203
	v_cvt_pk_bf16_f32 v163, v200, v201
	global_store_dwordx4 v164, v[160:163], s[0:1]
	v_pk_mul_f32 v[202:203], v[150:151], v[180:181] op_sel_hi:[1,0]
	v_lshl_add_u64 v[200:201], s[0:1], 0, v[164:165]
	v_pk_mul_f32 v[160:161], v[158:159], v[180:181] op_sel_hi:[1,0]
	v_pk_mul_f32 v[162:163], v[156:157], v[180:181] op_sel_hi:[1,0]
	v_max_f32_e32 v160, 0, v160
	v_mul_f32_e32 v206, v160, v160
	v_max_f32_e32 v160, 0, v202
	v_mul_f32_e32 v202, v160, v160
	v_max_f32_e32 v160, 0, v161
	v_pk_mul_f32 v[204:205], v[148:149], v[180:181] op_sel_hi:[1,0]
	v_max_f32_e32 v162, 0, v162
	v_max_f32_e32 v163, 0, v163
	v_mul_f32_e32 v161, v160, v160
	v_max_f32_e32 v160, 0, v203
	v_add_co_u32_e32 v200, vcc, s74, v200
	v_mul_f32_e32 v162, v162, v162
	v_max_f32_e32 v204, 0, v204
	v_mul_f32_e32 v163, v163, v163
	v_max_f32_e32 v205, 0, v205
	v_mul_f32_e32 v203, v160, v160
	v_cvt_pk_bf16_f32 v160, v162, v163
	v_cvt_pk_bf16_f32 v161, v206, v161
	v_addc_co_u32_e32 v201, vcc, 0, v201, vcc
	v_mul_f32_e32 v204, v204, v204
	v_mul_f32_e32 v205, v205, v205
	v_cvt_pk_bf16_f32 v162, v204, v205
	v_cvt_pk_bf16_f32 v163, v202, v203
	global_store_dwordx4 v[200:201], v[160:163], off
	v_pk_mul_f32 v[202:203], v[130:131], v[178:179] op_sel_hi:[1,0]
	v_pk_mul_f32 v[204:205], v[128:129], v[178:179] op_sel_hi:[1,0]
	v_pk_mul_f32 v[160:161], v[138:139], v[178:179] op_sel_hi:[1,0]
	v_pk_mul_f32 v[162:163], v[136:137], v[178:179] op_sel_hi:[1,0]
	v_max_f32_e32 v160, 0, v160
	v_mul_f32_e32 v206, v160, v160
	v_max_f32_e32 v160, 0, v202
	v_mul_f32_e32 v202, v160, v160
	v_max_f32_e32 v160, 0, v161
	v_max_f32_e32 v162, 0, v162
	v_max_f32_e32 v163, 0, v163
	v_mul_f32_e32 v161, v160, v160
	v_max_f32_e32 v160, 0, v203
	v_mul_f32_e32 v162, v162, v162
	v_max_f32_e32 v204, 0, v204
	v_mul_f32_e32 v163, v163, v163
	v_max_f32_e32 v205, 0, v205
	v_mul_f32_e32 v203, v160, v160
	v_cvt_pk_bf16_f32 v160, v162, v163
	v_cvt_pk_bf16_f32 v161, v206, v161
	v_mul_f32_e32 v204, v204, v204
	v_mul_f32_e32 v205, v205, v205
	v_cvt_pk_bf16_f32 v162, v204, v205
	v_cvt_pk_bf16_f32 v163, v202, v203
	global_store_dwordx4 v164, v[160:163], s[0:1] offset:1024
	v_pk_mul_f32 v[202:203], v[134:135], v[178:179] op_sel_hi:[1,0]
	v_pk_mul_f32 v[204:205], v[132:133], v[178:179] op_sel_hi:[1,0]
	v_pk_mul_f32 v[160:161], v[142:143], v[178:179] op_sel_hi:[1,0]
	v_pk_mul_f32 v[162:163], v[140:141], v[178:179] op_sel_hi:[1,0]
	v_max_f32_e32 v160, 0, v160
	v_mul_f32_e32 v206, v160, v160
	v_max_f32_e32 v160, 0, v202
	v_mul_f32_e32 v202, v160, v160
	v_max_f32_e32 v160, 0, v161
	v_max_f32_e32 v162, 0, v162
	v_max_f32_e32 v163, 0, v163
	v_mul_f32_e32 v161, v160, v160
	v_max_f32_e32 v160, 0, v203
	v_mul_f32_e32 v162, v162, v162
	v_max_f32_e32 v204, 0, v204
	v_mul_f32_e32 v163, v163, v163
	v_max_f32_e32 v205, 0, v205
	v_mul_f32_e32 v203, v160, v160
	v_cvt_pk_bf16_f32 v160, v162, v163
	v_cvt_pk_bf16_f32 v161, v206, v161
	v_mul_f32_e32 v204, v204, v204
	v_mul_f32_e32 v205, v205, v205
	v_cvt_pk_bf16_f32 v162, v204, v205
	v_cvt_pk_bf16_f32 v163, v202, v203
	global_store_dwordx4 v[200:201], v[160:163], off offset:1024
	v_pk_mul_f32 v[202:203], v[114:115], v[176:177] op_sel_hi:[1,0]
	v_pk_mul_f32 v[204:205], v[112:113], v[176:177] op_sel_hi:[1,0]
	v_pk_mul_f32 v[160:161], v[122:123], v[176:177] op_sel_hi:[1,0]
	v_pk_mul_f32 v[162:163], v[120:121], v[176:177] op_sel_hi:[1,0]
	v_max_f32_e32 v160, 0, v160
	v_mul_f32_e32 v206, v160, v160
	v_max_f32_e32 v160, 0, v202
	v_mul_f32_e32 v202, v160, v160
	v_max_f32_e32 v160, 0, v161
	v_max_f32_e32 v162, 0, v162
	v_max_f32_e32 v163, 0, v163
	v_mul_f32_e32 v161, v160, v160
	v_max_f32_e32 v160, 0, v203
	v_mul_f32_e32 v162, v162, v162
	v_max_f32_e32 v204, 0, v204
	v_mul_f32_e32 v163, v163, v163
	v_max_f32_e32 v205, 0, v205
	v_mul_f32_e32 v203, v160, v160
	v_cvt_pk_bf16_f32 v160, v162, v163
	v_cvt_pk_bf16_f32 v161, v206, v161
	v_mul_f32_e32 v204, v204, v204
	v_mul_f32_e32 v205, v205, v205
	v_cvt_pk_bf16_f32 v162, v204, v205
	v_cvt_pk_bf16_f32 v163, v202, v203
	global_store_dwordx4 v164, v[160:163], s[0:1] offset:2048
	v_pk_mul_f32 v[202:203], v[118:119], v[176:177] op_sel_hi:[1,0]
	v_pk_mul_f32 v[204:205], v[116:117], v[176:177] op_sel_hi:[1,0]
	v_pk_mul_f32 v[160:161], v[126:127], v[176:177] op_sel_hi:[1,0]
	v_pk_mul_f32 v[162:163], v[124:125], v[176:177] op_sel_hi:[1,0]
	v_max_f32_e32 v160, 0, v160
	v_mul_f32_e32 v206, v160, v160
	v_max_f32_e32 v160, 0, v202
	v_mul_f32_e32 v202, v160, v160
	v_max_f32_e32 v160, 0, v161
	v_max_f32_e32 v162, 0, v162
	v_max_f32_e32 v163, 0, v163
	v_mul_f32_e32 v161, v160, v160
	v_max_f32_e32 v160, 0, v203
	v_mul_f32_e32 v162, v162, v162
	v_max_f32_e32 v204, 0, v204
	v_mul_f32_e32 v163, v163, v163
	v_max_f32_e32 v205, 0, v205
	v_mul_f32_e32 v203, v160, v160
	v_cvt_pk_bf16_f32 v160, v162, v163
	v_cvt_pk_bf16_f32 v161, v206, v161
	v_mul_f32_e32 v204, v204, v204
	v_mul_f32_e32 v205, v205, v205
	v_cvt_pk_bf16_f32 v162, v204, v205
	v_cvt_pk_bf16_f32 v163, v202, v203
	global_store_dwordx4 v[200:201], v[160:163], off offset:2048
	v_pk_mul_f32 v[200:201], v[98:99], v[174:175] op_sel_hi:[1,0]
	v_pk_mul_f32 v[202:203], v[96:97], v[174:175] op_sel_hi:[1,0]
	v_pk_mul_f32 v[160:161], v[106:107], v[174:175] op_sel_hi:[1,0]
	v_pk_mul_f32 v[162:163], v[104:105], v[174:175] op_sel_hi:[1,0]
	v_max_f32_e32 v160, 0, v160
	v_mul_f32_e32 v204, v160, v160
	v_max_f32_e32 v160, 0, v200
	v_mul_f32_e32 v200, v160, v160
	v_max_f32_e32 v160, 0, v161
	v_max_f32_e32 v162, 0, v162
	v_max_f32_e32 v163, 0, v163
	v_mul_f32_e32 v161, v160, v160
	v_max_f32_e32 v160, 0, v201
	v_mul_f32_e32 v162, v162, v162
	v_max_f32_e32 v202, 0, v202
	v_mul_f32_e32 v163, v163, v163
	v_max_f32_e32 v203, 0, v203
	v_mul_f32_e32 v201, v160, v160
	v_cvt_pk_bf16_f32 v160, v162, v163
	v_cvt_pk_bf16_f32 v161, v204, v161
	v_mul_f32_e32 v202, v202, v202
	v_mul_f32_e32 v203, v203, v203
	v_cvt_pk_bf16_f32 v162, v202, v203
	v_cvt_pk_bf16_f32 v163, v200, v201
	global_store_dwordx4 v164, v[160:163], s[0:1] offset:3072
	v_pk_mul_f32 v[200:201], v[102:103], v[174:175] op_sel_hi:[1,0]
	v_pk_mul_f32 v[202:203], v[100:101], v[174:175] op_sel_hi:[1,0]
	v_pk_mul_f32 v[160:161], v[110:111], v[174:175] op_sel_hi:[1,0]
	v_pk_mul_f32 v[162:163], v[108:109], v[174:175] op_sel_hi:[1,0]
	v_max_f32_e32 v160, 0, v160
	v_mul_f32_e32 v204, v160, v160
	v_max_f32_e32 v160, 0, v200
	v_max_f32_e32 v162, 0, v162
	v_max_f32_e32 v163, 0, v163
	v_mul_f32_e32 v200, v160, v160
	v_max_f32_e32 v160, 0, v161
	v_mul_f32_e32 v162, v162, v162
	v_max_f32_e32 v202, 0, v202
	v_mul_f32_e32 v163, v163, v163
	v_max_f32_e32 v203, 0, v203
	v_mul_f32_e32 v161, v160, v160
	v_max_f32_e32 v160, 0, v201
	v_mul_f32_e32 v202, v202, v202
	v_mul_f32_e32 v203, v203, v203
	v_mul_f32_e32 v201, v160, v160
	v_cvt_pk_bf16_f32 v160, v162, v163
	v_cvt_pk_bf16_f32 v161, v204, v161
	v_cvt_pk_bf16_f32 v162, v202, v203
	v_cvt_pk_bf16_f32 v163, v200, v201
	v_add_u32_e32 v164, 0x80c00, v164
	s_cbranch_execnz .LBB0_238

.LBB0_273:
	v_and_b32_e32 v2, 15, v0
	s_bfe_u32 s64, s86, 0x30003
	v_and_b32_e32 v3, 48, v0
	v_lshlrev_b32_e32 v134, 4, v135
	v_and_b32_e32 v5, 32, v0
	s_movk_i32 s65, 0x3f0
	v_and_b32_e32 v6, 64, v135
	v_lshlrev_b32_e32 v2, 6, v2
	v_lshlrev_b32_e32 v9, 2, v0
	v_lshlrev_b32_e32 v0, 6, v0
	s_lshl_b32 s66, s64, 14
	v_and_b32_e32 v4, 0x3f0, v134
	v_bitop3_b32 v155, v134, v5, s65 bitop3:0x6c
	v_lshlrev_b32_e32 v156, 13, v6
	v_lshlrev_b32_e32 v7, 3, v135
	v_mul_i32_i24_e32 v6, 0xffffe800, v6
	s_add_i32 s65, s20, -2
	v_or_b32_e32 v8, v2, v3
	v_and_b32_e32 v9, 32, v9
	s_mov_b32 s67, 0x14000
	v_and_b32_e32 v0, 0x3c0, v0
	v_and_b32_e32 v157, 0xfffffc00, v7
	v_bitop3_b32 v2, v2, v9, v3 bitop3:0x36
	v_bitop3_b32 v11, v8, s67, v9 bitop3:0xde
	s_mov_b32 s67, 0x1c000
	v_bitop3_b32 v3, v0, v9, v3 bitop3:0x36
	v_bitop3_b32 v0, v6, v4, v5 bitop3:0xf6
	s_add_u32 s66, s70, s66
	v_bitop3_b32 v10, v8, s74, v9 bitop3:0xde
	v_bitop3_b32 v12, v8, s75, v9 bitop3:0xde
	v_bitop3_b32 v8, v8, s67, v9 bitop3:0xde
	v_add3_u32 v128, v0, v156, v157
	s_addc_u32 s67, s71, 0
	v_lshlrev_b32_e32 v13, 13, v1
	v_lshl_add_u64 v[0:1], s[66:67], 0, v[128:129]
	s_mov_b64 s[66:67], 0xc3000
	v_lshl_add_u64 v[130:131], v[0:1], 0, s[66:67]
	s_lshl_b32 s66, s86, 11
	s_and_b32 s67, s86, 7
	s_and_b32 s66, s66, 0x60000
	s_lshl_b32 s67, s67, 14
	s_or_b32 s66, s66, s67
	v_bitop3_b32 v0, v4, v156, v5 bitop3:0xde
	s_add_u32 s66, s68, s66
	v_add_u32_e32 v128, v0, v157
	s_addc_u32 s67, s69, 0
	v_lshlrev_b32_e32 v7, 6, v135
	v_lshl_add_u64 v[0:1], s[66:67], 0, v[128:129]
	s_mov_b64 s[66:67], 0x301000
	v_and_b32_e32 v7, 0x3000, v7
	v_or_b32_e32 v9, 0x800, v13
	v_or_b32_e32 v14, 0x1000, v13
	v_or_b32_e32 v15, 0x1800, v13
	v_lshl_add_u64 v[132:133], v[0:1], 0, s[66:67]
	v_mov_b32_e32 v0, 0
	s_mov_b32 s66, 0
	v_add_u32_e32 v161, v10, v7
	v_add_u32_e32 v152, v2, v13
	v_add_u32_e32 v151, v3, v9
	v_add_u32_e32 v150, v3, v14
	v_add_u32_e32 v149, v3, v15
	v_add_u32_e32 v160, 0xc000, v134
	v_add_u32_e32 v159, 0xe000, v134
	v_add_u32_e32 v158, v11, v7
	v_add_u32_e32 v148, 0x10000, v134
	v_add_u32_e32 v147, 0x12000, v134
	v_add_u32_e32 v146, 0x2000, v134
	v_add_u32_e32 v145, 0x14000, v134
	v_add_u32_e32 v144, 0x16000, v134
	v_add_u32_e32 v154, v12, v7
	v_add_u32_e32 v143, 0x4000, v134
	v_add_u32_e32 v142, 0x6000, v134
	v_add_u32_e32 v153, v8, v7
	v_add_u32_e32 v141, 0x18000, v134
	v_add_u32_e32 v140, 0x1a000, v134
	v_add_u32_e32 v139, 0x8000, v134
	v_add_u32_e32 v138, 0xa000, v134
	v_add_u32_e32 v137, 0x1c000, v134
	v_add_u32_e32 v136, 0x1e000, v134
	v_mov_b32_e32 v1, v0
	v_mov_b32_e32 v2, v0
	v_mov_b32_e32 v3, v0
	v_mov_b32_e32 v4, v0
	v_mov_b32_e32 v5, v0
	v_mov_b32_e32 v6, v0
	v_mov_b32_e32 v7, v0
	v_mov_b32_e32 v8, v0
	v_mov_b32_e32 v9, v0
	v_mov_b32_e32 v10, v0
	v_mov_b32_e32 v11, v0
	v_mov_b32_e32 v12, v0
	v_mov_b32_e32 v13, v0
	v_mov_b32_e32 v14, v0
	v_mov_b32_e32 v15, v0
	v_mov_b32_e32 v16, v0
	v_mov_b32_e32 v17, v0
	v_mov_b32_e32 v18, v0
	v_mov_b32_e32 v19, v0
	v_mov_b32_e32 v20, v0
	v_mov_b32_e32 v21, v0
	v_mov_b32_e32 v22, v0
	v_mov_b32_e32 v23, v0
	v_mov_b32_e32 v24, v0
	v_mov_b32_e32 v25, v0
	v_mov_b32_e32 v26, v0
	v_mov_b32_e32 v27, v0
	v_mov_b32_e32 v28, v0
	v_mov_b32_e32 v29, v0
	v_mov_b32_e32 v30, v0
	v_mov_b32_e32 v31, v0
	v_mov_b32_e32 v32, v0
	v_mov_b32_e32 v33, v0
	v_mov_b32_e32 v34, v0
	v_mov_b32_e32 v35, v0
	v_mov_b32_e32 v36, v0
	v_mov_b32_e32 v37, v0
	v_mov_b32_e32 v38, v0
	v_mov_b32_e32 v39, v0
	v_mov_b32_e32 v40, v0
	v_mov_b32_e32 v41, v0
	v_mov_b32_e32 v42, v0
	v_mov_b32_e32 v43, v0
	v_mov_b32_e32 v44, v0
	v_mov_b32_e32 v45, v0
	v_mov_b32_e32 v46, v0
	v_mov_b32_e32 v47, v0
	v_mov_b32_e32 v48, v0
	v_mov_b32_e32 v49, v0
	v_mov_b32_e32 v50, v0
	v_mov_b32_e32 v51, v0
	v_mov_b32_e32 v52, v0
	v_mov_b32_e32 v53, v0
	v_mov_b32_e32 v54, v0
	v_mov_b32_e32 v55, v0
	v_mov_b32_e32 v56, v0
	v_mov_b32_e32 v57, v0
	v_mov_b32_e32 v58, v0
	v_mov_b32_e32 v59, v0
	v_mov_b32_e32 v60, v0
	v_mov_b32_e32 v61, v0
	v_mov_b32_e32 v62, v0
	v_mov_b32_e32 v63, v0
	v_mov_b32_e32 v64, v0
	v_mov_b32_e32 v65, v0
	v_mov_b32_e32 v66, v0
	v_mov_b32_e32 v67, v0
	v_mov_b32_e32 v68, v0
	v_mov_b32_e32 v69, v0
	v_mov_b32_e32 v70, v0
	v_mov_b32_e32 v71, v0
	v_mov_b32_e32 v72, v0
	v_mov_b32_e32 v73, v0
	v_mov_b32_e32 v74, v0
	v_mov_b32_e32 v75, v0
	v_mov_b32_e32 v76, v0
	v_mov_b32_e32 v77, v0
	v_mov_b32_e32 v78, v0
	v_mov_b32_e32 v79, v0
	v_mov_b32_e32 v80, v0
	v_mov_b32_e32 v81, v0
	v_mov_b32_e32 v82, v0
	v_mov_b32_e32 v83, v0
	v_mov_b32_e32 v84, v0
	v_mov_b32_e32 v85, v0
	v_mov_b32_e32 v86, v0
	v_mov_b32_e32 v87, v0
	v_mov_b32_e32 v88, v0
	v_mov_b32_e32 v89, v0
	v_mov_b32_e32 v90, v0
	v_mov_b32_e32 v91, v0
	v_mov_b32_e32 v92, v0
	v_mov_b32_e32 v93, v0
	v_mov_b32_e32 v94, v0
	v_mov_b32_e32 v95, v0
	v_mov_b32_e32 v96, v0
	v_mov_b32_e32 v97, v0
	v_mov_b32_e32 v98, v0
	v_mov_b32_e32 v99, v0
	v_mov_b32_e32 v100, v0
	v_mov_b32_e32 v101, v0
	v_mov_b32_e32 v102, v0
	v_mov_b32_e32 v103, v0
	v_mov_b32_e32 v104, v0
	v_mov_b32_e32 v105, v0
	v_mov_b32_e32 v106, v0
	v_mov_b32_e32 v107, v0
	v_mov_b32_e32 v108, v0
	v_mov_b32_e32 v109, v0
	v_mov_b32_e32 v110, v0
	v_mov_b32_e32 v111, v0
	v_mov_b32_e32 v112, v0
	v_mov_b32_e32 v113, v0
	v_mov_b32_e32 v114, v0
	v_mov_b32_e32 v115, v0
	v_mov_b32_e32 v116, v0
	v_mov_b32_e32 v117, v0
	v_mov_b32_e32 v118, v0
	v_mov_b32_e32 v119, v0
	v_mov_b32_e32 v120, v0
	v_mov_b32_e32 v121, v0
	v_mov_b32_e32 v122, v0
	v_mov_b32_e32 v123, v0
	v_mov_b32_e32 v124, v0
	v_mov_b32_e32 v125, v0
	v_mov_b32_e32 v126, v0
	v_mov_b32_e32 v127, v0
	s_barrier
	s_mov_b32 vcc_lo, 0xffe01000
	s_mov_b32 vcc_hi, -1
	v_lshl_add_u64 v[164:165], v[132:133], 0, vcc
	v_readfirstlane_b32 s67, v160
	s_mov_b32 vcc_lo, 0xffe02000
	s_mov_b32 m0, s67
	s_mov_b32 vcc_hi, -1
	v_readfirstlane_b32 s67, v159
	global_load_lds_dwordx4 v[164:165], off
	v_lshl_add_u64 v[164:165], v[132:133], 0, vcc
	s_mov_b32 m0, s67
	s_nop 0
	global_load_lds_dwordx4 v[164:165], off
.LBB0_274:
	ds_read_b128 v[162:165], v161
	ds_read_b128 v[166:169], v161 offset:1024
	ds_read_b128 v[170:173], v161 offset:2048
	ds_read_b128 v[174:177], v161 offset:3072
	ds_read_b128 v[178:181], v152
	ds_read_b128 v[182:185], v152 offset:1024
	ds_read_b128 v[186:189], v151
	ds_read_b128 v[190:193], v151 offset:1024
	ds_read_b128 v[194:197], v150
	ds_read_b128 v[198:201], v150 offset:1024
	ds_read_b128 v[202:205], v149
	ds_read_b128 v[206:209], v149 offset:1024
	s_waitcnt lgkmcnt(8)
	s_barrier
	s_waitcnt lgkmcnt(0)
	s_setprio 1
	s_waitcnt lgkmcnt(0)
	v_mfma_f32_16x16x32_bf16 v[124:127], v[162:165], v[178:181], v[124:127]
	v_mfma_f32_16x16x32_bf16 v[120:123], v[170:173], v[178:181], v[120:123]
	v_mfma_f32_16x16x32_bf16 v[116:119], v[162:165], v[186:189], v[116:119]
	v_mfma_f32_16x16x32_bf16 v[112:115], v[170:173], v[186:189], v[112:115]
	v_mfma_f32_16x16x32_bf16 v[108:111], v[162:165], v[194:197], v[108:111]
	v_mfma_f32_16x16x32_bf16 v[104:107], v[170:173], v[194:197], v[104:107]
	v_mfma_f32_16x16x32_bf16 v[100:103], v[162:165], v[202:205], v[100:103]
	v_mfma_f32_16x16x32_bf16 v[96:99], v[170:173], v[202:205], v[96:99]
	v_mfma_f32_16x16x32_bf16 v[124:127], v[166:169], v[182:185], v[124:127]
	v_mfma_f32_16x16x32_bf16 v[120:123], v[174:177], v[182:185], v[120:123]
	v_mfma_f32_16x16x32_bf16 v[116:119], v[166:169], v[190:193], v[116:119]
	v_mfma_f32_16x16x32_bf16 v[112:115], v[174:177], v[190:193], v[112:115]
	v_mfma_f32_16x16x32_bf16 v[108:111], v[166:169], v[198:201], v[108:111]
	v_mfma_f32_16x16x32_bf16 v[104:107], v[174:177], v[198:201], v[104:107]
	v_mfma_f32_16x16x32_bf16 v[100:103], v[166:169], v[206:209], v[100:103]
	v_mfma_f32_16x16x32_bf16 v[96:99], v[174:177], v[206:209], v[96:99]
	s_setprio 0
	s_barrier
	s_mov_b32 vcc_lo, 0xfffbd000
	s_mov_b32 vcc_hi, -1
	v_readfirstlane_b32 s67, v148
	v_lshl_add_u64 v[226:227], v[130:131], 0, vcc
	s_mov_b32 m0, s67
	v_readfirstlane_b32 s67, v147
	ds_read_b128 v[210:213], v158
	ds_read_b128 v[214:217], v158 offset:1024
	ds_read_b128 v[218:221], v158 offset:2048
	ds_read_b128 v[222:225], v158 offset:3072
	global_load_lds_dwordx4 v[226:227], off
	v_lshl_add_u64 v[226:227], v[130:131], 0, s[22:23]
	s_mov_b32 m0, s67
	s_add_i32 s66, s66, 2
	global_load_lds_dwordx4 v[226:227], off
	s_barrier
	s_waitcnt lgkmcnt(0)
	s_setprio 1
	s_waitcnt lgkmcnt(0)
	v_mfma_f32_16x16x32_bf16 v[92:95], v[210:213], v[178:181], v[92:95]
	v_mfma_f32_16x16x32_bf16 v[88:91], v[218:221], v[178:181], v[88:91]
	v_mfma_f32_16x16x32_bf16 v[84:87], v[210:213], v[186:189], v[84:87]
	v_mfma_f32_16x16x32_bf16 v[80:83], v[218:221], v[186:189], v[80:83]
	v_mfma_f32_16x16x32_bf16 v[76:79], v[210:213], v[194:197], v[76:79]
	v_mfma_f32_16x16x32_bf16 v[72:75], v[218:221], v[194:197], v[72:75]
	v_mfma_f32_16x16x32_bf16 v[68:71], v[210:213], v[202:205], v[68:71]
	v_mfma_f32_16x16x32_bf16 v[64:67], v[218:221], v[202:205], v[64:67]
	v_mfma_f32_16x16x32_bf16 v[92:95], v[214:217], v[182:185], v[92:95]
	v_mfma_f32_16x16x32_bf16 v[88:91], v[222:225], v[182:185], v[88:91]
	v_mfma_f32_16x16x32_bf16 v[84:87], v[214:217], v[190:193], v[84:87]
	v_mfma_f32_16x16x32_bf16 v[80:83], v[222:225], v[190:193], v[80:83]
	v_mfma_f32_16x16x32_bf16 v[76:79], v[214:217], v[198:201], v[76:79]
	v_mfma_f32_16x16x32_bf16 v[72:75], v[222:225], v[198:201], v[72:75]
	v_mfma_f32_16x16x32_bf16 v[68:71], v[214:217], v[206:209], v[68:71]
	v_mfma_f32_16x16x32_bf16 v[64:67], v[222:225], v[206:209], v[64:67]
	s_setprio 0
	v_readfirstlane_b32 s67, v134
	v_lshl_add_u64 v[226:227], v[132:133], 0, s[24:25]
	s_mov_b32 m0, s67
	v_readfirstlane_b32 s67, v146
	s_barrier
	ds_read_b128 v[178:181], v152 offset:16384
	ds_read_b128 v[182:185], v152 offset:17408
	ds_read_b128 v[186:189], v151 offset:16384
	ds_read_b128 v[190:193], v151 offset:17408
	ds_read_b128 v[194:197], v150 offset:16384
	ds_read_b128 v[198:201], v150 offset:17408
	ds_read_b128 v[202:205], v149 offset:16384
	ds_read_b128 v[206:209], v149 offset:17408
	global_load_lds_dwordx4 v[226:227], off
	v_lshl_add_u64 v[226:227], v[132:133], 0, s[26:27]
	s_mov_b32 m0, s67
	s_nop 0
	global_load_lds_dwordx4 v[226:227], off
	s_barrier
	s_waitcnt lgkmcnt(0)
	s_setprio 1
	s_waitcnt lgkmcnt(0)
	v_mfma_f32_16x16x32_bf16 v[60:63], v[162:165], v[178:181], v[60:63]
	v_mfma_f32_16x16x32_bf16 v[56:59], v[170:173], v[178:181], v[56:59]
	v_mfma_f32_16x16x32_bf16 v[52:55], v[162:165], v[186:189], v[52:55]
	v_mfma_f32_16x16x32_bf16 v[48:51], v[170:173], v[186:189], v[48:51]
	v_mfma_f32_16x16x32_bf16 v[44:47], v[162:165], v[194:197], v[44:47]
	v_mfma_f32_16x16x32_bf16 v[40:43], v[170:173], v[194:197], v[40:43]
	v_mfma_f32_16x16x32_bf16 v[36:39], v[162:165], v[202:205], v[36:39]
	v_mfma_f32_16x16x32_bf16 v[32:35], v[170:173], v[202:205], v[32:35]
	v_mfma_f32_16x16x32_bf16 v[60:63], v[166:169], v[182:185], v[60:63]
	v_mfma_f32_16x16x32_bf16 v[56:59], v[174:177], v[182:185], v[56:59]
	v_mfma_f32_16x16x32_bf16 v[52:55], v[166:169], v[190:193], v[52:55]
	v_mfma_f32_16x16x32_bf16 v[48:51], v[174:177], v[190:193], v[48:51]
	v_mfma_f32_16x16x32_bf16 v[44:47], v[166:169], v[198:201], v[44:47]
	v_mfma_f32_16x16x32_bf16 v[40:43], v[174:177], v[198:201], v[40:43]
	v_mfma_f32_16x16x32_bf16 v[36:39], v[166:169], v[206:209], v[36:39]
	v_mfma_f32_16x16x32_bf16 v[32:35], v[174:177], v[206:209], v[32:35]
	s_setprio 0
	s_barrier
	v_readfirstlane_b32 s67, v145
	v_lshl_add_u64 v[162:163], v[130:131], 0, s[28:29]
	s_mov_b32 m0, s67
	v_readfirstlane_b32 s67, v144
	global_load_lds_dwordx4 v[162:163], off
	v_lshl_add_u64 v[162:163], v[130:131], 0, s[30:31]
	s_mov_b32 m0, s67
	s_nop 0
	global_load_lds_dwordx4 v[162:163], off
	v_readfirstlane_b32 s67, v143
	v_lshl_add_u64 v[164:165], v[132:133], 0, s[34:35]
	s_mov_b32 m0, s67
	v_readfirstlane_b32 s67, v142
	global_load_lds_dwordx4 v[164:165], off
	v_lshl_add_u64 v[164:165], v[132:133], 0, s[44:45]
	s_mov_b32 m0, s67
	s_nop 0
	global_load_lds_dwordx4 v[164:165], off
	s_waitcnt vmcnt(8)
	s_barrier
	s_setprio 1
	v_mfma_f32_16x16x32_bf16 v[28:31], v[210:213], v[178:181], v[28:31]
	v_mfma_f32_16x16x32_bf16 v[24:27], v[218:221], v[178:181], v[24:27]
	v_mfma_f32_16x16x32_bf16 v[20:23], v[210:213], v[186:189], v[20:23]
	v_mfma_f32_16x16x32_bf16 v[16:19], v[218:221], v[186:189], v[16:19]
	v_mfma_f32_16x16x32_bf16 v[12:15], v[210:213], v[194:197], v[12:15]
	v_mfma_f32_16x16x32_bf16 v[8:11], v[218:221], v[194:197], v[8:11]
	v_mfma_f32_16x16x32_bf16 v[4:7], v[210:213], v[202:205], v[4:7]
	v_mfma_f32_16x16x32_bf16 v[0:3], v[218:221], v[202:205], v[0:3]
	v_mfma_f32_16x16x32_bf16 v[28:31], v[214:217], v[182:185], v[28:31]
	v_mfma_f32_16x16x32_bf16 v[24:27], v[222:225], v[182:185], v[24:27]
	v_mfma_f32_16x16x32_bf16 v[20:23], v[214:217], v[190:193], v[20:23]
	v_mfma_f32_16x16x32_bf16 v[16:19], v[222:225], v[190:193], v[16:19]
	v_mfma_f32_16x16x32_bf16 v[12:15], v[214:217], v[198:201], v[12:15]
	v_mfma_f32_16x16x32_bf16 v[8:11], v[222:225], v[198:201], v[8:11]
	v_mfma_f32_16x16x32_bf16 v[4:7], v[214:217], v[206:209], v[4:7]
	v_mfma_f32_16x16x32_bf16 v[0:3], v[222:225], v[206:209], v[0:3]
	s_setprio 0
	s_barrier
	ds_read_b128 v[162:165], v154
	ds_read_b128 v[166:169], v154 offset:1024
	ds_read_b128 v[170:173], v154 offset:2048
	ds_read_b128 v[174:177], v154 offset:3072
	ds_read_b128 v[178:181], v152 offset:32768
	ds_read_b128 v[182:185], v152 offset:33792
	ds_read_b128 v[186:189], v151 offset:32768
	ds_read_b128 v[190:193], v151 offset:33792
	ds_read_b128 v[194:197], v150 offset:32768
	ds_read_b128 v[198:201], v150 offset:33792
	ds_read_b128 v[202:205], v149 offset:32768
	ds_read_b128 v[206:209], v149 offset:33792
	s_waitcnt lgkmcnt(8)
	s_barrier
	s_waitcnt lgkmcnt(0)
	s_setprio 1
	s_waitcnt lgkmcnt(0)
	v_mfma_f32_16x16x32_bf16 v[124:127], v[162:165], v[178:181], v[124:127]
	v_mfma_f32_16x16x32_bf16 v[120:123], v[170:173], v[178:181], v[120:123]
	v_mfma_f32_16x16x32_bf16 v[116:119], v[162:165], v[186:189], v[116:119]
	v_mfma_f32_16x16x32_bf16 v[112:115], v[170:173], v[186:189], v[112:115]
	v_mfma_f32_16x16x32_bf16 v[108:111], v[162:165], v[194:197], v[108:111]
	v_mfma_f32_16x16x32_bf16 v[104:107], v[170:173], v[194:197], v[104:107]
	v_mfma_f32_16x16x32_bf16 v[100:103], v[162:165], v[202:205], v[100:103]
	v_mfma_f32_16x16x32_bf16 v[96:99], v[170:173], v[202:205], v[96:99]
	v_mfma_f32_16x16x32_bf16 v[124:127], v[166:169], v[182:185], v[124:127]
	v_mfma_f32_16x16x32_bf16 v[120:123], v[174:177], v[182:185], v[120:123]
	v_mfma_f32_16x16x32_bf16 v[116:119], v[166:169], v[190:193], v[116:119]
	v_mfma_f32_16x16x32_bf16 v[112:115], v[174:177], v[190:193], v[112:115]
	v_mfma_f32_16x16x32_bf16 v[108:111], v[166:169], v[198:201], v[108:111]
	v_mfma_f32_16x16x32_bf16 v[104:107], v[174:177], v[198:201], v[104:107]
	v_mfma_f32_16x16x32_bf16 v[100:103], v[166:169], v[206:209], v[100:103]
	v_mfma_f32_16x16x32_bf16 v[96:99], v[174:177], v[206:209], v[96:99]
	s_setprio 0
	s_barrier
	v_readfirstlane_b32 s67, v141
	v_lshl_add_u64 v[226:227], v[130:131], 0, s[46:47]
	s_mov_b32 m0, s67
	v_readfirstlane_b32 s67, v140
	ds_read_b128 v[210:213], v153
	ds_read_b128 v[214:217], v153 offset:1024
	ds_read_b128 v[218:221], v153 offset:2048
	ds_read_b128 v[222:225], v153 offset:3072
	global_load_lds_dwordx4 v[226:227], off
	v_lshl_add_u64 v[226:227], v[130:131], 0, s[56:57]
	s_mov_b32 m0, s67
	s_nop 0
	global_load_lds_dwordx4 v[226:227], off
	s_barrier
	s_waitcnt lgkmcnt(0)
	s_setprio 1
	s_waitcnt lgkmcnt(0)
	v_mfma_f32_16x16x32_bf16 v[92:95], v[210:213], v[178:181], v[92:95]
	v_mfma_f32_16x16x32_bf16 v[88:91], v[218:221], v[178:181], v[88:91]
	v_mfma_f32_16x16x32_bf16 v[84:87], v[210:213], v[186:189], v[84:87]
	v_mfma_f32_16x16x32_bf16 v[80:83], v[218:221], v[186:189], v[80:83]
	v_mfma_f32_16x16x32_bf16 v[76:79], v[210:213], v[194:197], v[76:79]
	v_mfma_f32_16x16x32_bf16 v[72:75], v[218:221], v[194:197], v[72:75]
	v_mfma_f32_16x16x32_bf16 v[68:71], v[210:213], v[202:205], v[68:71]
	v_mfma_f32_16x16x32_bf16 v[64:67], v[218:221], v[202:205], v[64:67]
	v_mfma_f32_16x16x32_bf16 v[92:95], v[214:217], v[182:185], v[92:95]
	v_mfma_f32_16x16x32_bf16 v[88:91], v[222:225], v[182:185], v[88:91]
	v_mfma_f32_16x16x32_bf16 v[84:87], v[214:217], v[190:193], v[84:87]
	v_mfma_f32_16x16x32_bf16 v[80:83], v[222:225], v[190:193], v[80:83]
	v_mfma_f32_16x16x32_bf16 v[76:79], v[214:217], v[198:201], v[76:79]
	v_mfma_f32_16x16x32_bf16 v[72:75], v[222:225], v[198:201], v[72:75]
	v_mfma_f32_16x16x32_bf16 v[68:71], v[214:217], v[206:209], v[68:71]
	v_mfma_f32_16x16x32_bf16 v[64:67], v[222:225], v[206:209], v[64:67]
	s_setprio 0
	v_readfirstlane_b32 s67, v139
	v_lshl_add_u64 v[226:227], v[132:133], 0, s[58:59]
	s_mov_b32 m0, s67
	v_readfirstlane_b32 s67, v138
	s_barrier
	ds_read_b128 v[178:181], v152 offset:49152
	ds_read_b128 v[182:185], v152 offset:50176
	ds_read_b128 v[186:189], v151 offset:49152
	ds_read_b128 v[190:193], v151 offset:50176
	ds_read_b128 v[194:197], v150 offset:49152
	ds_read_b128 v[198:201], v150 offset:50176
	ds_read_b128 v[202:205], v149 offset:49152
	ds_read_b128 v[206:209], v149 offset:50176
	global_load_lds_dwordx4 v[226:227], off
	s_mov_b32 m0, s67
	s_nop 0
	global_load_lds_dwordx4 v[132:133], off
	s_barrier
	s_waitcnt lgkmcnt(0)
	s_setprio 1
	s_waitcnt lgkmcnt(0)
	v_mfma_f32_16x16x32_bf16 v[60:63], v[162:165], v[178:181], v[60:63]
	v_mfma_f32_16x16x32_bf16 v[56:59], v[170:173], v[178:181], v[56:59]
	v_mfma_f32_16x16x32_bf16 v[52:55], v[162:165], v[186:189], v[52:55]
	v_mfma_f32_16x16x32_bf16 v[48:51], v[170:173], v[186:189], v[48:51]
	v_mfma_f32_16x16x32_bf16 v[44:47], v[162:165], v[194:197], v[44:47]
	v_mfma_f32_16x16x32_bf16 v[40:43], v[170:173], v[194:197], v[40:43]
	v_mfma_f32_16x16x32_bf16 v[36:39], v[162:165], v[202:205], v[36:39]
	v_mfma_f32_16x16x32_bf16 v[32:35], v[170:173], v[202:205], v[32:35]
	v_mfma_f32_16x16x32_bf16 v[60:63], v[166:169], v[182:185], v[60:63]
	v_mfma_f32_16x16x32_bf16 v[56:59], v[174:177], v[182:185], v[56:59]
	v_mfma_f32_16x16x32_bf16 v[52:55], v[166:169], v[190:193], v[52:55]
	v_mfma_f32_16x16x32_bf16 v[48:51], v[174:177], v[190:193], v[48:51]
	v_mfma_f32_16x16x32_bf16 v[44:47], v[166:169], v[198:201], v[44:47]
	v_mfma_f32_16x16x32_bf16 v[40:43], v[174:177], v[198:201], v[40:43]
	v_mfma_f32_16x16x32_bf16 v[36:39], v[166:169], v[206:209], v[36:39]
	v_mfma_f32_16x16x32_bf16 v[32:35], v[174:177], v[206:209], v[32:35]
	s_setprio 0
	s_barrier
	v_readfirstlane_b32 s67, v137
	v_lshl_add_u64 v[162:163], v[130:131], 0, s[58:59]
	s_mov_b32 m0, s67
	v_readfirstlane_b32 s67, v136
	global_load_lds_dwordx4 v[162:163], off
	s_mov_b32 m0, s67
	s_nop 0
	global_load_lds_dwordx4 v[130:131], off
	v_lshl_add_u64 v[132:133], v[132:133], 0, s[62:63]
	s_mov_b32 vcc_lo, 0xffe01000
	s_mov_b32 vcc_hi, -1
	v_lshl_add_u64 v[164:165], v[132:133], 0, vcc
	v_readfirstlane_b32 s67, v160
	s_mov_b32 vcc_lo, 0xffe02000
	s_mov_b32 m0, s67
	s_mov_b32 vcc_hi, -1
	v_readfirstlane_b32 s67, v159
	global_load_lds_dwordx4 v[164:165], off
	v_lshl_add_u64 v[164:165], v[132:133], 0, vcc
	s_mov_b32 m0, s67
	s_nop 0
	global_load_lds_dwordx4 v[164:165], off
	s_waitcnt vmcnt(8)
	s_barrier
	s_setprio 1
	v_mfma_f32_16x16x32_bf16 v[28:31], v[210:213], v[178:181], v[28:31]
	v_mfma_f32_16x16x32_bf16 v[24:27], v[218:221], v[178:181], v[24:27]
	v_mfma_f32_16x16x32_bf16 v[20:23], v[210:213], v[186:189], v[20:23]
	v_mfma_f32_16x16x32_bf16 v[16:19], v[218:221], v[186:189], v[16:19]
	v_mfma_f32_16x16x32_bf16 v[12:15], v[210:213], v[194:197], v[12:15]
	v_mfma_f32_16x16x32_bf16 v[8:11], v[218:221], v[194:197], v[8:11]
	v_mfma_f32_16x16x32_bf16 v[4:7], v[210:213], v[202:205], v[4:7]
	v_mfma_f32_16x16x32_bf16 v[0:3], v[218:221], v[202:205], v[0:3]
	v_mfma_f32_16x16x32_bf16 v[28:31], v[214:217], v[182:185], v[28:31]
	v_mfma_f32_16x16x32_bf16 v[24:27], v[222:225], v[182:185], v[24:27]
	v_mfma_f32_16x16x32_bf16 v[20:23], v[214:217], v[190:193], v[20:23]
	v_mfma_f32_16x16x32_bf16 v[16:19], v[222:225], v[190:193], v[16:19]
	v_mfma_f32_16x16x32_bf16 v[12:15], v[214:217], v[198:201], v[12:15]
	v_mfma_f32_16x16x32_bf16 v[8:11], v[222:225], v[198:201], v[8:11]
	v_mfma_f32_16x16x32_bf16 v[4:7], v[214:217], v[206:209], v[4:7]
	v_mfma_f32_16x16x32_bf16 v[0:3], v[222:225], v[206:209], v[0:3]
	s_setprio 0
	v_lshl_add_u64 v[130:131], v[130:131], 0, s[60:61]
	s_cmp_lt_u32 s66, s65
	s_barrier
	s_cbranch_scc1 .LBB0_274
	s_lshl_b32 s65, s86, 5
	s_lshl_b32 s66, s86, 8
	s_and_b32 s65, s65, 0x1800
	s_and_b32 s66, s66, 0x700
	s_or_b32 s97, s66, s65
	s_lshl_b32 s65, s97, 6
	s_add_u32 s65, s68, s65
	s_addc_u32 s86, s69, 0
	s_add_i32 s20, s20, -1
	s_lshl_b64 s[66:67], s[20:21], 20
	v_add_u32_e32 v128, v156, v157
	s_add_u32 s66, s65, s66
	v_or_b32_e32 v128, v128, v155
	s_addc_u32 s67, s86, s67
	v_lshl_add_u64 v[156:157], s[66:67], 0, v[128:129]
	v_readfirstlane_b32 s20, v160
	v_lshl_add_u64 v[206:207], v[156:157], 0, s[4:5]
	s_mov_b32 m0, s20
	v_readfirstlane_b32 s20, v159
	ds_read_b128 v[130:133], v161
	ds_read_b128 v[162:165], v161 offset:1024
	ds_read_b128 v[166:169], v161 offset:2048
	ds_read_b128 v[170:173], v161 offset:3072
	ds_read_b128 v[174:177], v152
	ds_read_b128 v[178:181], v152 offset:1024
	ds_read_b128 v[182:185], v151
	ds_read_b128 v[186:189], v151 offset:1024
	ds_read_b128 v[190:193], v150
	ds_read_b128 v[194:197], v150 offset:1024
	ds_read_b128 v[198:201], v149
	ds_read_b128 v[202:205], v149 offset:1024
	global_load_lds_dwordx4 v[206:207], off
	v_lshl_add_u64 v[156:157], v[156:157], 0, s[6:7]
	s_mov_b32 m0, s20
	s_nop 0
	global_load_lds_dwordx4 v[156:157], off
	s_barrier
	s_waitcnt lgkmcnt(0)
	s_setprio 1
	s_waitcnt lgkmcnt(0)
	v_mfma_f32_16x16x32_bf16 v[124:127], v[130:133], v[174:177], v[124:127]
	v_mfma_f32_16x16x32_bf16 v[120:123], v[166:169], v[174:177], v[120:123]
	v_mfma_f32_16x16x32_bf16 v[116:119], v[130:133], v[182:185], v[116:119]
	v_mfma_f32_16x16x32_bf16 v[112:115], v[166:169], v[182:185], v[112:115]
	v_mfma_f32_16x16x32_bf16 v[108:111], v[130:133], v[190:193], v[108:111]
	v_mfma_f32_16x16x32_bf16 v[104:107], v[166:169], v[190:193], v[104:107]
	v_mfma_f32_16x16x32_bf16 v[100:103], v[130:133], v[198:201], v[100:103]
	v_mfma_f32_16x16x32_bf16 v[96:99], v[166:169], v[198:201], v[96:99]
	v_mfma_f32_16x16x32_bf16 v[124:127], v[162:165], v[178:181], v[124:127]
	v_mfma_f32_16x16x32_bf16 v[120:123], v[170:173], v[178:181], v[120:123]
	v_mfma_f32_16x16x32_bf16 v[116:119], v[162:165], v[186:189], v[116:119]
	v_mfma_f32_16x16x32_bf16 v[112:115], v[170:173], v[186:189], v[112:115]
	v_mfma_f32_16x16x32_bf16 v[108:111], v[162:165], v[194:197], v[108:111]
	v_mfma_f32_16x16x32_bf16 v[104:107], v[170:173], v[194:197], v[104:107]
	v_mfma_f32_16x16x32_bf16 v[100:103], v[162:165], v[202:205], v[100:103]
	v_mfma_f32_16x16x32_bf16 v[96:99], v[170:173], v[202:205], v[96:99]
	s_setprio 0
	s_barrier
	ds_read_b128 v[206:209], v158
	ds_read_b128 v[210:213], v158 offset:1024
	ds_read_b128 v[214:217], v158 offset:2048
	ds_read_b128 v[156:159], v158 offset:3072
	s_barrier
	s_waitcnt lgkmcnt(0)
	s_setprio 1
	s_waitcnt lgkmcnt(0)
	v_mfma_f32_16x16x32_bf16 v[92:95], v[206:209], v[174:177], v[92:95]
	v_mfma_f32_16x16x32_bf16 v[88:91], v[214:217], v[174:177], v[88:91]
	v_mfma_f32_16x16x32_bf16 v[84:87], v[206:209], v[182:185], v[84:87]
	v_mfma_f32_16x16x32_bf16 v[80:83], v[214:217], v[182:185], v[80:83]
	v_mfma_f32_16x16x32_bf16 v[76:79], v[206:209], v[190:193], v[76:79]
	v_mfma_f32_16x16x32_bf16 v[72:75], v[214:217], v[190:193], v[72:75]
	v_mfma_f32_16x16x32_bf16 v[68:71], v[206:209], v[198:201], v[68:71]
	v_mfma_f32_16x16x32_bf16 v[64:67], v[214:217], v[198:201], v[64:67]
	v_mfma_f32_16x16x32_bf16 v[174:177], v[210:213], v[178:181], v[92:95]
	v_mfma_f32_16x16x32_bf16 v[178:181], v[156:159], v[178:181], v[88:91]
	v_mfma_f32_16x16x32_bf16 v[182:185], v[210:213], v[186:189], v[84:87]
	v_mfma_f32_16x16x32_bf16 v[186:189], v[156:159], v[186:189], v[80:83]
	v_mfma_f32_16x16x32_bf16 v[190:193], v[210:213], v[194:197], v[76:79]
	v_mfma_f32_16x16x32_bf16 v[194:197], v[156:159], v[194:197], v[72:75]
	v_mfma_f32_16x16x32_bf16 v[198:201], v[210:213], v[202:205], v[68:71]
	v_mfma_f32_16x16x32_bf16 v[202:205], v[156:159], v[202:205], v[64:67]
	s_setprio 0
	s_barrier
	s_nop 0
	ds_read_b128 v[64:67], v152 offset:16384
	ds_read_b128 v[68:71], v152 offset:17408
	ds_read_b128 v[72:75], v151 offset:16384
	ds_read_b128 v[76:79], v151 offset:17408
	ds_read_b128 v[80:83], v150 offset:16384
	ds_read_b128 v[84:87], v150 offset:17408
	ds_read_b128 v[88:91], v149 offset:16384
	ds_read_b128 v[92:95], v149 offset:17408
	s_waitcnt vmcnt(4)
	s_barrier
	s_waitcnt lgkmcnt(0)
	s_setprio 1
	s_waitcnt lgkmcnt(0)
	v_mfma_f32_16x16x32_bf16 v[60:63], v[130:133], v[64:67], v[60:63]
	v_mfma_f32_16x16x32_bf16 v[56:59], v[166:169], v[64:67], v[56:59]
	v_mfma_f32_16x16x32_bf16 v[52:55], v[130:133], v[72:75], v[52:55]
	v_mfma_f32_16x16x32_bf16 v[48:51], v[166:169], v[72:75], v[48:51]
	v_mfma_f32_16x16x32_bf16 v[218:221], v[130:133], v[80:83], v[44:47]
	v_mfma_f32_16x16x32_bf16 v[222:225], v[166:169], v[80:83], v[40:43]
	v_mfma_f32_16x16x32_bf16 v[130:133], v[130:133], v[88:91], v[36:39]
	v_mfma_f32_16x16x32_bf16 v[166:169], v[166:169], v[88:91], v[32:35]
	v_mfma_f32_16x16x32_bf16 v[32:35], v[162:165], v[68:71], v[60:63]
	v_mfma_f32_16x16x32_bf16 v[36:39], v[170:173], v[68:71], v[56:59]
	v_mfma_f32_16x16x32_bf16 v[40:43], v[162:165], v[76:79], v[52:55]
	v_mfma_f32_16x16x32_bf16 v[44:47], v[170:173], v[76:79], v[48:51]
	v_mfma_f32_16x16x32_bf16 v[48:51], v[162:165], v[84:87], v[218:221]
	v_mfma_f32_16x16x32_bf16 v[52:55], v[170:173], v[84:87], v[222:225]
	v_mfma_f32_16x16x32_bf16 v[56:59], v[162:165], v[92:95], v[130:133]
	v_mfma_f32_16x16x32_bf16 v[60:63], v[170:173], v[92:95], v[166:169]
	s_setprio 0
	s_setprio 1
	v_mfma_f32_16x16x32_bf16 v[28:31], v[206:209], v[64:67], v[28:31]
	v_mfma_f32_16x16x32_bf16 v[24:27], v[214:217], v[64:67], v[24:27]
	v_mfma_f32_16x16x32_bf16 v[20:23], v[206:209], v[72:75], v[20:23]
	v_mfma_f32_16x16x32_bf16 v[64:67], v[214:217], v[72:75], v[16:19]
	v_mfma_f32_16x16x32_bf16 v[72:75], v[206:209], v[80:83], v[12:15]
	v_mfma_f32_16x16x32_bf16 v[8:11], v[214:217], v[80:83], v[8:11]
	v_mfma_f32_16x16x32_bf16 v[80:83], v[206:209], v[88:91], v[4:7]
	v_mfma_f32_16x16x32_bf16 v[0:3], v[214:217], v[88:91], v[0:3]
	v_mfma_f32_16x16x32_bf16 v[4:7], v[210:213], v[68:71], v[28:31]
	v_mfma_f32_16x16x32_bf16 v[12:15], v[156:159], v[68:71], v[24:27]
	v_mfma_f32_16x16x32_bf16 v[16:19], v[210:213], v[76:79], v[20:23]
	v_mfma_f32_16x16x32_bf16 v[20:23], v[156:159], v[76:79], v[64:67]
	v_mfma_f32_16x16x32_bf16 v[24:27], v[210:213], v[84:87], v[72:75]
	v_mfma_f32_16x16x32_bf16 v[28:31], v[156:159], v[84:87], v[8:11]
	v_mfma_f32_16x16x32_bf16 v[64:67], v[210:213], v[92:95], v[80:83]
	v_mfma_f32_16x16x32_bf16 v[68:71], v[156:159], v[92:95], v[0:3]
	s_setprio 0
	s_barrier
	ds_read_b128 v[8:11], v154
	ds_read_b128 v[0:3], v154 offset:1024
	ds_read_b128 v[76:79], v154 offset:2048
	ds_read_b128 v[72:75], v154 offset:3072
	ds_read_b128 v[130:133], v152 offset:32768
	ds_read_b128 v[154:157], v152 offset:33792
	ds_read_b128 v[158:161], v151 offset:32768
	ds_read_b128 v[162:165], v151 offset:33792
	ds_read_b128 v[166:169], v150 offset:32768
	ds_read_b128 v[170:173], v150 offset:33792
	ds_read_b128 v[206:209], v149 offset:32768
	ds_read_b128 v[210:213], v149 offset:33792
	s_waitcnt vmcnt(2)
	s_barrier
	s_waitcnt lgkmcnt(0)
	s_setprio 1
	s_waitcnt lgkmcnt(0)
	v_mfma_f32_16x16x32_bf16 v[80:83], v[8:11], v[130:133], v[124:127]
	v_mfma_f32_16x16x32_bf16 v[84:87], v[76:79], v[130:133], v[120:123]
	v_mfma_f32_16x16x32_bf16 v[88:91], v[8:11], v[158:161], v[116:119]
	v_mfma_f32_16x16x32_bf16 v[92:95], v[76:79], v[158:161], v[112:115]
	v_mfma_f32_16x16x32_bf16 v[108:111], v[8:11], v[166:169], v[108:111]
	v_mfma_f32_16x16x32_bf16 v[104:107], v[76:79], v[166:169], v[104:107]
	v_mfma_f32_16x16x32_bf16 v[100:103], v[8:11], v[206:209], v[100:103]
	v_mfma_f32_16x16x32_bf16 v[96:99], v[76:79], v[206:209], v[96:99]
	v_mfma_f32_16x16x32_bf16 v[112:115], v[0:3], v[154:157], v[80:83]
	v_mfma_f32_16x16x32_bf16 v[116:119], v[72:75], v[154:157], v[84:87]
	v_mfma_f32_16x16x32_bf16 v[120:123], v[0:3], v[162:165], v[88:91]
	v_mfma_f32_16x16x32_bf16 v[124:127], v[72:75], v[162:165], v[92:95]
	v_mfma_f32_16x16x32_bf16 v[108:111], v[0:3], v[170:173], v[108:111]
	v_mfma_f32_16x16x32_bf16 v[104:107], v[72:75], v[170:173], v[104:107]
	v_mfma_f32_16x16x32_bf16 v[100:103], v[0:3], v[210:213], v[100:103]
	v_mfma_f32_16x16x32_bf16 v[96:99], v[72:75], v[210:213], v[96:99]
	s_setprio 0
	s_barrier
	ds_read_b128 v[88:91], v153
	ds_read_b128 v[80:83], v153 offset:1024
	ds_read_b128 v[92:95], v153 offset:2048
	ds_read_b128 v[84:87], v153 offset:3072
	s_waitcnt vmcnt(0)
	s_barrier
	s_waitcnt lgkmcnt(0)
	s_setprio 1
	s_waitcnt lgkmcnt(0)
	v_mfma_f32_16x16x32_bf16 v[174:177], v[88:91], v[130:133], v[174:177]
	v_mfma_f32_16x16x32_bf16 v[130:133], v[92:95], v[130:133], v[178:181]
	v_mfma_f32_16x16x32_bf16 v[178:181], v[88:91], v[158:161], v[182:185]
	v_mfma_f32_16x16x32_bf16 v[158:161], v[92:95], v[158:161], v[186:189]
	v_mfma_f32_16x16x32_bf16 v[182:185], v[88:91], v[166:169], v[190:193]
	v_mfma_f32_16x16x32_bf16 v[166:169], v[92:95], v[166:169], v[194:197]
	v_mfma_f32_16x16x32_bf16 v[186:189], v[88:91], v[206:209], v[198:201]
	v_mfma_f32_16x16x32_bf16 v[190:193], v[92:95], v[206:209], v[202:205]
	v_mfma_f32_16x16x32_bf16 v[174:177], v[80:83], v[154:157], v[174:177]
	v_mfma_f32_16x16x32_bf16 v[130:133], v[84:87], v[154:157], v[130:133]
	v_mfma_f32_16x16x32_bf16 v[154:157], v[80:83], v[162:165], v[178:181]
	v_mfma_f32_16x16x32_bf16 v[158:161], v[84:87], v[162:165], v[158:161]
	v_mfma_f32_16x16x32_bf16 v[162:165], v[80:83], v[170:173], v[182:185]
	v_mfma_f32_16x16x32_bf16 v[166:169], v[84:87], v[170:173], v[166:169]
	v_mfma_f32_16x16x32_bf16 v[170:173], v[80:83], v[210:213], v[186:189]
	v_mfma_f32_16x16x32_bf16 v[178:181], v[84:87], v[210:213], v[190:193]
	s_setprio 0
	s_barrier
	v_mbcnt_lo_u32_b32 v128, -1, 0
	v_mbcnt_hi_u32_b32 v128, -1, v128
	v_cvt_pk_bf16_f32 v112, v112, v113
	v_cvt_pk_bf16_f32 v113, v114, v115
	v_cvt_pk_bf16_f32 v114, v116, v117
	v_cvt_pk_bf16_f32 v115, v118, v119
	s_lshl_b32 s89, s64, 9
	v_add_u32_e32 v153, s72, v128
	v_ashrrev_i32_e32 v182, 6, v153
	v_and_b32_e32 v183, 15, v128
	v_and_b32_e32 v184, 48, v128
	v_mul_lo_u32 v185, v182, s77
	v_bfe_u32 v186, v128, 3, 3
	v_lshlrev_b32_e32 v128, 4, v128
	v_add_u32_e32 v185, 0x20000, v185
	v_lshrrev_b32_e32 v153, 2, v153
	v_and_b32_e32 v128, 0x70, v128
	v_mul_u32_u24_e32 v183, 0x90, v183
	v_and_b32_e32 v153, 64, v153
	v_add3_u32 v183, v185, v183, v184
	v_or_b32_e32 v184, v185, v128
	v_or3_b32 v153, s97, v153, v186
	v_mad_u32_u24 v184, v186, s79, v184
	ds_write_b128 v183, v[112:115]
	v_cvt_pk_bf16_f32 v112, v174, v175
	v_cvt_pk_bf16_f32 v113, v176, v177
	v_cvt_pk_bf16_f32 v114, v130, v131
	v_cvt_pk_bf16_f32 v115, v132, v133
	ds_write_b128 v183, v[112:115] offset:64
	v_lshlrev_b32_e32 v182, 7, v182
	ds_read_b128 v[112:115], v184
	v_lshlrev_b32_e32 v116, 12, v153
	v_and_or_b32 v116, v182, s80, v116
	v_or3_b32 v128, v116, s89, v128
	ds_read_b128 v[116:119], v184 offset:1152
	v_lshl_add_u64 v[130:131], s[0:1], 0, v[128:129]
	s_mov_b32 s20, 0x8000
	s_waitcnt lgkmcnt(0)
	global_store_dwordx4 v128, v[112:115], s[0:1]
	v_cvt_pk_bf16_f32 v108, v108, v109
	v_cvt_pk_bf16_f32 v109, v110, v111
	v_cvt_pk_bf16_f32 v110, v104, v105
	v_cvt_pk_bf16_f32 v111, v106, v107
	v_cvt_pk_bf16_f32 v104, v162, v163
	s_nop 1
	v_add_co_u32_e32 v112, vcc, s20, v130
	v_cvt_pk_bf16_f32 v114, v124, v125
	v_cvt_pk_bf16_f32 v115, v126, v127
	v_cvt_pk_bf16_f32 v105, v164, v165
	v_cvt_pk_bf16_f32 v106, v166, v167
	s_nop 1
	v_addc_co_u32_e32 v113, vcc, 0, v131, vcc
	global_store_dwordx4 v[112:113], v[116:119], off
	v_cvt_pk_bf16_f32 v112, v120, v121
	v_cvt_pk_bf16_f32 v113, v122, v123
	ds_write_b128 v183, v[112:115]
	v_cvt_pk_bf16_f32 v112, v154, v155
	v_cvt_pk_bf16_f32 v113, v156, v157
	v_cvt_pk_bf16_f32 v114, v158, v159
	v_cvt_pk_bf16_f32 v115, v160, v161
	ds_write_b128 v183, v[112:115] offset:64
	ds_read_b128 v[112:115], v184
	ds_read_b128 v[116:119], v184 offset:1152
	v_add_co_u32_e32 v120, vcc, s74, v130
	ds_write_b128 v183, v[108:111]
	v_cvt_pk_bf16_f32 v107, v168, v169
	ds_write_b128 v183, v[104:107] offset:64
	v_addc_co_u32_e32 v121, vcc, 0, v131, vcc
	ds_read_b128 v[104:107], v184
	ds_read_b128 v[108:111], v184 offset:1152
	s_waitcnt lgkmcnt(0)
	global_store_dwordx4 v[120:121], v[112:115], off
	v_cvt_pk_bf16_f32 v100, v100, v101
	v_cvt_pk_bf16_f32 v101, v102, v103
	v_cvt_pk_bf16_f32 v102, v96, v97
	v_cvt_pk_bf16_f32 v103, v98, v99
	ds_write_b128 v183, v[100:103]
	s_nop 0
	v_add_co_u32_e32 v112, vcc, s75, v130
	v_cvt_pk_bf16_f32 v96, v170, v171
	v_cvt_pk_bf16_f32 v97, v172, v173
	v_cvt_pk_bf16_f32 v98, v178, v179
	v_cvt_pk_bf16_f32 v99, v180, v181
	s_nop 1
	v_addc_co_u32_e32 v113, vcc, 0, v131, vcc
	global_store_dwordx4 v[112:113], v[116:119], off
	v_add_co_u32_e32 v112, vcc, s78, v130
	ds_write_b128 v183, v[96:99] offset:64
	s_nop 0
	v_addc_co_u32_e32 v113, vcc, 0, v131, vcc
	ds_read_b128 v[96:99], v184
	ds_read_b128 v[100:103], v184 offset:1152
	global_store_dwordx4 v[112:113], v[104:107], off
	s_nop 1
	v_add_co_u32_e32 v104, vcc, s81, v130
	s_nop 1
	v_addc_co_u32_e32 v105, vcc, 0, v131, vcc
	global_store_dwordx4 v[104:105], v[108:111], off
	v_add_co_u32_e32 v104, vcc, s82, v130
	s_nop 1
	v_addc_co_u32_e32 v105, vcc, 0, v131, vcc
	s_waitcnt lgkmcnt(0)
	global_store_dwordx4 v[104:105], v[96:99], off
	s_nop 1
	v_add_co_u32_e32 v96, vcc, s83, v130
	s_nop 1
	v_addc_co_u32_e32 v97, vcc, 0, v131, vcc
	global_store_dwordx4 v[96:97], v[100:103], off
	ds_read_b128 v[96:99], v152 offset:49152
	ds_read_b128 v[100:103], v152 offset:50176
	ds_read_b128 v[104:107], v151 offset:49152
	ds_read_b128 v[108:111], v151 offset:50176
	ds_read_b128 v[112:115], v150 offset:49152
	ds_read_b128 v[116:119], v150 offset:50176
	ds_read_b128 v[120:123], v149 offset:49152
	ds_read_b128 v[124:127], v149 offset:50176
	s_barrier
	s_waitcnt lgkmcnt(0)
	s_setprio 1
	s_waitcnt lgkmcnt(0)
	v_mfma_f32_16x16x32_bf16 v[32:35], v[8:11], v[96:99], v[32:35]
	v_mfma_f32_16x16x32_bf16 v[36:39], v[76:79], v[96:99], v[36:39]
	v_mfma_f32_16x16x32_bf16 v[40:43], v[8:11], v[104:107], v[40:43]
	v_mfma_f32_16x16x32_bf16 v[130:133], v[76:79], v[104:107], v[44:47]
	v_mfma_f32_16x16x32_bf16 v[150:153], v[8:11], v[112:115], v[48:51]
	v_mfma_f32_16x16x32_bf16 v[52:55], v[76:79], v[112:115], v[52:55]
	v_mfma_f32_16x16x32_bf16 v[8:11], v[8:11], v[120:123], v[56:59]
	v_mfma_f32_16x16x32_bf16 v[60:63], v[76:79], v[120:123], v[60:63]
	v_mfma_f32_16x16x32_bf16 v[56:59], v[0:3], v[100:103], v[32:35]
	v_mfma_f32_16x16x32_bf16 v[48:51], v[72:75], v[100:103], v[36:39]
	v_mfma_f32_16x16x32_bf16 v[44:47], v[0:3], v[108:111], v[40:43]
	v_mfma_f32_16x16x32_bf16 v[40:43], v[72:75], v[108:111], v[130:133]
	v_mfma_f32_16x16x32_bf16 v[36:39], v[0:3], v[116:119], v[150:153]
	v_mfma_f32_16x16x32_bf16 v[32:35], v[72:75], v[116:119], v[52:55]
	v_mfma_f32_16x16x32_bf16 v[8:11], v[0:3], v[124:127], v[8:11]
	v_mfma_f32_16x16x32_bf16 v[0:3], v[72:75], v[124:127], v[60:63]
	s_setprio 0
	s_setprio 1
	v_mfma_f32_16x16x32_bf16 v[4:7], v[88:91], v[96:99], v[4:7]
	v_mfma_f32_16x16x32_bf16 v[12:15], v[92:95], v[96:99], v[12:15]
	v_mfma_f32_16x16x32_bf16 v[16:19], v[88:91], v[104:107], v[16:19]
	v_mfma_f32_16x16x32_bf16 v[20:23], v[92:95], v[104:107], v[20:23]
	v_mfma_f32_16x16x32_bf16 v[72:75], v[88:91], v[112:115], v[24:27]
	v_mfma_f32_16x16x32_bf16 v[76:79], v[92:95], v[112:115], v[28:31]
	v_mfma_f32_16x16x32_bf16 v[64:67], v[88:91], v[120:123], v[64:67]
	v_mfma_f32_16x16x32_bf16 v[68:71], v[92:95], v[120:123], v[68:71]
	v_mfma_f32_16x16x32_bf16 v[60:63], v[80:83], v[100:103], v[4:7]
	v_mfma_f32_16x16x32_bf16 v[52:55], v[84:87], v[100:103], v[12:15]
	v_mfma_f32_16x16x32_bf16 v[28:31], v[80:83], v[108:111], v[16:19]
	v_mfma_f32_16x16x32_bf16 v[24:27], v[84:87], v[108:111], v[20:23]
	v_mfma_f32_16x16x32_bf16 v[20:23], v[80:83], v[116:119], v[72:75]
	v_mfma_f32_16x16x32_bf16 v[16:19], v[84:87], v[116:119], v[76:79]
	v_mfma_f32_16x16x32_bf16 v[12:15], v[80:83], v[124:127], v[64:67]
	v_mfma_f32_16x16x32_bf16 v[4:7], v[84:87], v[124:127], v[68:71]
	s_setprio 0
	v_cmp_gt_u32_e32 vcc, s85, v135
	s_barrier
	s_and_saveexec_b64 s[64:65], vcc
	s_cbranch_execz .LBB0_277
	s_barrier

.LBB0_464:
	v_bfe_i32 v5, v136, 27, 1
	v_lshlrev_b32_e32 v135, 4, v136
	v_lshrrev_b32_e32 v5, 22, v5
	v_add_u32_e32 v5, v135, v5
	v_and_b32_e32 v5, 0xfffffc00, v5
	v_sub_u32_e32 v5, v135, v5
	v_lshrrev_b32_e32 v6, 4, v5
	v_bitop3_b32 v5, v6, v5, 32 bitop3:0x6c
	v_ashrrev_i32_e32 v6, 31, v5
	v_lshrrev_b32_e32 v6, 26, v6
	v_add_u32_e32 v6, v5, v6
	v_ashrrev_i32_e32 v157, 6, v6
	v_and_b32_e32 v6, 0xc0, v6
	v_sub_u32_e32 v5, v5, v6
	v_ashrrev_i16_sdwa v5, v134, sext(v5) dst_sel:DWORD dst_unused:UNUSED_PAD src0_sel:DWORD src1_sel:BYTE_0
	v_and_b32_e32 v2, 15, v0
	v_and_b32_e32 v3, 48, v0
	v_bfe_i32 v158, v5, 0, 16
	v_and_b32_e32 v5, 32, v0
	v_lshlrev_b32_e32 v8, 2, v0
	v_lshlrev_b32_e32 v0, 6, v0
	s_movk_i32 s36, 0x3f0
	v_lshlrev_b32_e32 v2, 6, v2
	v_and_b32_e32 v8, 32, v8
	v_and_b32_e32 v0, 0x3c0, v0
	v_ashrrev_i32_e32 v4, 31, v136
	v_bitop3_b32 v5, v135, v5, s36 bitop3:0x6c
	v_or_b32_e32 v7, v2, v3
	v_bitop3_b32 v2, v2, v8, v3 bitop3:0x36
	v_bitop3_b32 v3, v0, v8, v3 bitop3:0x36
	v_lshlrev_b32_e32 v0, 11, v136
	v_lshrrev_b32_e32 v4, 26, v4
	v_and_or_b32 v0, v0, s78, v5
	v_lshlrev_b32_e32 v5, 3, v136
	s_bfe_u32 s66, s86, 0x30003
	v_add_u32_e32 v4, v136, v4
	s_mov_b32 s36, 0x14000
	v_and_b32_e32 v5, 0xfffffc00, v5
	s_lshl_b32 s24, s66, 14
	v_ashrrev_i32_e32 v156, 6, v4
	v_bitop3_b32 v10, v7, s36, v8 bitop3:0xde
	s_mov_b32 s36, 0x1c000
	v_add_u32_e32 v128, v0, v5
	v_bitop3_b32 v9, v7, s76, v8 bitop3:0xde
	v_bitop3_b32 v11, v7, s77, v8 bitop3:0xde
	v_bitop3_b32 v7, v7, s36, v8 bitop3:0xde
	v_lshl_add_u64 v[130:131], s[24:25], 0, v[128:129]
	v_lshlrev_b32_e32 v0, 15, v156
	s_lshl_b32 s24, s86, 17
	s_and_b32 s36, s86, 7
	v_and_b32_e32 v0, 0xffff0000, v0
	s_and_b32 s24, s24, 0x1800000
	s_lshl_b32 s36, s36, 20
	v_lshl_add_u32 v0, v157, 12, v0
	s_or_b32 s24, s24, s36
	v_lshlrev_b32_e32 v6, 6, v136
	v_lshlrev_b32_e32 v1, 13, v1
	v_and_or_b32 v0, v4, 64, v0
	s_add_u32 s68, s24, s90
	v_and_b32_e32 v6, 0x3000, v6
	v_or_b32_e32 v8, 0x800, v1
	v_or_b32_e32 v12, 0x1000, v1
	v_or_b32_e32 v13, 0x1800, v1
	v_lshl_add_u32 v128, v158, 1, v0
	s_addc_u32 s69, 0, 0
	v_mov_b32_e32 v0, 0
	v_lshl_add_u64 v[132:133], s[68:69], 0, v[128:129]
	s_mov_b32 s24, -2
	v_add_u32_e32 v162, v9, v6
	v_add_u32_e32 v153, v2, v1
	v_add_u32_e32 v152, v3, v8
	v_add_u32_e32 v151, v3, v12
	v_add_u32_e32 v150, v3, v13
	v_add_u32_e32 v161, 0xc000, v135
	v_add_u32_e32 v160, 0xe000, v135
	v_add_u32_e32 v159, v10, v6
	v_add_u32_e32 v149, 0x10000, v135
	v_add_u32_e32 v148, 0x12000, v135
	v_add_u32_e32 v147, 0x2000, v135
	v_add_u32_e32 v146, 0x14000, v135
	v_add_u32_e32 v145, 0x16000, v135
	v_add_u32_e32 v155, v11, v6
	v_add_u32_e32 v144, 0x4000, v135
	v_add_u32_e32 v143, 0x6000, v135
	v_add_u32_e32 v154, v7, v6
	v_add_u32_e32 v142, 0x18000, v135
	v_add_u32_e32 v141, 0x1a000, v135
	v_add_u32_e32 v140, 0x8000, v135
	v_add_u32_e32 v139, 0xa000, v135
	v_add_u32_e32 v138, 0x1c000, v135
	v_add_u32_e32 v137, 0x1e000, v135
	v_mov_b32_e32 v1, v0
	v_mov_b32_e32 v2, v0
	v_mov_b32_e32 v3, v0
	v_mov_b32_e32 v4, v0
	v_mov_b32_e32 v5, v0
	v_mov_b32_e32 v6, v0
	v_mov_b32_e32 v7, v0
	v_mov_b32_e32 v8, v0
	v_mov_b32_e32 v9, v0
	v_mov_b32_e32 v10, v0
	v_mov_b32_e32 v11, v0
	v_mov_b32_e32 v12, v0
	v_mov_b32_e32 v13, v0
	v_mov_b32_e32 v14, v0
	v_mov_b32_e32 v15, v0
	v_mov_b32_e32 v16, v0
	v_mov_b32_e32 v17, v0
	v_mov_b32_e32 v18, v0
	v_mov_b32_e32 v19, v0
	v_mov_b32_e32 v20, v0
	v_mov_b32_e32 v21, v0
	v_mov_b32_e32 v22, v0
	v_mov_b32_e32 v23, v0
	v_mov_b32_e32 v24, v0
	v_mov_b32_e32 v25, v0
	v_mov_b32_e32 v26, v0
	v_mov_b32_e32 v27, v0
	v_mov_b32_e32 v28, v0
	v_mov_b32_e32 v29, v0
	v_mov_b32_e32 v30, v0
	v_mov_b32_e32 v31, v0
	v_mov_b32_e32 v32, v0
	v_mov_b32_e32 v33, v0
	v_mov_b32_e32 v34, v0
	v_mov_b32_e32 v35, v0
	v_mov_b32_e32 v36, v0
	v_mov_b32_e32 v37, v0
	v_mov_b32_e32 v38, v0
	v_mov_b32_e32 v39, v0
	v_mov_b32_e32 v40, v0
	v_mov_b32_e32 v41, v0
	v_mov_b32_e32 v42, v0
	v_mov_b32_e32 v43, v0
	v_mov_b32_e32 v44, v0
	v_mov_b32_e32 v45, v0
	v_mov_b32_e32 v46, v0
	v_mov_b32_e32 v47, v0
	v_mov_b32_e32 v48, v0
	v_mov_b32_e32 v49, v0
	v_mov_b32_e32 v50, v0
	v_mov_b32_e32 v51, v0
	v_mov_b32_e32 v52, v0
	v_mov_b32_e32 v53, v0
	v_mov_b32_e32 v54, v0
	v_mov_b32_e32 v55, v0
	v_mov_b32_e32 v56, v0
	v_mov_b32_e32 v57, v0
	v_mov_b32_e32 v58, v0
	v_mov_b32_e32 v59, v0
	v_mov_b32_e32 v60, v0
	v_mov_b32_e32 v61, v0
	v_mov_b32_e32 v62, v0
	v_mov_b32_e32 v63, v0
	v_mov_b32_e32 v64, v0
	v_mov_b32_e32 v65, v0
	v_mov_b32_e32 v66, v0
	v_mov_b32_e32 v67, v0
	v_mov_b32_e32 v68, v0
	v_mov_b32_e32 v69, v0
	v_mov_b32_e32 v70, v0
	v_mov_b32_e32 v71, v0
	v_mov_b32_e32 v72, v0
	v_mov_b32_e32 v73, v0
	v_mov_b32_e32 v74, v0
	v_mov_b32_e32 v75, v0
	v_mov_b32_e32 v76, v0
	v_mov_b32_e32 v77, v0
	v_mov_b32_e32 v78, v0
	v_mov_b32_e32 v79, v0
	v_mov_b32_e32 v80, v0
	v_mov_b32_e32 v81, v0
	v_mov_b32_e32 v82, v0
	v_mov_b32_e32 v83, v0
	v_mov_b32_e32 v84, v0
	v_mov_b32_e32 v85, v0
	v_mov_b32_e32 v86, v0
	v_mov_b32_e32 v87, v0
	v_mov_b32_e32 v88, v0
	v_mov_b32_e32 v89, v0
	v_mov_b32_e32 v90, v0
	v_mov_b32_e32 v91, v0
	v_mov_b32_e32 v92, v0
	v_mov_b32_e32 v93, v0
	v_mov_b32_e32 v94, v0
	v_mov_b32_e32 v95, v0
	v_mov_b32_e32 v96, v0
	v_mov_b32_e32 v97, v0
	v_mov_b32_e32 v98, v0
	v_mov_b32_e32 v99, v0
	v_mov_b32_e32 v100, v0
	v_mov_b32_e32 v101, v0
	v_mov_b32_e32 v102, v0
	v_mov_b32_e32 v103, v0
	v_mov_b32_e32 v104, v0
	v_mov_b32_e32 v105, v0
	v_mov_b32_e32 v106, v0
	v_mov_b32_e32 v107, v0
	v_mov_b32_e32 v108, v0
	v_mov_b32_e32 v109, v0
	v_mov_b32_e32 v110, v0
	v_mov_b32_e32 v111, v0
	v_mov_b32_e32 v112, v0
	v_mov_b32_e32 v113, v0
	v_mov_b32_e32 v114, v0
	v_mov_b32_e32 v115, v0
	v_mov_b32_e32 v116, v0
	v_mov_b32_e32 v117, v0
	v_mov_b32_e32 v118, v0
	v_mov_b32_e32 v119, v0
	v_mov_b32_e32 v120, v0
	v_mov_b32_e32 v121, v0
	v_mov_b32_e32 v122, v0
	v_mov_b32_e32 v123, v0
	v_mov_b32_e32 v124, v0
	v_mov_b32_e32 v125, v0
	v_mov_b32_e32 v126, v0
	v_mov_b32_e32 v127, v0
	s_barrier
	v_lshl_add_u64 v[228:229], s[50:51], 0, v[132:133]
	s_mov_b64 s[68:69], 0xe080080
	v_readfirstlane_b32 s36, v161
	v_lshl_add_u64 v[166:167], v[228:229], 0, s[68:69]
	s_mov_b32 m0, s36
	s_mov_b64 s[68:69], 0xe0c0080
	v_readfirstlane_b32 s36, v160
	global_load_lds_dwordx4 v[166:167], off
	v_lshl_add_u64 v[166:167], v[228:229], 0, s[68:69]
	s_mov_b32 m0, s36
	s_nop 0
	global_load_lds_dwordx4 v[166:167], off
.LBB0_465:
	ds_read_b128 v[164:167], v162
	ds_read_b128 v[168:171], v162 offset:1024
	ds_read_b128 v[172:175], v162 offset:2048
	ds_read_b128 v[176:179], v162 offset:3072
	ds_read_b128 v[180:183], v153
	ds_read_b128 v[184:187], v153 offset:1024
	ds_read_b128 v[188:191], v152
	ds_read_b128 v[192:195], v152 offset:1024
	ds_read_b128 v[196:199], v151
	ds_read_b128 v[200:203], v151 offset:1024
	ds_read_b128 v[204:207], v150
	ds_read_b128 v[208:211], v150 offset:1024
	s_waitcnt lgkmcnt(8)
	s_barrier
	s_waitcnt lgkmcnt(0)
	s_setprio 1
	s_waitcnt lgkmcnt(0)
	v_mfma_f32_16x16x32_bf16 v[124:127], v[164:167], v[180:183], v[124:127]
	v_mfma_f32_16x16x32_bf16 v[120:123], v[172:175], v[180:183], v[120:123]
	v_mfma_f32_16x16x32_bf16 v[116:119], v[164:167], v[188:191], v[116:119]
	v_mfma_f32_16x16x32_bf16 v[112:115], v[172:175], v[188:191], v[112:115]
	v_mfma_f32_16x16x32_bf16 v[108:111], v[164:167], v[196:199], v[108:111]
	v_mfma_f32_16x16x32_bf16 v[104:107], v[172:175], v[196:199], v[104:107]
	v_mfma_f32_16x16x32_bf16 v[100:103], v[164:167], v[204:207], v[100:103]
	v_mfma_f32_16x16x32_bf16 v[96:99], v[172:175], v[204:207], v[96:99]
	v_mfma_f32_16x16x32_bf16 v[124:127], v[168:171], v[184:187], v[124:127]
	v_mfma_f32_16x16x32_bf16 v[120:123], v[176:179], v[184:187], v[120:123]
	v_mfma_f32_16x16x32_bf16 v[116:119], v[168:171], v[192:195], v[116:119]
	v_mfma_f32_16x16x32_bf16 v[112:115], v[176:179], v[192:195], v[112:115]
	v_mfma_f32_16x16x32_bf16 v[108:111], v[168:171], v[200:203], v[108:111]
	v_mfma_f32_16x16x32_bf16 v[104:107], v[176:179], v[200:203], v[104:107]
	v_mfma_f32_16x16x32_bf16 v[100:103], v[168:171], v[208:211], v[100:103]
	v_mfma_f32_16x16x32_bf16 v[96:99], v[176:179], v[208:211], v[96:99]
	s_setprio 0
	s_barrier
	v_lshl_add_u64 v[230:231], s[50:51], 0, v[130:131]
	s_mov_b64 s[68:69], 0x3880000
	v_readfirstlane_b32 s36, v149
	v_lshl_add_u64 v[232:233], v[230:231], 0, s[68:69]
	s_mov_b32 m0, s36
	s_mov_b64 s[68:69], 0x3881000
	v_readfirstlane_b32 s36, v148
	ds_read_b128 v[212:215], v159
	ds_read_b128 v[216:219], v159 offset:1024
	ds_read_b128 v[220:223], v159 offset:2048
	ds_read_b128 v[224:227], v159 offset:3072
	global_load_lds_dwordx4 v[232:233], off
	v_lshl_add_u64 v[232:233], v[230:231], 0, s[68:69]
	s_mov_b32 m0, s36
	s_nop 0
	global_load_lds_dwordx4 v[232:233], off
	s_barrier
	s_waitcnt lgkmcnt(0)
	s_setprio 1
	s_waitcnt lgkmcnt(0)
	v_mfma_f32_16x16x32_bf16 v[92:95], v[212:215], v[180:183], v[92:95]
	v_mfma_f32_16x16x32_bf16 v[88:91], v[220:223], v[180:183], v[88:91]
	v_mfma_f32_16x16x32_bf16 v[84:87], v[212:215], v[188:191], v[84:87]
	v_mfma_f32_16x16x32_bf16 v[80:83], v[220:223], v[188:191], v[80:83]
	v_mfma_f32_16x16x32_bf16 v[76:79], v[212:215], v[196:199], v[76:79]
	v_mfma_f32_16x16x32_bf16 v[72:75], v[220:223], v[196:199], v[72:75]
	v_mfma_f32_16x16x32_bf16 v[68:71], v[212:215], v[204:207], v[68:71]
	v_mfma_f32_16x16x32_bf16 v[64:67], v[220:223], v[204:207], v[64:67]
	v_mfma_f32_16x16x32_bf16 v[92:95], v[216:219], v[184:187], v[92:95]
	v_mfma_f32_16x16x32_bf16 v[88:91], v[224:227], v[184:187], v[88:91]
	v_mfma_f32_16x16x32_bf16 v[84:87], v[216:219], v[192:195], v[84:87]
	v_mfma_f32_16x16x32_bf16 v[80:83], v[224:227], v[192:195], v[80:83]
	v_mfma_f32_16x16x32_bf16 v[76:79], v[216:219], v[200:203], v[76:79]
	v_mfma_f32_16x16x32_bf16 v[72:75], v[224:227], v[200:203], v[72:75]
	v_mfma_f32_16x16x32_bf16 v[68:71], v[216:219], v[208:211], v[68:71]
	v_mfma_f32_16x16x32_bf16 v[64:67], v[224:227], v[208:211], v[64:67]
	s_setprio 0
	s_mov_b64 s[68:69], 0xe000100
	v_readfirstlane_b32 s36, v135
	v_lshl_add_u64 v[232:233], v[228:229], 0, s[68:69]
	s_mov_b32 m0, s36
	s_mov_b64 s[68:69], 0xe040100
	v_readfirstlane_b32 s36, v147
	s_barrier
	ds_read_b128 v[180:183], v153 offset:16384
	ds_read_b128 v[184:187], v153 offset:17408
	ds_read_b128 v[188:191], v152 offset:16384
	ds_read_b128 v[192:195], v152 offset:17408
	ds_read_b128 v[196:199], v151 offset:16384
	ds_read_b128 v[200:203], v151 offset:17408
	ds_read_b128 v[204:207], v150 offset:16384
	ds_read_b128 v[208:211], v150 offset:17408
	global_load_lds_dwordx4 v[232:233], off
	v_lshl_add_u64 v[232:233], v[228:229], 0, s[68:69]
	s_mov_b32 m0, s36
	s_nop 0
	global_load_lds_dwordx4 v[232:233], off
	s_barrier
	s_waitcnt lgkmcnt(0)
	s_setprio 1
	s_waitcnt lgkmcnt(0)
	v_mfma_f32_16x16x32_bf16 v[60:63], v[164:167], v[180:183], v[60:63]
	v_mfma_f32_16x16x32_bf16 v[56:59], v[172:175], v[180:183], v[56:59]
	v_mfma_f32_16x16x32_bf16 v[52:55], v[164:167], v[188:191], v[52:55]
	v_mfma_f32_16x16x32_bf16 v[48:51], v[172:175], v[188:191], v[48:51]
	v_mfma_f32_16x16x32_bf16 v[44:47], v[164:167], v[196:199], v[44:47]
	v_mfma_f32_16x16x32_bf16 v[40:43], v[172:175], v[196:199], v[40:43]
	v_mfma_f32_16x16x32_bf16 v[36:39], v[164:167], v[204:207], v[36:39]
	v_mfma_f32_16x16x32_bf16 v[32:35], v[172:175], v[204:207], v[32:35]
	v_mfma_f32_16x16x32_bf16 v[60:63], v[168:171], v[184:187], v[60:63]
	v_mfma_f32_16x16x32_bf16 v[56:59], v[176:179], v[184:187], v[56:59]
	v_mfma_f32_16x16x32_bf16 v[52:55], v[168:171], v[192:195], v[52:55]
	v_mfma_f32_16x16x32_bf16 v[48:51], v[176:179], v[192:195], v[48:51]
	v_mfma_f32_16x16x32_bf16 v[44:47], v[168:171], v[200:203], v[44:47]
	v_mfma_f32_16x16x32_bf16 v[40:43], v[176:179], v[200:203], v[40:43]
	v_mfma_f32_16x16x32_bf16 v[36:39], v[168:171], v[208:211], v[36:39]
	v_mfma_f32_16x16x32_bf16 v[32:35], v[176:179], v[208:211], v[32:35]
	s_setprio 0
	s_barrier
	s_mov_b64 s[68:69], 0x3882000
	v_readfirstlane_b32 s36, v146
	v_lshl_add_u64 v[164:165], v[230:231], 0, s[68:69]
	s_mov_b32 m0, s36
	s_mov_b64 s[68:69], 0x3883000
	v_readfirstlane_b32 s36, v145
	global_load_lds_dwordx4 v[164:165], off
	v_lshl_add_u64 v[164:165], v[230:231], 0, s[68:69]
	s_mov_b32 m0, s36
	s_nop 0
	global_load_lds_dwordx4 v[164:165], off
	v_readfirstlane_b32 s36, v144
	v_lshl_add_u64 v[166:167], v[228:229], 0, s[26:27]
	s_mov_b32 m0, s36
	v_readfirstlane_b32 s36, v143
	global_load_lds_dwordx4 v[166:167], off
	v_lshl_add_u64 v[166:167], v[228:229], 0, s[28:29]
	s_mov_b32 m0, s36
	s_nop 0
	global_load_lds_dwordx4 v[166:167], off
	s_waitcnt vmcnt(8)
	s_barrier
	s_setprio 1
	v_mfma_f32_16x16x32_bf16 v[28:31], v[212:215], v[180:183], v[28:31]
	v_mfma_f32_16x16x32_bf16 v[24:27], v[220:223], v[180:183], v[24:27]
	v_mfma_f32_16x16x32_bf16 v[20:23], v[212:215], v[188:191], v[20:23]
	v_mfma_f32_16x16x32_bf16 v[16:19], v[220:223], v[188:191], v[16:19]
	v_mfma_f32_16x16x32_bf16 v[12:15], v[212:215], v[196:199], v[12:15]
	v_mfma_f32_16x16x32_bf16 v[8:11], v[220:223], v[196:199], v[8:11]
	v_mfma_f32_16x16x32_bf16 v[4:7], v[212:215], v[204:207], v[4:7]
	v_mfma_f32_16x16x32_bf16 v[0:3], v[220:223], v[204:207], v[0:3]
	v_mfma_f32_16x16x32_bf16 v[28:31], v[216:219], v[184:187], v[28:31]
	v_mfma_f32_16x16x32_bf16 v[24:27], v[224:227], v[184:187], v[24:27]
	v_mfma_f32_16x16x32_bf16 v[20:23], v[216:219], v[192:195], v[20:23]
	v_mfma_f32_16x16x32_bf16 v[16:19], v[224:227], v[192:195], v[16:19]
	v_mfma_f32_16x16x32_bf16 v[12:15], v[216:219], v[200:203], v[12:15]
	v_mfma_f32_16x16x32_bf16 v[8:11], v[224:227], v[200:203], v[8:11]
	v_mfma_f32_16x16x32_bf16 v[4:7], v[216:219], v[208:211], v[4:7]
	v_mfma_f32_16x16x32_bf16 v[0:3], v[224:227], v[208:211], v[0:3]
	s_setprio 0
	s_barrier
	ds_read_b128 v[164:167], v155
	ds_read_b128 v[168:171], v155 offset:1024
	ds_read_b128 v[172:175], v155 offset:2048
	ds_read_b128 v[176:179], v155 offset:3072
	ds_read_b128 v[180:183], v153 offset:32768
	ds_read_b128 v[184:187], v153 offset:33792
	ds_read_b128 v[188:191], v152 offset:32768
	ds_read_b128 v[192:195], v152 offset:33792
	ds_read_b128 v[196:199], v151 offset:32768
	ds_read_b128 v[200:203], v151 offset:33792
	ds_read_b128 v[204:207], v150 offset:32768
	ds_read_b128 v[208:211], v150 offset:33792
	s_waitcnt lgkmcnt(8)
	s_barrier
	s_waitcnt lgkmcnt(0)
	s_setprio 1
	s_waitcnt lgkmcnt(0)
	v_mfma_f32_16x16x32_bf16 v[124:127], v[164:167], v[180:183], v[124:127]
	v_mfma_f32_16x16x32_bf16 v[120:123], v[172:175], v[180:183], v[120:123]
	v_mfma_f32_16x16x32_bf16 v[116:119], v[164:167], v[188:191], v[116:119]
	v_mfma_f32_16x16x32_bf16 v[112:115], v[172:175], v[188:191], v[112:115]
	v_mfma_f32_16x16x32_bf16 v[108:111], v[164:167], v[196:199], v[108:111]
	v_mfma_f32_16x16x32_bf16 v[104:107], v[172:175], v[196:199], v[104:107]
	v_mfma_f32_16x16x32_bf16 v[100:103], v[164:167], v[204:207], v[100:103]
	v_mfma_f32_16x16x32_bf16 v[96:99], v[172:175], v[204:207], v[96:99]
	v_mfma_f32_16x16x32_bf16 v[124:127], v[168:171], v[184:187], v[124:127]
	v_mfma_f32_16x16x32_bf16 v[120:123], v[176:179], v[184:187], v[120:123]
	v_mfma_f32_16x16x32_bf16 v[116:119], v[168:171], v[192:195], v[116:119]
	v_mfma_f32_16x16x32_bf16 v[112:115], v[176:179], v[192:195], v[112:115]
	v_mfma_f32_16x16x32_bf16 v[108:111], v[168:171], v[200:203], v[108:111]
	v_mfma_f32_16x16x32_bf16 v[104:107], v[176:179], v[200:203], v[104:107]
	v_mfma_f32_16x16x32_bf16 v[100:103], v[168:171], v[208:211], v[100:103]
	v_mfma_f32_16x16x32_bf16 v[96:99], v[176:179], v[208:211], v[96:99]
	s_setprio 0
	s_barrier
	v_readfirstlane_b32 s36, v142
	v_lshl_add_u64 v[232:233], v[230:231], 0, s[30:31]
	s_mov_b32 m0, s36
	v_readfirstlane_b32 s36, v141
	ds_read_b128 v[212:215], v154
	ds_read_b128 v[216:219], v154 offset:1024
	ds_read_b128 v[220:223], v154 offset:2048
	ds_read_b128 v[224:227], v154 offset:3072
	global_load_lds_dwordx4 v[232:233], off
	v_lshl_add_u64 v[232:233], v[230:231], 0, s[34:35]
	s_mov_b32 m0, s36
	s_nop 0
	global_load_lds_dwordx4 v[232:233], off
	s_barrier
	s_waitcnt lgkmcnt(0)
	s_setprio 1
	s_waitcnt lgkmcnt(0)
	v_mfma_f32_16x16x32_bf16 v[92:95], v[212:215], v[180:183], v[92:95]
	v_mfma_f32_16x16x32_bf16 v[88:91], v[220:223], v[180:183], v[88:91]
	v_mfma_f32_16x16x32_bf16 v[84:87], v[212:215], v[188:191], v[84:87]
	v_mfma_f32_16x16x32_bf16 v[80:83], v[220:223], v[188:191], v[80:83]
	v_mfma_f32_16x16x32_bf16 v[76:79], v[212:215], v[196:199], v[76:79]
	v_mfma_f32_16x16x32_bf16 v[72:75], v[220:223], v[196:199], v[72:75]
	v_mfma_f32_16x16x32_bf16 v[68:71], v[212:215], v[204:207], v[68:71]
	v_mfma_f32_16x16x32_bf16 v[64:67], v[220:223], v[204:207], v[64:67]
	v_mfma_f32_16x16x32_bf16 v[92:95], v[216:219], v[184:187], v[92:95]
	v_mfma_f32_16x16x32_bf16 v[88:91], v[224:227], v[184:187], v[88:91]
	v_mfma_f32_16x16x32_bf16 v[84:87], v[216:219], v[192:195], v[84:87]
	v_mfma_f32_16x16x32_bf16 v[80:83], v[224:227], v[192:195], v[80:83]
	v_mfma_f32_16x16x32_bf16 v[76:79], v[216:219], v[200:203], v[76:79]
	v_mfma_f32_16x16x32_bf16 v[72:75], v[224:227], v[200:203], v[72:75]
	v_mfma_f32_16x16x32_bf16 v[68:71], v[216:219], v[208:211], v[68:71]
	v_mfma_f32_16x16x32_bf16 v[64:67], v[224:227], v[208:211], v[64:67]
	s_setprio 0
	v_readfirstlane_b32 s36, v140
	v_lshl_add_u64 v[232:233], v[228:229], 0, s[44:45]
	s_mov_b32 m0, s36
	v_readfirstlane_b32 s36, v139
	s_barrier
	ds_read_b128 v[180:183], v153 offset:49152
	ds_read_b128 v[184:187], v153 offset:50176
	ds_read_b128 v[188:191], v152 offset:49152
	ds_read_b128 v[192:195], v152 offset:50176
	ds_read_b128 v[196:199], v151 offset:49152
	ds_read_b128 v[200:203], v151 offset:50176
	ds_read_b128 v[204:207], v150 offset:49152
	ds_read_b128 v[208:211], v150 offset:50176
	global_load_lds_dwordx4 v[232:233], off
	v_lshl_add_u64 v[228:229], v[228:229], 0, s[46:47]
	s_mov_b32 m0, s36
	s_nop 0
	global_load_lds_dwordx4 v[228:229], off
	s_barrier
	s_waitcnt lgkmcnt(0)
	s_setprio 1
	s_waitcnt lgkmcnt(0)
	v_mfma_f32_16x16x32_bf16 v[60:63], v[164:167], v[180:183], v[60:63]
	v_mfma_f32_16x16x32_bf16 v[56:59], v[172:175], v[180:183], v[56:59]
	v_mfma_f32_16x16x32_bf16 v[52:55], v[164:167], v[188:191], v[52:55]
	v_mfma_f32_16x16x32_bf16 v[48:51], v[172:175], v[188:191], v[48:51]
	v_mfma_f32_16x16x32_bf16 v[44:47], v[164:167], v[196:199], v[44:47]
	v_mfma_f32_16x16x32_bf16 v[40:43], v[172:175], v[196:199], v[40:43]
	v_mfma_f32_16x16x32_bf16 v[36:39], v[164:167], v[204:207], v[36:39]
	v_mfma_f32_16x16x32_bf16 v[32:35], v[172:175], v[204:207], v[32:35]
	v_mfma_f32_16x16x32_bf16 v[60:63], v[168:171], v[184:187], v[60:63]
	v_mfma_f32_16x16x32_bf16 v[56:59], v[176:179], v[184:187], v[56:59]
	v_mfma_f32_16x16x32_bf16 v[52:55], v[168:171], v[192:195], v[52:55]
	v_mfma_f32_16x16x32_bf16 v[48:51], v[176:179], v[192:195], v[48:51]
	v_mfma_f32_16x16x32_bf16 v[44:47], v[168:171], v[200:203], v[44:47]
	v_mfma_f32_16x16x32_bf16 v[40:43], v[176:179], v[200:203], v[40:43]
	v_mfma_f32_16x16x32_bf16 v[36:39], v[168:171], v[208:211], v[36:39]
	v_mfma_f32_16x16x32_bf16 v[32:35], v[176:179], v[208:211], v[32:35]
	s_setprio 0
	s_barrier
	v_readfirstlane_b32 s36, v138
	v_lshl_add_u64 v[164:165], v[230:231], 0, s[56:57]
	s_mov_b32 m0, s36
	v_readfirstlane_b32 s36, v137
	global_load_lds_dwordx4 v[164:165], off
	v_lshl_add_u64 v[164:165], v[230:231], 0, s[58:59]
	s_mov_b32 m0, s36
	s_nop 0
	global_load_lds_dwordx4 v[164:165], off
	v_lshl_add_u64 v[132:133], v[132:133], 0, s[60:61]
	v_lshl_add_u64 v[228:229], s[50:51], 0, v[132:133]
	s_mov_b64 s[68:69], 0xe080080
	v_readfirstlane_b32 s36, v161
	v_lshl_add_u64 v[166:167], v[228:229], 0, s[68:69]
	s_mov_b32 m0, s36
	s_mov_b64 s[68:69], 0xe0c0080
	v_readfirstlane_b32 s36, v160
	global_load_lds_dwordx4 v[166:167], off
	v_lshl_add_u64 v[166:167], v[228:229], 0, s[68:69]
	s_mov_b32 m0, s36
	s_nop 0
	global_load_lds_dwordx4 v[166:167], off
	s_waitcnt vmcnt(8)
	s_barrier
	s_setprio 1
	v_mfma_f32_16x16x32_bf16 v[28:31], v[212:215], v[180:183], v[28:31]
	v_mfma_f32_16x16x32_bf16 v[24:27], v[220:223], v[180:183], v[24:27]
	v_mfma_f32_16x16x32_bf16 v[20:23], v[212:215], v[188:191], v[20:23]
	v_mfma_f32_16x16x32_bf16 v[16:19], v[220:223], v[188:191], v[16:19]
	v_mfma_f32_16x16x32_bf16 v[12:15], v[212:215], v[196:199], v[12:15]
	v_mfma_f32_16x16x32_bf16 v[8:11], v[220:223], v[196:199], v[8:11]
	v_mfma_f32_16x16x32_bf16 v[4:7], v[212:215], v[204:207], v[4:7]
	v_mfma_f32_16x16x32_bf16 v[0:3], v[220:223], v[204:207], v[0:3]
	v_mfma_f32_16x16x32_bf16 v[28:31], v[216:219], v[184:187], v[28:31]
	v_mfma_f32_16x16x32_bf16 v[24:27], v[224:227], v[184:187], v[24:27]
	v_mfma_f32_16x16x32_bf16 v[20:23], v[216:219], v[192:195], v[20:23]
	v_mfma_f32_16x16x32_bf16 v[16:19], v[224:227], v[192:195], v[16:19]
	v_mfma_f32_16x16x32_bf16 v[12:15], v[216:219], v[200:203], v[12:15]
	v_mfma_f32_16x16x32_bf16 v[8:11], v[224:227], v[200:203], v[8:11]
	v_mfma_f32_16x16x32_bf16 v[4:7], v[216:219], v[208:211], v[4:7]
	v_mfma_f32_16x16x32_bf16 v[0:3], v[224:227], v[208:211], v[0:3]
	s_setprio 0
	s_add_i32 s24, s24, 2
	v_lshl_add_u64 v[130:131], v[130:131], 0, s[10:11]
	s_cmp_lt_u32 s24, 28
	s_barrier
	s_cbranch_scc1 .LBB0_465
	s_lshl_b32 s24, s86, 5
	s_lshl_b32 s36, s86, 8
	s_and_b32 s24, s24, 0x1800
	s_and_b32 s36, s36, 0x700
	s_or_b32 s24, s36, s24
	v_lshlrev_b32_e32 v128, 3, v156
	v_lshlrev_b32_e32 v130, 5, v156
	v_and_b32_e32 v128, 0xffff0, v128
	v_and_b32_e32 v130, 32, v130
	s_lshl_b32 s36, s24, 12
	v_add_u32_e32 v130, v130, v158
	v_add_lshl_u32 v128, v157, v128, 12
	s_add_u32 s68, s70, s36
	v_lshl_add_u32 v128, v130, 1, v128
	s_addc_u32 s69, s71, 0
	v_lshl_add_u64 v[156:157], s[68:69], 0, v[128:129]
	v_readfirstlane_b32 s36, v161
	ds_read_b128 v[130:133], v162
	ds_read_b128 v[164:167], v162 offset:1024
	ds_read_b128 v[168:171], v162 offset:2048
	ds_read_b128 v[172:175], v162 offset:3072
	ds_read_b128 v[176:179], v153
	ds_read_b128 v[180:183], v153 offset:1024
	ds_read_b128 v[184:187], v152
	ds_read_b128 v[188:191], v152 offset:1024
	ds_read_b128 v[192:195], v151
	ds_read_b128 v[196:199], v151 offset:1024
	ds_read_b128 v[200:203], v150
	ds_read_b128 v[204:207], v150 offset:1024
	v_lshl_add_u64 v[162:163], v[156:157], 0, s[62:63]
	s_mov_b32 m0, s36
	v_readfirstlane_b32 s36, v160
	global_load_lds_dwordx4 v[162:163], off
	v_lshl_add_u64 v[156:157], v[156:157], 0, s[64:65]
	s_mov_b32 m0, s36
	s_nop 0
	global_load_lds_dwordx4 v[156:157], off
	s_barrier
	s_waitcnt lgkmcnt(0)
	s_setprio 1
	s_waitcnt lgkmcnt(0)
	v_mfma_f32_16x16x32_bf16 v[124:127], v[130:133], v[176:179], v[124:127]
	v_mfma_f32_16x16x32_bf16 v[120:123], v[168:171], v[176:179], v[120:123]
	v_mfma_f32_16x16x32_bf16 v[116:119], v[130:133], v[184:187], v[116:119]
	v_mfma_f32_16x16x32_bf16 v[112:115], v[168:171], v[184:187], v[112:115]
	v_mfma_f32_16x16x32_bf16 v[108:111], v[130:133], v[192:195], v[108:111]
	v_mfma_f32_16x16x32_bf16 v[104:107], v[168:171], v[192:195], v[104:107]
	v_mfma_f32_16x16x32_bf16 v[100:103], v[130:133], v[200:203], v[100:103]
	v_mfma_f32_16x16x32_bf16 v[96:99], v[168:171], v[200:203], v[96:99]
	v_mfma_f32_16x16x32_bf16 v[124:127], v[164:167], v[180:183], v[124:127]
	v_mfma_f32_16x16x32_bf16 v[120:123], v[172:175], v[180:183], v[120:123]
	v_mfma_f32_16x16x32_bf16 v[116:119], v[164:167], v[188:191], v[116:119]
	v_mfma_f32_16x16x32_bf16 v[112:115], v[172:175], v[188:191], v[112:115]
	v_mfma_f32_16x16x32_bf16 v[108:111], v[164:167], v[196:199], v[108:111]
	v_mfma_f32_16x16x32_bf16 v[104:107], v[172:175], v[196:199], v[104:107]
	v_mfma_f32_16x16x32_bf16 v[100:103], v[164:167], v[204:207], v[100:103]
	v_mfma_f32_16x16x32_bf16 v[96:99], v[172:175], v[204:207], v[96:99]
	s_setprio 0
	s_barrier
	ds_read_b128 v[160:163], v159
	ds_read_b128 v[208:211], v159 offset:1024
	ds_read_b128 v[212:215], v159 offset:2048
	ds_read_b128 v[156:159], v159 offset:3072
	s_barrier
	s_waitcnt lgkmcnt(0)
	s_setprio 1
	s_waitcnt lgkmcnt(0)
	v_mfma_f32_16x16x32_bf16 v[92:95], v[160:163], v[176:179], v[92:95]
	v_mfma_f32_16x16x32_bf16 v[88:91], v[212:215], v[176:179], v[88:91]
	v_mfma_f32_16x16x32_bf16 v[84:87], v[160:163], v[184:187], v[84:87]
	v_mfma_f32_16x16x32_bf16 v[80:83], v[212:215], v[184:187], v[80:83]
	v_mfma_f32_16x16x32_bf16 v[76:79], v[160:163], v[192:195], v[76:79]
	v_mfma_f32_16x16x32_bf16 v[72:75], v[212:215], v[192:195], v[72:75]
	v_mfma_f32_16x16x32_bf16 v[68:71], v[160:163], v[200:203], v[68:71]
	v_mfma_f32_16x16x32_bf16 v[64:67], v[212:215], v[200:203], v[64:67]
	v_mfma_f32_16x16x32_bf16 v[176:179], v[208:211], v[180:183], v[92:95]
	v_mfma_f32_16x16x32_bf16 v[180:183], v[156:159], v[180:183], v[88:91]
	v_mfma_f32_16x16x32_bf16 v[184:187], v[208:211], v[188:191], v[84:87]
	v_mfma_f32_16x16x32_bf16 v[188:191], v[156:159], v[188:191], v[80:83]
	v_mfma_f32_16x16x32_bf16 v[192:195], v[208:211], v[196:199], v[76:79]
	v_mfma_f32_16x16x32_bf16 v[196:199], v[156:159], v[196:199], v[72:75]
	v_mfma_f32_16x16x32_bf16 v[200:203], v[208:211], v[204:207], v[68:71]
	v_mfma_f32_16x16x32_bf16 v[204:207], v[156:159], v[204:207], v[64:67]
	s_setprio 0
	s_barrier
	s_nop 0
	ds_read_b128 v[64:67], v153 offset:16384
	ds_read_b128 v[68:71], v153 offset:17408
	ds_read_b128 v[72:75], v152 offset:16384
	ds_read_b128 v[76:79], v152 offset:17408
	ds_read_b128 v[80:83], v151 offset:16384
	ds_read_b128 v[84:87], v151 offset:17408
	ds_read_b128 v[88:91], v150 offset:16384
	ds_read_b128 v[92:95], v150 offset:17408
	s_waitcnt vmcnt(4)
	s_barrier
	s_waitcnt lgkmcnt(0)
	s_setprio 1
	s_waitcnt lgkmcnt(0)
	v_mfma_f32_16x16x32_bf16 v[60:63], v[130:133], v[64:67], v[60:63]
	v_mfma_f32_16x16x32_bf16 v[56:59], v[168:171], v[64:67], v[56:59]
	v_mfma_f32_16x16x32_bf16 v[52:55], v[130:133], v[72:75], v[52:55]
	v_mfma_f32_16x16x32_bf16 v[48:51], v[168:171], v[72:75], v[48:51]
	v_mfma_f32_16x16x32_bf16 v[216:219], v[130:133], v[80:83], v[44:47]
	v_mfma_f32_16x16x32_bf16 v[220:223], v[168:171], v[80:83], v[40:43]
	v_mfma_f32_16x16x32_bf16 v[130:133], v[130:133], v[88:91], v[36:39]
	v_mfma_f32_16x16x32_bf16 v[168:171], v[168:171], v[88:91], v[32:35]
	v_mfma_f32_16x16x32_bf16 v[32:35], v[164:167], v[68:71], v[60:63]
	v_mfma_f32_16x16x32_bf16 v[36:39], v[172:175], v[68:71], v[56:59]
	v_mfma_f32_16x16x32_bf16 v[40:43], v[164:167], v[76:79], v[52:55]
	v_mfma_f32_16x16x32_bf16 v[44:47], v[172:175], v[76:79], v[48:51]
	v_mfma_f32_16x16x32_bf16 v[48:51], v[164:167], v[84:87], v[216:219]
	v_mfma_f32_16x16x32_bf16 v[52:55], v[172:175], v[84:87], v[220:223]
	v_mfma_f32_16x16x32_bf16 v[56:59], v[164:167], v[92:95], v[130:133]
	v_mfma_f32_16x16x32_bf16 v[60:63], v[172:175], v[92:95], v[168:171]
	s_setprio 0
	s_setprio 1
	v_mfma_f32_16x16x32_bf16 v[28:31], v[160:163], v[64:67], v[28:31]
	v_mfma_f32_16x16x32_bf16 v[24:27], v[212:215], v[64:67], v[24:27]
	v_mfma_f32_16x16x32_bf16 v[20:23], v[160:163], v[72:75], v[20:23]
	v_mfma_f32_16x16x32_bf16 v[64:67], v[212:215], v[72:75], v[16:19]
	v_mfma_f32_16x16x32_bf16 v[72:75], v[160:163], v[80:83], v[12:15]
	v_mfma_f32_16x16x32_bf16 v[8:11], v[212:215], v[80:83], v[8:11]
	v_mfma_f32_16x16x32_bf16 v[80:83], v[160:163], v[88:91], v[4:7]
	v_mfma_f32_16x16x32_bf16 v[0:3], v[212:215], v[88:91], v[0:3]
	v_mfma_f32_16x16x32_bf16 v[4:7], v[208:211], v[68:71], v[28:31]
	v_mfma_f32_16x16x32_bf16 v[12:15], v[156:159], v[68:71], v[24:27]
	v_mfma_f32_16x16x32_bf16 v[16:19], v[208:211], v[76:79], v[20:23]
	v_mfma_f32_16x16x32_bf16 v[20:23], v[156:159], v[76:79], v[64:67]
	v_mfma_f32_16x16x32_bf16 v[24:27], v[208:211], v[84:87], v[72:75]
	v_mfma_f32_16x16x32_bf16 v[28:31], v[156:159], v[84:87], v[8:11]
	v_mfma_f32_16x16x32_bf16 v[64:67], v[208:211], v[92:95], v[80:83]
	v_mfma_f32_16x16x32_bf16 v[68:71], v[156:159], v[92:95], v[0:3]
	s_setprio 0
	s_barrier
	ds_read_b128 v[8:11], v155
	ds_read_b128 v[0:3], v155 offset:1024
	ds_read_b128 v[76:79], v155 offset:2048
	ds_read_b128 v[72:75], v155 offset:3072
	ds_read_b128 v[130:133], v153 offset:32768
	ds_read_b128 v[156:159], v153 offset:33792
	ds_read_b128 v[160:163], v152 offset:32768
	ds_read_b128 v[164:167], v152 offset:33792
	ds_read_b128 v[168:171], v151 offset:32768
	ds_read_b128 v[172:175], v151 offset:33792
	ds_read_b128 v[208:211], v150 offset:32768
	ds_read_b128 v[212:215], v150 offset:33792
	s_waitcnt vmcnt(2)
	s_barrier
	s_waitcnt lgkmcnt(0)
	s_setprio 1
	s_waitcnt lgkmcnt(0)
	v_mfma_f32_16x16x32_bf16 v[80:83], v[8:11], v[130:133], v[124:127]
	v_mfma_f32_16x16x32_bf16 v[84:87], v[76:79], v[130:133], v[120:123]
	v_mfma_f32_16x16x32_bf16 v[88:91], v[8:11], v[160:163], v[116:119]
	v_mfma_f32_16x16x32_bf16 v[92:95], v[76:79], v[160:163], v[112:115]
	v_mfma_f32_16x16x32_bf16 v[108:111], v[8:11], v[168:171], v[108:111]
	v_mfma_f32_16x16x32_bf16 v[104:107], v[76:79], v[168:171], v[104:107]
	v_mfma_f32_16x16x32_bf16 v[100:103], v[8:11], v[208:211], v[100:103]
	v_mfma_f32_16x16x32_bf16 v[96:99], v[76:79], v[208:211], v[96:99]
	v_mfma_f32_16x16x32_bf16 v[112:115], v[0:3], v[156:159], v[80:83]
	v_mfma_f32_16x16x32_bf16 v[116:119], v[72:75], v[156:159], v[84:87]
	v_mfma_f32_16x16x32_bf16 v[120:123], v[0:3], v[164:167], v[88:91]
	v_mfma_f32_16x16x32_bf16 v[124:127], v[72:75], v[164:167], v[92:95]
	v_mfma_f32_16x16x32_bf16 v[108:111], v[0:3], v[172:175], v[108:111]
	v_mfma_f32_16x16x32_bf16 v[104:107], v[72:75], v[172:175], v[104:107]
	v_mfma_f32_16x16x32_bf16 v[100:103], v[0:3], v[212:215], v[100:103]
	v_mfma_f32_16x16x32_bf16 v[96:99], v[72:75], v[212:215], v[96:99]
	s_setprio 0
	s_barrier
	ds_read_b128 v[88:91], v154
	ds_read_b128 v[80:83], v154 offset:1024
	ds_read_b128 v[92:95], v154 offset:2048
	ds_read_b128 v[84:87], v154 offset:3072
	s_waitcnt vmcnt(0)
	s_barrier
	s_waitcnt lgkmcnt(0)
	s_setprio 1
	s_waitcnt lgkmcnt(0)
	v_mfma_f32_16x16x32_bf16 v[176:179], v[88:91], v[130:133], v[176:179]
	v_mfma_f32_16x16x32_bf16 v[130:133], v[92:95], v[130:133], v[180:183]
	v_mfma_f32_16x16x32_bf16 v[180:183], v[88:91], v[160:163], v[184:187]
	v_mfma_f32_16x16x32_bf16 v[160:163], v[92:95], v[160:163], v[188:191]
	v_mfma_f32_16x16x32_bf16 v[184:187], v[88:91], v[168:171], v[192:195]
	v_mfma_f32_16x16x32_bf16 v[168:171], v[92:95], v[168:171], v[196:199]
	v_mfma_f32_16x16x32_bf16 v[188:191], v[88:91], v[208:211], v[200:203]
	v_mfma_f32_16x16x32_bf16 v[192:195], v[92:95], v[208:211], v[204:207]
	v_mfma_f32_16x16x32_bf16 v[176:179], v[80:83], v[156:159], v[176:179]
	v_mfma_f32_16x16x32_bf16 v[130:133], v[84:87], v[156:159], v[130:133]
	v_mfma_f32_16x16x32_bf16 v[154:157], v[80:83], v[164:167], v[180:183]
	v_mfma_f32_16x16x32_bf16 v[158:161], v[84:87], v[164:167], v[160:163]
	v_mfma_f32_16x16x32_bf16 v[162:165], v[80:83], v[172:175], v[184:187]
	v_mfma_f32_16x16x32_bf16 v[166:169], v[84:87], v[172:175], v[168:171]
	v_mfma_f32_16x16x32_bf16 v[170:173], v[80:83], v[212:215], v[188:191]
	v_mfma_f32_16x16x32_bf16 v[180:183], v[84:87], v[212:215], v[192:195]
	s_setprio 0
	s_barrier
	v_mbcnt_lo_u32_b32 v128, -1, 0
	v_mbcnt_hi_u32_b32 v128, -1, v128
	v_cvt_pk_bf16_f32 v112, v112, v113
	v_cvt_pk_bf16_f32 v113, v114, v115
	v_cvt_pk_bf16_f32 v114, v116, v117
	v_cvt_pk_bf16_f32 v115, v118, v119
	s_lshl_b32 s68, s66, 9
	v_add_u32_e32 v174, s74, v128
	v_ashrrev_i32_e32 v175, 6, v174
	v_and_b32_e32 v184, 15, v128
	v_and_b32_e32 v185, 48, v128
	v_mul_lo_u32 v186, v175, s79
	v_bfe_u32 v187, v128, 3, 3
	v_lshlrev_b32_e32 v128, 4, v128
	v_add_u32_e32 v186, 0x20000, v186
	v_lshrrev_b32_e32 v174, 2, v174
	v_and_b32_e32 v128, 0x70, v128
	v_mul_u32_u24_e32 v184, 0x90, v184
	v_and_b32_e32 v174, 64, v174
	v_add3_u32 v184, v186, v184, v185
	v_or_b32_e32 v185, v186, v128
	v_or3_b32 v174, s24, v174, v187
	v_mad_u32_u24 v185, v187, s80, v185
	ds_write_b128 v184, v[112:115]
	v_cvt_pk_bf16_f32 v112, v176, v177
	v_cvt_pk_bf16_f32 v113, v178, v179
	v_cvt_pk_bf16_f32 v114, v130, v131
	v_cvt_pk_bf16_f32 v115, v132, v133
	ds_write_b128 v184, v[112:115] offset:64
	v_lshlrev_b32_e32 v175, 7, v175
	ds_read_b128 v[112:115], v185
	v_lshlrev_b32_e32 v116, 12, v174
	v_and_or_b32 v116, v175, s81, v116
	v_or3_b32 v128, v116, s68, v128
	ds_read_b128 v[116:119], v185 offset:1152
	v_lshl_add_u64 v[130:131], s[0:1], 0, v[128:129]
	s_mov_b32 s36, 0x8000
	s_waitcnt lgkmcnt(0)
	global_store_dwordx4 v128, v[112:115], s[0:1]
	v_cvt_pk_bf16_f32 v108, v108, v109
	v_cvt_pk_bf16_f32 v109, v110, v111
	v_cvt_pk_bf16_f32 v110, v104, v105
	v_cvt_pk_bf16_f32 v111, v106, v107
	v_cvt_pk_bf16_f32 v104, v162, v163
	s_nop 1
	v_add_co_u32_e32 v112, vcc, s36, v130
	v_cvt_pk_bf16_f32 v114, v124, v125
	v_cvt_pk_bf16_f32 v115, v126, v127
	v_cvt_pk_bf16_f32 v105, v164, v165
	v_cvt_pk_bf16_f32 v106, v166, v167
	s_nop 1
	v_addc_co_u32_e32 v113, vcc, 0, v131, vcc
	global_store_dwordx4 v[112:113], v[116:119], off
	v_cvt_pk_bf16_f32 v112, v120, v121
	v_cvt_pk_bf16_f32 v113, v122, v123
	ds_write_b128 v184, v[112:115]
	v_cvt_pk_bf16_f32 v112, v154, v155
	v_cvt_pk_bf16_f32 v113, v156, v157
	v_cvt_pk_bf16_f32 v114, v158, v159
	v_cvt_pk_bf16_f32 v115, v160, v161
	ds_write_b128 v184, v[112:115] offset:64
	ds_read_b128 v[112:115], v185
	ds_read_b128 v[116:119], v185 offset:1152
	v_add_co_u32_e32 v120, vcc, s76, v130
	ds_write_b128 v184, v[108:111]
	v_cvt_pk_bf16_f32 v107, v168, v169
	ds_write_b128 v184, v[104:107] offset:64
	v_addc_co_u32_e32 v121, vcc, 0, v131, vcc
	ds_read_b128 v[104:107], v185
	ds_read_b128 v[108:111], v185 offset:1152
	s_waitcnt lgkmcnt(0)
	global_store_dwordx4 v[120:121], v[112:115], off
	v_cvt_pk_bf16_f32 v100, v100, v101
	v_cvt_pk_bf16_f32 v101, v102, v103
	v_cvt_pk_bf16_f32 v102, v96, v97
	v_cvt_pk_bf16_f32 v103, v98, v99
	ds_write_b128 v184, v[100:103]
	s_nop 0
	v_add_co_u32_e32 v112, vcc, s77, v130
	v_cvt_pk_bf16_f32 v96, v170, v171
	v_cvt_pk_bf16_f32 v97, v172, v173
	v_cvt_pk_bf16_f32 v98, v180, v181
	v_cvt_pk_bf16_f32 v99, v182, v183
	s_nop 1
	v_addc_co_u32_e32 v113, vcc, 0, v131, vcc
	global_store_dwordx4 v[112:113], v[116:119], off
	v_add_co_u32_e32 v112, vcc, s78, v130
	ds_write_b128 v184, v[96:99] offset:64
	s_nop 0
	v_addc_co_u32_e32 v113, vcc, 0, v131, vcc
	ds_read_b128 v[96:99], v185
	ds_read_b128 v[100:103], v185 offset:1152
	global_store_dwordx4 v[112:113], v[104:107], off
	s_nop 1
	v_add_co_u32_e32 v104, vcc, s82, v130
	s_nop 1
	v_addc_co_u32_e32 v105, vcc, 0, v131, vcc
	global_store_dwordx4 v[104:105], v[108:111], off
	v_add_co_u32_e32 v104, vcc, s83, v130
	s_nop 1
	v_addc_co_u32_e32 v105, vcc, 0, v131, vcc
	s_waitcnt lgkmcnt(0)
	global_store_dwordx4 v[104:105], v[96:99], off
	s_nop 1
	v_add_co_u32_e32 v96, vcc, s91, v130
	s_nop 1
	v_addc_co_u32_e32 v97, vcc, 0, v131, vcc
	global_store_dwordx4 v[96:97], v[100:103], off
	ds_read_b128 v[96:99], v153 offset:49152
	ds_read_b128 v[100:103], v153 offset:50176
	ds_read_b128 v[104:107], v152 offset:49152
	ds_read_b128 v[108:111], v152 offset:50176
	ds_read_b128 v[112:115], v151 offset:49152
	ds_read_b128 v[116:119], v151 offset:50176
	ds_read_b128 v[120:123], v150 offset:49152
	ds_read_b128 v[124:127], v150 offset:50176
	s_barrier
	s_waitcnt lgkmcnt(0)
	s_setprio 1
	s_waitcnt lgkmcnt(0)
	v_mfma_f32_16x16x32_bf16 v[32:35], v[8:11], v[96:99], v[32:35]
	v_mfma_f32_16x16x32_bf16 v[36:39], v[76:79], v[96:99], v[36:39]
	v_mfma_f32_16x16x32_bf16 v[40:43], v[8:11], v[104:107], v[40:43]
	v_mfma_f32_16x16x32_bf16 v[130:133], v[76:79], v[104:107], v[44:47]
	v_mfma_f32_16x16x32_bf16 v[150:153], v[8:11], v[112:115], v[48:51]
	v_mfma_f32_16x16x32_bf16 v[52:55], v[76:79], v[112:115], v[52:55]
	v_mfma_f32_16x16x32_bf16 v[8:11], v[8:11], v[120:123], v[56:59]
	v_mfma_f32_16x16x32_bf16 v[60:63], v[76:79], v[120:123], v[60:63]
	v_mfma_f32_16x16x32_bf16 v[56:59], v[0:3], v[100:103], v[32:35]
	v_mfma_f32_16x16x32_bf16 v[48:51], v[72:75], v[100:103], v[36:39]
	v_mfma_f32_16x16x32_bf16 v[44:47], v[0:3], v[108:111], v[40:43]
	v_mfma_f32_16x16x32_bf16 v[40:43], v[72:75], v[108:111], v[130:133]
	v_mfma_f32_16x16x32_bf16 v[36:39], v[0:3], v[116:119], v[150:153]
	v_mfma_f32_16x16x32_bf16 v[32:35], v[72:75], v[116:119], v[52:55]
	v_mfma_f32_16x16x32_bf16 v[8:11], v[0:3], v[124:127], v[8:11]
	v_mfma_f32_16x16x32_bf16 v[0:3], v[72:75], v[124:127], v[60:63]
	s_setprio 0
	s_setprio 1
	v_mfma_f32_16x16x32_bf16 v[4:7], v[88:91], v[96:99], v[4:7]
	v_mfma_f32_16x16x32_bf16 v[12:15], v[92:95], v[96:99], v[12:15]
	v_mfma_f32_16x16x32_bf16 v[16:19], v[88:91], v[104:107], v[16:19]
	v_mfma_f32_16x16x32_bf16 v[20:23], v[92:95], v[104:107], v[20:23]
	v_mfma_f32_16x16x32_bf16 v[72:75], v[88:91], v[112:115], v[24:27]
	v_mfma_f32_16x16x32_bf16 v[76:79], v[92:95], v[112:115], v[28:31]
	v_mfma_f32_16x16x32_bf16 v[64:67], v[88:91], v[120:123], v[64:67]
	v_mfma_f32_16x16x32_bf16 v[68:71], v[92:95], v[120:123], v[68:71]
	v_mfma_f32_16x16x32_bf16 v[60:63], v[80:83], v[100:103], v[4:7]
	v_mfma_f32_16x16x32_bf16 v[52:55], v[84:87], v[100:103], v[12:15]
	v_mfma_f32_16x16x32_bf16 v[28:31], v[80:83], v[108:111], v[16:19]
	v_mfma_f32_16x16x32_bf16 v[24:27], v[84:87], v[108:111], v[20:23]
	v_mfma_f32_16x16x32_bf16 v[20:23], v[80:83], v[116:119], v[72:75]
	v_mfma_f32_16x16x32_bf16 v[16:19], v[84:87], v[116:119], v[76:79]
	v_mfma_f32_16x16x32_bf16 v[12:15], v[80:83], v[124:127], v[64:67]
	v_mfma_f32_16x16x32_bf16 v[4:7], v[84:87], v[124:127], v[68:71]
	s_setprio 0
	v_cmp_gt_u32_e32 vcc, s92, v136
	s_barrier
	s_and_saveexec_b64 s[66:67], vcc
	s_cbranch_execz .LBB0_468
	s_barrier

.LBB0_520:
	v_bfe_i32 v5, v179, 27, 1
	v_lshlrev_b32_e32 v169, 4, v179
	v_lshrrev_b32_e32 v5, 22, v5
	v_add_u32_e32 v5, v169, v5
	v_and_b32_e32 v5, 0xfffffc00, v5
	v_sub_u32_e32 v5, v169, v5
	v_lshrrev_b32_e32 v6, 4, v5
	v_bitop3_b32 v5, v6, v5, 32 bitop3:0x6c
	v_ashrrev_i32_e32 v6, 31, v5
	v_lshrrev_b32_e32 v6, 26, v6
	v_ashrrev_i32_e32 v4, 31, v179
	v_add_u32_e32 v6, v5, v6
	s_lshl_b32 s36, s81, 3
	v_lshrrev_b32_e32 v4, 26, v4
	v_ashrrev_i32_e32 v133, 6, v6
	v_and_b32_e32 v6, 0xc0, v6
	s_ff1_i32_b32 s37, s36
	v_and_b32_e32 v2, 15, v0
	v_and_b32_e32 v3, 48, v0
	v_add_u32_e32 v4, v179, v4
	v_sub_u32_e32 v5, v5, v6
	v_and_b32_e32 v6, 32, v0
	v_lshlrev_b32_e32 v10, 2, v0
	v_lshlrev_b32_e32 v0, 6, v0
	s_lshr_b32 s60, s82, s37
	s_add_i32 s36, s36, -1
	s_and_b32 s61, s82, 7
	v_ashrrev_i32_e32 v131, 6, v4
	v_lshlrev_b32_e32 v2, 6, v2
	v_and_b32_e32 v10, 32, v10
	v_and_b32_e32 v0, 0x3c0, v0
	s_and_b32 s36, s82, s36
	v_or_b32_e32 v9, v2, v3
	v_bitop3_b32 v2, v2, v10, v3 bitop3:0x36
	v_bitop3_b32 v3, v0, v10, v3 bitop3:0x36
	s_lshl_b32 s37, s60, 11
	s_lshl_b32 s46, s61, 8
	v_lshlrev_b32_e32 v0, 16, v131
	s_lshr_b32 s78, s36, 3
	s_or_b32 s46, s37, s46
	s_mov_b32 s47, s15
	v_and_b32_e32 v0, 0xfffe0000, v0
	s_lshl_b32 s36, s78, 14
	v_ashrrev_i16_sdwa v5, v167, sext(v5) dst_sel:DWORD dst_unused:UNUSED_PAD src0_sel:DWORD src1_sel:BYTE_0
	s_lshl_b64 s[46:47], s[46:47], 13
	v_lshl_add_u32 v0, v133, 13, v0
	v_bfe_i32 v134, v5, 0, 16
	v_and_or_b32 v0, v4, 64, v0
	s_add_u32 s46, s40, s46
	v_lshl_add_u32 v164, v134, 1, v0
	s_addc_u32 s47, s41, s47
	v_lshlrev_b32_e32 v14, 13, v1
	v_lshl_add_u64 v[0:1], s[46:47], 0, v[164:165]
	s_mul_i32 s46, s14, 0x1800
	s_mul_hi_u32 s37, s14, 0x1800
	s_add_u32 s46, s46, s36
	s_addc_u32 s37, s37, 0
	s_add_u32 s46, s62, s46
	v_bfe_i32 v7, v179, 6, 1
	s_addc_u32 s47, s63, s37
	s_lshl_b64 s[56:57], s[14:15], 12
	v_and_b32_e32 v7, s14, v7
	v_lshrrev_b32_e32 v8, 7, v179
	s_add_u32 s14, s56, s36
	v_add_lshl_u32 v7, v7, v8, 10
	v_lshlrev_b32_e32 v8, 6, v179
	s_addc_u32 s36, s57, 0
	v_and_b32_e32 v5, 0x3f0, v169
	v_and_b32_e32 v8, 0x3000, v8
	v_bitop3_b32 v11, v9, s65, v10 bitop3:0xde
	v_bitop3_b32 v12, v9, s67, v10 bitop3:0xde
	v_bitop3_b32 v13, v9, s68, v10 bitop3:0xde
	v_bitop3_b32 v9, v9, s69, v10 bitop3:0xde
	v_or_b32_e32 v10, 0x800, v14
	v_or_b32_e32 v15, 0x1000, v14
	v_or_b32_e32 v16, 0x1800, v14
	v_lshl_add_u64 v[128:129], v[0:1], 0, s[16:17]
	s_add_u32 s58, s62, s14
	v_mov_b32_e32 v0, 0
	v_bitop3_b32 v164, v5, v7, v6 bitop3:0xde
	s_addc_u32 s59, s63, s36
	s_mov_b32 s14, -2
	v_add_u32_e32 v138, v11, v8
	v_add_u32_e32 v193, v2, v14
	v_add_u32_e32 v192, v3, v10
	v_add_u32_e32 v191, v3, v15
	v_add_u32_e32 v190, v3, v16
	v_add_u32_e32 v137, 0xc000, v169
	v_add_u32_e32 v136, 0xe000, v169
	v_add_u32_e32 v135, v12, v8
	v_add_u32_e32 v189, 0x10000, v169
	v_add_u32_e32 v188, 0x12000, v169
	v_add_u32_e32 v187, 0x2000, v169
	v_add_u32_e32 v186, 0x14000, v169
	v_add_u32_e32 v185, 0x16000, v169
	v_add_u32_e32 v130, v13, v8
	v_add_u32_e32 v184, 0x4000, v169
	v_add_u32_e32 v183, 0x6000, v169
	v_add_u32_e32 v132, v9, v8
	v_add_u32_e32 v182, 0x18000, v169
	v_add_u32_e32 v181, 0x1a000, v169
	v_add_u32_e32 v177, 0x8000, v169
	v_add_u32_e32 v175, 0xa000, v169
	v_add_u32_e32 v173, 0x1c000, v169
	v_add_u32_e32 v171, 0x1e000, v169
	v_mov_b32_e32 v1, v0
	v_mov_b32_e32 v2, v0
	v_mov_b32_e32 v3, v0
	v_mov_b32_e32 v4, v0
	v_mov_b32_e32 v5, v0
	v_mov_b32_e32 v6, v0
	v_mov_b32_e32 v7, v0
	v_mov_b32_e32 v8, v0
	v_mov_b32_e32 v9, v0
	v_mov_b32_e32 v10, v0
	v_mov_b32_e32 v11, v0
	v_mov_b32_e32 v12, v0
	v_mov_b32_e32 v13, v0
	v_mov_b32_e32 v14, v0
	v_mov_b32_e32 v15, v0
	v_mov_b32_e32 v16, v0
	v_mov_b32_e32 v17, v0
	v_mov_b32_e32 v18, v0
	v_mov_b32_e32 v19, v0
	v_mov_b32_e32 v20, v0
	v_mov_b32_e32 v21, v0
	v_mov_b32_e32 v22, v0
	v_mov_b32_e32 v23, v0
	v_mov_b32_e32 v24, v0
	v_mov_b32_e32 v25, v0
	v_mov_b32_e32 v26, v0
	v_mov_b32_e32 v27, v0
	v_mov_b32_e32 v28, v0
	v_mov_b32_e32 v29, v0
	v_mov_b32_e32 v30, v0
	v_mov_b32_e32 v31, v0
	v_mov_b32_e32 v32, v0
	v_mov_b32_e32 v33, v0
	v_mov_b32_e32 v34, v0
	v_mov_b32_e32 v35, v0
	v_mov_b32_e32 v36, v0
	v_mov_b32_e32 v37, v0
	v_mov_b32_e32 v38, v0
	v_mov_b32_e32 v39, v0
	v_mov_b32_e32 v40, v0
	v_mov_b32_e32 v41, v0
	v_mov_b32_e32 v42, v0
	v_mov_b32_e32 v43, v0
	v_mov_b32_e32 v44, v0
	v_mov_b32_e32 v45, v0
	v_mov_b32_e32 v46, v0
	v_mov_b32_e32 v47, v0
	v_mov_b32_e32 v48, v0
	v_mov_b32_e32 v49, v0
	v_mov_b32_e32 v50, v0
	v_mov_b32_e32 v51, v0
	v_mov_b32_e32 v52, v0
	v_mov_b32_e32 v53, v0
	v_mov_b32_e32 v54, v0
	v_mov_b32_e32 v55, v0
	v_mov_b32_e32 v56, v0
	v_mov_b32_e32 v57, v0
	v_mov_b32_e32 v58, v0
	v_mov_b32_e32 v59, v0
	v_mov_b32_e32 v60, v0
	v_mov_b32_e32 v61, v0
	v_mov_b32_e32 v62, v0
	v_mov_b32_e32 v63, v0
	v_mov_b32_e32 v64, v0
	v_mov_b32_e32 v65, v0
	v_mov_b32_e32 v66, v0
	v_mov_b32_e32 v67, v0
	v_mov_b32_e32 v68, v0
	v_mov_b32_e32 v69, v0
	v_mov_b32_e32 v70, v0
	v_mov_b32_e32 v71, v0
	v_mov_b32_e32 v72, v0
	v_mov_b32_e32 v73, v0
	v_mov_b32_e32 v74, v0
	v_mov_b32_e32 v75, v0
	v_mov_b32_e32 v76, v0
	v_mov_b32_e32 v77, v0
	v_mov_b32_e32 v78, v0
	v_mov_b32_e32 v79, v0
	v_mov_b32_e32 v80, v0
	v_mov_b32_e32 v81, v0
	v_mov_b32_e32 v82, v0
	v_mov_b32_e32 v83, v0
	v_mov_b32_e32 v84, v0
	v_mov_b32_e32 v85, v0
	v_mov_b32_e32 v86, v0
	v_mov_b32_e32 v87, v0
	v_mov_b32_e32 v88, v0
	v_mov_b32_e32 v89, v0
	v_mov_b32_e32 v90, v0
	v_mov_b32_e32 v91, v0
	v_mov_b32_e32 v92, v0
	v_mov_b32_e32 v93, v0
	v_mov_b32_e32 v94, v0
	v_mov_b32_e32 v95, v0
	v_mov_b32_e32 v96, v0
	v_mov_b32_e32 v97, v0
	v_mov_b32_e32 v98, v0
	v_mov_b32_e32 v99, v0
	v_mov_b32_e32 v100, v0
	v_mov_b32_e32 v101, v0
	v_mov_b32_e32 v102, v0
	v_mov_b32_e32 v103, v0
	v_mov_b32_e32 v104, v0
	v_mov_b32_e32 v105, v0
	v_mov_b32_e32 v106, v0
	v_mov_b32_e32 v107, v0
	v_mov_b32_e32 v108, v0
	v_mov_b32_e32 v109, v0
	v_mov_b32_e32 v110, v0
	v_mov_b32_e32 v111, v0
	v_mov_b32_e32 v112, v0
	v_mov_b32_e32 v113, v0
	v_mov_b32_e32 v114, v0
	v_mov_b32_e32 v115, v0
	v_mov_b32_e32 v116, v0
	v_mov_b32_e32 v117, v0
	v_mov_b32_e32 v118, v0
	v_mov_b32_e32 v119, v0
	v_mov_b32_e32 v120, v0
	v_mov_b32_e32 v121, v0
	v_mov_b32_e32 v122, v0
	v_mov_b32_e32 v123, v0
	v_mov_b32_e32 v124, v0
	v_mov_b32_e32 v125, v0
	v_mov_b32_e32 v126, v0
	v_mov_b32_e32 v127, v0
	s_barrier
	v_readfirstlane_b32 s36, v137
	v_lshl_add_u64 v[142:143], v[128:129], 0, s[18:19]
	s_mov_b32 m0, s36
	v_readfirstlane_b32 s36, v136
	global_load_lds_dwordx4 v[142:143], off
	v_lshl_add_u64 v[142:143], v[128:129], 0, s[20:21]
	s_mov_b32 m0, s36
	s_nop 0
	global_load_lds_dwordx4 v[142:143], off
.LBB0_521:
	ds_read_b128 v[140:143], v138
	ds_read_b128 v[144:147], v138 offset:1024
	ds_read_b128 v[148:151], v138 offset:2048
	ds_read_b128 v[152:155], v138 offset:3072
	ds_read_b128 v[156:159], v193
	ds_read_b128 v[160:163], v193 offset:1024
	ds_read_b128 v[194:197], v192
	ds_read_b128 v[198:201], v192 offset:1024
	ds_read_b128 v[202:205], v191
	ds_read_b128 v[206:209], v191 offset:1024
	ds_read_b128 v[210:213], v190
	ds_read_b128 v[214:217], v190 offset:1024
	s_waitcnt lgkmcnt(8)
	s_barrier
	s_waitcnt lgkmcnt(0)
	s_setprio 1
	s_waitcnt lgkmcnt(0)
	v_mfma_f32_16x16x32_bf16 v[124:127], v[140:143], v[156:159], v[124:127]
	v_mfma_f32_16x16x32_bf16 v[120:123], v[148:151], v[156:159], v[120:123]
	v_mfma_f32_16x16x32_bf16 v[116:119], v[140:143], v[194:197], v[116:119]
	v_mfma_f32_16x16x32_bf16 v[112:115], v[148:151], v[194:197], v[112:115]
	v_mfma_f32_16x16x32_bf16 v[108:111], v[140:143], v[202:205], v[108:111]
	v_mfma_f32_16x16x32_bf16 v[104:107], v[148:151], v[202:205], v[104:107]
	v_mfma_f32_16x16x32_bf16 v[100:103], v[140:143], v[210:213], v[100:103]
	v_mfma_f32_16x16x32_bf16 v[96:99], v[148:151], v[210:213], v[96:99]
	v_mfma_f32_16x16x32_bf16 v[124:127], v[144:147], v[160:163], v[124:127]
	v_mfma_f32_16x16x32_bf16 v[120:123], v[152:155], v[160:163], v[120:123]
	v_mfma_f32_16x16x32_bf16 v[116:119], v[144:147], v[198:201], v[116:119]
	v_mfma_f32_16x16x32_bf16 v[112:115], v[152:155], v[198:201], v[112:115]
	v_mfma_f32_16x16x32_bf16 v[108:111], v[144:147], v[206:209], v[108:111]
	v_mfma_f32_16x16x32_bf16 v[104:107], v[152:155], v[206:209], v[104:107]
	v_mfma_f32_16x16x32_bf16 v[100:103], v[144:147], v[214:217], v[100:103]
	v_mfma_f32_16x16x32_bf16 v[96:99], v[152:155], v[214:217], v[96:99]
	s_setprio 0
	s_barrier
	v_readfirstlane_b32 s36, v189
	v_lshl_add_u64 v[234:235], s[58:59], 0, v[164:165]
	s_mov_b32 m0, s36
	v_readfirstlane_b32 s36, v188
	ds_read_b128 v[218:221], v135
	ds_read_b128 v[222:225], v135 offset:1024
	ds_read_b128 v[226:229], v135 offset:2048
	ds_read_b128 v[230:233], v135 offset:3072
	global_load_lds_dwordx4 v[234:235], off
	v_lshl_add_u64 v[236:237], v[234:235], 0, s[2:3]
	s_mov_b32 m0, s36
	s_nop 0
	global_load_lds_dwordx4 v[236:237], off
	s_barrier
	s_waitcnt lgkmcnt(0)
	s_setprio 1
	s_waitcnt lgkmcnt(0)
	v_mfma_f32_16x16x32_bf16 v[92:95], v[218:221], v[156:159], v[92:95]
	v_mfma_f32_16x16x32_bf16 v[88:91], v[226:229], v[156:159], v[88:91]
	v_mfma_f32_16x16x32_bf16 v[84:87], v[218:221], v[194:197], v[84:87]
	v_mfma_f32_16x16x32_bf16 v[80:83], v[226:229], v[194:197], v[80:83]
	v_mfma_f32_16x16x32_bf16 v[76:79], v[218:221], v[202:205], v[76:79]
	v_mfma_f32_16x16x32_bf16 v[72:75], v[226:229], v[202:205], v[72:75]
	v_mfma_f32_16x16x32_bf16 v[68:71], v[218:221], v[210:213], v[68:71]
	v_mfma_f32_16x16x32_bf16 v[64:67], v[226:229], v[210:213], v[64:67]
	v_mfma_f32_16x16x32_bf16 v[92:95], v[222:225], v[160:163], v[92:95]
	v_mfma_f32_16x16x32_bf16 v[88:91], v[230:233], v[160:163], v[88:91]
	v_mfma_f32_16x16x32_bf16 v[84:87], v[222:225], v[198:201], v[84:87]
	v_mfma_f32_16x16x32_bf16 v[80:83], v[230:233], v[198:201], v[80:83]
	v_mfma_f32_16x16x32_bf16 v[76:79], v[222:225], v[206:209], v[76:79]
	v_mfma_f32_16x16x32_bf16 v[72:75], v[230:233], v[206:209], v[72:75]
	v_mfma_f32_16x16x32_bf16 v[68:71], v[222:225], v[214:217], v[68:71]
	v_mfma_f32_16x16x32_bf16 v[64:67], v[230:233], v[214:217], v[64:67]
	s_setprio 0
	v_readfirstlane_b32 s36, v169
	v_lshl_add_u64 v[236:237], v[128:129], 0, s[22:23]
	s_mov_b32 m0, s36
	v_readfirstlane_b32 s36, v187
	s_barrier
	ds_read_b128 v[156:159], v193 offset:16384
	ds_read_b128 v[160:163], v193 offset:17408
	ds_read_b128 v[194:197], v192 offset:16384
	ds_read_b128 v[198:201], v192 offset:17408
	ds_read_b128 v[202:205], v191 offset:16384
	ds_read_b128 v[206:209], v191 offset:17408
	ds_read_b128 v[210:213], v190 offset:16384
	ds_read_b128 v[214:217], v190 offset:17408
	global_load_lds_dwordx4 v[236:237], off
	v_lshl_add_u64 v[236:237], v[128:129], 0, s[24:25]
	s_mov_b32 m0, s36
	s_nop 0
	global_load_lds_dwordx4 v[236:237], off
	s_barrier
	s_waitcnt lgkmcnt(0)
	s_setprio 1
	s_waitcnt lgkmcnt(0)
	v_mfma_f32_16x16x32_bf16 v[60:63], v[140:143], v[156:159], v[60:63]
	v_mfma_f32_16x16x32_bf16 v[56:59], v[148:151], v[156:159], v[56:59]
	v_mfma_f32_16x16x32_bf16 v[52:55], v[140:143], v[194:197], v[52:55]
	v_mfma_f32_16x16x32_bf16 v[48:51], v[148:151], v[194:197], v[48:51]
	v_mfma_f32_16x16x32_bf16 v[44:47], v[140:143], v[202:205], v[44:47]
	v_mfma_f32_16x16x32_bf16 v[40:43], v[148:151], v[202:205], v[40:43]
	v_mfma_f32_16x16x32_bf16 v[36:39], v[140:143], v[210:213], v[36:39]
	v_mfma_f32_16x16x32_bf16 v[32:35], v[148:151], v[210:213], v[32:35]
	v_mfma_f32_16x16x32_bf16 v[60:63], v[144:147], v[160:163], v[60:63]
	v_mfma_f32_16x16x32_bf16 v[56:59], v[152:155], v[160:163], v[56:59]
	v_mfma_f32_16x16x32_bf16 v[52:55], v[144:147], v[198:201], v[52:55]
	v_mfma_f32_16x16x32_bf16 v[48:51], v[152:155], v[198:201], v[48:51]
	v_mfma_f32_16x16x32_bf16 v[44:47], v[144:147], v[206:209], v[44:47]
	v_mfma_f32_16x16x32_bf16 v[40:43], v[152:155], v[206:209], v[40:43]
	v_mfma_f32_16x16x32_bf16 v[36:39], v[144:147], v[214:217], v[36:39]
	v_mfma_f32_16x16x32_bf16 v[32:35], v[152:155], v[214:217], v[32:35]
	s_setprio 0
	s_barrier
	v_readfirstlane_b32 s36, v186
	v_lshl_add_u64 v[140:141], v[234:235], 0, s[6:7]
	s_mov_b32 m0, s36
	v_readfirstlane_b32 s36, v185
	global_load_lds_dwordx4 v[140:141], off
	v_lshl_add_u64 v[140:141], v[234:235], 0, s[8:9]
	s_mov_b32 m0, s36
	s_nop 0
	global_load_lds_dwordx4 v[140:141], off
	v_readfirstlane_b32 s36, v184
	v_lshl_add_u64 v[142:143], v[128:129], 0, s[26:27]
	s_mov_b32 m0, s36
	v_readfirstlane_b32 s36, v183
	global_load_lds_dwordx4 v[142:143], off
	s_mov_b32 m0, s36
	s_nop 0
	global_load_lds_dwordx4 v[128:129], off
	s_waitcnt vmcnt(8)
	s_barrier
	s_setprio 1
	v_mfma_f32_16x16x32_bf16 v[28:31], v[218:221], v[156:159], v[28:31]
	v_mfma_f32_16x16x32_bf16 v[24:27], v[226:229], v[156:159], v[24:27]
	v_mfma_f32_16x16x32_bf16 v[20:23], v[218:221], v[194:197], v[20:23]
	v_mfma_f32_16x16x32_bf16 v[16:19], v[226:229], v[194:197], v[16:19]
	v_mfma_f32_16x16x32_bf16 v[12:15], v[218:221], v[202:205], v[12:15]
	v_mfma_f32_16x16x32_bf16 v[8:11], v[226:229], v[202:205], v[8:11]
	v_mfma_f32_16x16x32_bf16 v[4:7], v[218:221], v[210:213], v[4:7]
	v_mfma_f32_16x16x32_bf16 v[0:3], v[226:229], v[210:213], v[0:3]
	v_mfma_f32_16x16x32_bf16 v[28:31], v[222:225], v[160:163], v[28:31]
	v_mfma_f32_16x16x32_bf16 v[24:27], v[230:233], v[160:163], v[24:27]
	v_mfma_f32_16x16x32_bf16 v[20:23], v[222:225], v[198:201], v[20:23]
	v_mfma_f32_16x16x32_bf16 v[16:19], v[230:233], v[198:201], v[16:19]
	v_mfma_f32_16x16x32_bf16 v[12:15], v[222:225], v[206:209], v[12:15]
	v_mfma_f32_16x16x32_bf16 v[8:11], v[230:233], v[206:209], v[8:11]
	v_mfma_f32_16x16x32_bf16 v[4:7], v[222:225], v[214:217], v[4:7]
	v_mfma_f32_16x16x32_bf16 v[0:3], v[230:233], v[214:217], v[0:3]
	s_setprio 0
	s_barrier
	ds_read_b128 v[140:143], v130
	ds_read_b128 v[144:147], v130 offset:1024
	ds_read_b128 v[148:151], v130 offset:2048
	ds_read_b128 v[152:155], v130 offset:3072
	ds_read_b128 v[156:159], v193 offset:32768
	ds_read_b128 v[160:163], v193 offset:33792
	ds_read_b128 v[194:197], v192 offset:32768
	ds_read_b128 v[198:201], v192 offset:33792
	ds_read_b128 v[202:205], v191 offset:32768
	ds_read_b128 v[206:209], v191 offset:33792
	ds_read_b128 v[210:213], v190 offset:32768
	ds_read_b128 v[214:217], v190 offset:33792
	s_waitcnt lgkmcnt(8)
	s_barrier
	s_waitcnt lgkmcnt(0)
	s_setprio 1
	s_waitcnt lgkmcnt(0)
	v_mfma_f32_16x16x32_bf16 v[124:127], v[140:143], v[156:159], v[124:127]
	v_mfma_f32_16x16x32_bf16 v[120:123], v[148:151], v[156:159], v[120:123]
	v_mfma_f32_16x16x32_bf16 v[116:119], v[140:143], v[194:197], v[116:119]
	v_mfma_f32_16x16x32_bf16 v[112:115], v[148:151], v[194:197], v[112:115]
	v_mfma_f32_16x16x32_bf16 v[108:111], v[140:143], v[202:205], v[108:111]
	v_mfma_f32_16x16x32_bf16 v[104:107], v[148:151], v[202:205], v[104:107]
	v_mfma_f32_16x16x32_bf16 v[100:103], v[140:143], v[210:213], v[100:103]
	v_mfma_f32_16x16x32_bf16 v[96:99], v[148:151], v[210:213], v[96:99]
	v_mfma_f32_16x16x32_bf16 v[124:127], v[144:147], v[160:163], v[124:127]
	v_mfma_f32_16x16x32_bf16 v[120:123], v[152:155], v[160:163], v[120:123]
	v_mfma_f32_16x16x32_bf16 v[116:119], v[144:147], v[198:201], v[116:119]
	v_mfma_f32_16x16x32_bf16 v[112:115], v[152:155], v[198:201], v[112:115]
	v_mfma_f32_16x16x32_bf16 v[108:111], v[144:147], v[206:209], v[108:111]
	v_mfma_f32_16x16x32_bf16 v[104:107], v[152:155], v[206:209], v[104:107]
	v_mfma_f32_16x16x32_bf16 v[100:103], v[144:147], v[214:217], v[100:103]
	v_mfma_f32_16x16x32_bf16 v[96:99], v[152:155], v[214:217], v[96:99]
	s_setprio 0
	s_barrier
	v_readfirstlane_b32 s36, v182
	v_lshl_add_u64 v[234:235], s[46:47], 0, v[164:165]
	s_mov_b32 m0, s36
	v_readfirstlane_b32 s36, v181
	ds_read_b128 v[218:221], v132
	ds_read_b128 v[222:225], v132 offset:1024
	ds_read_b128 v[226:229], v132 offset:2048
	ds_read_b128 v[230:233], v132 offset:3072
	global_load_lds_dwordx4 v[234:235], off
	v_lshl_add_u64 v[236:237], v[234:235], 0, s[2:3]
	s_mov_b32 m0, s36
	s_nop 0
	global_load_lds_dwordx4 v[236:237], off
	s_barrier
	s_waitcnt lgkmcnt(0)
	s_setprio 1
	s_waitcnt lgkmcnt(0)
	v_mfma_f32_16x16x32_bf16 v[92:95], v[218:221], v[156:159], v[92:95]
	v_mfma_f32_16x16x32_bf16 v[88:91], v[226:229], v[156:159], v[88:91]
	v_mfma_f32_16x16x32_bf16 v[84:87], v[218:221], v[194:197], v[84:87]
	v_mfma_f32_16x16x32_bf16 v[80:83], v[226:229], v[194:197], v[80:83]
	v_mfma_f32_16x16x32_bf16 v[76:79], v[218:221], v[202:205], v[76:79]
	v_mfma_f32_16x16x32_bf16 v[72:75], v[226:229], v[202:205], v[72:75]
	v_mfma_f32_16x16x32_bf16 v[68:71], v[218:221], v[210:213], v[68:71]
	v_mfma_f32_16x16x32_bf16 v[64:67], v[226:229], v[210:213], v[64:67]
	v_mfma_f32_16x16x32_bf16 v[92:95], v[222:225], v[160:163], v[92:95]
	v_mfma_f32_16x16x32_bf16 v[88:91], v[230:233], v[160:163], v[88:91]
	v_mfma_f32_16x16x32_bf16 v[84:87], v[222:225], v[198:201], v[84:87]
	v_mfma_f32_16x16x32_bf16 v[80:83], v[230:233], v[198:201], v[80:83]
	v_mfma_f32_16x16x32_bf16 v[76:79], v[222:225], v[206:209], v[76:79]
	v_mfma_f32_16x16x32_bf16 v[72:75], v[230:233], v[206:209], v[72:75]
	v_mfma_f32_16x16x32_bf16 v[68:71], v[222:225], v[214:217], v[68:71]
	v_mfma_f32_16x16x32_bf16 v[64:67], v[230:233], v[214:217], v[64:67]
	s_setprio 0
	v_readfirstlane_b32 s36, v177
	v_lshl_add_u64 v[236:237], v[128:129], 0, s[28:29]
	s_mov_b32 m0, s36
	v_readfirstlane_b32 s36, v175
	s_barrier
	ds_read_b128 v[156:159], v193 offset:49152
	ds_read_b128 v[160:163], v193 offset:50176
	ds_read_b128 v[194:197], v192 offset:49152
	ds_read_b128 v[198:201], v192 offset:50176
	ds_read_b128 v[202:205], v191 offset:49152
	ds_read_b128 v[206:209], v191 offset:50176
	ds_read_b128 v[210:213], v190 offset:49152
	ds_read_b128 v[214:217], v190 offset:50176
	global_load_lds_dwordx4 v[236:237], off
	v_lshl_add_u64 v[236:237], v[128:129], 0, s[30:31]
	s_mov_b32 m0, s36
	s_nop 0
	global_load_lds_dwordx4 v[236:237], off
	s_barrier
	s_waitcnt lgkmcnt(0)
	s_setprio 1
	s_waitcnt lgkmcnt(0)
	v_mfma_f32_16x16x32_bf16 v[60:63], v[140:143], v[156:159], v[60:63]
	v_mfma_f32_16x16x32_bf16 v[56:59], v[148:151], v[156:159], v[56:59]
	v_mfma_f32_16x16x32_bf16 v[52:55], v[140:143], v[194:197], v[52:55]
	v_mfma_f32_16x16x32_bf16 v[48:51], v[148:151], v[194:197], v[48:51]
	v_mfma_f32_16x16x32_bf16 v[44:47], v[140:143], v[202:205], v[44:47]
	v_mfma_f32_16x16x32_bf16 v[40:43], v[148:151], v[202:205], v[40:43]
	v_mfma_f32_16x16x32_bf16 v[36:39], v[140:143], v[210:213], v[36:39]
	v_mfma_f32_16x16x32_bf16 v[32:35], v[148:151], v[210:213], v[32:35]
	v_mfma_f32_16x16x32_bf16 v[60:63], v[144:147], v[160:163], v[60:63]
	v_mfma_f32_16x16x32_bf16 v[56:59], v[152:155], v[160:163], v[56:59]
	v_mfma_f32_16x16x32_bf16 v[52:55], v[144:147], v[198:201], v[52:55]
	v_mfma_f32_16x16x32_bf16 v[48:51], v[152:155], v[198:201], v[48:51]
	v_mfma_f32_16x16x32_bf16 v[44:47], v[144:147], v[206:209], v[44:47]
	v_mfma_f32_16x16x32_bf16 v[40:43], v[152:155], v[206:209], v[40:43]
	v_mfma_f32_16x16x32_bf16 v[36:39], v[144:147], v[214:217], v[36:39]
	v_mfma_f32_16x16x32_bf16 v[32:35], v[152:155], v[214:217], v[32:35]
	s_setprio 0
	s_barrier
	v_readfirstlane_b32 s36, v173
	v_lshl_add_u64 v[140:141], v[234:235], 0, s[6:7]
	s_mov_b32 m0, s36
	v_readfirstlane_b32 s36, v171
	global_load_lds_dwordx4 v[140:141], off
	v_lshl_add_u64 v[140:141], v[234:235], 0, s[8:9]
	s_mov_b32 m0, s36
	s_nop 0
	global_load_lds_dwordx4 v[140:141], off
	v_lshl_add_u64 v[128:129], v[128:129], 0, s[34:35]
	v_readfirstlane_b32 s36, v137
	v_lshl_add_u64 v[142:143], v[128:129], 0, s[18:19]
	s_mov_b32 m0, s36
	v_readfirstlane_b32 s36, v136
	global_load_lds_dwordx4 v[142:143], off
	v_lshl_add_u64 v[142:143], v[128:129], 0, s[20:21]
	s_mov_b32 m0, s36
	s_nop 0
	global_load_lds_dwordx4 v[142:143], off
	s_waitcnt vmcnt(8)
	s_barrier
	s_setprio 1
	v_mfma_f32_16x16x32_bf16 v[28:31], v[218:221], v[156:159], v[28:31]
	v_mfma_f32_16x16x32_bf16 v[24:27], v[226:229], v[156:159], v[24:27]
	v_mfma_f32_16x16x32_bf16 v[20:23], v[218:221], v[194:197], v[20:23]
	v_mfma_f32_16x16x32_bf16 v[16:19], v[226:229], v[194:197], v[16:19]
	v_mfma_f32_16x16x32_bf16 v[12:15], v[218:221], v[202:205], v[12:15]
	v_mfma_f32_16x16x32_bf16 v[8:11], v[226:229], v[202:205], v[8:11]
	v_mfma_f32_16x16x32_bf16 v[4:7], v[218:221], v[210:213], v[4:7]
	v_mfma_f32_16x16x32_bf16 v[0:3], v[226:229], v[210:213], v[0:3]
	v_mfma_f32_16x16x32_bf16 v[28:31], v[222:225], v[160:163], v[28:31]
	v_mfma_f32_16x16x32_bf16 v[24:27], v[230:233], v[160:163], v[24:27]
	v_mfma_f32_16x16x32_bf16 v[20:23], v[222:225], v[198:201], v[20:23]
	v_mfma_f32_16x16x32_bf16 v[16:19], v[230:233], v[198:201], v[16:19]
	v_mfma_f32_16x16x32_bf16 v[12:15], v[222:225], v[206:209], v[12:15]
	v_mfma_f32_16x16x32_bf16 v[8:11], v[230:233], v[206:209], v[8:11]
	v_mfma_f32_16x16x32_bf16 v[4:7], v[222:225], v[214:217], v[4:7]
	v_mfma_f32_16x16x32_bf16 v[0:3], v[230:233], v[214:217], v[0:3]
	s_setprio 0
	s_add_i32 s14, s14, 2
	s_add_u32 s46, s46, s56
	s_addc_u32 s47, s47, s57
	s_add_u32 s58, s58, s56
	s_addc_u32 s59, s59, s57
	s_cmp_lt_u32 s14, 28
	s_barrier
	s_cbranch_scc1 .LBB0_521
	s_lshl_b32 s14, s60, 3
	s_or_b32 s80, s61, s14
	s_lshl_b32 s46, s80, 8
	v_lshlrev_b32_e32 v128, 3, v131
	v_lshlrev_b32_e32 v129, 5, v131
	s_or_b32 s14, s46, 0x80
	v_and_b32_e32 v128, 0x7fff0, v128
	v_and_b32_e32 v129, 32, v129
	s_lshl_b64 s[56:57], s[14:15], 13
	v_add_u32_e32 v129, v129, v134
	v_add_lshl_u32 v128, v133, v128, 13
	s_add_u32 s56, s40, s56
	v_lshl_add_u32 v164, v129, 1, v128
	s_addc_u32 s57, s41, s57
	v_lshl_add_u64 v[128:129], s[56:57], 0, v[164:165]
	v_readfirstlane_b32 s14, v137
	ds_read_b128 v[140:143], v138
	ds_read_b128 v[144:147], v138 offset:1024
	ds_read_b128 v[148:151], v138 offset:2048
	ds_read_b128 v[152:155], v138 offset:3072
	ds_read_b128 v[156:159], v193
	ds_read_b128 v[160:163], v193 offset:1024
	ds_read_b128 v[194:197], v192
	ds_read_b128 v[198:201], v192 offset:1024
	ds_read_b128 v[202:205], v191
	ds_read_b128 v[206:209], v191 offset:1024
	ds_read_b128 v[210:213], v190
	ds_read_b128 v[214:217], v190 offset:1024
	v_lshl_add_u64 v[138:139], v[128:129], 0, s[38:39]
	s_mov_b32 m0, s14
	v_readfirstlane_b32 s14, v136
	global_load_lds_dwordx4 v[138:139], off
	v_lshl_add_u64 v[128:129], v[128:129], 0, s[44:45]
	s_mov_b32 m0, s14
	s_mov_b32 s47, s15
	global_load_lds_dwordx4 v[128:129], off
	s_barrier
	s_waitcnt lgkmcnt(0)
	s_setprio 1
	s_waitcnt lgkmcnt(0)
	v_mfma_f32_16x16x32_bf16 v[124:127], v[140:143], v[156:159], v[124:127]
	v_mfma_f32_16x16x32_bf16 v[120:123], v[148:151], v[156:159], v[120:123]
	v_mfma_f32_16x16x32_bf16 v[116:119], v[140:143], v[194:197], v[116:119]
	v_mfma_f32_16x16x32_bf16 v[112:115], v[148:151], v[194:197], v[112:115]
	v_mfma_f32_16x16x32_bf16 v[108:111], v[140:143], v[202:205], v[108:111]
	v_mfma_f32_16x16x32_bf16 v[104:107], v[148:151], v[202:205], v[104:107]
	v_mfma_f32_16x16x32_bf16 v[100:103], v[140:143], v[210:213], v[100:103]
	v_mfma_f32_16x16x32_bf16 v[96:99], v[148:151], v[210:213], v[96:99]
	v_mfma_f32_16x16x32_bf16 v[124:127], v[144:147], v[160:163], v[124:127]
	v_mfma_f32_16x16x32_bf16 v[120:123], v[152:155], v[160:163], v[120:123]
	v_mfma_f32_16x16x32_bf16 v[116:119], v[144:147], v[198:201], v[116:119]
	v_mfma_f32_16x16x32_bf16 v[112:115], v[152:155], v[198:201], v[112:115]
	v_mfma_f32_16x16x32_bf16 v[108:111], v[144:147], v[206:209], v[108:111]
	v_mfma_f32_16x16x32_bf16 v[104:107], v[152:155], v[206:209], v[104:107]
	v_mfma_f32_16x16x32_bf16 v[100:103], v[144:147], v[214:217], v[100:103]
	v_mfma_f32_16x16x32_bf16 v[96:99], v[152:155], v[214:217], v[96:99]
	s_setprio 0
	s_barrier
	ds_read_b128 v[136:139], v135
	ds_read_b128 v[218:221], v135 offset:1024
	ds_read_b128 v[222:225], v135 offset:2048
	ds_read_b128 v[226:229], v135 offset:3072
	s_barrier
	s_waitcnt lgkmcnt(0)
	s_setprio 1
	s_waitcnt lgkmcnt(0)
	v_mfma_f32_16x16x32_bf16 v[92:95], v[136:139], v[156:159], v[92:95]
	v_mfma_f32_16x16x32_bf16 v[84:87], v[136:139], v[194:197], v[84:87]
	v_mfma_f32_16x16x32_bf16 v[80:83], v[222:225], v[194:197], v[80:83]
	v_mfma_f32_16x16x32_bf16 v[88:91], v[222:225], v[156:159], v[88:91]
	v_mfma_f32_16x16x32_bf16 v[76:79], v[136:139], v[202:205], v[76:79]
	v_mfma_f32_16x16x32_bf16 v[72:75], v[222:225], v[202:205], v[72:75]
	v_mfma_f32_16x16x32_bf16 v[68:71], v[136:139], v[210:213], v[68:71]
	v_mfma_f32_16x16x32_bf16 v[64:67], v[222:225], v[210:213], v[64:67]
	v_mfma_f32_16x16x32_bf16 v[156:159], v[218:221], v[160:163], v[92:95]
	v_mfma_f32_16x16x32_bf16 v[194:197], v[218:221], v[198:201], v[84:87]
	v_mfma_f32_16x16x32_bf16 v[198:201], v[226:229], v[198:201], v[80:83]
	v_mfma_f32_16x16x32_bf16 v[160:163], v[226:229], v[160:163], v[88:91]
	v_mfma_f32_16x16x32_bf16 v[202:205], v[218:221], v[206:209], v[76:79]
	v_mfma_f32_16x16x32_bf16 v[206:209], v[226:229], v[206:209], v[72:75]
	v_mfma_f32_16x16x32_bf16 v[210:213], v[218:221], v[214:217], v[68:71]
	v_mfma_f32_16x16x32_bf16 v[214:217], v[226:229], v[214:217], v[64:67]
	s_setprio 0
	s_barrier
	s_nop 0
	ds_read_b128 v[64:67], v193 offset:16384
	ds_read_b128 v[68:71], v193 offset:17408
	ds_read_b128 v[72:75], v192 offset:16384
	ds_read_b128 v[76:79], v192 offset:17408
	ds_read_b128 v[80:83], v191 offset:16384
	ds_read_b128 v[84:87], v191 offset:17408
	ds_read_b128 v[88:91], v190 offset:16384
	ds_read_b128 v[92:95], v190 offset:17408
	s_waitcnt vmcnt(4)
	s_barrier
	s_waitcnt lgkmcnt(0)
	s_setprio 1
	s_waitcnt lgkmcnt(0)
	v_mfma_f32_16x16x32_bf16 v[60:63], v[140:143], v[64:67], v[60:63]
	v_mfma_f32_16x16x32_bf16 v[56:59], v[148:151], v[64:67], v[56:59]
	v_mfma_f32_16x16x32_bf16 v[52:55], v[140:143], v[72:75], v[52:55]
	v_mfma_f32_16x16x32_bf16 v[48:51], v[148:151], v[72:75], v[48:51]
	v_mfma_f32_16x16x32_bf16 v[230:233], v[140:143], v[80:83], v[44:47]
	v_mfma_f32_16x16x32_bf16 v[234:237], v[148:151], v[80:83], v[40:43]
	v_mfma_f32_16x16x32_bf16 v[140:143], v[140:143], v[88:91], v[36:39]
	v_mfma_f32_16x16x32_bf16 v[148:151], v[148:151], v[88:91], v[32:35]
	v_mfma_f32_16x16x32_bf16 v[32:35], v[144:147], v[68:71], v[60:63]
	v_mfma_f32_16x16x32_bf16 v[36:39], v[152:155], v[68:71], v[56:59]
	v_mfma_f32_16x16x32_bf16 v[40:43], v[144:147], v[76:79], v[52:55]
	v_mfma_f32_16x16x32_bf16 v[44:47], v[152:155], v[76:79], v[48:51]
	v_mfma_f32_16x16x32_bf16 v[48:51], v[144:147], v[84:87], v[230:233]
	v_mfma_f32_16x16x32_bf16 v[52:55], v[152:155], v[84:87], v[234:237]
	v_mfma_f32_16x16x32_bf16 v[56:59], v[144:147], v[92:95], v[140:143]
	v_mfma_f32_16x16x32_bf16 v[60:63], v[152:155], v[92:95], v[148:151]
	s_setprio 0
	s_setprio 1
	v_mfma_f32_16x16x32_bf16 v[28:31], v[136:139], v[64:67], v[28:31]
	v_mfma_f32_16x16x32_bf16 v[24:27], v[222:225], v[64:67], v[24:27]
	v_mfma_f32_16x16x32_bf16 v[20:23], v[136:139], v[72:75], v[20:23]
	v_mfma_f32_16x16x32_bf16 v[64:67], v[222:225], v[72:75], v[16:19]
	v_mfma_f32_16x16x32_bf16 v[12:15], v[136:139], v[80:83], v[12:15]
	v_mfma_f32_16x16x32_bf16 v[8:11], v[222:225], v[80:83], v[8:11]
	v_mfma_f32_16x16x32_bf16 v[72:75], v[136:139], v[88:91], v[4:7]
	v_mfma_f32_16x16x32_bf16 v[80:83], v[222:225], v[88:91], v[0:3]
	v_mfma_f32_16x16x32_bf16 v[0:3], v[218:221], v[68:71], v[28:31]
	v_mfma_f32_16x16x32_bf16 v[4:7], v[226:229], v[68:71], v[24:27]
	v_mfma_f32_16x16x32_bf16 v[16:19], v[218:221], v[76:79], v[20:23]
	v_mfma_f32_16x16x32_bf16 v[20:23], v[226:229], v[76:79], v[64:67]
	v_mfma_f32_16x16x32_bf16 v[24:27], v[218:221], v[84:87], v[12:15]
	v_mfma_f32_16x16x32_bf16 v[28:31], v[226:229], v[84:87], v[8:11]
	v_mfma_f32_16x16x32_bf16 v[64:67], v[218:221], v[92:95], v[72:75]
	v_mfma_f32_16x16x32_bf16 v[68:71], v[226:229], v[92:95], v[80:83]
	s_setprio 0
	s_barrier
	ds_read_b128 v[12:15], v130
	ds_read_b128 v[8:11], v130 offset:1024
	ds_read_b128 v[76:79], v130 offset:2048
	ds_read_b128 v[72:75], v130 offset:3072
	ds_read_b128 v[140:143], v193 offset:32768
	ds_read_b128 v[148:151], v193 offset:33792
	ds_read_b128 v[218:221], v192 offset:32768
	ds_read_b128 v[222:225], v192 offset:33792
	ds_read_b128 v[226:229], v191 offset:32768
	ds_read_b128 v[230:233], v191 offset:33792
	ds_read_b128 v[234:237], v190 offset:32768
	ds_read_b128 v[238:241], v190 offset:33792
	s_waitcnt vmcnt(2)
	s_barrier
	s_waitcnt lgkmcnt(0)
	s_setprio 1
	s_waitcnt lgkmcnt(0)
	v_mfma_f32_16x16x32_bf16 v[80:83], v[12:15], v[140:143], v[124:127]
	v_mfma_f32_16x16x32_bf16 v[84:87], v[76:79], v[140:143], v[120:123]
	v_mfma_f32_16x16x32_bf16 v[88:91], v[12:15], v[218:221], v[116:119]
	v_mfma_f32_16x16x32_bf16 v[92:95], v[76:79], v[218:221], v[112:115]
	v_mfma_f32_16x16x32_bf16 v[108:111], v[12:15], v[226:229], v[108:111]
	v_mfma_f32_16x16x32_bf16 v[104:107], v[76:79], v[226:229], v[104:107]
	v_mfma_f32_16x16x32_bf16 v[100:103], v[12:15], v[234:237], v[100:103]
	v_mfma_f32_16x16x32_bf16 v[96:99], v[76:79], v[234:237], v[96:99]
	v_mfma_f32_16x16x32_bf16 v[152:155], v[8:11], v[148:151], v[80:83]
	v_mfma_f32_16x16x32_bf16 v[144:147], v[72:75], v[148:151], v[84:87]
	v_mfma_f32_16x16x32_bf16 v[136:139], v[8:11], v[222:225], v[88:91]
	v_mfma_f32_16x16x32_bf16 v[128:131], v[72:75], v[222:225], v[92:95]
	v_mfma_f32_16x16x32_bf16 v[120:123], v[8:11], v[230:233], v[108:111]
	v_mfma_f32_16x16x32_bf16 v[112:115], v[72:75], v[230:233], v[104:107]
	v_mfma_f32_16x16x32_bf16 v[104:107], v[8:11], v[238:241], v[100:103]
	v_mfma_f32_16x16x32_bf16 v[96:99], v[72:75], v[238:241], v[96:99]
	s_setprio 0
	s_barrier
	ds_read_b128 v[88:91], v132
	ds_read_b128 v[80:83], v132 offset:1024
	ds_read_b128 v[92:95], v132 offset:2048
	ds_read_b128 v[84:87], v132 offset:3072
	s_waitcnt vmcnt(0)
	s_barrier
	s_waitcnt lgkmcnt(0)
	s_setprio 1
	s_waitcnt lgkmcnt(0)
	v_mfma_f32_16x16x32_bf16 v[100:103], v[88:91], v[140:143], v[156:159]
	v_mfma_f32_16x16x32_bf16 v[108:111], v[92:95], v[140:143], v[160:163]
	v_mfma_f32_16x16x32_bf16 v[116:119], v[88:91], v[218:221], v[194:197]
	v_mfma_f32_16x16x32_bf16 v[124:127], v[92:95], v[218:221], v[198:201]
	v_mfma_f32_16x16x32_bf16 v[160:163], v[88:91], v[226:229], v[202:205]
	v_mfma_f32_16x16x32_bf16 v[194:197], v[92:95], v[226:229], v[206:209]
	v_mfma_f32_16x16x32_bf16 v[198:201], v[88:91], v[234:237], v[210:213]
	v_mfma_f32_16x16x32_bf16 v[202:205], v[92:95], v[234:237], v[214:217]
	v_mfma_f32_16x16x32_bf16 v[156:159], v[80:83], v[148:151], v[100:103]
	v_mfma_f32_16x16x32_bf16 v[148:151], v[84:87], v[148:151], v[108:111]
	v_mfma_f32_16x16x32_bf16 v[140:143], v[80:83], v[222:225], v[116:119]
	v_mfma_f32_16x16x32_bf16 v[132:135], v[84:87], v[222:225], v[124:127]
	v_mfma_f32_16x16x32_bf16 v[124:127], v[80:83], v[230:233], v[160:163]
	v_mfma_f32_16x16x32_bf16 v[116:119], v[84:87], v[230:233], v[194:197]
	v_mfma_f32_16x16x32_bf16 v[108:111], v[80:83], v[238:241], v[198:201]
	v_mfma_f32_16x16x32_bf16 v[100:103], v[84:87], v[238:241], v[202:205]
	s_setprio 0
	s_lshl_b64 s[56:57], s[46:47], 2
	s_barrier
	v_mbcnt_lo_u32_b32 v162, -1, 0
	v_mbcnt_hi_u32_b32 v162, -1, v162
	s_add_u32 s56, s87, s56
	v_add_u32_e32 v160, s64, v162
	s_addc_u32 s57, s88, s57
	v_and_b32_e32 v164, 0x100, v160
	v_and_b32_e32 v162, 15, v162
	v_lshl_add_u64 v[160:161], s[56:57], 0, v[164:165]
	v_lshlrev_b32_e32 v164, 2, v162
	v_lshl_add_u64 v[160:161], v[160:161], 0, v[164:165]
	global_load_dword v180, v[160:161], off
	global_load_dword v178, v[160:161], off offset:64
	global_load_dword v176, v[160:161], off offset:128
	global_load_dword v174, v[160:161], off offset:192
	global_load_dword v172, v[160:161], off offset:512
	global_load_dword v170, v[160:161], off offset:576
	global_load_dword v168, v[160:161], off offset:640
	global_load_dword v166, v[160:161], off offset:704
	v_mbcnt_lo_u32_b32 v194, -1, 0
	v_mbcnt_hi_u32_b32 v194, -1, v194
	s_cmp_lg_u32 s79, 0
	v_add_u32_e32 v160, s64, v194
	v_bfe_u32 v196, v160, 8, 1
	v_ashrrev_i32_e32 v199, 6, v160
	v_bfe_u32 v160, v194, 4, 2
	s_cselect_b64 s[56:57], -1, 0
	v_and_b32_e32 v197, 3, v199
	v_and_b32_e32 v195, 15, v194
	s_and_b64 vcc, exec, s[56:57]
	v_lshlrev_b32_e32 v198, 4, v160
	s_cbranch_vccz .LBB0_533
	s_lshl_b32 s14, s78, 22
	s_lshl_b32 s36, s80, 14
	s_add_i32 s36, s36, s14
	v_lshlrev_b32_e32 v160, 6, v195
	v_or3_b32 v160, s36, v160, v198
	v_lshl_add_u32 v160, v197, 20, v160
	v_lshl_or_b32 v164, v196, 12, v160
	s_waitcnt vmcnt(0)
	v_pk_mul_f32 v[160:161], v[154:155], v[180:181] op_sel_hi:[1,0]
	v_pk_mul_f32 v[200:201], v[146:147], v[180:181] op_sel_hi:[1,0]
	v_max_f32_e32 v160, 0, v160
	v_mul_f32_e32 v204, v160, v160
	v_max_f32_e32 v160, 0, v200
	v_pk_mul_f32 v[162:163], v[152:153], v[180:181] op_sel_hi:[1,0]
	v_mul_f32_e32 v200, v160, v160
	v_max_f32_e32 v160, 0, v161
	v_pk_mul_f32 v[202:203], v[144:145], v[180:181] op_sel_hi:[1,0]
	v_max_f32_e32 v162, 0, v162
	v_max_f32_e32 v163, 0, v163
	v_mul_f32_e32 v161, v160, v160
	v_max_f32_e32 v160, 0, v201
	v_mul_f32_e32 v162, v162, v162
	v_max_f32_e32 v202, 0, v202
	v_mul_f32_e32 v163, v163, v163
	v_max_f32_e32 v203, 0, v203
	v_mul_f32_e32 v201, v160, v160
	v_cvt_pk_bf16_f32 v160, v162, v163
	v_cvt_pk_bf16_f32 v161, v204, v161
	v_mul_f32_e32 v202, v202, v202
	v_mul_f32_e32 v203, v203, v203
	v_cvt_pk_bf16_f32 v162, v202, v203
	v_cvt_pk_bf16_f32 v163, v200, v201
	global_store_dwordx4 v164, v[160:163], s[0:1]
	v_pk_mul_f32 v[202:203], v[150:151], v[180:181] op_sel_hi:[1,0]
	v_lshl_add_u64 v[200:201], s[0:1], 0, v[164:165]
	v_pk_mul_f32 v[160:161], v[158:159], v[180:181] op_sel_hi:[1,0]
	v_pk_mul_f32 v[162:163], v[156:157], v[180:181] op_sel_hi:[1,0]
	v_max_f32_e32 v160, 0, v160
	v_mul_f32_e32 v206, v160, v160
	v_max_f32_e32 v160, 0, v202
	v_mul_f32_e32 v202, v160, v160
	v_max_f32_e32 v160, 0, v161
	v_pk_mul_f32 v[204:205], v[148:149], v[180:181] op_sel_hi:[1,0]
	v_max_f32_e32 v162, 0, v162
	v_max_f32_e32 v163, 0, v163
	v_mul_f32_e32 v161, v160, v160
	v_max_f32_e32 v160, 0, v203
	v_add_co_u32_e32 v200, vcc, s72, v200
	v_mul_f32_e32 v162, v162, v162
	v_max_f32_e32 v204, 0, v204
	v_mul_f32_e32 v163, v163, v163
	v_max_f32_e32 v205, 0, v205
	v_mul_f32_e32 v203, v160, v160
	v_cvt_pk_bf16_f32 v160, v162, v163
	v_cvt_pk_bf16_f32 v161, v206, v161
	v_addc_co_u32_e32 v201, vcc, 0, v201, vcc
	v_mul_f32_e32 v204, v204, v204
	v_mul_f32_e32 v205, v205, v205
	v_cvt_pk_bf16_f32 v162, v204, v205
	v_cvt_pk_bf16_f32 v163, v202, v203
	global_store_dwordx4 v[200:201], v[160:163], off
	v_pk_mul_f32 v[202:203], v[130:131], v[178:179] op_sel_hi:[1,0]
	v_pk_mul_f32 v[204:205], v[128:129], v[178:179] op_sel_hi:[1,0]
	v_pk_mul_f32 v[160:161], v[138:139], v[178:179] op_sel_hi:[1,0]
	v_pk_mul_f32 v[162:163], v[136:137], v[178:179] op_sel_hi:[1,0]
	v_max_f32_e32 v160, 0, v160
	v_mul_f32_e32 v206, v160, v160
	v_max_f32_e32 v160, 0, v202
	v_mul_f32_e32 v202, v160, v160
	v_max_f32_e32 v160, 0, v161
	v_max_f32_e32 v162, 0, v162
	v_max_f32_e32 v163, 0, v163
	v_mul_f32_e32 v161, v160, v160
	v_max_f32_e32 v160, 0, v203
	v_mul_f32_e32 v162, v162, v162
	v_max_f32_e32 v204, 0, v204
	v_mul_f32_e32 v163, v163, v163
	v_max_f32_e32 v205, 0, v205
	v_mul_f32_e32 v203, v160, v160
	v_cvt_pk_bf16_f32 v160, v162, v163
	v_cvt_pk_bf16_f32 v161, v206, v161
	v_mul_f32_e32 v204, v204, v204
	v_mul_f32_e32 v205, v205, v205
	v_cvt_pk_bf16_f32 v162, v204, v205
	v_cvt_pk_bf16_f32 v163, v202, v203
	global_store_dwordx4 v164, v[160:163], s[0:1] offset:1024
	v_pk_mul_f32 v[202:203], v[134:135], v[178:179] op_sel_hi:[1,0]
	v_pk_mul_f32 v[204:205], v[132:133], v[178:179] op_sel_hi:[1,0]
	v_pk_mul_f32 v[160:161], v[142:143], v[178:179] op_sel_hi:[1,0]
	v_pk_mul_f32 v[162:163], v[140:141], v[178:179] op_sel_hi:[1,0]
	v_max_f32_e32 v160, 0, v160
	v_mul_f32_e32 v206, v160, v160
	v_max_f32_e32 v160, 0, v202
	v_mul_f32_e32 v202, v160, v160
	v_max_f32_e32 v160, 0, v161
	v_max_f32_e32 v162, 0, v162
	v_max_f32_e32 v163, 0, v163
	v_mul_f32_e32 v161, v160, v160
	v_max_f32_e32 v160, 0, v203
	v_mul_f32_e32 v162, v162, v162
	v_max_f32_e32 v204, 0, v204
	v_mul_f32_e32 v163, v163, v163
	v_max_f32_e32 v205, 0, v205
	v_mul_f32_e32 v203, v160, v160
	v_cvt_pk_bf16_f32 v160, v162, v163
	v_cvt_pk_bf16_f32 v161, v206, v161
	v_mul_f32_e32 v204, v204, v204
	v_mul_f32_e32 v205, v205, v205
	v_cvt_pk_bf16_f32 v162, v204, v205
	v_cvt_pk_bf16_f32 v163, v202, v203
	global_store_dwordx4 v[200:201], v[160:163], off offset:1024
	v_pk_mul_f32 v[202:203], v[114:115], v[176:177] op_sel_hi:[1,0]
	v_pk_mul_f32 v[204:205], v[112:113], v[176:177] op_sel_hi:[1,0]
	v_pk_mul_f32 v[160:161], v[122:123], v[176:177] op_sel_hi:[1,0]
	v_pk_mul_f32 v[162:163], v[120:121], v[176:177] op_sel_hi:[1,0]
	v_max_f32_e32 v160, 0, v160
	v_mul_f32_e32 v206, v160, v160
	v_max_f32_e32 v160, 0, v202
	v_mul_f32_e32 v202, v160, v160
	v_max_f32_e32 v160, 0, v161
	v_max_f32_e32 v162, 0, v162
	v_max_f32_e32 v163, 0, v163
	v_mul_f32_e32 v161, v160, v160
	v_max_f32_e32 v160, 0, v203
	v_mul_f32_e32 v162, v162, v162
	v_max_f32_e32 v204, 0, v204
	v_mul_f32_e32 v163, v163, v163
	v_max_f32_e32 v205, 0, v205
	v_mul_f32_e32 v203, v160, v160
	v_cvt_pk_bf16_f32 v160, v162, v163
	v_cvt_pk_bf16_f32 v161, v206, v161
	v_mul_f32_e32 v204, v204, v204
	v_mul_f32_e32 v205, v205, v205
	v_cvt_pk_bf16_f32 v162, v204, v205
	v_cvt_pk_bf16_f32 v163, v202, v203
	global_store_dwordx4 v164, v[160:163], s[0:1] offset:2048
	v_pk_mul_f32 v[202:203], v[118:119], v[176:177] op_sel_hi:[1,0]
	v_pk_mul_f32 v[204:205], v[116:117], v[176:177] op_sel_hi:[1,0]
	v_pk_mul_f32 v[160:161], v[126:127], v[176:177] op_sel_hi:[1,0]
	v_pk_mul_f32 v[162:163], v[124:125], v[176:177] op_sel_hi:[1,0]
	v_max_f32_e32 v160, 0, v160
	v_mul_f32_e32 v206, v160, v160
	v_max_f32_e32 v160, 0, v202
	v_mul_f32_e32 v202, v160, v160
	v_max_f32_e32 v160, 0, v161
	v_max_f32_e32 v162, 0, v162
	v_max_f32_e32 v163, 0, v163
	v_mul_f32_e32 v161, v160, v160
	v_max_f32_e32 v160, 0, v203
	v_mul_f32_e32 v162, v162, v162
	v_max_f32_e32 v204, 0, v204
	v_mul_f32_e32 v163, v163, v163
	v_max_f32_e32 v205, 0, v205
	v_mul_f32_e32 v203, v160, v160
	v_cvt_pk_bf16_f32 v160, v162, v163
	v_cvt_pk_bf16_f32 v161, v206, v161
	v_mul_f32_e32 v204, v204, v204
	v_mul_f32_e32 v205, v205, v205
	v_cvt_pk_bf16_f32 v162, v204, v205
	v_cvt_pk_bf16_f32 v163, v202, v203
	global_store_dwordx4 v[200:201], v[160:163], off offset:2048
	v_pk_mul_f32 v[200:201], v[98:99], v[174:175] op_sel_hi:[1,0]
	v_pk_mul_f32 v[202:203], v[96:97], v[174:175] op_sel_hi:[1,0]
	v_pk_mul_f32 v[160:161], v[106:107], v[174:175] op_sel_hi:[1,0]
	v_pk_mul_f32 v[162:163], v[104:105], v[174:175] op_sel_hi:[1,0]
	v_max_f32_e32 v160, 0, v160
	v_mul_f32_e32 v204, v160, v160
	v_max_f32_e32 v160, 0, v200
	v_mul_f32_e32 v200, v160, v160
	v_max_f32_e32 v160, 0, v161
	v_max_f32_e32 v162, 0, v162
	v_max_f32_e32 v163, 0, v163
	v_mul_f32_e32 v161, v160, v160
	v_max_f32_e32 v160, 0, v201
	v_mul_f32_e32 v162, v162, v162
	v_max_f32_e32 v202, 0, v202
	v_mul_f32_e32 v163, v163, v163
	v_max_f32_e32 v203, 0, v203
	v_mul_f32_e32 v201, v160, v160
	v_cvt_pk_bf16_f32 v160, v162, v163
	v_cvt_pk_bf16_f32 v161, v204, v161
	v_mul_f32_e32 v202, v202, v202
	v_mul_f32_e32 v203, v203, v203
	v_cvt_pk_bf16_f32 v162, v202, v203
	v_cvt_pk_bf16_f32 v163, v200, v201
	global_store_dwordx4 v164, v[160:163], s[0:1] offset:3072
	v_pk_mul_f32 v[200:201], v[102:103], v[174:175] op_sel_hi:[1,0]
	v_pk_mul_f32 v[202:203], v[100:101], v[174:175] op_sel_hi:[1,0]
	v_pk_mul_f32 v[160:161], v[110:111], v[174:175] op_sel_hi:[1,0]
	v_pk_mul_f32 v[162:163], v[108:109], v[174:175] op_sel_hi:[1,0]
	v_max_f32_e32 v160, 0, v160
	v_mul_f32_e32 v204, v160, v160
	v_max_f32_e32 v160, 0, v200
	v_max_f32_e32 v162, 0, v162
	v_max_f32_e32 v163, 0, v163
	v_mul_f32_e32 v200, v160, v160
	v_max_f32_e32 v160, 0, v161
	v_mul_f32_e32 v162, v162, v162
	v_max_f32_e32 v202, 0, v202
	v_mul_f32_e32 v163, v163, v163
	v_max_f32_e32 v203, 0, v203
	v_mul_f32_e32 v161, v160, v160
	v_max_f32_e32 v160, 0, v201
	v_mul_f32_e32 v202, v202, v202
	v_mul_f32_e32 v203, v203, v203
	v_mul_f32_e32 v201, v160, v160
	v_cvt_pk_bf16_f32 v160, v162, v163
	v_cvt_pk_bf16_f32 v161, v204, v161
	v_cvt_pk_bf16_f32 v162, v202, v203
	v_cvt_pk_bf16_f32 v163, v200, v201
	v_add_u32_e32 v164, 0x80c00, v164
	s_cbranch_execnz .LBB0_525

.LBB0_560:
	v_and_b32_e32 v2, 15, v0
	s_bfe_u32 s66, s86, 0x30003
	v_and_b32_e32 v3, 48, v0
	v_lshlrev_b32_e32 v134, 4, v135
	v_and_b32_e32 v5, 32, v0
	s_movk_i32 s37, 0x3f0
	v_lshlrev_b32_e32 v2, 6, v2
	v_lshlrev_b32_e32 v9, 2, v0
	s_lshl_b32 s36, s66, 14
	v_bitop3_b32 v155, v134, v5, s37 bitop3:0x6c
	v_and_b32_e32 v6, 64, v135
	s_add_i32 s67, s20, -2
	v_or_b32_e32 v8, v2, v3
	v_and_b32_e32 v9, 32, v9
	s_mov_b32 s37, 0x14000
	v_lshlrev_b32_e32 v0, 6, v0
	v_and_b32_e32 v4, 0x3f0, v134
	v_lshlrev_b32_e32 v156, 13, v6
	v_lshlrev_b32_e32 v7, 3, v135
	v_mul_i32_i24_e32 v6, 0xffffe800, v6
	v_bitop3_b32 v11, v8, s37, v9 bitop3:0xde
	s_mov_b32 s37, 0x1c000
	v_and_b32_e32 v0, 0x3c0, v0
	s_add_u32 s68, s72, s36
	v_and_b32_e32 v157, 0xfffffc00, v7
	v_bitop3_b32 v2, v2, v9, v3 bitop3:0x36
	v_bitop3_b32 v10, v8, s76, v9 bitop3:0xde
	v_bitop3_b32 v12, v8, s77, v9 bitop3:0xde
	v_bitop3_b32 v8, v8, s37, v9 bitop3:0xde
	v_bitop3_b32 v3, v0, v9, v3 bitop3:0x36
	v_bitop3_b32 v0, v6, v4, v5 bitop3:0xf6
	s_addc_u32 s69, s73, 0
	s_lshl_b32 s36, s86, 11
	s_and_b32 s37, s86, 7
	v_add3_u32 v128, v0, v156, v157
	s_and_b32 s36, s36, 0x60000
	s_lshl_b32 s37, s37, 14
	v_lshlrev_b32_e32 v13, 13, v1
	v_lshl_add_u64 v[0:1], s[68:69], 0, v[128:129]
	s_mov_b64 s[68:69], 0xc3000
	s_or_b32 s36, s36, s37
	v_lshl_add_u64 v[130:131], v[0:1], 0, s[68:69]
	v_bitop3_b32 v0, v4, v156, v5 bitop3:0xde
	s_add_u32 s68, s70, s36
	v_add_u32_e32 v128, v0, v157
	s_addc_u32 s69, s71, 0
	v_lshlrev_b32_e32 v7, 6, v135
	v_lshl_add_u64 v[0:1], s[68:69], 0, v[128:129]
	s_mov_b64 s[68:69], 0x301000
	v_and_b32_e32 v7, 0x3000, v7
	v_or_b32_e32 v9, 0x800, v13
	v_or_b32_e32 v14, 0x1000, v13
	v_or_b32_e32 v15, 0x1800, v13
	v_lshl_add_u64 v[132:133], v[0:1], 0, s[68:69]
	v_mov_b32_e32 v0, 0
	s_mov_b32 s68, 0
	v_add_u32_e32 v161, v10, v7
	v_add_u32_e32 v152, v2, v13
	v_add_u32_e32 v151, v3, v9
	v_add_u32_e32 v150, v3, v14
	v_add_u32_e32 v149, v3, v15
	v_add_u32_e32 v160, 0xc000, v134
	v_add_u32_e32 v159, 0xe000, v134
	v_add_u32_e32 v158, v11, v7
	v_add_u32_e32 v148, 0x10000, v134
	v_add_u32_e32 v147, 0x12000, v134
	v_add_u32_e32 v146, 0x2000, v134
	v_add_u32_e32 v145, 0x14000, v134
	v_add_u32_e32 v144, 0x16000, v134
	v_add_u32_e32 v154, v12, v7
	v_add_u32_e32 v143, 0x4000, v134
	v_add_u32_e32 v142, 0x6000, v134
	v_add_u32_e32 v153, v8, v7
	v_add_u32_e32 v141, 0x18000, v134
	v_add_u32_e32 v140, 0x1a000, v134
	v_add_u32_e32 v139, 0x8000, v134
	v_add_u32_e32 v138, 0xa000, v134
	v_add_u32_e32 v137, 0x1c000, v134
	v_add_u32_e32 v136, 0x1e000, v134
	v_mov_b32_e32 v1, v0
	v_mov_b32_e32 v2, v0
	v_mov_b32_e32 v3, v0
	v_mov_b32_e32 v4, v0
	v_mov_b32_e32 v5, v0
	v_mov_b32_e32 v6, v0
	v_mov_b32_e32 v7, v0
	v_mov_b32_e32 v8, v0
	v_mov_b32_e32 v9, v0
	v_mov_b32_e32 v10, v0
	v_mov_b32_e32 v11, v0
	v_mov_b32_e32 v12, v0
	v_mov_b32_e32 v13, v0
	v_mov_b32_e32 v14, v0
	v_mov_b32_e32 v15, v0
	v_mov_b32_e32 v16, v0
	v_mov_b32_e32 v17, v0
	v_mov_b32_e32 v18, v0
	v_mov_b32_e32 v19, v0
	v_mov_b32_e32 v20, v0
	v_mov_b32_e32 v21, v0
	v_mov_b32_e32 v22, v0
	v_mov_b32_e32 v23, v0
	v_mov_b32_e32 v24, v0
	v_mov_b32_e32 v25, v0
	v_mov_b32_e32 v26, v0
	v_mov_b32_e32 v27, v0
	v_mov_b32_e32 v28, v0
	v_mov_b32_e32 v29, v0
	v_mov_b32_e32 v30, v0
	v_mov_b32_e32 v31, v0
	v_mov_b32_e32 v32, v0
	v_mov_b32_e32 v33, v0
	v_mov_b32_e32 v34, v0
	v_mov_b32_e32 v35, v0
	v_mov_b32_e32 v36, v0
	v_mov_b32_e32 v37, v0
	v_mov_b32_e32 v38, v0
	v_mov_b32_e32 v39, v0
	v_mov_b32_e32 v40, v0
	v_mov_b32_e32 v41, v0
	v_mov_b32_e32 v42, v0
	v_mov_b32_e32 v43, v0
	v_mov_b32_e32 v44, v0
	v_mov_b32_e32 v45, v0
	v_mov_b32_e32 v46, v0
	v_mov_b32_e32 v47, v0
	v_mov_b32_e32 v48, v0
	v_mov_b32_e32 v49, v0
	v_mov_b32_e32 v50, v0
	v_mov_b32_e32 v51, v0
	v_mov_b32_e32 v52, v0
	v_mov_b32_e32 v53, v0
	v_mov_b32_e32 v54, v0
	v_mov_b32_e32 v55, v0
	v_mov_b32_e32 v56, v0
	v_mov_b32_e32 v57, v0
	v_mov_b32_e32 v58, v0
	v_mov_b32_e32 v59, v0
	v_mov_b32_e32 v60, v0
	v_mov_b32_e32 v61, v0
	v_mov_b32_e32 v62, v0
	v_mov_b32_e32 v63, v0
	v_mov_b32_e32 v64, v0
	v_mov_b32_e32 v65, v0
	v_mov_b32_e32 v66, v0
	v_mov_b32_e32 v67, v0
	v_mov_b32_e32 v68, v0
	v_mov_b32_e32 v69, v0
	v_mov_b32_e32 v70, v0
	v_mov_b32_e32 v71, v0
	v_mov_b32_e32 v72, v0
	v_mov_b32_e32 v73, v0
	v_mov_b32_e32 v74, v0
	v_mov_b32_e32 v75, v0
	v_mov_b32_e32 v76, v0
	v_mov_b32_e32 v77, v0
	v_mov_b32_e32 v78, v0
	v_mov_b32_e32 v79, v0
	v_mov_b32_e32 v80, v0
	v_mov_b32_e32 v81, v0
	v_mov_b32_e32 v82, v0
	v_mov_b32_e32 v83, v0
	v_mov_b32_e32 v84, v0
	v_mov_b32_e32 v85, v0
	v_mov_b32_e32 v86, v0
	v_mov_b32_e32 v87, v0
	v_mov_b32_e32 v88, v0
	v_mov_b32_e32 v89, v0
	v_mov_b32_e32 v90, v0
	v_mov_b32_e32 v91, v0
	v_mov_b32_e32 v92, v0
	v_mov_b32_e32 v93, v0
	v_mov_b32_e32 v94, v0
	v_mov_b32_e32 v95, v0
	v_mov_b32_e32 v96, v0
	v_mov_b32_e32 v97, v0
	v_mov_b32_e32 v98, v0
	v_mov_b32_e32 v99, v0
	v_mov_b32_e32 v100, v0
	v_mov_b32_e32 v101, v0
	v_mov_b32_e32 v102, v0
	v_mov_b32_e32 v103, v0
	v_mov_b32_e32 v104, v0
	v_mov_b32_e32 v105, v0
	v_mov_b32_e32 v106, v0
	v_mov_b32_e32 v107, v0
	v_mov_b32_e32 v108, v0
	v_mov_b32_e32 v109, v0
	v_mov_b32_e32 v110, v0
	v_mov_b32_e32 v111, v0
	v_mov_b32_e32 v112, v0
	v_mov_b32_e32 v113, v0
	v_mov_b32_e32 v114, v0
	v_mov_b32_e32 v115, v0
	v_mov_b32_e32 v116, v0
	v_mov_b32_e32 v117, v0
	v_mov_b32_e32 v118, v0
	v_mov_b32_e32 v119, v0
	v_mov_b32_e32 v120, v0
	v_mov_b32_e32 v121, v0
	v_mov_b32_e32 v122, v0
	v_mov_b32_e32 v123, v0
	v_mov_b32_e32 v124, v0
	v_mov_b32_e32 v125, v0
	v_mov_b32_e32 v126, v0
	v_mov_b32_e32 v127, v0
	s_barrier
	v_readfirstlane_b32 s36, v160
	v_lshl_add_u64 v[164:165], v[132:133], 0, s[22:23]
	s_mov_b32 m0, s36
	v_readfirstlane_b32 s36, v159
	global_load_lds_dwordx4 v[164:165], off
	v_lshl_add_u64 v[164:165], v[132:133], 0, s[24:25]
	s_mov_b32 m0, s36
	s_nop 0
	global_load_lds_dwordx4 v[164:165], off
.LBB0_561:
	ds_read_b128 v[162:165], v161
	ds_read_b128 v[166:169], v161 offset:1024
	ds_read_b128 v[170:173], v161 offset:2048
	ds_read_b128 v[174:177], v161 offset:3072
	ds_read_b128 v[178:181], v152
	ds_read_b128 v[182:185], v152 offset:1024
	ds_read_b128 v[186:189], v151
	ds_read_b128 v[190:193], v151 offset:1024
	ds_read_b128 v[194:197], v150
	ds_read_b128 v[198:201], v150 offset:1024
	ds_read_b128 v[202:205], v149
	ds_read_b128 v[206:209], v149 offset:1024
	s_waitcnt lgkmcnt(8)
	s_barrier
	s_waitcnt lgkmcnt(0)
	s_setprio 1
	s_waitcnt lgkmcnt(0)
	v_mfma_f32_16x16x32_bf16 v[124:127], v[162:165], v[178:181], v[124:127]
	v_mfma_f32_16x16x32_bf16 v[120:123], v[170:173], v[178:181], v[120:123]
	v_mfma_f32_16x16x32_bf16 v[116:119], v[162:165], v[186:189], v[116:119]
	v_mfma_f32_16x16x32_bf16 v[112:115], v[170:173], v[186:189], v[112:115]
	v_mfma_f32_16x16x32_bf16 v[108:111], v[162:165], v[194:197], v[108:111]
	v_mfma_f32_16x16x32_bf16 v[104:107], v[170:173], v[194:197], v[104:107]
	v_mfma_f32_16x16x32_bf16 v[100:103], v[162:165], v[202:205], v[100:103]
	v_mfma_f32_16x16x32_bf16 v[96:99], v[170:173], v[202:205], v[96:99]
	v_mfma_f32_16x16x32_bf16 v[124:127], v[166:169], v[182:185], v[124:127]
	v_mfma_f32_16x16x32_bf16 v[120:123], v[174:177], v[182:185], v[120:123]
	v_mfma_f32_16x16x32_bf16 v[116:119], v[166:169], v[190:193], v[116:119]
	v_mfma_f32_16x16x32_bf16 v[112:115], v[174:177], v[190:193], v[112:115]
	v_mfma_f32_16x16x32_bf16 v[108:111], v[166:169], v[198:201], v[108:111]
	v_mfma_f32_16x16x32_bf16 v[104:107], v[174:177], v[198:201], v[104:107]
	v_mfma_f32_16x16x32_bf16 v[100:103], v[166:169], v[206:209], v[100:103]
	v_mfma_f32_16x16x32_bf16 v[96:99], v[174:177], v[206:209], v[96:99]
	s_setprio 0
	s_barrier
	v_readfirstlane_b32 s36, v148
	v_lshl_add_u64 v[226:227], v[130:131], 0, s[26:27]
	s_mov_b32 m0, s36
	v_readfirstlane_b32 s36, v147
	ds_read_b128 v[210:213], v158
	ds_read_b128 v[214:217], v158 offset:1024
	ds_read_b128 v[218:221], v158 offset:2048
	ds_read_b128 v[222:225], v158 offset:3072
	global_load_lds_dwordx4 v[226:227], off
	v_lshl_add_u64 v[226:227], v[130:131], 0, s[28:29]
	s_mov_b32 m0, s36
	s_add_i32 s68, s68, 2
	global_load_lds_dwordx4 v[226:227], off
	s_barrier
	s_waitcnt lgkmcnt(0)
	s_setprio 1
	s_waitcnt lgkmcnt(0)
	v_mfma_f32_16x16x32_bf16 v[92:95], v[210:213], v[178:181], v[92:95]
	v_mfma_f32_16x16x32_bf16 v[88:91], v[218:221], v[178:181], v[88:91]
	v_mfma_f32_16x16x32_bf16 v[84:87], v[210:213], v[186:189], v[84:87]
	v_mfma_f32_16x16x32_bf16 v[80:83], v[218:221], v[186:189], v[80:83]
	v_mfma_f32_16x16x32_bf16 v[76:79], v[210:213], v[194:197], v[76:79]
	v_mfma_f32_16x16x32_bf16 v[72:75], v[218:221], v[194:197], v[72:75]
	v_mfma_f32_16x16x32_bf16 v[68:71], v[210:213], v[202:205], v[68:71]
	v_mfma_f32_16x16x32_bf16 v[64:67], v[218:221], v[202:205], v[64:67]
	v_mfma_f32_16x16x32_bf16 v[92:95], v[214:217], v[182:185], v[92:95]
	v_mfma_f32_16x16x32_bf16 v[88:91], v[222:225], v[182:185], v[88:91]
	v_mfma_f32_16x16x32_bf16 v[84:87], v[214:217], v[190:193], v[84:87]
	v_mfma_f32_16x16x32_bf16 v[80:83], v[222:225], v[190:193], v[80:83]
	v_mfma_f32_16x16x32_bf16 v[76:79], v[214:217], v[198:201], v[76:79]
	v_mfma_f32_16x16x32_bf16 v[72:75], v[222:225], v[198:201], v[72:75]
	v_mfma_f32_16x16x32_bf16 v[68:71], v[214:217], v[206:209], v[68:71]
	v_mfma_f32_16x16x32_bf16 v[64:67], v[222:225], v[206:209], v[64:67]
	s_setprio 0
	v_readfirstlane_b32 s36, v134
	v_lshl_add_u64 v[226:227], v[132:133], 0, s[30:31]
	s_mov_b32 m0, s36
	v_readfirstlane_b32 s36, v146
	s_barrier
	ds_read_b128 v[178:181], v152 offset:16384
	ds_read_b128 v[182:185], v152 offset:17408
	ds_read_b128 v[186:189], v151 offset:16384
	ds_read_b128 v[190:193], v151 offset:17408
	ds_read_b128 v[194:197], v150 offset:16384
	ds_read_b128 v[198:201], v150 offset:17408
	ds_read_b128 v[202:205], v149 offset:16384
	ds_read_b128 v[206:209], v149 offset:17408
	global_load_lds_dwordx4 v[226:227], off
	v_lshl_add_u64 v[226:227], v[132:133], 0, s[34:35]
	s_mov_b32 m0, s36
	s_nop 0
	global_load_lds_dwordx4 v[226:227], off
	s_barrier
	s_waitcnt lgkmcnt(0)
	s_setprio 1
	s_waitcnt lgkmcnt(0)
	v_mfma_f32_16x16x32_bf16 v[60:63], v[162:165], v[178:181], v[60:63]
	v_mfma_f32_16x16x32_bf16 v[56:59], v[170:173], v[178:181], v[56:59]
	v_mfma_f32_16x16x32_bf16 v[52:55], v[162:165], v[186:189], v[52:55]
	v_mfma_f32_16x16x32_bf16 v[48:51], v[170:173], v[186:189], v[48:51]
	v_mfma_f32_16x16x32_bf16 v[44:47], v[162:165], v[194:197], v[44:47]
	v_mfma_f32_16x16x32_bf16 v[40:43], v[170:173], v[194:197], v[40:43]
	v_mfma_f32_16x16x32_bf16 v[36:39], v[162:165], v[202:205], v[36:39]
	v_mfma_f32_16x16x32_bf16 v[32:35], v[170:173], v[202:205], v[32:35]
	v_mfma_f32_16x16x32_bf16 v[60:63], v[166:169], v[182:185], v[60:63]
	v_mfma_f32_16x16x32_bf16 v[56:59], v[174:177], v[182:185], v[56:59]
	v_mfma_f32_16x16x32_bf16 v[52:55], v[166:169], v[190:193], v[52:55]
	v_mfma_f32_16x16x32_bf16 v[48:51], v[174:177], v[190:193], v[48:51]
	v_mfma_f32_16x16x32_bf16 v[44:47], v[166:169], v[198:201], v[44:47]
	v_mfma_f32_16x16x32_bf16 v[40:43], v[174:177], v[198:201], v[40:43]
	v_mfma_f32_16x16x32_bf16 v[36:39], v[166:169], v[206:209], v[36:39]
	v_mfma_f32_16x16x32_bf16 v[32:35], v[174:177], v[206:209], v[32:35]
	s_setprio 0
	s_barrier
	v_readfirstlane_b32 s36, v145
	v_lshl_add_u64 v[162:163], v[130:131], 0, s[38:39]
	s_mov_b32 m0, s36
	v_readfirstlane_b32 s36, v144
	global_load_lds_dwordx4 v[162:163], off
	v_lshl_add_u64 v[162:163], v[130:131], 0, s[44:45]
	s_mov_b32 m0, s36
	s_nop 0
	global_load_lds_dwordx4 v[162:163], off
	v_readfirstlane_b32 s36, v143
	v_lshl_add_u64 v[164:165], v[132:133], 0, s[46:47]
	s_mov_b32 m0, s36
	v_readfirstlane_b32 s36, v142
	global_load_lds_dwordx4 v[164:165], off
	v_lshl_add_u64 v[164:165], v[132:133], 0, s[50:51]
	s_mov_b32 m0, s36
	s_nop 0
	global_load_lds_dwordx4 v[164:165], off
	s_waitcnt vmcnt(8)
	s_barrier
	s_setprio 1
	v_mfma_f32_16x16x32_bf16 v[28:31], v[210:213], v[178:181], v[28:31]
	v_mfma_f32_16x16x32_bf16 v[24:27], v[218:221], v[178:181], v[24:27]
	v_mfma_f32_16x16x32_bf16 v[20:23], v[210:213], v[186:189], v[20:23]
	v_mfma_f32_16x16x32_bf16 v[16:19], v[218:221], v[186:189], v[16:19]
	v_mfma_f32_16x16x32_bf16 v[12:15], v[210:213], v[194:197], v[12:15]
	v_mfma_f32_16x16x32_bf16 v[8:11], v[218:221], v[194:197], v[8:11]
	v_mfma_f32_16x16x32_bf16 v[4:7], v[210:213], v[202:205], v[4:7]
	v_mfma_f32_16x16x32_bf16 v[0:3], v[218:221], v[202:205], v[0:3]
	v_mfma_f32_16x16x32_bf16 v[28:31], v[214:217], v[182:185], v[28:31]
	v_mfma_f32_16x16x32_bf16 v[24:27], v[222:225], v[182:185], v[24:27]
	v_mfma_f32_16x16x32_bf16 v[20:23], v[214:217], v[190:193], v[20:23]
	v_mfma_f32_16x16x32_bf16 v[16:19], v[222:225], v[190:193], v[16:19]
	v_mfma_f32_16x16x32_bf16 v[12:15], v[214:217], v[198:201], v[12:15]
	v_mfma_f32_16x16x32_bf16 v[8:11], v[222:225], v[198:201], v[8:11]
	v_mfma_f32_16x16x32_bf16 v[4:7], v[214:217], v[206:209], v[4:7]
	v_mfma_f32_16x16x32_bf16 v[0:3], v[222:225], v[206:209], v[0:3]
	s_setprio 0
	s_barrier
	ds_read_b128 v[162:165], v154
	ds_read_b128 v[166:169], v154 offset:1024
	ds_read_b128 v[170:173], v154 offset:2048
	ds_read_b128 v[174:177], v154 offset:3072
	ds_read_b128 v[178:181], v152 offset:32768
	ds_read_b128 v[182:185], v152 offset:33792
	ds_read_b128 v[186:189], v151 offset:32768
	ds_read_b128 v[190:193], v151 offset:33792
	ds_read_b128 v[194:197], v150 offset:32768
	ds_read_b128 v[198:201], v150 offset:33792
	ds_read_b128 v[202:205], v149 offset:32768
	ds_read_b128 v[206:209], v149 offset:33792
	s_waitcnt lgkmcnt(8)
	s_barrier
	s_waitcnt lgkmcnt(0)
	s_setprio 1
	s_waitcnt lgkmcnt(0)
	v_mfma_f32_16x16x32_bf16 v[124:127], v[162:165], v[178:181], v[124:127]
	v_mfma_f32_16x16x32_bf16 v[120:123], v[170:173], v[178:181], v[120:123]
	v_mfma_f32_16x16x32_bf16 v[116:119], v[162:165], v[186:189], v[116:119]
	v_mfma_f32_16x16x32_bf16 v[112:115], v[170:173], v[186:189], v[112:115]
	v_mfma_f32_16x16x32_bf16 v[108:111], v[162:165], v[194:197], v[108:111]
	v_mfma_f32_16x16x32_bf16 v[104:107], v[170:173], v[194:197], v[104:107]
	v_mfma_f32_16x16x32_bf16 v[100:103], v[162:165], v[202:205], v[100:103]
	v_mfma_f32_16x16x32_bf16 v[96:99], v[170:173], v[202:205], v[96:99]
	v_mfma_f32_16x16x32_bf16 v[124:127], v[166:169], v[182:185], v[124:127]
	v_mfma_f32_16x16x32_bf16 v[120:123], v[174:177], v[182:185], v[120:123]
	v_mfma_f32_16x16x32_bf16 v[116:119], v[166:169], v[190:193], v[116:119]
	v_mfma_f32_16x16x32_bf16 v[112:115], v[174:177], v[190:193], v[112:115]
	v_mfma_f32_16x16x32_bf16 v[108:111], v[166:169], v[198:201], v[108:111]
	v_mfma_f32_16x16x32_bf16 v[104:107], v[174:177], v[198:201], v[104:107]
	v_mfma_f32_16x16x32_bf16 v[100:103], v[166:169], v[206:209], v[100:103]
	v_mfma_f32_16x16x32_bf16 v[96:99], v[174:177], v[206:209], v[96:99]
	s_setprio 0
	s_barrier
	v_readfirstlane_b32 s36, v141
	v_lshl_add_u64 v[226:227], v[130:131], 0, s[56:57]
	s_mov_b32 m0, s36
	v_readfirstlane_b32 s36, v140
	ds_read_b128 v[210:213], v153
	ds_read_b128 v[214:217], v153 offset:1024
	ds_read_b128 v[218:221], v153 offset:2048
	ds_read_b128 v[222:225], v153 offset:3072
	global_load_lds_dwordx4 v[226:227], off
	v_lshl_add_u64 v[226:227], v[130:131], 0, s[58:59]
	s_mov_b32 m0, s36
	s_nop 0
	global_load_lds_dwordx4 v[226:227], off
	s_barrier
	s_waitcnt lgkmcnt(0)
	s_setprio 1
	s_waitcnt lgkmcnt(0)
	v_mfma_f32_16x16x32_bf16 v[92:95], v[210:213], v[178:181], v[92:95]
	v_mfma_f32_16x16x32_bf16 v[88:91], v[218:221], v[178:181], v[88:91]
	v_mfma_f32_16x16x32_bf16 v[84:87], v[210:213], v[186:189], v[84:87]
	v_mfma_f32_16x16x32_bf16 v[80:83], v[218:221], v[186:189], v[80:83]
	v_mfma_f32_16x16x32_bf16 v[76:79], v[210:213], v[194:197], v[76:79]
	v_mfma_f32_16x16x32_bf16 v[72:75], v[218:221], v[194:197], v[72:75]
	v_mfma_f32_16x16x32_bf16 v[68:71], v[210:213], v[202:205], v[68:71]
	v_mfma_f32_16x16x32_bf16 v[64:67], v[218:221], v[202:205], v[64:67]
	v_mfma_f32_16x16x32_bf16 v[92:95], v[214:217], v[182:185], v[92:95]
	v_mfma_f32_16x16x32_bf16 v[88:91], v[222:225], v[182:185], v[88:91]
	v_mfma_f32_16x16x32_bf16 v[84:87], v[214:217], v[190:193], v[84:87]
	v_mfma_f32_16x16x32_bf16 v[80:83], v[222:225], v[190:193], v[80:83]
	v_mfma_f32_16x16x32_bf16 v[76:79], v[214:217], v[198:201], v[76:79]
	v_mfma_f32_16x16x32_bf16 v[72:75], v[222:225], v[198:201], v[72:75]
	v_mfma_f32_16x16x32_bf16 v[68:71], v[214:217], v[206:209], v[68:71]
	v_mfma_f32_16x16x32_bf16 v[64:67], v[222:225], v[206:209], v[64:67]
	s_setprio 0
	v_readfirstlane_b32 s36, v139
	v_lshl_add_u64 v[226:227], v[132:133], 0, s[60:61]
	s_mov_b32 m0, s36
	v_readfirstlane_b32 s36, v138
	s_barrier
	ds_read_b128 v[178:181], v152 offset:49152
	ds_read_b128 v[182:185], v152 offset:50176
	ds_read_b128 v[186:189], v151 offset:49152
	ds_read_b128 v[190:193], v151 offset:50176
	ds_read_b128 v[194:197], v150 offset:49152
	ds_read_b128 v[198:201], v150 offset:50176
	ds_read_b128 v[202:205], v149 offset:49152
	ds_read_b128 v[206:209], v149 offset:50176
	global_load_lds_dwordx4 v[226:227], off
	s_mov_b32 m0, s36
	s_nop 0
	global_load_lds_dwordx4 v[132:133], off
	s_barrier
	s_waitcnt lgkmcnt(0)
	s_setprio 1
	s_waitcnt lgkmcnt(0)
	v_mfma_f32_16x16x32_bf16 v[60:63], v[162:165], v[178:181], v[60:63]
	v_mfma_f32_16x16x32_bf16 v[56:59], v[170:173], v[178:181], v[56:59]
	v_mfma_f32_16x16x32_bf16 v[52:55], v[162:165], v[186:189], v[52:55]
	v_mfma_f32_16x16x32_bf16 v[48:51], v[170:173], v[186:189], v[48:51]
	v_mfma_f32_16x16x32_bf16 v[44:47], v[162:165], v[194:197], v[44:47]
	v_mfma_f32_16x16x32_bf16 v[40:43], v[170:173], v[194:197], v[40:43]
	v_mfma_f32_16x16x32_bf16 v[36:39], v[162:165], v[202:205], v[36:39]
	v_mfma_f32_16x16x32_bf16 v[32:35], v[170:173], v[202:205], v[32:35]
	v_mfma_f32_16x16x32_bf16 v[60:63], v[166:169], v[182:185], v[60:63]
	v_mfma_f32_16x16x32_bf16 v[56:59], v[174:177], v[182:185], v[56:59]
	v_mfma_f32_16x16x32_bf16 v[52:55], v[166:169], v[190:193], v[52:55]
	v_mfma_f32_16x16x32_bf16 v[48:51], v[174:177], v[190:193], v[48:51]
	v_mfma_f32_16x16x32_bf16 v[44:47], v[166:169], v[198:201], v[44:47]
	v_mfma_f32_16x16x32_bf16 v[40:43], v[174:177], v[198:201], v[40:43]
	v_mfma_f32_16x16x32_bf16 v[36:39], v[166:169], v[206:209], v[36:39]
	v_mfma_f32_16x16x32_bf16 v[32:35], v[174:177], v[206:209], v[32:35]
	s_setprio 0
	s_barrier
	v_readfirstlane_b32 s36, v137
	v_lshl_add_u64 v[162:163], v[130:131], 0, s[60:61]
	s_mov_b32 m0, s36
	v_readfirstlane_b32 s36, v136
	global_load_lds_dwordx4 v[162:163], off
	s_mov_b32 m0, s36
	s_nop 0
	global_load_lds_dwordx4 v[130:131], off
	v_lshl_add_u64 v[132:133], v[132:133], 0, s[64:65]
	v_readfirstlane_b32 s36, v160
	v_lshl_add_u64 v[164:165], v[132:133], 0, s[22:23]
	s_mov_b32 m0, s36
	v_readfirstlane_b32 s36, v159
	global_load_lds_dwordx4 v[164:165], off
	v_lshl_add_u64 v[164:165], v[132:133], 0, s[24:25]
	s_mov_b32 m0, s36
	s_nop 0
	global_load_lds_dwordx4 v[164:165], off
	s_waitcnt vmcnt(8)
	s_barrier
	s_setprio 1
	v_mfma_f32_16x16x32_bf16 v[28:31], v[210:213], v[178:181], v[28:31]
	v_mfma_f32_16x16x32_bf16 v[24:27], v[218:221], v[178:181], v[24:27]
	v_mfma_f32_16x16x32_bf16 v[20:23], v[210:213], v[186:189], v[20:23]
	v_mfma_f32_16x16x32_bf16 v[16:19], v[218:221], v[186:189], v[16:19]
	v_mfma_f32_16x16x32_bf16 v[12:15], v[210:213], v[194:197], v[12:15]
	v_mfma_f32_16x16x32_bf16 v[8:11], v[218:221], v[194:197], v[8:11]
	v_mfma_f32_16x16x32_bf16 v[4:7], v[210:213], v[202:205], v[4:7]
	v_mfma_f32_16x16x32_bf16 v[0:3], v[218:221], v[202:205], v[0:3]
	v_mfma_f32_16x16x32_bf16 v[28:31], v[214:217], v[182:185], v[28:31]
	v_mfma_f32_16x16x32_bf16 v[24:27], v[222:225], v[182:185], v[24:27]
	v_mfma_f32_16x16x32_bf16 v[20:23], v[214:217], v[190:193], v[20:23]
	v_mfma_f32_16x16x32_bf16 v[16:19], v[222:225], v[190:193], v[16:19]
	v_mfma_f32_16x16x32_bf16 v[12:15], v[214:217], v[198:201], v[12:15]
	v_mfma_f32_16x16x32_bf16 v[8:11], v[222:225], v[198:201], v[8:11]
	v_mfma_f32_16x16x32_bf16 v[4:7], v[214:217], v[206:209], v[4:7]
	v_mfma_f32_16x16x32_bf16 v[0:3], v[222:225], v[206:209], v[0:3]
	s_setprio 0
	v_lshl_add_u64 v[130:131], v[130:131], 0, s[62:63]
	s_cmp_lt_u32 s68, s67
	s_barrier
	s_cbranch_scc1 .LBB0_561
	s_lshl_b32 s36, s86, 5
	s_lshl_b32 s37, s86, 8
	s_and_b32 s36, s36, 0x1800
	s_and_b32 s37, s37, 0x700
	s_or_b32 s96, s37, s36
	s_lshl_b32 s36, s96, 6
	s_add_u32 s36, s70, s36
	s_addc_u32 s37, s71, 0
	s_add_i32 s20, s20, -1
	s_lshl_b64 s[68:69], s[20:21], 20
	v_add_u32_e32 v128, v156, v157
	s_add_u32 s68, s36, s68
	v_or_b32_e32 v128, v128, v155
	s_addc_u32 s69, s37, s69
	v_lshl_add_u64 v[156:157], s[68:69], 0, v[128:129]
	v_readfirstlane_b32 s20, v160
	v_lshl_add_u64 v[206:207], v[156:157], 0, s[4:5]
	s_mov_b32 m0, s20
	v_readfirstlane_b32 s20, v159
	ds_read_b128 v[130:133], v161
	ds_read_b128 v[162:165], v161 offset:1024
	ds_read_b128 v[166:169], v161 offset:2048
	ds_read_b128 v[170:173], v161 offset:3072
	ds_read_b128 v[174:177], v152
	ds_read_b128 v[178:181], v152 offset:1024
	ds_read_b128 v[182:185], v151
	ds_read_b128 v[186:189], v151 offset:1024
	ds_read_b128 v[190:193], v150
	ds_read_b128 v[194:197], v150 offset:1024
	ds_read_b128 v[198:201], v149
	ds_read_b128 v[202:205], v149 offset:1024
	global_load_lds_dwordx4 v[206:207], off
	v_lshl_add_u64 v[156:157], v[156:157], 0, s[6:7]
	s_mov_b32 m0, s20
	s_nop 0
	global_load_lds_dwordx4 v[156:157], off
	s_barrier
	s_waitcnt lgkmcnt(0)
	s_setprio 1
	s_waitcnt lgkmcnt(0)
	v_mfma_f32_16x16x32_bf16 v[124:127], v[130:133], v[174:177], v[124:127]
	v_mfma_f32_16x16x32_bf16 v[120:123], v[166:169], v[174:177], v[120:123]
	v_mfma_f32_16x16x32_bf16 v[116:119], v[130:133], v[182:185], v[116:119]
	v_mfma_f32_16x16x32_bf16 v[112:115], v[166:169], v[182:185], v[112:115]
	v_mfma_f32_16x16x32_bf16 v[108:111], v[130:133], v[190:193], v[108:111]
	v_mfma_f32_16x16x32_bf16 v[104:107], v[166:169], v[190:193], v[104:107]
	v_mfma_f32_16x16x32_bf16 v[100:103], v[130:133], v[198:201], v[100:103]
	v_mfma_f32_16x16x32_bf16 v[96:99], v[166:169], v[198:201], v[96:99]
	v_mfma_f32_16x16x32_bf16 v[124:127], v[162:165], v[178:181], v[124:127]
	v_mfma_f32_16x16x32_bf16 v[120:123], v[170:173], v[178:181], v[120:123]
	v_mfma_f32_16x16x32_bf16 v[116:119], v[162:165], v[186:189], v[116:119]
	v_mfma_f32_16x16x32_bf16 v[112:115], v[170:173], v[186:189], v[112:115]
	v_mfma_f32_16x16x32_bf16 v[108:111], v[162:165], v[194:197], v[108:111]
	v_mfma_f32_16x16x32_bf16 v[104:107], v[170:173], v[194:197], v[104:107]
	v_mfma_f32_16x16x32_bf16 v[100:103], v[162:165], v[202:205], v[100:103]
	v_mfma_f32_16x16x32_bf16 v[96:99], v[170:173], v[202:205], v[96:99]
	s_setprio 0
	s_barrier
	ds_read_b128 v[206:209], v158
	ds_read_b128 v[210:213], v158 offset:1024
	ds_read_b128 v[214:217], v158 offset:2048
	ds_read_b128 v[156:159], v158 offset:3072
	s_barrier
	s_waitcnt lgkmcnt(0)
	s_setprio 1
	s_waitcnt lgkmcnt(0)
	v_mfma_f32_16x16x32_bf16 v[92:95], v[206:209], v[174:177], v[92:95]
	v_mfma_f32_16x16x32_bf16 v[88:91], v[214:217], v[174:177], v[88:91]
	v_mfma_f32_16x16x32_bf16 v[84:87], v[206:209], v[182:185], v[84:87]
	v_mfma_f32_16x16x32_bf16 v[80:83], v[214:217], v[182:185], v[80:83]
	v_mfma_f32_16x16x32_bf16 v[76:79], v[206:209], v[190:193], v[76:79]
	v_mfma_f32_16x16x32_bf16 v[72:75], v[214:217], v[190:193], v[72:75]
	v_mfma_f32_16x16x32_bf16 v[68:71], v[206:209], v[198:201], v[68:71]
	v_mfma_f32_16x16x32_bf16 v[64:67], v[214:217], v[198:201], v[64:67]
	v_mfma_f32_16x16x32_bf16 v[174:177], v[210:213], v[178:181], v[92:95]
	v_mfma_f32_16x16x32_bf16 v[178:181], v[156:159], v[178:181], v[88:91]
	v_mfma_f32_16x16x32_bf16 v[182:185], v[210:213], v[186:189], v[84:87]
	v_mfma_f32_16x16x32_bf16 v[186:189], v[156:159], v[186:189], v[80:83]
	v_mfma_f32_16x16x32_bf16 v[190:193], v[210:213], v[194:197], v[76:79]
	v_mfma_f32_16x16x32_bf16 v[194:197], v[156:159], v[194:197], v[72:75]
	v_mfma_f32_16x16x32_bf16 v[198:201], v[210:213], v[202:205], v[68:71]
	v_mfma_f32_16x16x32_bf16 v[202:205], v[156:159], v[202:205], v[64:67]
	s_setprio 0
	s_barrier
	s_nop 0
	ds_read_b128 v[64:67], v152 offset:16384
	ds_read_b128 v[68:71], v152 offset:17408
	ds_read_b128 v[72:75], v151 offset:16384
	ds_read_b128 v[76:79], v151 offset:17408
	ds_read_b128 v[80:83], v150 offset:16384
	ds_read_b128 v[84:87], v150 offset:17408
	ds_read_b128 v[88:91], v149 offset:16384
	ds_read_b128 v[92:95], v149 offset:17408
	s_waitcnt vmcnt(4)
	s_barrier
	s_waitcnt lgkmcnt(0)
	s_setprio 1
	s_waitcnt lgkmcnt(0)
	v_mfma_f32_16x16x32_bf16 v[60:63], v[130:133], v[64:67], v[60:63]
	v_mfma_f32_16x16x32_bf16 v[56:59], v[166:169], v[64:67], v[56:59]
	v_mfma_f32_16x16x32_bf16 v[52:55], v[130:133], v[72:75], v[52:55]
	v_mfma_f32_16x16x32_bf16 v[48:51], v[166:169], v[72:75], v[48:51]
	v_mfma_f32_16x16x32_bf16 v[218:221], v[130:133], v[80:83], v[44:47]
	v_mfma_f32_16x16x32_bf16 v[222:225], v[166:169], v[80:83], v[40:43]
	v_mfma_f32_16x16x32_bf16 v[130:133], v[130:133], v[88:91], v[36:39]
	v_mfma_f32_16x16x32_bf16 v[166:169], v[166:169], v[88:91], v[32:35]
	v_mfma_f32_16x16x32_bf16 v[32:35], v[162:165], v[68:71], v[60:63]
	v_mfma_f32_16x16x32_bf16 v[36:39], v[170:173], v[68:71], v[56:59]
	v_mfma_f32_16x16x32_bf16 v[40:43], v[162:165], v[76:79], v[52:55]
	v_mfma_f32_16x16x32_bf16 v[44:47], v[170:173], v[76:79], v[48:51]
	v_mfma_f32_16x16x32_bf16 v[48:51], v[162:165], v[84:87], v[218:221]
	v_mfma_f32_16x16x32_bf16 v[52:55], v[170:173], v[84:87], v[222:225]
	v_mfma_f32_16x16x32_bf16 v[56:59], v[162:165], v[92:95], v[130:133]
	v_mfma_f32_16x16x32_bf16 v[60:63], v[170:173], v[92:95], v[166:169]
	s_setprio 0
	s_setprio 1
	v_mfma_f32_16x16x32_bf16 v[28:31], v[206:209], v[64:67], v[28:31]
	v_mfma_f32_16x16x32_bf16 v[24:27], v[214:217], v[64:67], v[24:27]
	v_mfma_f32_16x16x32_bf16 v[20:23], v[206:209], v[72:75], v[20:23]
	v_mfma_f32_16x16x32_bf16 v[64:67], v[214:217], v[72:75], v[16:19]
	v_mfma_f32_16x16x32_bf16 v[72:75], v[206:209], v[80:83], v[12:15]
	v_mfma_f32_16x16x32_bf16 v[8:11], v[214:217], v[80:83], v[8:11]
	v_mfma_f32_16x16x32_bf16 v[80:83], v[206:209], v[88:91], v[4:7]
	v_mfma_f32_16x16x32_bf16 v[0:3], v[214:217], v[88:91], v[0:3]
	v_mfma_f32_16x16x32_bf16 v[4:7], v[210:213], v[68:71], v[28:31]
	v_mfma_f32_16x16x32_bf16 v[12:15], v[156:159], v[68:71], v[24:27]
	v_mfma_f32_16x16x32_bf16 v[16:19], v[210:213], v[76:79], v[20:23]
	v_mfma_f32_16x16x32_bf16 v[20:23], v[156:159], v[76:79], v[64:67]
	v_mfma_f32_16x16x32_bf16 v[24:27], v[210:213], v[84:87], v[72:75]
	v_mfma_f32_16x16x32_bf16 v[28:31], v[156:159], v[84:87], v[8:11]
	v_mfma_f32_16x16x32_bf16 v[64:67], v[210:213], v[92:95], v[80:83]
	v_mfma_f32_16x16x32_bf16 v[68:71], v[156:159], v[92:95], v[0:3]
	s_setprio 0
	s_barrier
	ds_read_b128 v[8:11], v154
	ds_read_b128 v[0:3], v154 offset:1024
	ds_read_b128 v[76:79], v154 offset:2048
	ds_read_b128 v[72:75], v154 offset:3072
	ds_read_b128 v[130:133], v152 offset:32768
	ds_read_b128 v[154:157], v152 offset:33792
	ds_read_b128 v[158:161], v151 offset:32768
	ds_read_b128 v[162:165], v151 offset:33792
	ds_read_b128 v[166:169], v150 offset:32768
	ds_read_b128 v[170:173], v150 offset:33792
	ds_read_b128 v[206:209], v149 offset:32768
	ds_read_b128 v[210:213], v149 offset:33792
	s_waitcnt vmcnt(2)
	s_barrier
	s_waitcnt lgkmcnt(0)
	s_setprio 1
	s_waitcnt lgkmcnt(0)
	v_mfma_f32_16x16x32_bf16 v[80:83], v[8:11], v[130:133], v[124:127]
	v_mfma_f32_16x16x32_bf16 v[84:87], v[76:79], v[130:133], v[120:123]
	v_mfma_f32_16x16x32_bf16 v[88:91], v[8:11], v[158:161], v[116:119]
	v_mfma_f32_16x16x32_bf16 v[92:95], v[76:79], v[158:161], v[112:115]
	v_mfma_f32_16x16x32_bf16 v[108:111], v[8:11], v[166:169], v[108:111]
	v_mfma_f32_16x16x32_bf16 v[104:107], v[76:79], v[166:169], v[104:107]
	v_mfma_f32_16x16x32_bf16 v[100:103], v[8:11], v[206:209], v[100:103]
	v_mfma_f32_16x16x32_bf16 v[96:99], v[76:79], v[206:209], v[96:99]
	v_mfma_f32_16x16x32_bf16 v[112:115], v[0:3], v[154:157], v[80:83]
	v_mfma_f32_16x16x32_bf16 v[116:119], v[72:75], v[154:157], v[84:87]
	v_mfma_f32_16x16x32_bf16 v[120:123], v[0:3], v[162:165], v[88:91]
	v_mfma_f32_16x16x32_bf16 v[124:127], v[72:75], v[162:165], v[92:95]
	v_mfma_f32_16x16x32_bf16 v[108:111], v[0:3], v[170:173], v[108:111]
	v_mfma_f32_16x16x32_bf16 v[104:107], v[72:75], v[170:173], v[104:107]
	v_mfma_f32_16x16x32_bf16 v[100:103], v[0:3], v[210:213], v[100:103]
	v_mfma_f32_16x16x32_bf16 v[96:99], v[72:75], v[210:213], v[96:99]
	s_setprio 0
	s_barrier
	ds_read_b128 v[88:91], v153
	ds_read_b128 v[80:83], v153 offset:1024
	ds_read_b128 v[92:95], v153 offset:2048
	ds_read_b128 v[84:87], v153 offset:3072
	s_waitcnt vmcnt(0)
	s_barrier
	s_waitcnt lgkmcnt(0)
	s_setprio 1
	s_waitcnt lgkmcnt(0)
	v_mfma_f32_16x16x32_bf16 v[174:177], v[88:91], v[130:133], v[174:177]
	v_mfma_f32_16x16x32_bf16 v[130:133], v[92:95], v[130:133], v[178:181]
	v_mfma_f32_16x16x32_bf16 v[178:181], v[88:91], v[158:161], v[182:185]
	v_mfma_f32_16x16x32_bf16 v[158:161], v[92:95], v[158:161], v[186:189]
	v_mfma_f32_16x16x32_bf16 v[182:185], v[88:91], v[166:169], v[190:193]
	v_mfma_f32_16x16x32_bf16 v[166:169], v[92:95], v[166:169], v[194:197]
	v_mfma_f32_16x16x32_bf16 v[186:189], v[88:91], v[206:209], v[198:201]
	v_mfma_f32_16x16x32_bf16 v[190:193], v[92:95], v[206:209], v[202:205]
	v_mfma_f32_16x16x32_bf16 v[174:177], v[80:83], v[154:157], v[174:177]
	v_mfma_f32_16x16x32_bf16 v[130:133], v[84:87], v[154:157], v[130:133]
	v_mfma_f32_16x16x32_bf16 v[154:157], v[80:83], v[162:165], v[178:181]
	v_mfma_f32_16x16x32_bf16 v[158:161], v[84:87], v[162:165], v[158:161]
	v_mfma_f32_16x16x32_bf16 v[162:165], v[80:83], v[170:173], v[182:185]
	v_mfma_f32_16x16x32_bf16 v[166:169], v[84:87], v[170:173], v[166:169]
	v_mfma_f32_16x16x32_bf16 v[170:173], v[80:83], v[210:213], v[186:189]
	v_mfma_f32_16x16x32_bf16 v[178:181], v[84:87], v[210:213], v[190:193]
	s_setprio 0
	s_barrier
	v_mbcnt_lo_u32_b32 v128, -1, 0
	v_mbcnt_hi_u32_b32 v128, -1, v128
	v_cvt_pk_bf16_f32 v112, v112, v113
	v_cvt_pk_bf16_f32 v113, v114, v115
	v_cvt_pk_bf16_f32 v114, v116, v117
	v_cvt_pk_bf16_f32 v115, v118, v119
	s_lshl_b32 s89, s66, 9
	v_add_u32_e32 v153, s74, v128
	v_ashrrev_i32_e32 v182, 6, v153
	v_and_b32_e32 v183, 15, v128
	v_and_b32_e32 v184, 48, v128
	v_mul_lo_u32 v185, v182, s79
	v_bfe_u32 v186, v128, 3, 3
	v_lshlrev_b32_e32 v128, 4, v128
	v_add_u32_e32 v185, 0x20000, v185
	v_lshrrev_b32_e32 v153, 2, v153
	v_and_b32_e32 v128, 0x70, v128
	v_mul_u32_u24_e32 v183, 0x90, v183
	v_and_b32_e32 v153, 64, v153
	v_add3_u32 v183, v185, v183, v184
	v_or_b32_e32 v184, v185, v128
	v_or3_b32 v153, s96, v153, v186
	v_mad_u32_u24 v184, v186, s81, v184
	ds_write_b128 v183, v[112:115]
	v_cvt_pk_bf16_f32 v112, v174, v175
	v_cvt_pk_bf16_f32 v113, v176, v177
	v_cvt_pk_bf16_f32 v114, v130, v131
	v_cvt_pk_bf16_f32 v115, v132, v133
	ds_write_b128 v183, v[112:115] offset:64
	v_lshlrev_b32_e32 v182, 7, v182
	ds_read_b128 v[112:115], v184
	v_lshlrev_b32_e32 v116, 12, v153
	v_and_or_b32 v116, v182, s82, v116
	v_or3_b32 v128, v116, s89, v128
	ds_read_b128 v[116:119], v184 offset:1152
	v_lshl_add_u64 v[130:131], s[0:1], 0, v[128:129]
	s_mov_b32 s20, 0x8000
	s_waitcnt lgkmcnt(0)
	global_store_dwordx4 v128, v[112:115], s[0:1]
	v_cvt_pk_bf16_f32 v108, v108, v109
	v_cvt_pk_bf16_f32 v109, v110, v111
	v_cvt_pk_bf16_f32 v110, v104, v105
	v_cvt_pk_bf16_f32 v111, v106, v107
	v_cvt_pk_bf16_f32 v104, v162, v163
	s_nop 1
	v_add_co_u32_e32 v112, vcc, s20, v130
	v_cvt_pk_bf16_f32 v114, v124, v125
	v_cvt_pk_bf16_f32 v115, v126, v127
	v_cvt_pk_bf16_f32 v105, v164, v165
	v_cvt_pk_bf16_f32 v106, v166, v167
	s_nop 1
	v_addc_co_u32_e32 v113, vcc, 0, v131, vcc
	global_store_dwordx4 v[112:113], v[116:119], off
	v_cvt_pk_bf16_f32 v112, v120, v121
	v_cvt_pk_bf16_f32 v113, v122, v123
	ds_write_b128 v183, v[112:115]
	v_cvt_pk_bf16_f32 v112, v154, v155
	v_cvt_pk_bf16_f32 v113, v156, v157
	v_cvt_pk_bf16_f32 v114, v158, v159
	v_cvt_pk_bf16_f32 v115, v160, v161
	ds_write_b128 v183, v[112:115] offset:64
	ds_read_b128 v[112:115], v184
	ds_read_b128 v[116:119], v184 offset:1152
	v_add_co_u32_e32 v120, vcc, s76, v130
	ds_write_b128 v183, v[108:111]
	v_cvt_pk_bf16_f32 v107, v168, v169
	ds_write_b128 v183, v[104:107] offset:64
	v_addc_co_u32_e32 v121, vcc, 0, v131, vcc
	ds_read_b128 v[104:107], v184
	ds_read_b128 v[108:111], v184 offset:1152
	s_waitcnt lgkmcnt(0)
	global_store_dwordx4 v[120:121], v[112:115], off
	v_cvt_pk_bf16_f32 v100, v100, v101
	v_cvt_pk_bf16_f32 v101, v102, v103
	v_cvt_pk_bf16_f32 v102, v96, v97
	v_cvt_pk_bf16_f32 v103, v98, v99
	ds_write_b128 v183, v[100:103]
	s_nop 0
	v_add_co_u32_e32 v112, vcc, s77, v130
	v_cvt_pk_bf16_f32 v96, v170, v171
	v_cvt_pk_bf16_f32 v97, v172, v173
	v_cvt_pk_bf16_f32 v98, v178, v179
	v_cvt_pk_bf16_f32 v99, v180, v181
	s_nop 1
	v_addc_co_u32_e32 v113, vcc, 0, v131, vcc
	global_store_dwordx4 v[112:113], v[116:119], off
	v_add_co_u32_e32 v112, vcc, s80, v130
	ds_write_b128 v183, v[96:99] offset:64
	s_nop 0
	v_addc_co_u32_e32 v113, vcc, 0, v131, vcc
	ds_read_b128 v[96:99], v184
	ds_read_b128 v[100:103], v184 offset:1152
	global_store_dwordx4 v[112:113], v[104:107], off
	s_nop 1
	v_add_co_u32_e32 v104, vcc, s83, v130
	s_nop 1
	v_addc_co_u32_e32 v105, vcc, 0, v131, vcc
	global_store_dwordx4 v[104:105], v[108:111], off
	v_add_co_u32_e32 v104, vcc, s85, v130
	s_nop 1
	v_addc_co_u32_e32 v105, vcc, 0, v131, vcc
	s_waitcnt lgkmcnt(0)
	global_store_dwordx4 v[104:105], v[96:99], off
	s_nop 1
	v_add_co_u32_e32 v96, vcc, s87, v130
	s_nop 1
	v_addc_co_u32_e32 v97, vcc, 0, v131, vcc
	global_store_dwordx4 v[96:97], v[100:103], off
	ds_read_b128 v[96:99], v152 offset:49152
	ds_read_b128 v[100:103], v152 offset:50176
	ds_read_b128 v[104:107], v151 offset:49152
	ds_read_b128 v[108:111], v151 offset:50176
	ds_read_b128 v[112:115], v150 offset:49152
	ds_read_b128 v[116:119], v150 offset:50176
	ds_read_b128 v[120:123], v149 offset:49152
	ds_read_b128 v[124:127], v149 offset:50176
	s_barrier
	s_waitcnt lgkmcnt(0)
	s_setprio 1
	s_waitcnt lgkmcnt(0)
	v_mfma_f32_16x16x32_bf16 v[32:35], v[8:11], v[96:99], v[32:35]
	v_mfma_f32_16x16x32_bf16 v[36:39], v[76:79], v[96:99], v[36:39]
	v_mfma_f32_16x16x32_bf16 v[40:43], v[8:11], v[104:107], v[40:43]
	v_mfma_f32_16x16x32_bf16 v[130:133], v[76:79], v[104:107], v[44:47]
	v_mfma_f32_16x16x32_bf16 v[150:153], v[8:11], v[112:115], v[48:51]
	v_mfma_f32_16x16x32_bf16 v[52:55], v[76:79], v[112:115], v[52:55]
	v_mfma_f32_16x16x32_bf16 v[8:11], v[8:11], v[120:123], v[56:59]
	v_mfma_f32_16x16x32_bf16 v[60:63], v[76:79], v[120:123], v[60:63]
	v_mfma_f32_16x16x32_bf16 v[56:59], v[0:3], v[100:103], v[32:35]
	v_mfma_f32_16x16x32_bf16 v[48:51], v[72:75], v[100:103], v[36:39]
	v_mfma_f32_16x16x32_bf16 v[44:47], v[0:3], v[108:111], v[40:43]
	v_mfma_f32_16x16x32_bf16 v[40:43], v[72:75], v[108:111], v[130:133]
	v_mfma_f32_16x16x32_bf16 v[36:39], v[0:3], v[116:119], v[150:153]
	v_mfma_f32_16x16x32_bf16 v[32:35], v[72:75], v[116:119], v[52:55]
	v_mfma_f32_16x16x32_bf16 v[8:11], v[0:3], v[124:127], v[8:11]
	v_mfma_f32_16x16x32_bf16 v[0:3], v[72:75], v[124:127], v[60:63]
	s_setprio 0
	s_setprio 1
	v_mfma_f32_16x16x32_bf16 v[4:7], v[88:91], v[96:99], v[4:7]
	v_mfma_f32_16x16x32_bf16 v[12:15], v[92:95], v[96:99], v[12:15]
	v_mfma_f32_16x16x32_bf16 v[16:19], v[88:91], v[104:107], v[16:19]
	v_mfma_f32_16x16x32_bf16 v[20:23], v[92:95], v[104:107], v[20:23]
	v_mfma_f32_16x16x32_bf16 v[72:75], v[88:91], v[112:115], v[24:27]
	v_mfma_f32_16x16x32_bf16 v[76:79], v[92:95], v[112:115], v[28:31]
	v_mfma_f32_16x16x32_bf16 v[64:67], v[88:91], v[120:123], v[64:67]
	v_mfma_f32_16x16x32_bf16 v[68:71], v[92:95], v[120:123], v[68:71]
	v_mfma_f32_16x16x32_bf16 v[60:63], v[80:83], v[100:103], v[4:7]
	v_mfma_f32_16x16x32_bf16 v[52:55], v[84:87], v[100:103], v[12:15]
	v_mfma_f32_16x16x32_bf16 v[28:31], v[80:83], v[108:111], v[16:19]
	v_mfma_f32_16x16x32_bf16 v[24:27], v[84:87], v[108:111], v[20:23]
	v_mfma_f32_16x16x32_bf16 v[20:23], v[80:83], v[116:119], v[72:75]
	v_mfma_f32_16x16x32_bf16 v[16:19], v[84:87], v[116:119], v[76:79]
	v_mfma_f32_16x16x32_bf16 v[12:15], v[80:83], v[124:127], v[64:67]
	v_mfma_f32_16x16x32_bf16 v[4:7], v[84:87], v[124:127], v[68:71]
	s_setprio 0
	v_cmp_gt_u32_e32 vcc, s88, v135
	s_barrier
	s_and_saveexec_b64 s[66:67], vcc
	s_cbranch_execz .LBB0_564
	s_barrier
